# dense attention: V fragment buffers shared between the two PV accumulator chains, o0 chain then o1 chain; grid-barrier polls without s_sleep; packed f32 VALU ops split into single ops
# speedup vs baseline: 1.0060x; 1.0060x over previous
; __global__ void __launch_bounds__(256, 2) mega(Params p, int ph_lo, int ph_hi) {
;     ...
;   if (ph_hi == 12345) grid.sync();
.LBB0_14:
	s_nop 0
	global_load_dword v2, v0, s[6:7] offset:32 sc1
	s_waitcnt vmcnt(0)
	v_and_b32_e32 v2, 0xffff0000, v2
	v_cmp_ne_u32_e32 vcc, v2, v1
	s_or_b64 s[8:9], vcc, s[8:9]
	s_andn2_b64 exec, exec, s[8:9]
	s_cbranch_execnz .LBB0_14

; DI int otid() { int t; asm volatile("v_mov_b32 %0, %1" : "=v"(t) : "v"((int)threadIdx.x)); __builtin_assume(t >= 0 && t < 256); return t; }
; DI void norm_rows_f32(float* io, const float* __restrict__ g, int item) {
;   const int lane = otid() & 63, wid = otid() >> 6;
;   for (int i = 0; i < 8; ++i) {
;     size_t row = (size_t)item * 32 + wid * 8 + i;
;     float4* s = (float4*)(io + row * 1024);
;     float4 v[4]; float ss = 0.f;
; #pragma unroll
;     for (int j = 0; j < 4; ++j) { v[j] = s[lane + 64 * j]; ss += v[j].x * v[j].x + v[j].y * v[j].y + v[j].z * v[j].z + v[j].w * v[j].w; }
;     ss = wave_sum(ss);
;     float sc = rsqrtf(ss * (1.0f / 1024.0f) + 1e-6f);
; #pragma unroll
;     for (int j = 0; j < 4; ++j) {
;       float4 gg = ((const float4*)g)[lane + 64 * j];
;       float4 o; o.x = v[j].x * sc * gg.x; o.y = v[j].y * sc * gg.y; o.z = v[j].z * sc * gg.z; o.w = v[j].w * sc * gg.w;
;       s[lane + 64 * j] = o;
;     }
;   }
; }
.LBB0_28:
	v_cmp_lt_i32_e32 vcc, v252, v189
	v_mov_b32 v4, v188
	v_mov_b32 v0, v188
	v_mov_b32_e32 v3, v1
	v_lshlrev_b32_e32 v0, 9, v0
	v_cndmask_b32_e32 v2, v204, v252, vcc
	v_cmp_lt_i32_e32 vcc, v191, v189
	v_lshlrev_b32_e32 v74, 2, v2
	v_and_b32_e32 v0, 0x18000, v0
	v_cndmask_b32_e32 v2, v204, v191, vcc
	v_cmp_lt_i32_e32 vcc, v192, v189
	v_lshlrev_b32_e32 v75, 2, v2
	s_add_i32 s6, s6, s26
	v_cndmask_b32_e32 v2, v204, v192, vcc
	v_cmp_lt_i32_e32 vcc, v193, v189
	v_lshlrev_b32_e32 v76, 2, v2
	s_nop 0
	v_cndmask_b32_e32 v2, v204, v193, vcc
	v_cmp_lt_i32_e32 vcc, v194, v189
	v_lshlrev_b32_e32 v77, 2, v2
	s_nop 0
	v_cndmask_b32_e32 v2, v204, v194, vcc
	v_cmp_lt_i32_e32 vcc, v195, v189
	v_lshlrev_b32_e32 v78, 2, v2
	s_nop 0
	v_cndmask_b32_e32 v2, v204, v195, vcc
	v_lshlrev_b32_e32 v79, 2, v2
	v_lshlrev_b32_e32 v2, 4, v4
	v_and_b32_e32 v80, 0x3f0, v2
	v_or_b32_e32 v2, v0, v80
	v_lshl_add_u64 v[58:59], s[22:23], 0, v[2:3]
	v_or_b32_e32 v2, 0xc0, v4
	v_lshlrev_b64 v[2:3], 4, v[2:3]
	v_lshl_add_u64 v[4:5], v[0:1], 0, v[2:3]
	v_lshl_add_u64 v[62:63], s[22:23], 0, v[4:5]
	v_lshl_add_u64 v[60:61], s[54:55], 0, v[2:3]
	global_load_dwordx4 v[18:21], v[62:63], off
	global_load_dwordx2 v[50:51], v[60:61], off
	global_load_dwordx4 v[2:5], v[60:61], off
	global_load_dwordx4 v[30:33], v[58:59], off
	global_load_dwordx2 v[54:55], v80, s[54:55]
	global_load_dwordx4 v[10:13], v80, s[54:55]
	global_load_dwordx4 v[26:29], v[58:59], off offset:1024
	global_load_dwordx2 v[52:53], v80, s[54:55] offset:1024
	global_load_dwordx4 v[6:9], v80, s[54:55] offset:1024
	v_add_co_u32_e32 v64, vcc, s11, v62
	s_add_u32 s22, s22, s78
	s_nop 0
	v_addc_co_u32_e32 v65, vcc, 0, v63, vcc
	v_add_co_u32_e32 v68, vcc, s85, v58
	s_addc_u32 s23, s23, s79
	s_nop 0
	v_addc_co_u32_e32 v69, vcc, 0, v59, vcc
	v_add_co_u32_e32 v66, vcc, s11, v58
	s_cmpk_gt_i32 s6, 0x3ff
	s_nop 0
	v_addc_co_u32_e32 v67, vcc, 0, v59, vcc
	s_waitcnt vmcnt(8)
	v_mov_b32_e32 v25, v19
	v_mov_b32_e32 v39, v21
	s_waitcnt vmcnt(5)
	v_mov_b32_e32 v16, v31
	v_mov_b32_e32 v14, v30
	v_mov_b32_e32 v22, v33
	s_waitcnt vmcnt(2)
	v_mov_b32_e32 v17, v27
	v_mov_b32_e32 v15, v26
	v_mul_f32_e32 v16, v16, v16
	v_mul_f32_e32 v17, v17, v17
	v_mov_b32_e32 v23, v29
	v_fma_f32 v14, v14, v14, v16
	v_fma_f32 v15, v15, v15, v17
	v_mov_b32_e32 v16, v32
	v_mov_b32_e32 v17, v28
	v_fma_f32 v14, v16, v16, v14
	v_fma_f32 v15, v17, v17, v15
	s_nop 0
	v_fma_f32 v70, v22, v22, v14
	v_fma_f32 v71, v23, v23, v15
	global_load_dwordx4 v[34:37], v[58:59], off offset:2048
	global_load_dwordx2 v[56:57], v80, s[54:55] offset:2048
	global_load_dwordx4 v[14:17], v80, s[54:55] offset:2048
	v_mov_b32_e32 v23, v18
	s_waitcnt vmcnt(2)
	v_mov_b32_e32 v24, v35
	v_mov_b32_e32 v22, v34
	v_mul_f32_e32 v24, v24, v24
	v_mul_f32_e32 v25, v25, v25
	v_mov_b32_e32 v38, v37
	v_fma_f32 v22, v22, v22, v24
	v_fma_f32 v23, v23, v23, v25
	v_mov_b32_e32 v24, v36
	v_mov_b32_e32 v25, v20
	v_fma_f32 v22, v24, v24, v22
	v_fma_f32 v23, v25, v25, v23
	s_nop 0
	v_fma_f32 v72, v38, v38, v22
	v_fma_f32 v73, v39, v39, v23
	global_load_dwordx4 v[22:25], v[64:65], off offset:-4096
	global_load_dwordx4 v[42:45], v[66:67], off offset:-4096
	global_load_dwordx4 v[38:41], v[68:69], off offset:1024
	s_waitcnt vmcnt(1)
	v_mov_b32_e32 v48, v43
	s_waitcnt vmcnt(0)
	v_mov_b32_e32 v49, v39
	v_mov_b32_e32 v46, v42
	v_mov_b32_e32 v47, v38
	v_mul_f32_e32 v48, v48, v48
	v_mul_f32_e32 v49, v49, v49
	v_mov_b32_e32 v82, v45
	v_fma_f32 v46, v46, v46, v48
	v_fma_f32 v47, v47, v47, v49
	v_mov_b32_e32 v48, v44
	v_mov_b32_e32 v49, v40
	v_mov_b32_e32 v83, v41
	v_fma_f32 v46, v48, v48, v46
	v_fma_f32 v47, v49, v49, v47
	v_mov_b32_e32 v87, v23
	v_fma_f32 v82, v82, v82, v46
	v_fma_f32 v83, v83, v83, v47
	global_load_dwordx4 v[46:49], v[68:69], off offset:2048
	v_mov_b32_e32 v85, v22
	v_mov_b32_e32 v89, v25
	s_waitcnt vmcnt(0)
	v_mov_b32_e32 v86, v47
	v_mov_b32_e32 v84, v46
	v_mul_f32_e32 v86, v86, v86
	v_mul_f32_e32 v87, v87, v87
	v_mov_b32_e32 v88, v49
	v_fma_f32 v84, v84, v84, v86
	v_fma_f32 v85, v85, v85, v87
	v_mov_b32_e32 v86, v48
	v_mov_b32_e32 v87, v24
	v_fma_f32 v84, v86, v86, v84
	v_fma_f32 v85, v87, v87, v85
	v_mov_b32_e32 v86, v82
	v_fma_f32 v84, v88, v88, v84
	v_fma_f32 v85, v89, v89, v85
	v_mov_b32_e32 v87, v70
	v_mov_b32_e32 v70, v83
	v_add_f32_e32 v70, v86, v70
	v_add_f32_e32 v71, v87, v71
	v_mov_b32_e32 v82, v84
	v_mov_b32_e32 v83, v72
	v_add_f32_e32 v70, v70, v82
	v_add_f32_e32 v71, v71, v83
	v_mov_b32_e32 v72, v85
	v_add_f32_e32 v70, v70, v72
	v_add_f32_e32 v71, v71, v73
	ds_bpermute_b32 v73, v74, v71
	ds_bpermute_b32 v72, v74, v70
	s_waitcnt lgkmcnt(0)
	v_add_f32_e32 v70, v70, v72
	v_add_f32_e32 v71, v71, v73
	ds_bpermute_b32 v73, v75, v71
	ds_bpermute_b32 v72, v75, v70
	s_waitcnt lgkmcnt(0)
	v_add_f32_e32 v70, v70, v72
	v_add_f32_e32 v71, v71, v73
	ds_bpermute_b32 v73, v76, v71
	ds_bpermute_b32 v72, v76, v70
	s_waitcnt lgkmcnt(0)
	v_add_f32_e32 v70, v70, v72
	v_add_f32_e32 v71, v71, v73
	ds_bpermute_b32 v73, v77, v71
	ds_bpermute_b32 v72, v77, v70
	s_waitcnt lgkmcnt(0)
	v_add_f32_e32 v70, v70, v72
	v_add_f32_e32 v71, v71, v73
	ds_bpermute_b32 v73, v78, v71
	ds_bpermute_b32 v72, v78, v70
	s_waitcnt lgkmcnt(0)
	v_add_f32_e32 v70, v70, v72
	v_add_f32_e32 v71, v71, v73
	ds_bpermute_b32 v73, v79, v71
	ds_bpermute_b32 v72, v79, v70
	s_waitcnt lgkmcnt(0)
; DI int otid() { int t; asm volatile("v_mov_b32 %0, %1" : "=v"(t) : "v"((int)threadIdx.x)); __builtin_assume(t >= 0 && t < 256); return t; }
; DI void norm_rows_f32(float* io, const float* __restrict__ g, int item) {
;   const int lane = otid() & 63, wid = otid() >> 6;
;   for (int i = 0; i < 8; ++i) {
;     size_t row = (size_t)item * 32 + wid * 8 + i;
;     float4* s = (float4*)(io + row * 1024);
;     float4 v[4]; float ss = 0.f;
; #pragma unroll
;     for (int j = 0; j < 4; ++j) { v[j] = s[lane + 64 * j]; ss += v[j].x * v[j].x + v[j].y * v[j].y + v[j].z * v[j].z + v[j].w * v[j].w; }
;     ss = wave_sum(ss);
;     float sc = rsqrtf(ss * (1.0f / 1024.0f) + 1e-6f);
; #pragma unroll
;     for (int j = 0; j < 4; ++j) {
;       float4 gg = ((const float4*)g)[lane + 64 * j];
;       float4 o; o.x = v[j].x * sc * gg.x; o.y = v[j].y * sc * gg.y; o.z = v[j].z * sc * gg.z; o.w = v[j].w * sc * gg.w;
;       s[lane + 64 * j] = o;
;     }
;   }
; }
	v_add_f32_e32 v70, v70, v72
	v_add_f32_e32 v71, v71, v73
	v_mov_b64_e32 v[72:73], s[24:25]
	v_fma_f32 v70, v70, s14, v72
	v_fma_f32 v71, v71, s14, v72
	s_nop 0
	v_mul_f32_e32 v0, 0x4b800000, v71
	v_cmp_gt_f32_e64 s[0:1], s3, v71
	v_cmp_gt_f32_e32 vcc, s3, v70
	s_nop 0
	v_cndmask_b32_e64 v0, v71, v0, s[0:1]
	v_rsq_f32_e32 v0, v0
	s_nop 0
	v_mul_f32_e32 v71, 0x45800000, v0
	v_cndmask_b32_e64 v0, v0, v71, s[0:1]
	v_mul_f32_e32 v26, v26, v0
	v_mul_f32_e32 v27, v27, v0
	v_mul_f32_e32 v28, v28, v0
	v_mul_f32_e32 v29, v29, v0
	v_mul_f32_e32 v26, v52, v26
	v_mul_f32_e32 v27, v53, v27
	v_mul_f32_e32 v28, v8, v28
	v_mul_f32_e32 v29, v9, v29
	v_mul_f32_e32 v30, v30, v0
	v_mul_f32_e32 v31, v31, v0
	v_mul_f32_e32 v32, v32, v0
	v_mul_f32_e32 v33, v33, v0
	global_store_dwordx4 v[58:59], v[26:29], off offset:1024
	v_mul_f32_e32 v18, v18, v0
	v_mul_f32_e32 v19, v19, v0
	v_mul_f32_e32 v20, v20, v0
	v_mul_f32_e32 v21, v21, v0
	v_mul_f32_e32 v26, v34, v0
	v_mul_f32_e32 v27, v35, v0
	v_mul_f32_e32 v28, v36, v0
	v_mul_f32_e32 v29, v37, v0
	v_mul_f32_e32 v0, 0x4b800000, v70
	v_cndmask_b32_e32 v0, v70, v0, vcc
	v_rsq_f32_e32 v0, v0
	v_mul_f32_e32 v30, v54, v30
	v_mul_f32_e32 v31, v55, v31
	v_mul_f32_e32 v32, v12, v32
	v_mul_f32_e32 v33, v13, v33
	v_mul_f32_e32 v26, v26, v56
	v_mul_f32_e32 v27, v27, v57
	v_mul_f32_e32 v28, v28, v16
	v_mul_f32_e32 v29, v29, v17
	v_mul_f32_e32 v18, v18, v50
	v_mul_f32_e32 v19, v19, v51
	v_mul_f32_e32 v20, v20, v4
	v_mul_f32_e32 v21, v21, v5
	global_store_dwordx4 v[58:59], v[30:33], off
	global_store_dwordx4 v[58:59], v[26:29], off offset:2048
	global_store_dwordx4 v[62:63], v[18:21], off
	s_nop 1
	v_mul_f32_e32 v18, 0x45800000, v0
	v_cndmask_b32_e32 v0, v0, v18, vcc
	v_mul_f32_e32 v18, v42, v0
	v_mul_f32_e32 v19, v43, v0
	v_mul_f32_e32 v20, v44, v0
	v_mul_f32_e32 v21, v45, v0
	v_mul_f32_e32 v18, v54, v18
	v_mul_f32_e32 v19, v55, v19
	v_mul_f32_e32 v20, v12, v20
	v_mul_f32_e32 v21, v13, v21
	global_store_dwordx4 v[66:67], v[18:21], off offset:-4096
	v_add_co_u32_e32 v82, vcc, s2, v62
	s_nop 0
	v_mul_f32_e32 v18, v38, v0
	v_mul_f32_e32 v19, v39, v0
	v_mul_f32_e32 v20, v40, v0
	v_mul_f32_e32 v21, v41, v0
	v_mul_f32_e32 v18, v52, v18
	v_mul_f32_e32 v19, v53, v19
	v_mul_f32_e32 v20, v8, v20
	v_mul_f32_e32 v21, v9, v21
	global_store_dwordx4 v[68:69], v[18:21], off offset:1024
	v_addc_co_u32_e32 v83, vcc, 0, v63, vcc
	s_nop 0
	v_mul_f32_e32 v18, v46, v0
	v_mul_f32_e32 v19, v47, v0
	v_mul_f32_e32 v20, v48, v0
	v_mul_f32_e32 v21, v49, v0
	v_mul_f32_e32 v18, v56, v18
	v_mul_f32_e32 v19, v57, v19
	v_mul_f32_e32 v20, v16, v20
	v_mul_f32_e32 v21, v17, v21
	global_store_dwordx4 v[68:69], v[18:21], off offset:2048
	v_add_co_u32_e32 v84, vcc, s7, v58
	s_nop 0
	v_mul_f32_e32 v18, v22, v0
	v_mul_f32_e32 v19, v23, v0
	v_mul_f32_e32 v20, v24, v0
	v_mul_f32_e32 v21, v25, v0
	v_mul_f32_e32 v18, v50, v18
	v_mul_f32_e32 v19, v51, v19
	v_mul_f32_e32 v20, v4, v20
	v_mul_f32_e32 v21, v5, v21
	global_store_dwordx4 v[64:65], v[18:21], off offset:-4096
	global_load_dwordx4 v[18:21], v[64:65], off
	s_nop 0
	global_load_dwordx4 v[22:25], v[66:67], off
	global_load_dwordx4 v[26:29], v[66:67], off offset:1024
	v_addc_co_u32_e32 v85, vcc, 0, v59, vcc
	v_add_co_u32_e32 v86, vcc, s2, v58
	s_waitcnt vmcnt(2)
	v_mov_b32_e32 v37, v19
	s_waitcnt vmcnt(1)
	v_mov_b32_e32 v32, v23
	s_waitcnt vmcnt(0)
	v_mov_b32_e32 v33, v27
	v_mov_b32_e32 v30, v22
	v_mov_b32_e32 v31, v26
	v_mul_f32_e32 v32, v32, v32
	v_mul_f32_e32 v33, v33, v33
	v_mov_b32_e32 v34, v25
	v_fma_f32 v30, v30, v30, v32
	v_fma_f32 v31, v31, v31, v33
	v_mov_b32_e32 v32, v24
	v_mov_b32_e32 v33, v28
	v_mov_b32_e32 v35, v29
	v_fma_f32 v30, v32, v32, v30
	v_fma_f32 v31, v33, v33, v31
	v_mov_b32_e32 v39, v21
	v_fma_f32 v68, v34, v34, v30
	v_fma_f32 v69, v35, v35, v31
	global_load_dwordx4 v[30:33], v[66:67], off offset:2048
	v_mov_b32_e32 v35, v18
	v_addc_co_u32_e32 v87, vcc, 0, v59, vcc
	s_waitcnt vmcnt(0)
	v_mov_b32_e32 v36, v31
	v_mov_b32_e32 v34, v30
	v_mul_f32_e32 v36, v36, v36
	v_mul_f32_e32 v37, v37, v37
	v_mov_b32_e32 v38, v33
	v_fma_f32 v34, v34, v34, v36
	v_fma_f32 v35, v35, v35, v37
	v_mov_b32_e32 v36, v32
	v_mov_b32_e32 v37, v20
	v_fma_f32 v34, v36, v36, v34
	v_fma_f32 v35, v37, v37, v35
	s_nop 0
	v_fma_f32 v70, v38, v38, v34
	v_fma_f32 v71, v39, v39, v35
	global_load_dwordx4 v[34:37], v[82:83], off offset:-4096
	global_load_dwordx4 v[38:41], v[86:87], off offset:-4096
	global_load_dwordx4 v[42:45], v[84:85], off offset:1024
	s_waitcnt vmcnt(1)
	v_mov_b32_e32 v48, v39
	s_waitcnt vmcnt(0)
	v_mov_b32_e32 v49, v43
	v_mov_b32_e32 v46, v38
	v_mov_b32_e32 v47, v42
	v_mul_f32_e32 v48, v48, v48
	v_mul_f32_e32 v49, v49, v49
	v_mov_b32_e32 v88, v41
	v_fma_f32 v46, v46, v46, v48
	v_fma_f32 v47, v47, v47, v49
	v_mov_b32_e32 v48, v40
	v_mov_b32_e32 v49, v44
	v_mov_b32_e32 v89, v45
	v_fma_f32 v46, v48, v48, v46
	v_fma_f32 v47, v49, v49, v47
	v_mov_b32_e32 v93, v35
	v_fma_f32 v88, v88, v88, v46
	v_fma_f32 v89, v89, v89, v47
	global_load_dwordx4 v[46:49], v[84:85], off offset:2048
	v_mov_b32_e32 v91, v34
	v_mov_b32_e32 v95, v37
	s_waitcnt vmcnt(0)
	v_mov_b32_e32 v92, v47
	v_mov_b32_e32 v90, v46
	v_mul_f32_e32 v92, v92, v92
	v_mul_f32_e32 v93, v93, v93
	v_mov_b32_e32 v94, v49
	v_fma_f32 v90, v90, v90, v92
	v_fma_f32 v91, v91, v91, v93
	v_mov_b32_e32 v92, v48
	v_mov_b32_e32 v93, v36
	v_fma_f32 v90, v92, v92, v90
	v_fma_f32 v91, v93, v93, v91
	v_mov_b32_e32 v92, v88
	v_fma_f32 v90, v94, v94, v90
	v_fma_f32 v91, v95, v95, v91
	v_mov_b32_e32 v93, v68
	v_mov_b32_e32 v68, v89
	v_add_f32_e32 v68, v92, v68
	v_add_f32_e32 v69, v93, v69
	v_mov_b32_e32 v88, v90
	v_mov_b32_e32 v89, v70
	v_add_f32_e32 v68, v68, v88
	v_add_f32_e32 v69, v69, v89
	v_mov_b32_e32 v70, v91
	v_add_f32_e32 v68, v68, v70
	v_add_f32_e32 v69, v69, v71
	ds_bpermute_b32 v71, v74, v69
	ds_bpermute_b32 v70, v74, v68
	s_waitcnt lgkmcnt(0)
; DI int otid() { int t; asm volatile("v_mov_b32 %0, %1" : "=v"(t) : "v"((int)threadIdx.x)); __builtin_assume(t >= 0 && t < 256); return t; }
; DI void norm_rows_f32(float* io, const float* __restrict__ g, int item) {
;   const int lane = otid() & 63, wid = otid() >> 6;
;   for (int i = 0; i < 8; ++i) {
;     size_t row = (size_t)item * 32 + wid * 8 + i;
;     float4* s = (float4*)(io + row * 1024);
;     float4 v[4]; float ss = 0.f;
; #pragma unroll
;     for (int j = 0; j < 4; ++j) { v[j] = s[lane + 64 * j]; ss += v[j].x * v[j].x + v[j].y * v[j].y + v[j].z * v[j].z + v[j].w * v[j].w; }
;     ss = wave_sum(ss);
;     float sc = rsqrtf(ss * (1.0f / 1024.0f) + 1e-6f);
; #pragma unroll
;     for (int j = 0; j < 4; ++j) {
;       float4 gg = ((const float4*)g)[lane + 64 * j];
;       float4 o; o.x = v[j].x * sc * gg.x; o.y = v[j].y * sc * gg.y; o.z = v[j].z * sc * gg.z; o.w = v[j].w * sc * gg.w;
;       s[lane + 64 * j] = o;
;     }
;   }
; }
	v_add_f32_e32 v68, v68, v70
	v_add_f32_e32 v69, v69, v71
	ds_bpermute_b32 v71, v75, v69
	ds_bpermute_b32 v70, v75, v68
	s_waitcnt lgkmcnt(0)
	v_add_f32_e32 v68, v68, v70
	v_add_f32_e32 v69, v69, v71
	ds_bpermute_b32 v71, v76, v69
	ds_bpermute_b32 v70, v76, v68
	s_waitcnt lgkmcnt(0)
	v_add_f32_e32 v68, v68, v70
	v_add_f32_e32 v69, v69, v71
	ds_bpermute_b32 v71, v77, v69
	ds_bpermute_b32 v70, v77, v68
	s_waitcnt lgkmcnt(0)
	v_add_f32_e32 v68, v68, v70
	v_add_f32_e32 v69, v69, v71
	ds_bpermute_b32 v71, v78, v69
	ds_bpermute_b32 v70, v78, v68
	s_waitcnt lgkmcnt(0)
	v_add_f32_e32 v68, v68, v70
	v_add_f32_e32 v69, v69, v71
	ds_bpermute_b32 v71, v79, v69
	ds_bpermute_b32 v70, v79, v68
	s_waitcnt lgkmcnt(0)
	v_add_f32_e32 v68, v68, v70
	v_add_f32_e32 v69, v69, v71
	s_nop 0
	v_fma_f32 v68, v68, s14, v72
	v_fma_f32 v69, v69, s14, v72
	s_nop 0
	v_mul_f32_e32 v0, 0x4b800000, v69
	v_cmp_gt_f32_e64 s[0:1], s3, v69
	v_cmp_gt_f32_e32 vcc, s3, v68
	s_nop 0
	v_cndmask_b32_e64 v0, v69, v0, s[0:1]
	v_rsq_f32_e32 v0, v0
	s_nop 0
	v_mul_f32_e32 v69, 0x45800000, v0
	v_cndmask_b32_e64 v0, v0, v69, s[0:1]
	v_mul_f32_e32 v22, v22, v0
	v_mul_f32_e32 v23, v23, v0
	v_mul_f32_e32 v24, v24, v0
	v_mul_f32_e32 v25, v25, v0
	v_mul_f32_e32 v22, v54, v22
	v_mul_f32_e32 v23, v55, v23
	v_mul_f32_e32 v24, v12, v24
	v_mul_f32_e32 v25, v13, v25
	global_store_dwordx4 v[66:67], v[22:25], off
	v_mul_f32_e32 v18, v18, v0
	v_mul_f32_e32 v19, v19, v0
	v_mul_f32_e32 v20, v20, v0
	v_mul_f32_e32 v21, v21, v0
	v_mul_f32_e32 v22, v26, v0
	v_mul_f32_e32 v23, v27, v0
	v_mul_f32_e32 v24, v28, v0
	v_mul_f32_e32 v25, v29, v0
	v_mul_f32_e32 v22, v52, v22
	v_mul_f32_e32 v23, v53, v23
	v_mul_f32_e32 v24, v8, v24
	v_mul_f32_e32 v25, v9, v25
	global_store_dwordx4 v[66:67], v[22:25], off offset:1024
	v_mul_f32_e32 v18, v50, v18
	v_mul_f32_e32 v19, v51, v19
	v_mul_f32_e32 v20, v4, v20
	v_mul_f32_e32 v21, v5, v21
	v_mul_f32_e32 v22, v30, v0
	v_mul_f32_e32 v23, v31, v0
	v_mul_f32_e32 v24, v32, v0
	v_mul_f32_e32 v25, v33, v0
	v_mul_f32_e32 v0, 0x4b800000, v68
	v_cndmask_b32_e32 v0, v68, v0, vcc
	v_rsq_f32_e32 v0, v0
	v_mul_f32_e32 v22, v56, v22
	v_mul_f32_e32 v23, v57, v23
	v_mul_f32_e32 v24, v16, v24
	v_mul_f32_e32 v25, v17, v25
	global_store_dwordx4 v[66:67], v[22:25], off offset:2048
	global_store_dwordx4 v[64:65], v[18:21], off
	s_nop 1
	v_mul_f32_e32 v18, 0x45800000, v0
	v_cndmask_b32_e32 v0, v0, v18, vcc
	v_mul_f32_e32 v18, v38, v0
	v_mul_f32_e32 v19, v39, v0
	v_mul_f32_e32 v20, v40, v0
	v_mul_f32_e32 v21, v41, v0
	v_mul_f32_e32 v18, v54, v18
	v_mul_f32_e32 v19, v55, v19
	v_mul_f32_e32 v20, v12, v20
	v_mul_f32_e32 v21, v13, v21
	global_store_dwordx4 v[86:87], v[18:21], off offset:-4096
	v_add_co_u32_e32 v68, vcc, s25, v62
	s_nop 0
	v_mul_f32_e32 v18, v42, v0
	v_mul_f32_e32 v19, v43, v0
	v_mul_f32_e32 v20, v44, v0
	v_mul_f32_e32 v21, v45, v0
	v_mul_f32_e32 v18, v52, v18
	v_mul_f32_e32 v19, v53, v19
	v_mul_f32_e32 v20, v8, v20
	v_mul_f32_e32 v21, v9, v21
	global_store_dwordx4 v[84:85], v[18:21], off offset:1024
	v_addc_co_u32_e32 v69, vcc, 0, v63, vcc
	s_nop 0
	v_mul_f32_e32 v18, v46, v0
	v_mul_f32_e32 v19, v47, v0
	v_mul_f32_e32 v20, v48, v0
	v_mul_f32_e32 v21, v49, v0
	v_mul_f32_e32 v18, v56, v18
	v_mul_f32_e32 v19, v57, v19
	v_mul_f32_e32 v20, v16, v20
	v_mul_f32_e32 v21, v17, v21
	global_store_dwordx4 v[84:85], v[18:21], off offset:2048
	v_add_co_u32_e32 v70, vcc, s12, v58
	s_nop 0
	v_mul_f32_e32 v18, v34, v0
	v_mul_f32_e32 v19, v35, v0
	v_mul_f32_e32 v20, v36, v0
	v_mul_f32_e32 v21, v37, v0
	v_mul_f32_e32 v18, v50, v18
	v_mul_f32_e32 v19, v51, v19
	v_mul_f32_e32 v20, v4, v20
	v_mul_f32_e32 v21, v5, v21
	global_store_dwordx4 v[82:83], v[18:21], off offset:-4096
	global_load_dwordx4 v[18:21], v[82:83], off
	s_nop 0
	global_load_dwordx4 v[22:25], v[86:87], off
	global_load_dwordx4 v[26:29], v[86:87], off offset:1024
	v_addc_co_u32_e32 v71, vcc, 0, v59, vcc
	v_add_co_u32_e32 v84, vcc, s25, v58
	s_waitcnt vmcnt(2)
	v_mov_b32_e32 v37, v19
	s_waitcnt vmcnt(1)
	v_mov_b32_e32 v32, v23
	s_waitcnt vmcnt(0)
	v_mov_b32_e32 v33, v27
	v_mov_b32_e32 v30, v22
	v_mov_b32_e32 v31, v26
	v_mul_f32_e32 v32, v32, v32
	v_mul_f32_e32 v33, v33, v33
	v_mov_b32_e32 v34, v25
	v_fma_f32 v30, v30, v30, v32
	v_fma_f32 v31, v31, v31, v33
	v_mov_b32_e32 v32, v24
	v_mov_b32_e32 v33, v28
	v_mov_b32_e32 v35, v29
	v_fma_f32 v30, v32, v32, v30
	v_fma_f32 v31, v33, v33, v31
	v_mov_b32_e32 v39, v21
	v_fma_f32 v64, v34, v34, v30
	v_fma_f32 v65, v35, v35, v31
	global_load_dwordx4 v[30:33], v[86:87], off offset:2048
	v_mov_b32_e32 v35, v18
	v_addc_co_u32_e32 v85, vcc, 0, v59, vcc
	s_waitcnt vmcnt(0)
	v_mov_b32_e32 v36, v31
	v_mov_b32_e32 v34, v30
	v_mul_f32_e32 v36, v36, v36
	v_mul_f32_e32 v37, v37, v37
	v_mov_b32_e32 v38, v33
	v_fma_f32 v34, v34, v34, v36
	v_fma_f32 v35, v35, v35, v37
	v_mov_b32_e32 v36, v32
	v_mov_b32_e32 v37, v20
	v_fma_f32 v34, v36, v36, v34
	v_fma_f32 v35, v37, v37, v35
	s_nop 0
	v_fma_f32 v66, v38, v38, v34
	v_fma_f32 v67, v39, v39, v35
	global_load_dwordx4 v[34:37], v[68:69], off offset:-4096
	global_load_dwordx4 v[38:41], v[84:85], off offset:-4096
	global_load_dwordx4 v[42:45], v[70:71], off offset:1024
	s_waitcnt vmcnt(1)
	v_mov_b32_e32 v48, v39
	s_waitcnt vmcnt(0)
	v_mov_b32_e32 v49, v43
	v_mov_b32_e32 v46, v38
	v_mov_b32_e32 v47, v42
	v_mul_f32_e32 v48, v48, v48
	v_mul_f32_e32 v49, v49, v49
	v_mov_b32_e32 v88, v41
	v_fma_f32 v46, v46, v46, v48
	v_fma_f32 v47, v47, v47, v49
	v_mov_b32_e32 v48, v40
	v_mov_b32_e32 v49, v44
	v_mov_b32_e32 v89, v45
	v_fma_f32 v46, v48, v48, v46
	v_fma_f32 v47, v49, v49, v47
	v_mov_b32_e32 v93, v35
	v_fma_f32 v88, v88, v88, v46
	v_fma_f32 v89, v89, v89, v47
	global_load_dwordx4 v[46:49], v[70:71], off offset:2048
	v_mov_b32_e32 v91, v34
	v_mov_b32_e32 v95, v37
	s_waitcnt vmcnt(0)
; DI int otid() { int t; asm volatile("v_mov_b32 %0, %1" : "=v"(t) : "v"((int)threadIdx.x)); __builtin_assume(t >= 0 && t < 256); return t; }
; DI void norm_rows_f32(float* io, const float* __restrict__ g, int item) {
;   const int lane = otid() & 63, wid = otid() >> 6;
;   for (int i = 0; i < 8; ++i) {
;     size_t row = (size_t)item * 32 + wid * 8 + i;
;     float4* s = (float4*)(io + row * 1024);
;     float4 v[4]; float ss = 0.f;
; #pragma unroll
;     for (int j = 0; j < 4; ++j) { v[j] = s[lane + 64 * j]; ss += v[j].x * v[j].x + v[j].y * v[j].y + v[j].z * v[j].z + v[j].w * v[j].w; }
;     ss = wave_sum(ss);
;     float sc = rsqrtf(ss * (1.0f / 1024.0f) + 1e-6f);
; #pragma unroll
;     for (int j = 0; j < 4; ++j) {
;       float4 gg = ((const float4*)g)[lane + 64 * j];
;       float4 o; o.x = v[j].x * sc * gg.x; o.y = v[j].y * sc * gg.y; o.z = v[j].z * sc * gg.z; o.w = v[j].w * sc * gg.w;
;       s[lane + 64 * j] = o;
;     }
;   }
; }
	v_mov_b32_e32 v92, v47
	v_mov_b32_e32 v90, v46
	v_mul_f32_e32 v92, v92, v92
	v_mul_f32_e32 v93, v93, v93
	v_mov_b32_e32 v94, v49
	v_fma_f32 v90, v90, v90, v92
	v_fma_f32 v91, v91, v91, v93
	v_mov_b32_e32 v92, v48
	v_mov_b32_e32 v93, v36
	v_fma_f32 v90, v92, v92, v90
	v_fma_f32 v91, v93, v93, v91
	v_mov_b32_e32 v92, v88
	v_fma_f32 v90, v94, v94, v90
	v_fma_f32 v91, v95, v95, v91
	v_mov_b32_e32 v93, v64
	v_mov_b32_e32 v64, v89
	v_add_f32_e32 v64, v92, v64
	v_add_f32_e32 v65, v93, v65
	v_mov_b32_e32 v88, v90
	v_mov_b32_e32 v89, v66
	v_add_f32_e32 v64, v64, v88
	v_add_f32_e32 v65, v65, v89
	v_mov_b32_e32 v66, v91
	v_add_f32_e32 v64, v64, v66
	v_add_f32_e32 v65, v65, v67
	ds_bpermute_b32 v67, v74, v65
	ds_bpermute_b32 v66, v74, v64
	s_waitcnt lgkmcnt(0)
	v_add_f32_e32 v64, v64, v66
	v_add_f32_e32 v65, v65, v67
	ds_bpermute_b32 v67, v75, v65
	ds_bpermute_b32 v66, v75, v64
	s_waitcnt lgkmcnt(0)
	v_add_f32_e32 v64, v64, v66
	v_add_f32_e32 v65, v65, v67
	ds_bpermute_b32 v67, v76, v65
	ds_bpermute_b32 v66, v76, v64
	s_waitcnt lgkmcnt(0)
	v_add_f32_e32 v64, v64, v66
	v_add_f32_e32 v65, v65, v67
	ds_bpermute_b32 v67, v77, v65
	ds_bpermute_b32 v66, v77, v64
	s_waitcnt lgkmcnt(0)
	v_add_f32_e32 v64, v64, v66
	v_add_f32_e32 v65, v65, v67
	ds_bpermute_b32 v67, v78, v65
	ds_bpermute_b32 v66, v78, v64
	s_waitcnt lgkmcnt(0)
	v_add_f32_e32 v64, v64, v66
	v_add_f32_e32 v65, v65, v67
	ds_bpermute_b32 v67, v79, v65
	ds_bpermute_b32 v66, v79, v64
	s_waitcnt lgkmcnt(0)
	v_add_f32_e32 v64, v64, v66
	v_add_f32_e32 v65, v65, v67
	s_nop 0
	v_fma_f32 v64, v64, s14, v72
	v_fma_f32 v65, v65, s14, v72
	s_nop 0
	v_mul_f32_e32 v0, 0x4b800000, v65
	v_cmp_gt_f32_e64 s[0:1], s3, v65
	v_cmp_gt_f32_e32 vcc, s3, v64
	s_nop 0
	v_cndmask_b32_e64 v0, v65, v0, s[0:1]
	v_rsq_f32_e32 v0, v0
	s_nop 0
	v_mul_f32_e32 v65, 0x45800000, v0
	v_cndmask_b32_e64 v0, v0, v65, s[0:1]
	v_mul_f32_e32 v22, v22, v0
	v_mul_f32_e32 v23, v23, v0
	v_mul_f32_e32 v24, v24, v0
	v_mul_f32_e32 v25, v25, v0
	v_mul_f32_e32 v22, v54, v22
	v_mul_f32_e32 v23, v55, v23
	v_mul_f32_e32 v24, v12, v24
	v_mul_f32_e32 v25, v13, v25
	global_store_dwordx4 v[86:87], v[22:25], off
	v_mul_f32_e32 v18, v18, v0
	v_mul_f32_e32 v19, v19, v0
	v_mul_f32_e32 v20, v20, v0
	v_mul_f32_e32 v21, v21, v0
	v_mul_f32_e32 v22, v26, v0
	v_mul_f32_e32 v23, v27, v0
	v_mul_f32_e32 v24, v28, v0
	v_mul_f32_e32 v25, v29, v0
	v_mul_f32_e32 v22, v52, v22
	v_mul_f32_e32 v23, v53, v23
	v_mul_f32_e32 v24, v8, v24
	v_mul_f32_e32 v25, v9, v25
	global_store_dwordx4 v[86:87], v[22:25], off offset:1024
	v_mul_f32_e32 v18, v50, v18
	v_mul_f32_e32 v19, v51, v19
	v_mul_f32_e32 v20, v4, v20
	v_mul_f32_e32 v21, v5, v21
	v_mul_f32_e32 v22, v30, v0
	v_mul_f32_e32 v23, v31, v0
	v_mul_f32_e32 v24, v32, v0
	v_mul_f32_e32 v25, v33, v0
	v_mul_f32_e32 v0, 0x4b800000, v64
	v_cndmask_b32_e32 v0, v64, v0, vcc
	v_rsq_f32_e32 v0, v0
	v_mul_f32_e32 v22, v56, v22
	v_mul_f32_e32 v23, v57, v23
	v_mul_f32_e32 v24, v16, v24
	v_mul_f32_e32 v25, v17, v25
	global_store_dwordx4 v[86:87], v[22:25], off offset:2048
	global_store_dwordx4 v[82:83], v[18:21], off
	s_nop 1
	v_mul_f32_e32 v18, 0x45800000, v0
	v_cndmask_b32_e32 v0, v0, v18, vcc
	v_mul_f32_e32 v18, v38, v0
	v_mul_f32_e32 v19, v39, v0
	v_mul_f32_e32 v20, v40, v0
	v_mul_f32_e32 v21, v41, v0
	v_mul_f32_e32 v18, v54, v18
	v_mul_f32_e32 v19, v55, v19
	v_mul_f32_e32 v20, v12, v20
	v_mul_f32_e32 v21, v13, v21
	global_store_dwordx4 v[84:85], v[18:21], off offset:-4096
	v_add_co_u32_e32 v62, vcc, s13, v62
	s_nop 0
	v_mul_f32_e32 v18, v42, v0
	v_mul_f32_e32 v19, v43, v0
	v_mul_f32_e32 v20, v44, v0
	v_mul_f32_e32 v21, v45, v0
	v_mul_f32_e32 v18, v52, v18
	v_mul_f32_e32 v19, v53, v19
	v_mul_f32_e32 v20, v8, v20
	v_mul_f32_e32 v21, v9, v21
	global_store_dwordx4 v[70:71], v[18:21], off offset:1024
	v_addc_co_u32_e32 v63, vcc, 0, v63, vcc
	s_nop 0
	v_mul_f32_e32 v18, v46, v0
	v_mul_f32_e32 v19, v47, v0
	v_mul_f32_e32 v20, v48, v0
	v_mul_f32_e32 v21, v49, v0
	v_mul_f32_e32 v18, v56, v18
	v_mul_f32_e32 v19, v57, v19
	v_mul_f32_e32 v20, v16, v20
	v_mul_f32_e32 v21, v17, v21
	global_store_dwordx4 v[70:71], v[18:21], off offset:2048
	v_add_co_u32_e32 v58, vcc, s13, v58
	s_nop 0
	v_mul_f32_e32 v18, v34, v0
	v_mul_f32_e32 v19, v35, v0
	v_mul_f32_e32 v20, v36, v0
	v_mul_f32_e32 v21, v37, v0
	v_mul_f32_e32 v18, v50, v18
	v_mul_f32_e32 v19, v51, v19
	v_mul_f32_e32 v20, v4, v20
	v_mul_f32_e32 v21, v5, v21
	global_store_dwordx4 v[68:69], v[18:21], off offset:-4096
	global_load_dwordx4 v[18:21], v[68:69], off
	s_nop 0
	global_load_dwordx4 v[22:25], v[84:85], off
	global_load_dwordx4 v[26:29], v[84:85], off offset:1024
	v_addc_co_u32_e32 v59, vcc, 0, v59, vcc
	s_waitcnt vmcnt(2)
	v_mov_b32_e32 v37, v19
	s_waitcnt vmcnt(1)
	v_mov_b32_e32 v32, v23
	s_waitcnt vmcnt(0)
	v_mov_b32_e32 v33, v27
	v_mov_b32_e32 v30, v22
	v_mov_b32_e32 v31, v26
	v_mul_f32_e32 v32, v32, v32
	v_mul_f32_e32 v33, v33, v33
	v_mov_b32_e32 v34, v25
	v_fma_f32 v30, v30, v30, v32
	v_fma_f32 v31, v31, v31, v33
	v_mov_b32_e32 v32, v24
	v_mov_b32_e32 v33, v28
	v_mov_b32_e32 v35, v29
	v_fma_f32 v30, v32, v32, v30
	v_fma_f32 v31, v33, v33, v31
	v_mov_b32_e32 v39, v21
	v_fma_f32 v64, v34, v34, v30
	v_fma_f32 v65, v35, v35, v31
	global_load_dwordx4 v[30:33], v[84:85], off offset:2048
	v_mov_b32_e32 v35, v18
	s_waitcnt vmcnt(0)
; DI int otid() { int t; asm volatile("v_mov_b32 %0, %1" : "=v"(t) : "v"((int)threadIdx.x)); __builtin_assume(t >= 0 && t < 256); return t; }
; DI void norm_rows_f32(float* io, const float* __restrict__ g, int item) {
;   const int lane = otid() & 63, wid = otid() >> 6;
;   for (int i = 0; i < 8; ++i) {
;     size_t row = (size_t)item * 32 + wid * 8 + i;
;     float4* s = (float4*)(io + row * 1024);
;     float4 v[4]; float ss = 0.f;
; #pragma unroll
;     for (int j = 0; j < 4; ++j) { v[j] = s[lane + 64 * j]; ss += v[j].x * v[j].x + v[j].y * v[j].y + v[j].z * v[j].z + v[j].w * v[j].w; }
;     ss = wave_sum(ss);
;     float sc = rsqrtf(ss * (1.0f / 1024.0f) + 1e-6f);
; #pragma unroll
;     for (int j = 0; j < 4; ++j) {
;       float4 gg = ((const float4*)g)[lane + 64 * j];
;       float4 o; o.x = v[j].x * sc * gg.x; o.y = v[j].y * sc * gg.y; o.z = v[j].z * sc * gg.z; o.w = v[j].w * sc * gg.w;
;       s[lane + 64 * j] = o;
;     }
;   }
; }
	v_mov_b32_e32 v36, v31
	v_mov_b32_e32 v34, v30
	v_mul_f32_e32 v36, v36, v36
	v_mul_f32_e32 v37, v37, v37
	v_mov_b32_e32 v38, v33
	v_fma_f32 v34, v34, v34, v36
	v_fma_f32 v35, v35, v35, v37
	v_mov_b32_e32 v36, v32
	v_mov_b32_e32 v37, v20
	v_fma_f32 v34, v36, v36, v34
	v_fma_f32 v35, v37, v37, v35
	s_nop 0
	v_fma_f32 v66, v38, v38, v34
	v_fma_f32 v67, v39, v39, v35
	global_load_dwordx4 v[34:37], v[62:63], off
	s_nop 0
	global_load_dwordx2 v[60:61], v[60:61], off offset:8
	s_nop 0
	global_load_dwordx4 v[38:41], v[58:59], off
	global_load_dwordx2 v[70:71], v80, s[54:55] offset:8
	global_load_dwordx4 v[42:45], v[58:59], off offset:1024
	global_load_dwordx2 v[82:83], v80, s[54:55] offset:1032
	s_waitcnt vmcnt(3)
	v_mov_b32_e32 v48, v39
	v_mov_b32_e32 v46, v38
	s_waitcnt vmcnt(1)
	v_mov_b32_e32 v49, v43
	v_mov_b32_e32 v47, v42
	v_mul_f32_e32 v48, v48, v48
	v_mul_f32_e32 v49, v49, v49
	v_mov_b32_e32 v86, v41
	v_fma_f32 v46, v46, v46, v48
	v_fma_f32 v47, v47, v47, v49
	v_mov_b32_e32 v48, v40
	v_mov_b32_e32 v49, v44
	v_mov_b32_e32 v87, v45
	v_fma_f32 v46, v48, v48, v46
	v_fma_f32 v47, v49, v49, v47
	v_mov_b32_e32 v91, v35
	v_fma_f32 v86, v86, v86, v46
	v_fma_f32 v87, v87, v87, v47
	global_load_dwordx4 v[46:49], v[58:59], off offset:2048
	s_nop 0
	global_load_dwordx2 v[80:81], v80, s[54:55] offset:2056
	v_mov_b32_e32 v89, v34
	v_mov_b32_e32 v93, v37
	s_waitcnt vmcnt(1)
	v_mov_b32_e32 v90, v47
	v_mov_b32_e32 v88, v46
	v_mul_f32_e32 v90, v90, v90
	v_mul_f32_e32 v91, v91, v91
	v_mov_b32_e32 v92, v49
	v_fma_f32 v88, v88, v88, v90
	v_fma_f32 v89, v89, v89, v91
	v_mov_b32_e32 v90, v48
	v_mov_b32_e32 v91, v36
	v_fma_f32 v88, v90, v90, v88
	v_fma_f32 v89, v91, v91, v89
	v_mov_b32_e32 v90, v86
	v_fma_f32 v88, v92, v92, v88
	v_fma_f32 v89, v93, v93, v89
	v_mov_b32_e32 v91, v64
	v_mov_b32_e32 v64, v87
	v_add_f32_e32 v64, v90, v64
	v_add_f32_e32 v65, v91, v65
	v_mov_b32_e32 v86, v88
	v_mov_b32_e32 v87, v66
	v_add_f32_e32 v64, v64, v86
	v_add_f32_e32 v65, v65, v87
	v_mov_b32_e32 v66, v89
	v_add_f32_e32 v64, v64, v66
	v_add_f32_e32 v65, v65, v67
	ds_bpermute_b32 v67, v74, v65
	ds_bpermute_b32 v66, v74, v64
	s_waitcnt lgkmcnt(0)
	v_add_f32_e32 v64, v64, v66
	v_add_f32_e32 v65, v65, v67
	ds_bpermute_b32 v67, v75, v65
	ds_bpermute_b32 v66, v75, v64
	s_waitcnt lgkmcnt(0)
	v_add_f32_e32 v64, v64, v66
	v_add_f32_e32 v65, v65, v67
	ds_bpermute_b32 v67, v76, v65
	ds_bpermute_b32 v66, v76, v64
	s_waitcnt lgkmcnt(0)
	v_add_f32_e32 v64, v64, v66
	v_add_f32_e32 v65, v65, v67
	ds_bpermute_b32 v67, v77, v65
	ds_bpermute_b32 v66, v77, v64
	s_waitcnt lgkmcnt(0)
	v_add_f32_e32 v64, v64, v66
	v_add_f32_e32 v65, v65, v67
	ds_bpermute_b32 v67, v78, v65
	ds_bpermute_b32 v66, v78, v64
	s_waitcnt lgkmcnt(0)
	v_add_f32_e32 v64, v64, v66
	v_add_f32_e32 v65, v65, v67
	ds_bpermute_b32 v67, v79, v65
	ds_bpermute_b32 v66, v79, v64
	s_waitcnt lgkmcnt(0)
	v_add_f32_e32 v64, v64, v66
	v_add_f32_e32 v65, v65, v67
	s_nop 0
	v_fma_f32 v64, v64, s14, v72
	v_fma_f32 v65, v65, s14, v72
	s_nop 0
	v_mul_f32_e32 v0, 0x4b800000, v65
	v_cmp_gt_f32_e64 s[0:1], s3, v65
	v_cmp_gt_f32_e32 vcc, s3, v64
	s_nop 0
	v_cndmask_b32_e64 v0, v65, v0, s[0:1]
	v_rsq_f32_e32 v0, v0
	s_nop 0
	v_mul_f32_e32 v65, 0x45800000, v0
	v_cndmask_b32_e64 v0, v0, v65, s[0:1]
	v_mul_f32_e32 v22, v22, v0
	v_mul_f32_e32 v23, v23, v0
	v_mul_f32_e32 v24, v24, v0
	v_mul_f32_e32 v25, v25, v0
	v_mul_f32_e32 v22, v54, v22
	v_mul_f32_e32 v23, v55, v23
	v_mul_f32_e32 v24, v12, v24
	v_mul_f32_e32 v25, v13, v25
	v_mul_f32_e32 v12, v26, v0
	v_mul_f32_e32 v13, v27, v0
	global_store_dwordx4 v[84:85], v[22:25], off
	s_nop 1
	v_mul_f32_e32 v22, v52, v12
	v_mul_f32_e32 v23, v53, v13
	v_mul_f32_e32 v12, v28, v0
	v_mul_f32_e32 v13, v29, v0
	s_nop 0
	v_mul_f32_e32 v24, v8, v12
	v_mul_f32_e32 v25, v9, v13
	v_mul_f32_e32 v8, v30, v0
	v_mul_f32_e32 v9, v31, v0
	global_store_dwordx4 v[84:85], v[22:25], off offset:1024
	s_nop 1
	v_mul_f32_e32 v22, v56, v8
	v_mul_f32_e32 v23, v57, v9
	v_mul_f32_e32 v8, v32, v0
	v_mul_f32_e32 v9, v33, v0
	s_nop 0
	v_mul_f32_e32 v24, v16, v8
	v_mul_f32_e32 v25, v17, v9
	v_mul_f32_e32 v8, v18, v0
	v_mul_f32_e32 v9, v19, v0
	global_store_dwordx4 v[84:85], v[22:25], off offset:2048
	v_mul_f32_e32 v16, v50, v8
	v_mul_f32_e32 v17, v51, v9
	v_mul_f32_e32 v8, v20, v0
	v_mul_f32_e32 v9, v21, v0
	v_mul_f32_e32 v0, 0x4b800000, v64
	v_cndmask_b32_e32 v0, v64, v0, vcc
	v_rsq_f32_e32 v0, v0
	v_mul_f32_e32 v18, v4, v8
	v_mul_f32_e32 v19, v5, v9
	global_store_dwordx4 v[68:69], v[16:19], off
	v_mul_f32_e32 v4, 0x45800000, v0
	v_cndmask_b32_e32 v0, v0, v4, vcc
	v_mul_f32_e32 v4, v38, v0
	v_mul_f32_e32 v5, v39, v0
	s_nop 0
	v_mul_f32_e32 v8, v10, v4
	v_mul_f32_e32 v9, v11, v5
	v_mul_f32_e32 v4, v40, v0
	v_mul_f32_e32 v5, v41, v0
	s_nop 0
	v_mul_f32_e32 v10, v70, v4
	v_mul_f32_e32 v11, v71, v5
	v_mul_f32_e32 v4, v42, v0
	v_mul_f32_e32 v5, v43, v0
	global_store_dwordx4 v[58:59], v[8:11], off
	v_mul_f32_e32 v4, v6, v4
	v_mul_f32_e32 v5, v7, v5
	v_mul_f32_e32 v6, v44, v0
	v_mul_f32_e32 v7, v45, v0
	s_nop 0
	v_mul_f32_e32 v6, v82, v6
	v_mul_f32_e32 v7, v83, v7
	global_store_dwordx4 v[58:59], v[4:7], off offset:1024
	s_nop 1
	v_mul_f32_e32 v4, v46, v0
	v_mul_f32_e32 v5, v47, v0
	v_mul_f32_e32 v6, v48, v0
	v_mul_f32_e32 v7, v49, v0
	v_mul_f32_e32 v4, v4, v14
	v_mul_f32_e32 v5, v5, v15
	s_waitcnt vmcnt(6)
	v_mul_f32_e32 v6, v6, v80
	v_mul_f32_e32 v7, v7, v81
	global_store_dwordx4 v[58:59], v[4:7], off offset:2048
	s_nop 1
	v_mul_f32_e32 v4, v34, v0
	v_mul_f32_e32 v5, v35, v0
	s_nop 0
	v_mul_f32_e32 v2, v4, v2
	v_mul_f32_e32 v3, v5, v3
	v_mul_f32_e32 v4, v36, v0
	v_mul_f32_e32 v5, v37, v0
	s_nop 0
	v_mul_f32_e32 v4, v4, v60
	v_mul_f32_e32 v5, v5, v61
	global_store_dwordx4 v[62:63], v[2:5], off
	s_cbranch_scc0 .LBB0_28

; DI unsigned pack2(float a, float b) { f2_t v = {a, b}; bf2_t r = __builtin_convertvector(v, bf2_t); return __builtin_bit_cast(unsigned, r); }
; DI int otid() { int t; asm volatile("v_mov_b32 %0, %1" : "=v"(t) : "v"((int)threadIdx.x)); __builtin_assume(t >= 0 && t < 256); return t; }
; DI void norm_rows_bf16(const float* __restrict__ src, const float* __restrict__ g, bf16_t* __restrict__ dst, int item) {
;   const int lane = otid() & 63, wid = otid() >> 6;
;   for (int i = 0; i < 8; ++i) {
;     size_t row = (size_t)item * 32 + wid * 8 + i;
;     const float4* s = (const float4*)(src + row * 1024);
;     float4 v[4]; float ss = 0.f;
; #pragma unroll
;     for (int j = 0; j < 4; ++j) { v[j] = s[2 * lane + (j & 1) + 128 * (j >> 1)]; ss += v[j].x * v[j].x + v[j].y * v[j].y + v[j].z * v[j].z + v[j].w * v[j].w; }
;     ss = wave_sum(ss);
;     float sc = rsqrtf(ss * (1.0f / 1024.0f) + 1e-6f);
; #pragma unroll
;     for (int jj = 0; jj < 2; ++jj) {
;       float4 g0 = ((const float4*)g)[2 * lane + 128 * jj], g1 = ((const float4*)g)[2 * lane + 1 + 128 * jj];
;       const float4 a = v[2 * jj], c = v[2 * jj + 1];
;       uint4 o; o.x = pack2(a.x * sc * g0.x, a.y * sc * g0.y); o.y = pack2(a.z * sc * g0.z, a.w * sc * g0.w);
;       o.z = pack2(c.x * sc * g1.x, c.y * sc * g1.y); o.w = pack2(c.z * sc * g1.z, c.w * sc * g1.w);
;       *(uint4*)(dst + row * 1024 + (2 * lane + 128 * jj) * 4) = o;
;     }
;   }
; }
.LBB0_34:
	v_cmp_lt_i32_e32 vcc, v252, v189
	v_mov_b32 v4, v188
	v_mov_b32 v0, v188
	s_mov_b64 s[0:1], 0x1000
	v_lshrrev_b32_e32 v0, 6, v0
	v_cndmask_b32_e32 v2, v204, v252, vcc
	v_cmp_lt_i32_e32 vcc, v191, v189
	v_lshlrev_b32_e32 v60, 2, v2
	v_and_b32_e32 v26, 63, v4
	v_cndmask_b32_e32 v2, v204, v191, vcc
	v_cmp_lt_i32_e32 vcc, v192, v189
	v_lshlrev_b32_e32 v61, 2, v2
	s_add_i32 s6, s6, s42
	v_cndmask_b32_e32 v2, v204, v192, vcc
	v_cmp_lt_i32_e32 vcc, v193, v189
	v_lshlrev_b32_e32 v62, 2, v2
	s_nop 0
	v_cndmask_b32_e32 v2, v204, v193, vcc
	v_cmp_lt_i32_e32 vcc, v194, v189
	v_lshlrev_b32_e32 v63, 2, v2
	s_nop 0
	v_cndmask_b32_e32 v2, v204, v194, vcc
	v_cmp_lt_i32_e32 vcc, v195, v189
	v_lshlrev_b32_e32 v64, 2, v2
	s_nop 0
	v_cndmask_b32_e32 v2, v204, v195, vcc
	v_lshlrev_b32_e32 v65, 2, v2
	v_lshlrev_b64 v[2:3], 15, v[0:1]
	v_lshl_or_b32 v2, v26, 5, v2
	v_lshl_add_u64 v[52:53], s[24:25], 0, v[2:3]
	v_lshlrev_b32_e32 v2, 5, v4
	v_and_b32_e32 v27, 0x7e0, v2
	global_load_dwordx4 v[18:21], v[52:53], off offset:16
	global_load_dwordx4 v[22:25], v[52:53], off
	global_load_dwordx4 v[2:5], v27, s[12:13] offset:16
	global_load_dwordx4 v[6:9], v27, s[12:13]
	s_add_u32 s24, s24, s78
	s_addc_u32 s25, s25, s79
	s_waitcnt vmcnt(3)
	v_mov_b32_e32 v17, v19
	s_waitcnt vmcnt(2)
	v_mov_b32_e32 v16, v23
	v_mov_b32_e32 v14, v22
	v_mov_b32_e32 v15, v18
	v_mul_f32_e32 v16, v16, v16
	v_mul_f32_e32 v17, v17, v17
	v_mov_b32_e32 v10, v24
	v_mov_b32_e32 v11, v20
	v_fma_f32 v14, v14, v14, v16
	v_fma_f32 v15, v15, v15, v17
	v_mov_b32_e32 v12, v25
	v_mov_b32_e32 v13, v21
	v_fma_f32 v10, v10, v10, v14
	v_fma_f32 v11, v11, v11, v15
	s_nop 0
	v_fma_f32 v56, v12, v12, v10
	v_fma_f32 v57, v13, v13, v11
	v_lshlrev_b64 v[10:11], 14, v[0:1]
	v_lshl_or_b32 v10, v26, 4, v10
	v_lshl_add_u64 v[50:51], s[22:23], 0, v[10:11]
	v_or_b32_e32 v0, 0x800, v27
	global_load_dwordx4 v[26:29], v[52:53], off offset:2064
	global_load_dwordx4 v[30:33], v[52:53], off offset:2048
	global_load_dwordx4 v[10:13], v0, s[12:13] offset:16
	global_load_dwordx4 v[14:17], v0, s[12:13]
	s_add_u32 s22, s22, s26
	s_addc_u32 s23, s23, s27
	s_cmpk_gt_i32 s6, 0x3ff
	s_waitcnt vmcnt(3)
	v_mov_b32_e32 v41, v27
	s_waitcnt vmcnt(2)
	v_mov_b32_e32 v40, v31
	v_mov_b32_e32 v38, v30
	v_mov_b32_e32 v39, v26
	v_mul_f32_e32 v40, v40, v40
	v_mul_f32_e32 v41, v41, v41
	v_mov_b32_e32 v34, v32
	v_fma_f32 v38, v38, v38, v40
	v_fma_f32 v39, v39, v39, v41
	v_add_co_u32_e32 v40, vcc, s85, v52
	v_mov_b32_e32 v35, v28
	s_nop 0
	v_addc_co_u32_e32 v41, vcc, 0, v53, vcc
	v_mov_b32_e32 v36, v33
	v_mov_b32_e32 v37, v29
	v_fma_f32 v34, v34, v34, v38
	v_fma_f32 v35, v35, v35, v39
	v_add_co_u32_e32 v54, vcc, s11, v52
	v_fma_f32 v58, v36, v36, v34
	v_fma_f32 v59, v37, v37, v35
	v_lshl_add_u64 v[34:35], v[52:53], 0, s[0:1]
	v_addc_co_u32_e32 v55, vcc, 0, v53, vcc
	global_load_dwordx4 v[42:45], v[54:55], off offset:-4096
	s_nop 0
	global_load_dwordx4 v[34:37], v[34:35], off offset:16
	s_mov_b64 s[0:1], 0x1800
	v_lshl_add_u64 v[38:39], v[52:53], 0, s[0:1]
	s_waitcnt vmcnt(1)
	v_mov_b32_e32 v68, v43
	s_waitcnt vmcnt(0)
	v_mov_b32_e32 v69, v35
	v_mov_b32_e32 v66, v42
	v_mov_b32_e32 v67, v34
	v_mul_f32_e32 v68, v68, v68
	v_mul_f32_e32 v69, v69, v69
	v_mov_b32_e32 v46, v44
	v_mov_b32_e32 v47, v36
	v_fma_f32 v66, v66, v66, v68
	v_fma_f32 v67, v67, v67, v69
	v_mov_b32_e32 v48, v45
	v_mov_b32_e32 v49, v37
	v_fma_f32 v46, v46, v46, v66
	v_fma_f32 v47, v47, v47, v67
	s_nop 0
	v_fma_f32 v66, v48, v48, v46
	v_fma_f32 v67, v49, v49, v47
	global_load_dwordx4 v[46:49], v[40:41], off offset:2048
	s_nop 0
	global_load_dwordx4 v[38:41], v[38:39], off offset:16
	s_waitcnt vmcnt(1)
	v_mov_b32_e32 v74, v47
	s_waitcnt vmcnt(0)
	v_mov_b32_e32 v75, v39
	v_mov_b32_e32 v72, v46
	v_mov_b32_e32 v73, v38
	v_mul_f32_e32 v74, v74, v74
	v_mul_f32_e32 v75, v75, v75
	v_mov_b32_e32 v68, v48
	v_mov_b32_e32 v69, v40
	v_fma_f32 v72, v72, v72, v74
	v_fma_f32 v73, v73, v73, v75
	v_mov_b32_e32 v70, v49
	v_mov_b32_e32 v71, v41
	v_fma_f32 v68, v68, v68, v72
	v_fma_f32 v69, v69, v69, v73
	s_nop 0
	v_fma_f32 v68, v70, v70, v68
	v_fma_f32 v69, v71, v71, v69
	v_mov_b32_e32 v70, v66
	v_mov_b32_e32 v71, v56
	v_mov_b32_e32 v56, v67
	v_add_f32_e32 v56, v70, v56
	v_add_f32_e32 v57, v71, v57
	v_mov_b32_e32 v66, v68
	v_mov_b32_e32 v67, v58
	v_add_f32_e32 v56, v56, v66
	v_add_f32_e32 v57, v57, v67
	v_mov_b32_e32 v58, v69
	v_add_f32_e32 v56, v56, v58
	v_add_f32_e32 v57, v57, v59
	ds_bpermute_b32 v59, v60, v57
	ds_bpermute_b32 v58, v60, v56
	s_waitcnt lgkmcnt(0)
	v_add_f32_e32 v56, v56, v58
	v_add_f32_e32 v57, v57, v59
	ds_bpermute_b32 v59, v61, v57
	ds_bpermute_b32 v58, v61, v56
	s_waitcnt lgkmcnt(0)
	v_add_f32_e32 v56, v56, v58
	v_add_f32_e32 v57, v57, v59
	ds_bpermute_b32 v59, v62, v57
	ds_bpermute_b32 v58, v62, v56
	s_waitcnt lgkmcnt(0)
	v_add_f32_e32 v56, v56, v58
	v_add_f32_e32 v57, v57, v59
	ds_bpermute_b32 v59, v63, v57
	ds_bpermute_b32 v58, v63, v56
	s_waitcnt lgkmcnt(0)
	v_add_f32_e32 v56, v56, v58
	v_add_f32_e32 v57, v57, v59
	ds_bpermute_b32 v59, v64, v57
	ds_bpermute_b32 v58, v64, v56
	s_waitcnt lgkmcnt(0)
	v_add_f32_e32 v56, v56, v58
	v_add_f32_e32 v57, v57, v59
	ds_bpermute_b32 v59, v65, v57
	ds_bpermute_b32 v58, v65, v56
	s_waitcnt lgkmcnt(0)
; DI unsigned pack2(float a, float b) { f2_t v = {a, b}; bf2_t r = __builtin_convertvector(v, bf2_t); return __builtin_bit_cast(unsigned, r); }
; DI int otid() { int t; asm volatile("v_mov_b32 %0, %1" : "=v"(t) : "v"((int)threadIdx.x)); __builtin_assume(t >= 0 && t < 256); return t; }
; DI void norm_rows_bf16(const float* __restrict__ src, const float* __restrict__ g, bf16_t* __restrict__ dst, int item) {
;   const int lane = otid() & 63, wid = otid() >> 6;
;   for (int i = 0; i < 8; ++i) {
;     size_t row = (size_t)item * 32 + wid * 8 + i;
;     const float4* s = (const float4*)(src + row * 1024);
;     float4 v[4]; float ss = 0.f;
; #pragma unroll
;     for (int j = 0; j < 4; ++j) { v[j] = s[2 * lane + (j & 1) + 128 * (j >> 1)]; ss += v[j].x * v[j].x + v[j].y * v[j].y + v[j].z * v[j].z + v[j].w * v[j].w; }
;     ss = wave_sum(ss);
;     float sc = rsqrtf(ss * (1.0f / 1024.0f) + 1e-6f);
; #pragma unroll
;     for (int jj = 0; jj < 2; ++jj) {
;       float4 g0 = ((const float4*)g)[2 * lane + 128 * jj], g1 = ((const float4*)g)[2 * lane + 1 + 128 * jj];
;       const float4 a = v[2 * jj], c = v[2 * jj + 1];
;       uint4 o; o.x = pack2(a.x * sc * g0.x, a.y * sc * g0.y); o.y = pack2(a.z * sc * g0.z, a.w * sc * g0.w);
;       o.z = pack2(c.x * sc * g1.x, c.y * sc * g1.y); o.w = pack2(c.z * sc * g1.z, c.w * sc * g1.w);
;       *(uint4*)(dst + row * 1024 + (2 * lane + 128 * jj) * 4) = o;
;     }
;   }
; }
	v_add_f32_e32 v56, v56, v58
	v_add_f32_e32 v57, v57, v59
	v_mov_b64_e32 v[58:59], s[30:31]
	v_fma_f32 v56, v56, s14, v58
	v_fma_f32 v57, v57, s14, v58
	s_nop 0
	v_mul_f32_e32 v0, 0x4b800000, v57
	v_cmp_gt_f32_e64 s[0:1], s3, v57
	v_cmp_gt_f32_e32 vcc, s3, v56
	s_nop 0
	v_cndmask_b32_e64 v0, v57, v0, s[0:1]
	v_rsq_f32_e32 v0, v0
	s_nop 0
	v_mul_f32_e32 v57, 0x45800000, v0
	v_cndmask_b32_e64 v0, v0, v57, s[0:1]
	v_mul_f32_e32 v22, v22, v0
	v_mul_f32_e32 v23, v23, v0
	v_mul_f32_e32 v24, v24, v0
	v_mul_f32_e32 v25, v25, v0
	v_mul_f32_e32 v18, v18, v0
	v_mul_f32_e32 v19, v19, v0
	v_mul_f32_e32 v22, v6, v22
	v_mul_f32_e32 v23, v7, v23
	v_mul_f32_e32 v24, v8, v24
	v_mul_f32_e32 v25, v9, v25
	v_mul_f32_e32 v18, v2, v18
	v_mul_f32_e32 v19, v3, v19
	v_cvt_pk_bf16_f32 v22, v22, v23
	v_cvt_pk_bf16_f32 v23, v24, v25
	v_cvt_pk_bf16_f32 v24, v18, v19
	v_mul_f32_e32 v18, v20, v0
	v_mul_f32_e32 v19, v21, v0
	v_mul_f32_e32 v20, v32, v0
	v_mul_f32_e32 v21, v33, v0
	v_mul_f32_e32 v18, v4, v18
	v_mul_f32_e32 v19, v5, v19
	v_mul_f32_e32 v20, v20, v16
	v_mul_f32_e32 v21, v21, v17
	v_cvt_pk_bf16_f32 v25, v18, v19
	v_mul_f32_e32 v18, v30, v0
	v_mul_f32_e32 v19, v31, v0
	global_store_dwordx4 v[50:51], v[22:25], off
	v_mul_f32_e32 v18, v18, v14
	v_mul_f32_e32 v19, v19, v15
	s_mov_b64 s[0:1], 0x2000
	v_cvt_pk_bf16_f32 v18, v18, v19
	v_cvt_pk_bf16_f32 v19, v20, v21
	v_mul_f32_e32 v20, v26, v0
	v_mul_f32_e32 v21, v27, v0
	v_mul_f32_e32 v22, v28, v0
	v_mul_f32_e32 v23, v29, v0
	v_mul_f32_e32 v0, 0x4b800000, v56
	v_cndmask_b32_e32 v0, v56, v0, vcc
	v_rsq_f32_e32 v0, v0
	v_mul_f32_e32 v20, v20, v10
	v_mul_f32_e32 v21, v21, v11
	v_mul_f32_e32 v22, v22, v12
	v_mul_f32_e32 v23, v23, v13
	v_cvt_pk_bf16_f32 v20, v20, v21
	v_cvt_pk_bf16_f32 v21, v22, v23
	global_store_dwordx4 v[50:51], v[18:21], off offset:1024
	s_nop 1
	v_mul_f32_e32 v18, 0x45800000, v0
	v_cndmask_b32_e32 v0, v0, v18, vcc
	v_mul_f32_e32 v18, v42, v0
	v_mul_f32_e32 v19, v43, v0
	v_mul_f32_e32 v20, v44, v0
	v_mul_f32_e32 v21, v45, v0
	v_mul_f32_e32 v18, v6, v18
	v_mul_f32_e32 v19, v7, v19
	v_mul_f32_e32 v20, v8, v20
	v_mul_f32_e32 v21, v9, v21
	v_cvt_pk_bf16_f32 v18, v18, v19
	v_cvt_pk_bf16_f32 v19, v20, v21
	v_mul_f32_e32 v20, v34, v0
	v_mul_f32_e32 v21, v35, v0
	v_mul_f32_e32 v22, v36, v0
	v_mul_f32_e32 v23, v37, v0
	v_mul_f32_e32 v20, v2, v20
	v_mul_f32_e32 v21, v3, v21
	v_mul_f32_e32 v22, v4, v22
	v_mul_f32_e32 v23, v5, v23
	v_cvt_pk_bf16_f32 v20, v20, v21
	v_cvt_pk_bf16_f32 v21, v22, v23
	global_store_dwordx4 v[50:51], v[18:21], off offset:2048
	v_mul_f32_e32 v22, v40, v0
	v_mul_f32_e32 v23, v41, v0
	v_add_co_u32_e32 v42, vcc, s7, v52
	v_mul_f32_e32 v18, v46, v0
	v_mul_f32_e32 v19, v47, v0
	v_mul_f32_e32 v20, v48, v0
	v_mul_f32_e32 v21, v49, v0
	v_mul_f32_e32 v18, v14, v18
	v_mul_f32_e32 v19, v15, v19
	v_mul_f32_e32 v20, v16, v20
	v_mul_f32_e32 v21, v17, v21
	v_cvt_pk_bf16_f32 v18, v18, v19
	v_cvt_pk_bf16_f32 v19, v20, v21
	v_mul_f32_e32 v20, v38, v0
	v_mul_f32_e32 v21, v39, v0
	v_mul_f32_e32 v22, v12, v22
	v_mul_f32_e32 v23, v13, v23
	v_mul_f32_e32 v20, v10, v20
	v_mul_f32_e32 v21, v11, v21
	v_addc_co_u32_e32 v43, vcc, 0, v53, vcc
	v_cvt_pk_bf16_f32 v20, v20, v21
	v_cvt_pk_bf16_f32 v21, v22, v23
	global_store_dwordx4 v[50:51], v[18:21], off offset:3072
	v_lshl_add_u64 v[22:23], v[52:53], 0, s[0:1]
	global_load_dwordx4 v[18:21], v[54:55], off
	s_nop 0
	global_load_dwordx4 v[22:25], v[22:23], off offset:16
	s_mov_b64 s[0:1], 0x2800
	v_lshl_add_u64 v[30:31], v[52:53], 0, s[0:1]
	s_mov_b64 s[0:1], 0x3000
	v_add_co_u32_e32 v66, vcc, s2, v52
	v_lshl_add_u64 v[46:47], v[52:53], 0, s[28:29]
	s_nop 0
	v_addc_co_u32_e32 v67, vcc, 0, v53, vcc
	s_waitcnt vmcnt(1)
	v_mov_b32_e32 v34, v19
	s_waitcnt vmcnt(0)
	v_mov_b32_e32 v35, v23
	v_mov_b32_e32 v32, v18
	v_mov_b32_e32 v33, v22
	v_mul_f32_e32 v34, v34, v34
	v_mul_f32_e32 v35, v35, v35
	v_mov_b32_e32 v26, v20
	v_mov_b32_e32 v27, v24
	v_fma_f32 v32, v32, v32, v34
	v_fma_f32 v33, v33, v33, v35
	v_mov_b32_e32 v28, v21
	v_mov_b32_e32 v29, v25
	v_fma_f32 v26, v26, v26, v32
	v_fma_f32 v27, v27, v27, v33
	s_nop 0
	v_fma_f32 v56, v28, v28, v26
	v_fma_f32 v57, v29, v29, v27
	global_load_dwordx4 v[26:29], v[54:55], off offset:2048
	s_nop 0
	global_load_dwordx4 v[30:33], v[30:31], off offset:16
	s_waitcnt vmcnt(1)
	v_mov_b32_e32 v40, v27
	s_waitcnt vmcnt(0)
	v_mov_b32_e32 v41, v31
	v_mov_b32_e32 v38, v26
	v_mov_b32_e32 v39, v30
	v_mul_f32_e32 v40, v40, v40
	v_mul_f32_e32 v41, v41, v41
	v_mov_b32_e32 v34, v28
	v_mov_b32_e32 v35, v32
	v_fma_f32 v38, v38, v38, v40
	v_fma_f32 v39, v39, v39, v41
	v_mov_b32_e32 v36, v29
	v_mov_b32_e32 v37, v33
	v_fma_f32 v34, v34, v34, v38
	v_fma_f32 v35, v35, v35, v39
	v_lshl_add_u64 v[38:39], v[52:53], 0, s[0:1]
	v_fma_f32 v54, v36, v36, v34
	v_fma_f32 v55, v37, v37, v35
	global_load_dwordx4 v[34:37], v[66:67], off offset:-4096
	s_nop 0
	global_load_dwordx4 v[38:41], v[38:39], off offset:16
	s_waitcnt vmcnt(1)
	v_mov_b32_e32 v70, v35
	s_waitcnt vmcnt(0)
	v_mov_b32_e32 v71, v39
	v_mov_b32_e32 v68, v34
	v_mov_b32_e32 v69, v38
	v_mul_f32_e32 v70, v70, v70
	v_mul_f32_e32 v71, v71, v71
	v_mov_b32_e32 v44, v36
	v_mov_b32_e32 v45, v40
	v_fma_f32 v68, v68, v68, v70
	v_fma_f32 v69, v69, v69, v71
	v_mov_b32_e32 v48, v37
	v_mov_b32_e32 v49, v41
	v_fma_f32 v44, v44, v44, v68
	v_fma_f32 v45, v45, v45, v69
	s_nop 0
	v_fma_f32 v68, v48, v48, v44
	v_fma_f32 v69, v49, v49, v45
	global_load_dwordx4 v[42:45], v[42:43], off offset:2048
	s_nop 0
	global_load_dwordx4 v[46:49], v[46:47], off offset:16
	s_waitcnt vmcnt(1)
	v_mov_b32_e32 v76, v43
	s_waitcnt vmcnt(0)
; DI unsigned pack2(float a, float b) { f2_t v = {a, b}; bf2_t r = __builtin_convertvector(v, bf2_t); return __builtin_bit_cast(unsigned, r); }
; DI int otid() { int t; asm volatile("v_mov_b32 %0, %1" : "=v"(t) : "v"((int)threadIdx.x)); __builtin_assume(t >= 0 && t < 256); return t; }
; DI void norm_rows_bf16(const float* __restrict__ src, const float* __restrict__ g, bf16_t* __restrict__ dst, int item) {
;   const int lane = otid() & 63, wid = otid() >> 6;
;   for (int i = 0; i < 8; ++i) {
;     size_t row = (size_t)item * 32 + wid * 8 + i;
;     const float4* s = (const float4*)(src + row * 1024);
;     float4 v[4]; float ss = 0.f;
; #pragma unroll
;     for (int j = 0; j < 4; ++j) { v[j] = s[2 * lane + (j & 1) + 128 * (j >> 1)]; ss += v[j].x * v[j].x + v[j].y * v[j].y + v[j].z * v[j].z + v[j].w * v[j].w; }
;     ss = wave_sum(ss);
;     float sc = rsqrtf(ss * (1.0f / 1024.0f) + 1e-6f);
; #pragma unroll
;     for (int jj = 0; jj < 2; ++jj) {
;       float4 g0 = ((const float4*)g)[2 * lane + 128 * jj], g1 = ((const float4*)g)[2 * lane + 1 + 128 * jj];
;       const float4 a = v[2 * jj], c = v[2 * jj + 1];
;       uint4 o; o.x = pack2(a.x * sc * g0.x, a.y * sc * g0.y); o.y = pack2(a.z * sc * g0.z, a.w * sc * g0.w);
;       o.z = pack2(c.x * sc * g1.x, c.y * sc * g1.y); o.w = pack2(c.z * sc * g1.z, c.w * sc * g1.w);
;       *(uint4*)(dst + row * 1024 + (2 * lane + 128 * jj) * 4) = o;
;     }
;   }
; }
	v_mov_b32_e32 v77, v47
	v_mov_b32_e32 v74, v42
	v_mov_b32_e32 v75, v46
	v_mul_f32_e32 v76, v76, v76
	v_mul_f32_e32 v77, v77, v77
	v_mov_b32_e32 v70, v44
	v_mov_b32_e32 v71, v48
	v_fma_f32 v74, v74, v74, v76
	v_fma_f32 v75, v75, v75, v77
	v_mov_b32_e32 v72, v45
	v_mov_b32_e32 v73, v49
	v_fma_f32 v70, v70, v70, v74
	v_fma_f32 v71, v71, v71, v75
	s_nop 0
	v_fma_f32 v70, v72, v72, v70
	v_fma_f32 v71, v73, v73, v71
	v_mov_b32_e32 v72, v68
	v_mov_b32_e32 v73, v56
	v_mov_b32_e32 v56, v69
	v_add_f32_e32 v56, v72, v56
	v_add_f32_e32 v57, v73, v57
	v_mov_b32_e32 v68, v70
	v_mov_b32_e32 v69, v54
	v_add_f32_e32 v56, v56, v68
	v_add_f32_e32 v57, v57, v69
	v_mov_b32_e32 v54, v71
	v_add_f32_e32 v54, v56, v54
	v_add_f32_e32 v55, v57, v55
	ds_bpermute_b32 v57, v60, v55
	ds_bpermute_b32 v56, v60, v54
	s_waitcnt lgkmcnt(0)
	v_add_f32_e32 v54, v54, v56
	v_add_f32_e32 v55, v55, v57
	ds_bpermute_b32 v57, v61, v55
	ds_bpermute_b32 v56, v61, v54
	s_waitcnt lgkmcnt(0)
	v_add_f32_e32 v54, v54, v56
	v_add_f32_e32 v55, v55, v57
	ds_bpermute_b32 v57, v62, v55
	ds_bpermute_b32 v56, v62, v54
	s_waitcnt lgkmcnt(0)
	v_add_f32_e32 v54, v54, v56
	v_add_f32_e32 v55, v55, v57
	ds_bpermute_b32 v57, v63, v55
	ds_bpermute_b32 v56, v63, v54
	s_waitcnt lgkmcnt(0)
	v_add_f32_e32 v54, v54, v56
	v_add_f32_e32 v55, v55, v57
	ds_bpermute_b32 v57, v64, v55
	ds_bpermute_b32 v56, v64, v54
	s_waitcnt lgkmcnt(0)
	v_add_f32_e32 v54, v54, v56
	v_add_f32_e32 v55, v55, v57
	ds_bpermute_b32 v57, v65, v55
	ds_bpermute_b32 v56, v65, v54
	s_waitcnt lgkmcnt(0)
	v_add_f32_e32 v54, v54, v56
	v_add_f32_e32 v55, v55, v57
	s_nop 0
	v_fma_f32 v54, v54, s14, v58
	v_fma_f32 v55, v55, s14, v58
	s_nop 0
	v_mul_f32_e32 v0, 0x4b800000, v55
	v_cmp_gt_f32_e64 s[0:1], s3, v55
	v_cmp_gt_f32_e32 vcc, s3, v54
	s_nop 0
	v_cndmask_b32_e64 v0, v55, v0, s[0:1]
	v_rsq_f32_e32 v0, v0
	s_nop 0
	v_mul_f32_e32 v55, 0x45800000, v0
	v_cndmask_b32_e64 v0, v0, v55, s[0:1]
	v_mul_f32_e32 v18, v18, v0
	v_mul_f32_e32 v19, v19, v0
	v_mul_f32_e32 v20, v20, v0
	v_mul_f32_e32 v21, v21, v0
	v_mul_f32_e32 v18, v6, v18
	v_mul_f32_e32 v19, v7, v19
	v_mul_f32_e32 v20, v8, v20
	v_mul_f32_e32 v21, v9, v21
	v_cvt_pk_bf16_f32 v18, v18, v19
	v_cvt_pk_bf16_f32 v19, v20, v21
	v_mul_f32_e32 v20, v22, v0
	v_mul_f32_e32 v21, v23, v0
	v_mul_f32_e32 v22, v24, v0
	v_mul_f32_e32 v23, v25, v0
	v_mul_f32_e32 v20, v2, v20
	v_mul_f32_e32 v21, v3, v21
	v_mul_f32_e32 v22, v4, v22
	v_mul_f32_e32 v23, v5, v23
	v_cvt_pk_bf16_f32 v20, v20, v21
	v_cvt_pk_bf16_f32 v21, v22, v23
	v_add_co_u32_e64 v22, s[0:1], s85, v50
	v_mul_f32_e32 v24, v32, v0
	v_mul_f32_e32 v25, v33, v0
	s_nop 0
	v_addc_co_u32_e64 v23, s[0:1], 0, v51, s[0:1]
	v_add_co_u32_e64 v56, s[0:1], s11, v50
	v_mul_f32_e32 v24, v12, v24
	v_mul_f32_e32 v25, v13, v25
	s_nop 0
	v_addc_co_u32_e64 v57, s[0:1], 0, v51, s[0:1]
	global_store_dwordx4 v[56:57], v[18:21], off offset:-4096
	s_nop 1
	v_mul_f32_e32 v18, v26, v0
	v_mul_f32_e32 v19, v27, v0
	v_mul_f32_e32 v20, v28, v0
	v_mul_f32_e32 v21, v29, v0
	v_mul_f32_e32 v18, v14, v18
	v_mul_f32_e32 v19, v15, v19
	v_mul_f32_e32 v20, v16, v20
	v_mul_f32_e32 v21, v17, v21
	v_cvt_pk_bf16_f32 v18, v18, v19
	v_cvt_pk_bf16_f32 v19, v20, v21
	v_mul_f32_e32 v20, v30, v0
	v_mul_f32_e32 v21, v31, v0
	v_mul_f32_e32 v0, 0x4b800000, v54
	v_cndmask_b32_e32 v0, v54, v0, vcc
	v_rsq_f32_e32 v0, v0
	v_mul_f32_e32 v20, v10, v20
	v_mul_f32_e32 v21, v11, v21
	v_lshl_add_u64 v[30:31], v[52:53], 0, s[90:91]
	v_cvt_pk_bf16_f32 v20, v20, v21
	v_cvt_pk_bf16_f32 v21, v24, v25
	global_store_dwordx4 v[22:23], v[18:21], off offset:1024
	s_nop 1
	v_mul_f32_e32 v18, 0x45800000, v0
	v_cndmask_b32_e32 v0, v0, v18, vcc
	v_mul_f32_e32 v18, v34, v0
	v_mul_f32_e32 v19, v35, v0
	v_mul_f32_e32 v20, v36, v0
	v_mul_f32_e32 v21, v37, v0
	v_mul_f32_e32 v18, v6, v18
	v_mul_f32_e32 v19, v7, v19
	v_mul_f32_e32 v20, v8, v20
	v_mul_f32_e32 v21, v9, v21
	v_cvt_pk_bf16_f32 v18, v18, v19
	v_cvt_pk_bf16_f32 v19, v20, v21
	v_mul_f32_e32 v20, v38, v0
	v_mul_f32_e32 v21, v39, v0
	v_mul_f32_e32 v24, v40, v0
	v_mul_f32_e32 v25, v41, v0
	v_mul_f32_e32 v20, v2, v20
	v_mul_f32_e32 v21, v3, v21
	v_mul_f32_e32 v24, v4, v24
	v_mul_f32_e32 v25, v5, v25
	v_cvt_pk_bf16_f32 v20, v20, v21
	v_cvt_pk_bf16_f32 v21, v24, v25
	global_store_dwordx4 v[22:23], v[18:21], off offset:2048
	v_mul_f32_e32 v24, v48, v0
	v_mul_f32_e32 v25, v49, v0
	s_nop 0
	v_mul_f32_e32 v18, v42, v0
	v_mul_f32_e32 v19, v43, v0
	v_mul_f32_e32 v20, v44, v0
	v_mul_f32_e32 v21, v45, v0
	v_mul_f32_e32 v18, v14, v18
	v_mul_f32_e32 v19, v15, v19
	v_mul_f32_e32 v20, v16, v20
	v_mul_f32_e32 v21, v17, v21
	v_cvt_pk_bf16_f32 v18, v18, v19
	v_cvt_pk_bf16_f32 v19, v20, v21
	v_mul_f32_e32 v20, v46, v0
	v_mul_f32_e32 v21, v47, v0
	v_mul_f32_e32 v24, v12, v24
	v_mul_f32_e32 v25, v13, v25
	v_mul_f32_e32 v20, v10, v20
	v_mul_f32_e32 v21, v11, v21
	v_add_co_u32_e32 v42, vcc, s31, v52
	v_cvt_pk_bf16_f32 v20, v20, v21
	v_cvt_pk_bf16_f32 v21, v24, v25
	global_store_dwordx4 v[22:23], v[18:21], off offset:3072
	v_lshl_add_u64 v[22:23], v[52:53], 0, s[86:87]
	global_load_dwordx4 v[18:21], v[66:67], off
	s_nop 0
	global_load_dwordx4 v[22:25], v[22:23], off offset:16
	v_addc_co_u32_e32 v43, vcc, 0, v53, vcc
	v_add_co_u32_e32 v68, vcc, s43, v52
	v_lshl_add_u64 v[46:47], v[52:53], 0, s[34:35]
	s_nop 0
	v_addc_co_u32_e32 v69, vcc, 0, v53, vcc
	s_waitcnt vmcnt(1)
	v_mov_b32_e32 v34, v19
	s_waitcnt vmcnt(0)
	v_mov_b32_e32 v35, v23
	v_mov_b32_e32 v32, v18
	v_mov_b32_e32 v33, v22
	v_mul_f32_e32 v34, v34, v34
	v_mul_f32_e32 v35, v35, v35
	v_mov_b32_e32 v26, v20
	v_mov_b32_e32 v27, v24
	v_fma_f32 v32, v32, v32, v34
	v_fma_f32 v33, v33, v33, v35
	v_mov_b32_e32 v28, v21
	v_mov_b32_e32 v29, v25
	v_fma_f32 v26, v26, v26, v32
	v_fma_f32 v27, v27, v27, v33
	s_nop 0
	v_fma_f32 v54, v28, v28, v26
	v_fma_f32 v55, v29, v29, v27
	global_load_dwordx4 v[26:29], v[66:67], off offset:2048
	s_nop 0
	global_load_dwordx4 v[30:33], v[30:31], off offset:16
	s_waitcnt vmcnt(1)
; DI unsigned pack2(float a, float b) { f2_t v = {a, b}; bf2_t r = __builtin_convertvector(v, bf2_t); return __builtin_bit_cast(unsigned, r); }
; DI int otid() { int t; asm volatile("v_mov_b32 %0, %1" : "=v"(t) : "v"((int)threadIdx.x)); __builtin_assume(t >= 0 && t < 256); return t; }
; DI void norm_rows_bf16(const float* __restrict__ src, const float* __restrict__ g, bf16_t* __restrict__ dst, int item) {
;   const int lane = otid() & 63, wid = otid() >> 6;
;   for (int i = 0; i < 8; ++i) {
;     size_t row = (size_t)item * 32 + wid * 8 + i;
;     const float4* s = (const float4*)(src + row * 1024);
;     float4 v[4]; float ss = 0.f;
; #pragma unroll
;     for (int j = 0; j < 4; ++j) { v[j] = s[2 * lane + (j & 1) + 128 * (j >> 1)]; ss += v[j].x * v[j].x + v[j].y * v[j].y + v[j].z * v[j].z + v[j].w * v[j].w; }
;     ss = wave_sum(ss);
;     float sc = rsqrtf(ss * (1.0f / 1024.0f) + 1e-6f);
; #pragma unroll
;     for (int jj = 0; jj < 2; ++jj) {
;       float4 g0 = ((const float4*)g)[2 * lane + 128 * jj], g1 = ((const float4*)g)[2 * lane + 1 + 128 * jj];
;       const float4 a = v[2 * jj], c = v[2 * jj + 1];
;       uint4 o; o.x = pack2(a.x * sc * g0.x, a.y * sc * g0.y); o.y = pack2(a.z * sc * g0.z, a.w * sc * g0.w);
;       o.z = pack2(c.x * sc * g1.x, c.y * sc * g1.y); o.w = pack2(c.z * sc * g1.z, c.w * sc * g1.w);
;       *(uint4*)(dst + row * 1024 + (2 * lane + 128 * jj) * 4) = o;
;     }
;   }
; }
	v_mov_b32_e32 v40, v27
	s_waitcnt vmcnt(0)
	v_mov_b32_e32 v41, v31
	v_mov_b32_e32 v38, v26
	v_mov_b32_e32 v39, v30
	v_mul_f32_e32 v40, v40, v40
	v_mul_f32_e32 v41, v41, v41
	v_mov_b32_e32 v34, v28
	v_mov_b32_e32 v35, v32
	v_fma_f32 v38, v38, v38, v40
	v_fma_f32 v39, v39, v39, v41
	v_mov_b32_e32 v36, v29
	v_mov_b32_e32 v37, v33
	v_fma_f32 v34, v34, v34, v38
	v_fma_f32 v35, v35, v35, v39
	v_lshl_add_u64 v[38:39], v[52:53], 0, s[4:5]
	v_fma_f32 v66, v36, v36, v34
	v_fma_f32 v67, v37, v37, v35
	global_load_dwordx4 v[34:37], v[68:69], off offset:-4096
	s_nop 0
	global_load_dwordx4 v[38:41], v[38:39], off offset:16
	s_waitcnt vmcnt(1)
	v_mov_b32_e32 v72, v35
	s_waitcnt vmcnt(0)
	v_mov_b32_e32 v73, v39
	v_mov_b32_e32 v70, v34
	v_mov_b32_e32 v71, v38
	v_mul_f32_e32 v72, v72, v72
	v_mul_f32_e32 v73, v73, v73
	v_mov_b32_e32 v44, v36
	v_mov_b32_e32 v45, v40
	v_fma_f32 v70, v70, v70, v72
	v_fma_f32 v71, v71, v71, v73
	v_mov_b32_e32 v48, v37
	v_mov_b32_e32 v49, v41
	v_fma_f32 v44, v44, v44, v70
	v_fma_f32 v45, v45, v45, v71
	s_nop 0
	v_fma_f32 v70, v48, v48, v44
	v_fma_f32 v71, v49, v49, v45
	global_load_dwordx4 v[42:45], v[42:43], off offset:2048
	s_nop 0
	global_load_dwordx4 v[46:49], v[46:47], off offset:16
	s_waitcnt vmcnt(1)
	v_mov_b32_e32 v78, v43
	s_waitcnt vmcnt(0)
	v_mov_b32_e32 v79, v47
	v_mov_b32_e32 v76, v42
	v_mov_b32_e32 v77, v46
	v_mul_f32_e32 v78, v78, v78
	v_mul_f32_e32 v79, v79, v79
	v_mov_b32_e32 v72, v44
	v_mov_b32_e32 v73, v48
	v_fma_f32 v76, v76, v76, v78
	v_fma_f32 v77, v77, v77, v79
	v_mov_b32_e32 v74, v45
	v_mov_b32_e32 v75, v49
	v_fma_f32 v72, v72, v72, v76
	v_fma_f32 v73, v73, v73, v77
	s_nop 0
	v_fma_f32 v72, v74, v74, v72
	v_fma_f32 v73, v75, v75, v73
	v_mov_b32_e32 v74, v70
	v_mov_b32_e32 v75, v54
	v_mov_b32_e32 v54, v71
	v_add_f32_e32 v54, v74, v54
	v_add_f32_e32 v55, v75, v55
	v_mov_b32_e32 v70, v72
	v_mov_b32_e32 v71, v66
	v_add_f32_e32 v54, v54, v70
	v_add_f32_e32 v55, v55, v71
	v_mov_b32_e32 v66, v73
	v_add_f32_e32 v54, v54, v66
	v_add_f32_e32 v55, v55, v67
	ds_bpermute_b32 v67, v60, v55
	ds_bpermute_b32 v66, v60, v54
	s_waitcnt lgkmcnt(0)
	v_add_f32_e32 v54, v54, v66
	v_add_f32_e32 v55, v55, v67
	ds_bpermute_b32 v67, v61, v55
	ds_bpermute_b32 v66, v61, v54
	s_waitcnt lgkmcnt(0)
	v_add_f32_e32 v54, v54, v66
	v_add_f32_e32 v55, v55, v67
	ds_bpermute_b32 v67, v62, v55
	ds_bpermute_b32 v66, v62, v54
	s_waitcnt lgkmcnt(0)
	v_add_f32_e32 v54, v54, v66
	v_add_f32_e32 v55, v55, v67
	ds_bpermute_b32 v67, v63, v55
	ds_bpermute_b32 v66, v63, v54
	s_waitcnt lgkmcnt(0)
	v_add_f32_e32 v54, v54, v66
	v_add_f32_e32 v55, v55, v67
	ds_bpermute_b32 v67, v64, v55
	ds_bpermute_b32 v66, v64, v54
	s_waitcnt lgkmcnt(0)
	v_add_f32_e32 v54, v54, v66
	v_add_f32_e32 v55, v55, v67
	ds_bpermute_b32 v67, v65, v55
	ds_bpermute_b32 v66, v65, v54
	s_waitcnt lgkmcnt(0)
	v_add_f32_e32 v54, v54, v66
	v_add_f32_e32 v55, v55, v67
	s_nop 0
	v_fma_f32 v54, v54, s14, v58
	v_fma_f32 v55, v55, s14, v58
	s_nop 0
	v_mul_f32_e32 v0, 0x4b800000, v55
	v_cmp_gt_f32_e64 s[0:1], s3, v55
	v_cmp_gt_f32_e32 vcc, s3, v54
	s_nop 0
	v_cndmask_b32_e64 v0, v55, v0, s[0:1]
	v_rsq_f32_e32 v0, v0
	s_nop 0
	v_mul_f32_e32 v55, 0x45800000, v0
	v_cndmask_b32_e64 v0, v0, v55, s[0:1]
	v_mul_f32_e32 v18, v18, v0
	v_mul_f32_e32 v19, v19, v0
	v_mul_f32_e32 v20, v20, v0
	v_mul_f32_e32 v21, v21, v0
	v_mul_f32_e32 v18, v6, v18
	v_mul_f32_e32 v19, v7, v19
	v_mul_f32_e32 v20, v8, v20
	v_mul_f32_e32 v21, v9, v21
	v_cvt_pk_bf16_f32 v18, v18, v19
	v_cvt_pk_bf16_f32 v19, v20, v21
	v_mul_f32_e32 v20, v22, v0
	v_mul_f32_e32 v21, v23, v0
	v_mul_f32_e32 v22, v24, v0
	v_mul_f32_e32 v23, v25, v0
	v_mul_f32_e32 v20, v2, v20
	v_mul_f32_e32 v21, v3, v21
	v_mul_f32_e32 v22, v4, v22
	v_mul_f32_e32 v23, v5, v23
	v_cvt_pk_bf16_f32 v20, v20, v21
	v_cvt_pk_bf16_f32 v21, v22, v23
	global_store_dwordx4 v[56:57], v[18:21], off
	v_mul_f32_e32 v22, v32, v0
	v_mul_f32_e32 v23, v33, v0
	s_nop 0
	v_mul_f32_e32 v18, v26, v0
	v_mul_f32_e32 v19, v27, v0
	v_mul_f32_e32 v20, v28, v0
	v_mul_f32_e32 v21, v29, v0
	v_mul_f32_e32 v18, v14, v18
	v_mul_f32_e32 v19, v15, v19
	v_mul_f32_e32 v20, v16, v20
	v_mul_f32_e32 v21, v17, v21
	v_cvt_pk_bf16_f32 v18, v18, v19
	v_cvt_pk_bf16_f32 v19, v20, v21
	v_mul_f32_e32 v20, v30, v0
	v_mul_f32_e32 v21, v31, v0
	v_mul_f32_e32 v0, 0x4b800000, v54
	v_cndmask_b32_e32 v0, v54, v0, vcc
	v_rsq_f32_e32 v0, v0
	v_mul_f32_e32 v20, v10, v20
	v_mul_f32_e32 v21, v11, v21
	v_mul_f32_e32 v22, v12, v22
	v_mul_f32_e32 v23, v13, v23
	v_cvt_pk_bf16_f32 v20, v20, v21
	v_cvt_pk_bf16_f32 v21, v22, v23
	global_store_dwordx4 v[56:57], v[18:21], off offset:1024
	v_lshl_add_u64 v[30:31], v[52:53], 0, s[96:97]
	s_nop 0
	v_mul_f32_e32 v18, 0x45800000, v0
	v_cndmask_b32_e32 v0, v0, v18, vcc
	v_mul_f32_e32 v18, v34, v0
	v_mul_f32_e32 v19, v35, v0
	v_mul_f32_e32 v20, v36, v0
	v_mul_f32_e32 v21, v37, v0
	v_mul_f32_e32 v18, v6, v18
	v_mul_f32_e32 v19, v7, v19
	v_mul_f32_e32 v20, v8, v20
	v_mul_f32_e32 v21, v9, v21
	v_cvt_pk_bf16_f32 v18, v18, v19
	v_cvt_pk_bf16_f32 v19, v20, v21
	v_mul_f32_e32 v20, v38, v0
	v_mul_f32_e32 v21, v39, v0
	v_mul_f32_e32 v22, v40, v0
	v_mul_f32_e32 v23, v41, v0
	v_mul_f32_e32 v20, v2, v20
	v_mul_f32_e32 v21, v3, v21
	v_mul_f32_e32 v22, v4, v22
	v_mul_f32_e32 v23, v5, v23
	v_cvt_pk_bf16_f32 v20, v20, v21
	v_cvt_pk_bf16_f32 v21, v22, v23
	global_store_dwordx4 v[56:57], v[18:21], off offset:2048
	v_mul_f32_e32 v22, v48, v0
	v_mul_f32_e32 v23, v49, v0
	s_nop 0
	v_mul_f32_e32 v18, v42, v0
	v_mul_f32_e32 v19, v43, v0
	v_mul_f32_e32 v20, v44, v0
	v_mul_f32_e32 v21, v45, v0
	v_mul_f32_e32 v18, v14, v18
	v_mul_f32_e32 v19, v15, v19
	v_mul_f32_e32 v20, v16, v20
	v_mul_f32_e32 v21, v17, v21
	v_cvt_pk_bf16_f32 v18, v18, v19
	v_cvt_pk_bf16_f32 v19, v20, v21
	v_mul_f32_e32 v20, v46, v0
	v_mul_f32_e32 v21, v47, v0
	v_mul_f32_e32 v22, v12, v22
	v_mul_f32_e32 v23, v13, v23
	v_mul_f32_e32 v20, v10, v20
	v_mul_f32_e32 v21, v11, v21
	v_add_co_u32_e32 v42, vcc, s84, v52
	v_cvt_pk_bf16_f32 v20, v20, v21
	v_cvt_pk_bf16_f32 v21, v22, v23
	global_store_dwordx4 v[56:57], v[18:21], off offset:3072
	v_lshl_add_u64 v[22:23], v[52:53], 0, s[82:83]
	global_load_dwordx4 v[18:21], v[68:69], off
	s_nop 0
	global_load_dwordx4 v[22:25], v[22:23], off offset:16
	v_addc_co_u32_e32 v43, vcc, 0, v53, vcc
	v_lshl_add_u64 v[46:47], v[52:53], 0, s[98:99]
	s_waitcnt vmcnt(1)
; DI unsigned pack2(float a, float b) { f2_t v = {a, b}; bf2_t r = __builtin_convertvector(v, bf2_t); return __builtin_bit_cast(unsigned, r); }
; DI int otid() { int t; asm volatile("v_mov_b32 %0, %1" : "=v"(t) : "v"((int)threadIdx.x)); __builtin_assume(t >= 0 && t < 256); return t; }
; DI void norm_rows_bf16(const float* __restrict__ src, const float* __restrict__ g, bf16_t* __restrict__ dst, int item) {
;   const int lane = otid() & 63, wid = otid() >> 6;
;   for (int i = 0; i < 8; ++i) {
;     size_t row = (size_t)item * 32 + wid * 8 + i;
;     const float4* s = (const float4*)(src + row * 1024);
;     float4 v[4]; float ss = 0.f;
; #pragma unroll
;     for (int j = 0; j < 4; ++j) { v[j] = s[2 * lane + (j & 1) + 128 * (j >> 1)]; ss += v[j].x * v[j].x + v[j].y * v[j].y + v[j].z * v[j].z + v[j].w * v[j].w; }
;     ss = wave_sum(ss);
;     float sc = rsqrtf(ss * (1.0f / 1024.0f) + 1e-6f);
; #pragma unroll
;     for (int jj = 0; jj < 2; ++jj) {
;       float4 g0 = ((const float4*)g)[2 * lane + 128 * jj], g1 = ((const float4*)g)[2 * lane + 1 + 128 * jj];
;       const float4 a = v[2 * jj], c = v[2 * jj + 1];
;       uint4 o; o.x = pack2(a.x * sc * g0.x, a.y * sc * g0.y); o.y = pack2(a.z * sc * g0.z, a.w * sc * g0.w);
;       o.z = pack2(c.x * sc * g1.x, c.y * sc * g1.y); o.w = pack2(c.z * sc * g1.z, c.w * sc * g1.w);
;       *(uint4*)(dst + row * 1024 + (2 * lane + 128 * jj) * 4) = o;
;     }
;   }
; }
	v_mov_b32_e32 v34, v19
	s_waitcnt vmcnt(0)
	v_mov_b32_e32 v35, v23
	v_mov_b32_e32 v32, v18
	v_mov_b32_e32 v33, v22
	v_mul_f32_e32 v34, v34, v34
	v_mul_f32_e32 v35, v35, v35
	v_mov_b32_e32 v26, v20
	v_mov_b32_e32 v27, v24
	v_fma_f32 v32, v32, v32, v34
	v_fma_f32 v33, v33, v33, v35
	v_mov_b32_e32 v28, v21
	v_mov_b32_e32 v29, v25
	v_fma_f32 v26, v26, v26, v32
	v_fma_f32 v27, v27, v27, v33
	s_nop 0
	v_fma_f32 v54, v28, v28, v26
	v_fma_f32 v55, v29, v29, v27
	global_load_dwordx4 v[26:29], v[68:69], off offset:2048
	s_nop 0
	global_load_dwordx4 v[30:33], v[30:31], off offset:16
	s_waitcnt vmcnt(1)
	v_mov_b32_e32 v40, v27
	s_waitcnt vmcnt(0)
	v_mov_b32_e32 v41, v31
	v_mov_b32_e32 v38, v26
	v_mov_b32_e32 v39, v30
	v_mul_f32_e32 v40, v40, v40
	v_mul_f32_e32 v41, v41, v41
	v_mov_b32_e32 v34, v28
	v_mov_b32_e32 v35, v32
	v_fma_f32 v38, v38, v38, v40
	v_fma_f32 v39, v39, v39, v41
	v_mov_b32_e32 v36, v29
	v_mov_b32_e32 v37, v33
	v_fma_f32 v34, v34, v34, v38
	v_fma_f32 v35, v35, v35, v39
	v_lshl_add_u64 v[38:39], v[52:53], 0, s[36:37]
	v_fma_f32 v56, v36, v36, v34
	v_fma_f32 v57, v37, v37, v35
	global_load_dwordx4 v[34:37], v[42:43], off
	s_nop 0
	global_load_dwordx4 v[38:41], v[38:39], off offset:16
	s_waitcnt vmcnt(1)
	v_mov_b32_e32 v66, v35
	s_waitcnt vmcnt(0)
	v_mov_b32_e32 v67, v39
	v_mov_b32_e32 v52, v34
	v_mov_b32_e32 v53, v38
	v_mul_f32_e32 v66, v66, v66
	v_mul_f32_e32 v67, v67, v67
	v_mov_b32_e32 v44, v36
	v_mov_b32_e32 v45, v40
	v_fma_f32 v52, v52, v52, v66
	v_fma_f32 v53, v53, v53, v67
	v_mov_b32_e32 v48, v37
	v_mov_b32_e32 v49, v41
	v_fma_f32 v44, v44, v44, v52
	v_fma_f32 v45, v45, v45, v53
	s_nop 0
	v_fma_f32 v52, v48, v48, v44
	v_fma_f32 v53, v49, v49, v45
	global_load_dwordx4 v[42:45], v[42:43], off offset:2048
	s_nop 0
	global_load_dwordx4 v[46:49], v[46:47], off offset:16
	s_waitcnt vmcnt(1)
	v_mov_b32_e32 v72, v43
	s_waitcnt vmcnt(0)
	v_mov_b32_e32 v73, v47
	v_mov_b32_e32 v70, v42
	v_mov_b32_e32 v71, v46
	v_mul_f32_e32 v72, v72, v72
	v_mul_f32_e32 v73, v73, v73
	v_mov_b32_e32 v66, v44
	v_mov_b32_e32 v67, v48
	v_fma_f32 v70, v70, v70, v72
	v_fma_f32 v71, v71, v71, v73
	v_mov_b32_e32 v68, v45
	v_mov_b32_e32 v69, v49
	v_fma_f32 v66, v66, v66, v70
	v_fma_f32 v67, v67, v67, v71
	s_nop 0
	v_fma_f32 v66, v68, v68, v66
	v_fma_f32 v67, v69, v69, v67
	v_mov_b32_e32 v68, v52
	v_mov_b32_e32 v69, v54
	v_mov_b32_e32 v54, v53
	v_add_f32_e32 v52, v68, v54
	v_add_f32_e32 v53, v69, v55
	v_mov_b32_e32 v54, v66
	v_mov_b32_e32 v55, v56
	v_add_f32_e32 v52, v52, v54
	v_add_f32_e32 v53, v53, v55
	v_mov_b32_e32 v56, v67
	v_add_f32_e32 v52, v52, v56
	v_add_f32_e32 v53, v53, v57
	ds_bpermute_b32 v55, v60, v53
	ds_bpermute_b32 v54, v60, v52
	s_waitcnt lgkmcnt(0)
	v_add_f32_e32 v52, v52, v54
	v_add_f32_e32 v53, v53, v55
	ds_bpermute_b32 v55, v61, v53
	ds_bpermute_b32 v54, v61, v52
	s_waitcnt lgkmcnt(0)
	v_add_f32_e32 v52, v52, v54
	v_add_f32_e32 v53, v53, v55
	ds_bpermute_b32 v55, v62, v53
	ds_bpermute_b32 v54, v62, v52
	s_waitcnt lgkmcnt(0)
	v_add_f32_e32 v52, v52, v54
	v_add_f32_e32 v53, v53, v55
	ds_bpermute_b32 v55, v63, v53
	ds_bpermute_b32 v54, v63, v52
	s_waitcnt lgkmcnt(0)
	v_add_f32_e32 v52, v52, v54
	v_add_f32_e32 v53, v53, v55
	ds_bpermute_b32 v55, v64, v53
	ds_bpermute_b32 v54, v64, v52
	s_waitcnt lgkmcnt(0)
	v_add_f32_e32 v52, v52, v54
	v_add_f32_e32 v53, v53, v55
	ds_bpermute_b32 v55, v65, v53
	ds_bpermute_b32 v54, v65, v52
	s_waitcnt lgkmcnt(0)
	v_add_f32_e32 v52, v52, v54
	v_add_f32_e32 v53, v53, v55
	s_nop 0
	v_fma_f32 v52, v52, s14, v58
	v_fma_f32 v53, v53, s14, v58
	s_nop 0
	v_mul_f32_e32 v0, 0x4b800000, v53
	v_cmp_gt_f32_e64 s[0:1], s3, v53
	v_cmp_gt_f32_e32 vcc, s3, v52
	s_nop 0
	v_cndmask_b32_e64 v0, v53, v0, s[0:1]
	v_rsq_f32_e32 v0, v0
	s_nop 0
	v_mul_f32_e32 v53, 0x45800000, v0
	v_cndmask_b32_e64 v0, v0, v53, s[0:1]
	v_mul_f32_e32 v18, v18, v0
	v_mul_f32_e32 v19, v19, v0
	v_mul_f32_e32 v20, v20, v0
	v_mul_f32_e32 v21, v21, v0
	v_mul_f32_e32 v18, v6, v18
	v_mul_f32_e32 v19, v7, v19
	v_mul_f32_e32 v20, v8, v20
	v_mul_f32_e32 v21, v9, v21
	v_cvt_pk_bf16_f32 v18, v18, v19
	v_cvt_pk_bf16_f32 v19, v20, v21
	v_mul_f32_e32 v20, v22, v0
	v_mul_f32_e32 v21, v23, v0
	v_mul_f32_e32 v22, v24, v0
	v_mul_f32_e32 v23, v25, v0
	v_mul_f32_e32 v20, v2, v20
	v_mul_f32_e32 v21, v3, v21
	v_mul_f32_e32 v22, v4, v22
	v_mul_f32_e32 v23, v5, v23
	v_cvt_pk_bf16_f32 v20, v20, v21
	v_cvt_pk_bf16_f32 v21, v22, v23
	v_add_co_u32_e64 v22, s[0:1], s7, v50
	v_mul_f32_e32 v24, v32, v0
	v_mul_f32_e32 v25, v33, v0
	s_nop 0
	v_addc_co_u32_e64 v23, s[0:1], 0, v51, s[0:1]
	global_store_dwordx4 v[22:23], v[18:21], off
	v_mul_f32_e32 v24, v12, v24
	v_mul_f32_e32 v25, v13, v25
	s_nop 0
	v_mul_f32_e32 v18, v26, v0
	v_mul_f32_e32 v19, v27, v0
	v_mul_f32_e32 v20, v28, v0
	v_mul_f32_e32 v21, v29, v0
	v_mul_f32_e32 v18, v14, v18
	v_mul_f32_e32 v19, v15, v19
	v_mul_f32_e32 v20, v16, v20
	v_mul_f32_e32 v21, v17, v21
	v_cvt_pk_bf16_f32 v18, v18, v19
	v_cvt_pk_bf16_f32 v19, v20, v21
	v_mul_f32_e32 v20, v30, v0
	v_mul_f32_e32 v21, v31, v0
	v_mul_f32_e32 v0, 0x4b800000, v52
	v_cndmask_b32_e32 v0, v52, v0, vcc
	v_rsq_f32_e32 v0, v0
	v_mul_f32_e32 v20, v10, v20
	v_mul_f32_e32 v21, v11, v21
	s_nop 0
	v_cvt_pk_bf16_f32 v20, v20, v21
	v_cvt_pk_bf16_f32 v21, v24, v25
	global_store_dwordx4 v[22:23], v[18:21], off offset:1024
	s_nop 1
	v_mul_f32_e32 v18, 0x45800000, v0
	v_cndmask_b32_e32 v0, v0, v18, vcc
	v_mul_f32_e32 v18, v34, v0
	v_mul_f32_e32 v19, v35, v0
	s_nop 0
	v_mul_f32_e32 v6, v6, v18
	v_mul_f32_e32 v7, v7, v19
	v_mul_f32_e32 v18, v36, v0
	v_mul_f32_e32 v19, v37, v0
	v_cvt_pk_bf16_f32 v6, v6, v7
	v_mul_f32_e32 v8, v8, v18
	v_mul_f32_e32 v9, v9, v19
	s_nop 0
	v_cvt_pk_bf16_f32 v7, v8, v9
	v_mul_f32_e32 v8, v38, v0
	v_mul_f32_e32 v9, v39, v0
	s_nop 0
	v_mul_f32_e32 v2, v2, v8
	v_mul_f32_e32 v3, v3, v9
	s_nop 0
	v_cvt_pk_bf16_f32 v8, v2, v3
	v_mul_f32_e32 v2, v40, v0
	v_mul_f32_e32 v3, v41, v0
	s_nop 0
	v_mul_f32_e32 v2, v4, v2
	v_mul_f32_e32 v3, v5, v3
	v_mul_f32_e32 v4, v44, v0
	v_mul_f32_e32 v5, v45, v0
	v_cvt_pk_bf16_f32 v9, v2, v3
	v_mul_f32_e32 v2, v42, v0
	v_mul_f32_e32 v3, v43, v0
	v_mul_f32_e32 v4, v16, v4
	v_mul_f32_e32 v5, v17, v5
	v_mul_f32_e32 v2, v14, v2
	v_mul_f32_e32 v3, v15, v3
	global_store_dwordx4 v[22:23], v[6:9], off offset:2048
	v_cvt_pk_bf16_f32 v2, v2, v3
	v_cvt_pk_bf16_f32 v3, v4, v5
	v_mul_f32_e32 v4, v46, v0
	v_mul_f32_e32 v5, v47, v0
	v_mul_f32_e32 v6, v48, v0
	v_mul_f32_e32 v7, v49, v0
	v_mul_f32_e32 v4, v10, v4
	v_mul_f32_e32 v5, v11, v5
	v_mul_f32_e32 v6, v12, v6
	v_mul_f32_e32 v7, v13, v7
	v_cvt_pk_bf16_f32 v4, v4, v5
	v_cvt_pk_bf16_f32 v5, v6, v7
	global_store_dwordx4 v[22:23], v[2:5], off offset:3072
	s_cbranch_scc0 .LBB0_34

; #define GLOAD(ko) do { \
;     _Pragma("unroll") for (int i = 0; i < 4; ++i) ra[i] = *(const u32x4*)(ap + (size_t)(32 * i) * lda + (ko)); \
;     _Pragma("unroll") for (int i = 0; i < NB; ++i) rb[i] = *(const u32x4*)(bp + (size_t)(bstride * i) * ldb + (ko)); } while (0)
; #define GSTORE(st) do { \
;     _Pragma("unroll") for (int i = 0; i < 4; ++i) *(u32x4*)(sA + (st) * GST + so + 32 * i * 64) = ra[i]; \
;     _Pragma("unroll") for (int i = 0; i < NB; ++i) *(u32x4*)(sB + (st) * GST + so + 32 * i * 64) = rb[i]; } while (0)
;     ...
;   __syncthreads();
;   GLOAD(0); GSTORE(0);
;   if (nk > 1) GLOAD(64);
;   __syncthreads();
;   for (int kt = 0; kt < nk; ++kt) {
;     const int cur = kt & 1;
;     if (kt + 1 < nk) { GSTORE(cur ^ 1); if (kt + 2 < nk) GLOAD((kt + 2) * 64); }
; DI void merge_tile(const Params& p, int l, int tile, char* smem) {
;     ...
; #pragma unroll 1
;   for (int n = 0; n < 4; ++n) {
;     f32x4 accB[4][2]; zero_acc<2>(accB);
;     gemm_mainloop<2>(accB, P_PROJ + (size_t)mt * 128 * PW + C_GATE + n * 256, PW, P_WBT + ((size_t)(l * 4 + n) * 1024 + nt * 64) * 256, 256, 256, sA, sB);
.LBB0_47:
	v_mov_b32_e32 v154, v111
	v_mov_b32_e32 v111, v164
	v_mov_b32_e32 v164, v88
	v_mov_b32_e32 v88, v183
	v_mov_b32_e32 v183, v97
	v_mov_b32_e32 v186, v106
	v_mov_b32_e32 v97, v213
	v_mov_b32_e32 v106, v214
	v_cvt_pk_bf16_f32 v214, v0, v158
	v_cvt_pk_bf16_f32 v213, v160, v161
	v_cvt_pk_bf16_f32 v160, v26, v27
	v_mov_b32 v26, v188
	s_add_u32 s12, s58, s22
	v_lshrrev_b32_e32 v0, 3, v26
	v_lshlrev_b32_e32 v4, 4, v26
	v_mul_u32_u24_e32 v2, 0x2600, v0
	v_and_b32_e32 v20, 0x70, v4
	v_mul_hi_u32_u24_e32 v3, 0x2600, v0
	v_or_b32_e32 v2, v2, v20
	s_addc_u32 s13, s59, s23
	v_lshl_add_u64 v[14:15], s[12:13], 0, v[2:3]
	v_add_co_u32_e32 v34, vcc, s11, v14
	s_mov_b32 s7, 0x6cf1000
	s_nop 0
	v_addc_co_u32_e32 v35, vcc, 0, v15, vcc
	v_add_co_u32_e32 v36, vcc, s7, v14
	s_mov_b32 s7, 0x6d3d000
	s_nop 0
	v_addc_co_u32_e32 v37, vcc, 0, v15, vcc
	v_mov_b32_e32 v157, v112
	v_mov_b32_e32 v112, v163
	v_mov_b32_e32 v163, v89
	v_mov_b32_e32 v89, v184
	v_mov_b32_e32 v184, v96
	v_mov_b32_e32 v96, v212
	v_cvt_pk_bf16_f32 v212, v171, v172
	v_cvt_pk_bf16_f32 v171, v70, v71
	v_add_co_u32_e32 v70, vcc, s7, v14
	v_lshlrev_b64 v[18:19], 9, v[0:1]
	s_nop 0
	v_addc_co_u32_e32 v71, vcc, 0, v15, vcc
	s_mov_b32 s7, 0x6d89000
	s_add_u32 s12, s58, s0
	v_mov_b32_e32 v155, v110
	v_mov_b32_e32 v110, v159
	v_mov_b32_e32 v159, v87
	v_mov_b32_e32 v87, v182
	v_mov_b32_e32 v182, v94
	v_mov_b32_e32 v94, v210
	v_cvt_pk_bf16_f32 v210, v169, v170
	v_cvt_pk_bf16_f32 v170, v72, v73
	v_add_co_u32_e32 v72, vcc, s7, v14
	v_or_b32_e32 v18, v18, v20
	s_addc_u32 s13, s59, s1
	s_barrier
	global_load_dwordx4 v[2:5], v[34:35], off offset:2560
	global_load_dwordx4 v[6:9], v[36:37], off offset:2560
	v_addc_co_u32_e32 v73, vcc, 0, v15, vcc
	v_lshl_add_u64 v[22:23], s[12:13], 0, v[18:19]
	s_mov_b32 s7, 0x2700000
	v_mov_b32_e32 v152, v121
	v_mov_b32_e32 v121, v167
	v_mov_b32_e32 v167, v78
	v_mov_b32_e32 v78, v74
	v_add_co_u32_e32 v74, vcc, s7, v22
	v_mov_b32_e32 v150, v119
	v_mov_b32_e32 v119, v178
	v_mov_b32_e32 v178, v80
	v_mov_b32_e32 v80, v75
	global_load_dwordx4 v[10:13], v[70:71], off offset:2560
	global_load_dwordx4 v[14:17], v[72:73], off offset:2560
	v_addc_co_u32_e32 v75, vcc, 0, v23, vcc
	s_mov_b32 s7, 0x2704000
	v_mov_b32_e32 v151, v118
	v_mov_b32_e32 v118, v177
	v_mov_b32_e32 v177, v81
	v_mov_b32_e32 v81, v76
	v_add_co_u32_e32 v76, vcc, s7, v22
	v_cvt_pk_bf16_f32 v169, v77, v207
	global_load_dwordx4 v[18:21], v[74:75], off
	v_addc_co_u32_e32 v77, vcc, 0, v23, vcc
	global_load_dwordx4 v[22:25], v[76:77], off
	v_lshrrev_b32_e32 v27, 4, v26
	v_cvt_pk_bf16_f32 v158, v28, v29
	v_xor_b32_e32 v28, v27, v26
	v_lshlrev_b32_e32 v28, 4, v28
	v_and_b32_e32 v28, 0x70, v28
	v_lshl_or_b32 v0, v0, 7, v28
	s_waitcnt vmcnt(5)
	ds_write_b128 v0, v[2:5]
	s_waitcnt vmcnt(4)
	ds_write_b128 v0, v[6:9] offset:4096
	s_waitcnt vmcnt(3)
	ds_write_b128 v0, v[10:13] offset:8192
	s_waitcnt vmcnt(2)
	ds_write_b128 v0, v[14:17] offset:12288
	s_waitcnt vmcnt(1)
	ds_write_b128 v0, v[18:21] offset:32768
	s_waitcnt vmcnt(0)
	ds_write_b128 v0, v[22:25] offset:36864
	global_load_dwordx4 v[2:5], v[34:35], off offset:2688
	global_load_dwordx4 v[6:9], v[36:37], off offset:2688
	global_load_dwordx4 v[10:13], v[70:71], off offset:2688
	global_load_dwordx4 v[14:17], v[72:73], off offset:2688
	global_load_dwordx4 v[18:21], v[74:75], off offset:128
	global_load_dwordx4 v[22:25], v[76:77], off offset:128
	s_waitcnt lgkmcnt(0)
	s_barrier
	s_waitcnt vmcnt(5)
	ds_write_b128 v0, v[2:5] offset:16384
	s_waitcnt vmcnt(4)
	ds_write_b128 v0, v[6:9] offset:20480
	s_waitcnt vmcnt(3)
	ds_write_b128 v0, v[10:13] offset:24576
	s_waitcnt vmcnt(2)
	ds_write_b128 v0, v[14:17] offset:28672
	s_waitcnt vmcnt(1)
	ds_write_b128 v0, v[18:21] offset:49152
	s_waitcnt vmcnt(0)
	ds_write_b128 v0, v[22:25] offset:53248
	global_load_dwordx4 v[2:5], v[34:35], off offset:2816
	global_load_dwordx4 v[6:9], v[36:37], off offset:2816
	global_load_dwordx4 v[10:13], v[70:71], off offset:2816
	global_load_dwordx4 v[14:17], v[72:73], off offset:2816
	global_load_dwordx4 v[18:21], v[74:75], off offset:256
	global_load_dwordx4 v[22:25], v[76:77], off offset:256
	v_cvt_pk_bf16_f32 v172, v179, v180
	v_and_b32_e32 v29, 15, v26
	v_bfe_u32 v179, v26, 4, 2
	v_bfe_u32 v180, v26, 1, 3
	v_lshrrev_b32_e32 v26, 1, v26
	v_cvt_pk_bf16_f32 v174, v173, v174
	v_cvt_pk_bf16_f32 v173, v175, v176
	v_and_or_b32 v28, v26, 64, v29
	v_and_or_b32 v176, v26, 32, v29
	v_bitop3_b32 v26, v27, v180, 3 bitop3:0x6c
	v_lshlrev_b32_e32 v190, 4, v26
	v_lshlrev_b32_e32 v191, 7, v28
	v_lshlrev_b32_e32 v192, 7, v176
	v_or_b32_e32 v175, v190, v191
	v_or_b32_e32 v176, v190, v192
	v_mov_b32_e32 v153, v120
	v_mov_b32_e32 v120, v162
	v_mov_b32_e32 v162, v86
	v_mov_b32_e32 v86, v181
	v_mov_b32_e32 v181, v95
	v_mov_b32_e32 v187, v109
	v_mov_b32_e32 v206, v108
	v_mov_b32_e32 v95, v211
	v_mov_b32_e32 v109, v217
	v_mov_b32_e32 v108, v216
	v_cvt_pk_bf16_f32 v211, v165, v168
	v_cvt_pk_bf16_f32 v161, v32, v33
	v_cvt_pk_bf16_f32 v165, v30, v31
	ds_read_b128 v[26:29], v175
	ds_read_b128 v[30:33], v175 offset:2048
	ds_read_b128 v[194:197], v175 offset:4096
	ds_read_b128 v[216:219], v175 offset:6144
	ds_read_b128 v[220:223], v176 offset:32768
	ds_read_b128 v[224:227], v176 offset:34816
	v_bitop3_b32 v179, v179, v180, 4 bitop3:0x36
	v_lshlrev_b32_e32 v179, 4, v179
	v_or_b32_e32 v180, v179, v191
	v_or_b32_e32 v179, v179, v192
	s_waitcnt lgkmcnt(1)
	v_mfma_f32_16x16x32_bf16 v[228:231], v[220:223], v[26:29], 0
	v_cvt_pk_bf16_f32 v168, v208, v209
	s_add_u32 s0, s0, 0x80000
	s_addc_u32 s1, s1, 0
	s_waitcnt lgkmcnt(0)
	v_mfma_f32_16x16x32_bf16 v[26:29], v[224:227], v[26:29], 0
	s_add_i32 s6, s6, -1
	s_add_u32 s22, s22, 0x200
	v_mov_b32_e32 v156, v113
	v_mfma_f32_16x16x32_bf16 v[232:235], v[220:223], v[30:33], 0
	v_mov_b32_e32 v113, v166
	v_mov_b32_e32 v166, v79
	v_mov_b32_e32 v79, v185
	v_mfma_f32_16x16x32_bf16 v[30:33], v[224:227], v[30:33], 0
	v_mov_b32_e32 v185, v107
	s_addc_u32 s23, s23, 0
	v_mov_b32_e32 v107, v215
	v_mfma_f32_16x16x32_bf16 v[236:239], v[220:223], v[194:197], 0
	s_cmp_lg_u32 s6, 0
	v_mov_b32_e32 v215, v123
	v_mov_b32_e32 v208, v206
	v_mfma_f32_16x16x32_bf16 v[194:197], v[224:227], v[194:197], 0
	v_mov_b32_e32 v209, v187
	v_mov_b32_e32 v207, v185
	v_mov_b32_e32 v185, v91
	v_mfma_f32_16x16x32_bf16 v[220:223], v[220:223], v[216:219], 0
	v_mfma_f32_16x16x32_bf16 v[216:219], v[224:227], v[216:219], 0
	ds_read_b128 v[224:227], v180
	ds_read_b128 v[240:243], v180 offset:2048
	ds_read_b128 v[244:247], v180 offset:4096
	ds_read_b128 v[248:251], v180 offset:6144
	ds_read_b128 v[190:193], v179 offset:32768
	ds_read_b128 v[198:201], v179 offset:34816
	s_waitcnt lgkmcnt(0)
	s_barrier
; #define GLOAD(ko) do { \
;     _Pragma("unroll") for (int i = 0; i < 4; ++i) ra[i] = *(const u32x4*)(ap + (size_t)(32 * i) * lda + (ko)); \
;     _Pragma("unroll") for (int i = 0; i < NB; ++i) rb[i] = *(const u32x4*)(bp + (size_t)(bstride * i) * ldb + (ko)); } while (0)
; #define GSTORE(st) do { \
;     _Pragma("unroll") for (int i = 0; i < 4; ++i) *(u32x4*)(sA + (st) * GST + so + 32 * i * 64) = ra[i]; \
;     _Pragma("unroll") for (int i = 0; i < NB; ++i) *(u32x4*)(sB + (st) * GST + so + 32 * i * 64) = rb[i]; } while (0)
;     ...
;   for (int kt = 0; kt < nk; ++kt) {
;     const int cur = kt & 1;
;     if (kt + 1 < nk) { GSTORE(cur ^ 1); if (kt + 2 < nk) GLOAD((kt + 2) * 64); }
;     if (LOWREG) {
;       const bf16_t* cA = sA + cur * GST; const bf16_t* cB = sB + cur * GST;
; #pragma nounroll
;       for (int ks = 0; ks < 2; ++ks) {
;         bf16x8 af[4], bfr[NT];
; #pragma unroll
;         for (int mi = 0; mi < 4; ++mi) af[mi] = *(const bf16x8*)(cA + (wm * 64 + mi * 16 + fr) * 64 + (((ks * 4 + fq) ^ fsw) * 8));
; #pragma unroll
;         for (int ni = 0; ni < NT; ++ni) bfr[ni] = *(const bf16x8*)(cB + (wn * NT * 16 + ni * 16 + fr) * 64 + (((ks * 4 + fq) ^ fsw) * 8));
; #pragma unroll
;         for (int mi = 0; mi < 4; ++mi)
; #pragma unroll
;           for (int ni = 0; ni < NT; ++ni) acc[mi][ni] = __builtin_amdgcn_mfma_f32_16x16x32_bf16(bfr[ni], af[mi], acc[mi][ni], 0, 0, 0);
;       }
;     } else GCOMPUTE(cur);
;     __syncthreads();
	s_waitcnt vmcnt(5)
	ds_write_b128 v0, v[2:5]
	s_waitcnt vmcnt(4)
	ds_write_b128 v0, v[6:9] offset:4096
	s_waitcnt vmcnt(3)
	ds_write_b128 v0, v[10:13] offset:8192
	s_waitcnt vmcnt(2)
	ds_write_b128 v0, v[14:17] offset:12288
	s_waitcnt vmcnt(1)
	ds_write_b128 v0, v[18:21] offset:32768
	s_waitcnt vmcnt(0)
	ds_write_b128 v0, v[22:25] offset:36864
	global_load_dwordx4 v[2:5], v[34:35], off offset:2944
	global_load_dwordx4 v[6:9], v[36:37], off offset:2944
	global_load_dwordx4 v[10:13], v[70:71], off offset:2944
	global_load_dwordx4 v[14:17], v[72:73], off offset:2944
	global_load_dwordx4 v[18:21], v[74:75], off offset:384
	global_load_dwordx4 v[22:25], v[76:77], off offset:384
	v_mfma_f32_16x16x32_bf16 v[228:231], v[190:193], v[224:227], v[228:231]
	v_mfma_f32_16x16x32_bf16 v[224:227], v[198:201], v[224:227], v[26:29]
	v_mfma_f32_16x16x32_bf16 v[232:235], v[190:193], v[240:243], v[232:235]
	v_mfma_f32_16x16x32_bf16 v[240:243], v[198:201], v[240:243], v[30:33]
	v_mfma_f32_16x16x32_bf16 v[236:239], v[190:193], v[244:247], v[236:239]
	v_mfma_f32_16x16x32_bf16 v[194:197], v[198:201], v[244:247], v[194:197]
	v_mfma_f32_16x16x32_bf16 v[26:29], v[190:193], v[248:251], v[220:223]
	v_mfma_f32_16x16x32_bf16 v[30:33], v[198:201], v[248:251], v[216:219]
	ds_read_b128 v[70:73], v175 offset:16384
	ds_read_b128 v[74:77], v175 offset:18432
	ds_read_b128 v[190:193], v175 offset:20480
	ds_read_b128 v[34:37], v175 offset:22528
	ds_read_b128 v[198:201], v176 offset:49152
	ds_read_b128 v[216:219], v176 offset:51200
	s_waitcnt lgkmcnt(1)
	v_mfma_f32_16x16x32_bf16 v[220:223], v[198:201], v[70:73], v[228:231]
	s_waitcnt lgkmcnt(0)
	v_mfma_f32_16x16x32_bf16 v[70:73], v[216:219], v[70:73], v[224:227]
	v_mfma_f32_16x16x32_bf16 v[224:227], v[198:201], v[74:77], v[232:235]
	v_mfma_f32_16x16x32_bf16 v[74:77], v[216:219], v[74:77], v[240:243]
	v_mfma_f32_16x16x32_bf16 v[228:231], v[198:201], v[190:193], v[236:239]
	v_mfma_f32_16x16x32_bf16 v[190:193], v[216:219], v[190:193], v[194:197]
	v_mfma_f32_16x16x32_bf16 v[26:29], v[198:201], v[34:37], v[26:29]
	v_mfma_f32_16x16x32_bf16 v[30:33], v[216:219], v[34:37], v[30:33]
	ds_read_b128 v[34:37], v180 offset:16384
	ds_read_b128 v[194:197], v180 offset:18432
	ds_read_b128 v[198:201], v180 offset:20480
	ds_read_b128 v[216:219], v180 offset:22528
	ds_read_b128 v[232:235], v179 offset:49152
	ds_read_b128 v[236:239], v179 offset:51200
	s_waitcnt lgkmcnt(0)
	s_barrier
	s_waitcnt vmcnt(5)
	ds_write_b128 v0, v[2:5] offset:16384
	s_waitcnt vmcnt(4)
	ds_write_b128 v0, v[6:9] offset:20480
	s_waitcnt vmcnt(3)
	ds_write_b128 v0, v[10:13] offset:24576
	s_waitcnt vmcnt(2)
	ds_write_b128 v0, v[14:17] offset:28672
	s_waitcnt vmcnt(1)
	ds_write_b128 v0, v[18:21] offset:49152
	s_waitcnt vmcnt(0)
	ds_write_b128 v0, v[22:25] offset:53248
	ds_read_b128 v[2:5], v175
	ds_read_b128 v[6:9], v175 offset:2048
	ds_read_b128 v[10:13], v175 offset:4096
	ds_read_b128 v[14:17], v175 offset:6144
	ds_read_b128 v[18:21], v176 offset:32768
	ds_read_b128 v[22:25], v176 offset:34816
	v_mfma_f32_16x16x32_bf16 v[220:223], v[232:235], v[34:37], v[220:223]
	v_mov_b32_e32 v0, v151
	v_mfma_f32_16x16x32_bf16 v[34:37], v[236:239], v[34:37], v[70:73]
	v_mfma_f32_16x16x32_bf16 v[70:73], v[232:235], v[194:197], v[224:227]
	v_mfma_f32_16x16x32_bf16 v[74:77], v[236:239], v[194:197], v[74:77]
	v_mfma_f32_16x16x32_bf16 v[194:197], v[232:235], v[198:201], v[228:231]
	v_mfma_f32_16x16x32_bf16 v[190:193], v[236:239], v[198:201], v[190:193]
	v_mfma_f32_16x16x32_bf16 v[26:29], v[232:235], v[216:219], v[26:29]
	v_mfma_f32_16x16x32_bf16 v[30:33], v[236:239], v[216:219], v[30:33]
	v_mov_b32_e32 v216, v124
	v_mov_b32_e32 v217, v125
	s_waitcnt lgkmcnt(1)
	v_mfma_f32_16x16x32_bf16 v[198:201], v[18:21], v[2:5], v[220:223]
	s_waitcnt lgkmcnt(0)
	v_mfma_f32_16x16x32_bf16 v[2:5], v[22:25], v[2:5], v[34:37]
	v_mfma_f32_16x16x32_bf16 v[34:37], v[18:21], v[6:9], v[70:73]
	v_mfma_f32_16x16x32_bf16 v[6:9], v[22:25], v[6:9], v[74:77]
	v_mfma_f32_16x16x32_bf16 v[70:73], v[18:21], v[10:13], v[194:197]
	v_mfma_f32_16x16x32_bf16 v[10:13], v[22:25], v[10:13], v[190:193]
	v_mfma_f32_16x16x32_bf16 v[18:21], v[18:21], v[14:17], v[26:29]
	v_mfma_f32_16x16x32_bf16 v[14:17], v[22:25], v[14:17], v[30:33]
	ds_read_b128 v[22:25], v180
	s_nop 0
	ds_read_b128 v[26:29], v180 offset:2048
	ds_read_b128 v[30:33], v180 offset:4096
	ds_read_b128 v[74:77], v180 offset:6144
	ds_read_b128 v[190:193], v179 offset:32768
	ds_read_b128 v[194:197], v179 offset:34816
	s_waitcnt lgkmcnt(0)
	s_barrier
; #define BLO(u) __uint_as_float((u) << 16)
; #define BHI(u) __uint_as_float((u) & 0xffff0000u)
; #define GLOAD(ko) do { \
;     _Pragma("unroll") for (int i = 0; i < 4; ++i) ra[i] = *(const u32x4*)(ap + (size_t)(32 * i) * lda + (ko)); \
;     _Pragma("unroll") for (int i = 0; i < NB; ++i) rb[i] = *(const u32x4*)(bp + (size_t)(bstride * i) * ldb + (ko)); } while (0)
; #define GSTORE(st) do { \
;     _Pragma("unroll") for (int i = 0; i < 4; ++i) *(u32x4*)(sA + (st) * GST + so + 32 * i * 64) = ra[i]; \
;     _Pragma("unroll") for (int i = 0; i < NB; ++i) *(u32x4*)(sB + (st) * GST + so + 32 * i * 64) = rb[i]; } while (0)
;     ...
;   for (int kt = 0; kt < nk; ++kt) {
;     const int cur = kt & 1;
;     if (kt + 1 < nk) { GSTORE(cur ^ 1); if (kt + 2 < nk) GLOAD((kt + 2) * 64); }
;     if (LOWREG) {
;       const bf16_t* cA = sA + cur * GST; const bf16_t* cB = sB + cur * GST;
; #pragma nounroll
;       for (int ks = 0; ks < 2; ++ks) {
;         bf16x8 af[4], bfr[NT];
; #pragma unroll
;         for (int mi = 0; mi < 4; ++mi) af[mi] = *(const bf16x8*)(cA + (wm * 64 + mi * 16 + fr) * 64 + (((ks * 4 + fq) ^ fsw) * 8));
; #pragma unroll
;         for (int ni = 0; ni < NT; ++ni) bfr[ni] = *(const bf16x8*)(cB + (wn * NT * 16 + ni * 16 + fr) * 64 + (((ks * 4 + fq) ^ fsw) * 8));
; #pragma unroll
;         for (int mi = 0; mi < 4; ++mi)
; #pragma unroll
;           for (int ni = 0; ni < NT; ++ni) acc[mi][ni] = __builtin_amdgcn_mfma_f32_16x16x32_bf16(bfr[ni], af[mi], acc[mi][ni], 0, 0, 0);
;       }
;     } else GCOMPUTE(cur);
;     __syncthreads();
; DI void merge_tile(const Params& p, int l, int tile, char* smem) {
;     ...
; #pragma unroll
;     for (int mi = 0; mi < 4; ++mi)
; #pragma unroll
;       for (int ni = 0; ni < 2; ++ni) {
;         accM[mi][ni][0] += accB[mi][ni][0] * BLO(sg[mi][ni][0]); accM[mi][ni][1] += accB[mi][ni][1] * BHI(sg[mi][ni][0]);
;         accM[mi][ni][2] += accB[mi][ni][2] * BLO(sg[mi][ni][1]); accM[mi][ni][3] += accB[mi][ni][3] * BHI(sg[mi][ni][1]);
;       }
; #pragma unroll
;     for (int mi = 0; mi < 4; ++mi)
; #pragma unroll
;       for (int k = 0; k < 6; ++k) { sg[mi][k][0] = sg[mi][k + 2][0]; sg[mi][k][1] = sg[mi][k + 2][1]; }
	v_mfma_f32_16x16x32_bf16 v[198:201], v[190:193], v[22:25], v[198:201]
	v_mfma_f32_16x16x32_bf16 v[2:5], v[194:197], v[22:25], v[2:5]
	v_mfma_f32_16x16x32_bf16 v[22:25], v[190:193], v[26:29], v[34:37]
	v_mfma_f32_16x16x32_bf16 v[6:9], v[194:197], v[26:29], v[6:9]
	v_mfma_f32_16x16x32_bf16 v[26:29], v[190:193], v[30:33], v[70:73]
	v_mfma_f32_16x16x32_bf16 v[10:13], v[194:197], v[30:33], v[10:13]
	v_mfma_f32_16x16x32_bf16 v[18:21], v[190:193], v[74:77], v[18:21]
	v_mfma_f32_16x16x32_bf16 v[14:17], v[194:197], v[74:77], v[14:17]
	ds_read_b128 v[30:33], v175 offset:16384
	ds_read_b128 v[34:37], v175 offset:18432
	ds_read_b128 v[70:73], v175 offset:20480
	ds_read_b128 v[74:77], v175 offset:22528
	ds_read_b128 v[190:193], v176 offset:49152
	ds_read_b128 v[194:197], v176 offset:51200
	v_mov_b32_e32 v175, v167
	v_mov_b32_e32 v176, v166
	s_waitcnt lgkmcnt(1)
	v_mfma_f32_16x16x32_bf16 v[198:201], v[190:193], v[30:33], v[198:201]
	v_mov_b32_e32 v166, v101
	v_mov_b32_e32 v167, v105
	s_waitcnt lgkmcnt(0)
	v_mfma_f32_16x16x32_bf16 v[2:5], v[194:197], v[30:33], v[2:5]
	v_mfma_f32_16x16x32_bf16 v[22:25], v[190:193], v[34:37], v[22:25]
	v_mfma_f32_16x16x32_bf16 v[6:9], v[194:197], v[34:37], v[6:9]
	v_mfma_f32_16x16x32_bf16 v[26:29], v[190:193], v[70:73], v[26:29]
	v_mfma_f32_16x16x32_bf16 v[10:13], v[194:197], v[70:73], v[10:13]
	v_mfma_f32_16x16x32_bf16 v[18:21], v[190:193], v[74:77], v[18:21]
	v_mfma_f32_16x16x32_bf16 v[14:17], v[194:197], v[74:77], v[14:17]
	ds_read_b128 v[30:33], v180 offset:16384
	ds_read_b128 v[34:37], v180 offset:18432
	ds_read_b128 v[70:73], v180 offset:20480
	ds_read_b128 v[74:77], v180 offset:22528
	ds_read_b128 v[190:193], v179 offset:49152
	ds_read_b128 v[194:197], v179 offset:51200
	v_mov_b32_e32 v179, v178
	v_mov_b32_e32 v180, v177
	s_waitcnt lgkmcnt(1)
	v_mfma_f32_16x16x32_bf16 v[198:201], v[190:193], v[30:33], v[198:201]
	v_mov_b32_e32 v177, v102
	v_mov_b32_e32 v178, v103
	s_waitcnt lgkmcnt(0)
	v_mfma_f32_16x16x32_bf16 v[2:5], v[194:197], v[30:33], v[2:5]
	v_lshlrev_b32_e32 v30, 16, v214
	v_and_b32_e32 v31, 0xffff0000, v214
	s_nop 1
	v_fma_f32 v66, v198, v30, v66
	v_fma_f32 v67, v199, v31, v67
	v_mfma_f32_16x16x32_bf16 v[22:25], v[190:193], v[34:37], v[22:25]
	v_lshlrev_b32_e32 v30, 16, v213
	v_and_b32_e32 v31, 0xffff0000, v213
	v_fma_f32 v68, v200, v30, v68
	v_fma_f32 v69, v201, v31, v69
	v_lshlrev_b32_e32 v30, 16, v211
	v_and_b32_e32 v31, 0xffff0000, v211
	v_mfma_f32_16x16x32_bf16 v[6:9], v[194:197], v[34:37], v[6:9]
	v_fma_f32 v62, v2, v30, v62
	v_fma_f32 v63, v3, v31, v63
	v_lshlrev_b32_e32 v2, 16, v210
	v_and_b32_e32 v3, 0xffff0000, v210
	v_fma_f32 v64, v4, v2, v64
	v_fma_f32 v65, v5, v3, v65
	v_lshlrev_b32_e32 v2, 16, v212
	v_and_b32_e32 v3, 0xffff0000, v212
	v_mfma_f32_16x16x32_bf16 v[26:29], v[190:193], v[70:73], v[26:29]
	v_fma_f32 v58, v22, v2, v58
	v_fma_f32 v59, v23, v3, v59
	v_lshlrev_b32_e32 v2, 16, v174
	v_and_b32_e32 v3, 0xffff0000, v174
	v_fma_f32 v60, v24, v2, v60
	v_fma_f32 v61, v25, v3, v61
	v_lshlrev_b32_e32 v2, 16, v173
	v_and_b32_e32 v3, 0xffff0000, v173
	v_mfma_f32_16x16x32_bf16 v[10:13], v[194:197], v[70:73], v[10:13]
	v_fma_f32 v54, v6, v2, v54
	v_fma_f32 v55, v7, v3, v55
	v_lshlrev_b32_e32 v2, 16, v172
	v_and_b32_e32 v3, 0xffff0000, v172
	v_fma_f32 v56, v8, v2, v56
	v_fma_f32 v57, v9, v3, v57
	v_lshlrev_b32_e32 v2, 16, v171
	v_and_b32_e32 v3, 0xffff0000, v171
	v_mfma_f32_16x16x32_bf16 v[18:21], v[190:193], v[74:77], v[18:21]
	v_fma_f32 v50, v26, v2, v50
	v_fma_f32 v51, v27, v3, v51
	v_lshlrev_b32_e32 v2, 16, v170
	v_and_b32_e32 v3, 0xffff0000, v170
	v_fma_f32 v52, v28, v2, v52
	v_fma_f32 v53, v29, v3, v53
	v_lshlrev_b32_e32 v2, 16, v169
	v_and_b32_e32 v3, 0xffff0000, v169
	v_mfma_f32_16x16x32_bf16 v[14:17], v[194:197], v[74:77], v[14:17]
	v_fma_f32 v46, v10, v2, v46
	v_fma_f32 v47, v11, v3, v47
	v_lshlrev_b32_e32 v2, 16, v168
	v_and_b32_e32 v3, 0xffff0000, v168
	v_fma_f32 v48, v12, v2, v48
	v_fma_f32 v49, v13, v3, v49
	v_lshlrev_b32_e32 v2, 16, v165
	v_and_b32_e32 v3, 0xffff0000, v165
	v_fma_f32 v42, v18, v2, v42
	v_fma_f32 v43, v19, v3, v43
	v_lshlrev_b32_e32 v2, 16, v161
	v_and_b32_e32 v3, 0xffff0000, v161
	v_fma_f32 v44, v20, v2, v44
	v_fma_f32 v45, v21, v3, v45
	v_lshlrev_b32_e32 v2, 16, v160
	v_and_b32_e32 v3, 0xffff0000, v160
	v_fma_f32 v38, v14, v2, v38
	v_fma_f32 v39, v15, v3, v39
	v_lshlrev_b32_e32 v2, 16, v158
	v_and_b32_e32 v3, 0xffff0000, v158
	v_fma_f32 v40, v16, v2, v40
	v_fma_f32 v41, v17, v3, v41
	v_mov_b32_e32 v30, v126
	v_mov_b32_e32 v31, v127
	v_mov_b32_e32 v32, v128
	v_mov_b32_e32 v33, v129
	v_mov_b32_e32 v26, v130
	v_mov_b32_e32 v27, v131
	v_mov_b32_e32 v28, v132
	v_mov_b32_e32 v29, v133
	v_mov_b32_e32 v214, v122
	v_mov_b32_e32 v212, v116
	v_mov_b32_e32 v213, v117
	v_mov_b32_e32 v210, v114
	v_mov_b32_e32 v211, v115
	v_mov_b32_e32 v77, v186
	v_mov_b32_e32 v72, v184
	v_mov_b32_e32 v73, v183
	v_mov_b32_e32 v70, v182
	v_mov_b32_e32 v71, v181
	v_mov_b32_e32 v126, v137
	v_mov_b32_e32 v127, v139
	v_mov_b32_e32 v128, v135
	v_mov_b32_e32 v129, v140
	v_mov_b32_e32 v130, v143
	v_mov_b32_e32 v131, v142
	v_mov_b32_e32 v132, v145
	v_mov_b32_e32 v133, v147
	v_mov_b32_e32 v75, v92
	v_mov_b32_e32 v76, v93
	v_mov_b32_e32 v74, v90
	v_mov_b32_e32 v183, v84
	v_mov_b32_e32 v184, v85
	v_mov_b32_e32 v181, v82
	v_mov_b32_e32 v182, v83
	v_mov_b32_e32 v173, v164
	v_mov_b32_e32 v174, v163
	v_mov_b32_e32 v171, v162
	v_mov_b32_e32 v172, v159
	v_mov_b32_e32 v137, v134
	v_mov_b32_e32 v139, v136
	v_mov_b32_e32 v135, v138
	v_mov_b32_e32 v140, v141
	v_mov_b32_e32 v143, v144
	v_mov_b32_e32 v142, v146
	v_mov_b32_e32 v145, v148
	v_mov_b32_e32 v147, v149
	v_mov_b32_e32 v163, v100
	v_mov_b32_e32 v159, v98
	v_mov_b32_e32 v164, v99
	v_mov_b32_e32 v162, v104
	v_mov_b32_e32 v169, v157
	v_mov_b32_e32 v170, v156
	v_mov_b32_e32 v165, v155
	v_mov_b32_e32 v168, v154
	v_mov_b32_e32 v160, v153
	v_mov_b32_e32 v161, v152
	v_mov_b32_e32 v158, v150
	s_barrier
; DI unsigned pack2(float a, float b) { f2_t v = {a, b}; bf2_t r = __builtin_convertvector(v, bf2_t); return __builtin_bit_cast(unsigned, r); }
; DI int otid() { int t; asm volatile("v_mov_b32 %0, %1" : "=v"(t) : "v"((int)threadIdx.x)); __builtin_assume(t >= 0 && t < 256); return t; }
; DI void merge_tile(const Params& p, int l, int tile, char* smem) {
;     ...
;   const int lane = otid() & 63, wid = otid() >> 6, wm = wid >> 1, wn = wid & 1, fr = lane & 15, fq = lane >> 4;
; #pragma unroll
;   for (int mi = 0; mi < 4; ++mi)
;     {
;       size_t row = (size_t)mt * 128 + wm * 64 + mi * 16 + fr; int col = nt * 64 + wn * 32 + (fq & 1) * 16 + (fq >> 1) * 8;
;       uint2 a, b;
;       a.x = pack2(accM[mi][0][0], accM[mi][0][1]); a.y = pack2(accM[mi][0][2], accM[mi][0][3]);
;       b.x = pack2(accM[mi][1][0], accM[mi][1][1]); b.y = pack2(accM[mi][1][2], accM[mi][1][3]);
;       *(uint4*)(P_PROJ + row * PW + C_MERGED + col) = widen16(a, b);
;     }
; DI void run_phase(const Params& p, int ph, char* smem, bool never) {
;     ...
;       for (int w = lb; w < 64 * 8; w += nl) {
;         const int it = w >> 6, l64 = w & 63, a = it >> 1, gn = it & 1;
;         const int mt = 8 * (xcd + 8 * a) + (l64 & 7), nt = 8 * gn + (l64 >> 3);
;         merge_tile(p, l, nt * 256 + mt, smem);
;       }
	s_cbranch_scc1 .LBB0_47
	v_mov_b32 v0, v188
	v_mov_b32 v2, v188
	v_readlane_b32 s0, v255, 26
	v_lshrrev_b32_e32 v2, 1, v2
	v_and_b32_e32 v3, 15, v0
	v_and_b32_e32 v4, 64, v2
	v_or3_b32 v8, v3, v4, s27
	v_lshrrev_b32_e32 v3, 2, v0
	v_and_b32_e32 v3, 8, v3
	v_and_b32_e32 v2, 32, v2
	v_and_or_b32 v0, v0, 16, v3
	v_or3_b32 v6, v0, v2, s28
	v_mul_u32_u24_e32 v0, 0x1300, v8
	v_lshlrev_b32_e32 v0, 1, v0
	v_ashrrev_i32_e32 v7, 31, v6
	v_lshl_add_u64 v[8:9], s[58:59], 0, v[0:1]
	v_lshl_add_u64 v[6:7], v[6:7], 1, v[8:9]
	v_readlane_b32 s1, v255, 27
	v_cvt_pk_bf16_f32 v2, v66, v67
	v_cvt_pk_bf16_f32 v3, v68, v69
	v_cvt_pk_bf16_f32 v4, v62, v63
	v_cvt_pk_bf16_f32 v5, v64, v65
	v_add_co_u32_e32 v8, vcc, s16, v6
	v_permlane16_swap_b32_e32 v2, v4
	v_permlane16_swap_b32_e32 v3, v5
	v_addc_co_u32_e32 v9, vcc, 0, v7, vcc
	s_mov_b32 s1, 0x6cca000
	global_store_dwordx4 v[8:9], v[2:5], off offset:1024
	v_add_co_u32_e32 v8, vcc, s1, v6
	s_nop 0
	v_cvt_pk_bf16_f32 v2, v58, v59
	v_cvt_pk_bf16_f32 v3, v60, v61
	v_cvt_pk_bf16_f32 v4, v54, v55
	v_cvt_pk_bf16_f32 v5, v56, v57
	s_nop 0
	v_permlane16_swap_b32_e32 v2, v4
	v_permlane16_swap_b32_e32 v3, v5
	v_addc_co_u32_e32 v9, vcc, 0, v7, vcc
	s_mov_b32 s1, 0x6cf0000
	global_store_dwordx4 v[8:9], v[2:5], off offset:1024
	v_add_co_u32_e32 v8, vcc, s1, v6
	s_nop 0
	v_cvt_pk_bf16_f32 v2, v50, v51
	v_cvt_pk_bf16_f32 v3, v52, v53
	v_cvt_pk_bf16_f32 v4, v46, v47
	v_cvt_pk_bf16_f32 v5, v48, v49
	s_lshr_b32 s0, s0, 3
	v_permlane16_swap_b32_e32 v2, v4
	v_permlane16_swap_b32_e32 v3, v5
	v_addc_co_u32_e32 v9, vcc, 0, v7, vcc
	v_readlane_b32 s1, v255, 33
	global_store_dwordx4 v[8:9], v[2:5], off offset:1024
	v_add_co_u32_e32 v6, vcc, 0x6d16000, v6
	s_nop 0
	v_cvt_pk_bf16_f32 v2, v42, v43
	v_cvt_pk_bf16_f32 v3, v44, v45
	v_cvt_pk_bf16_f32 v4, v38, v39
	v_cvt_pk_bf16_f32 v5, v40, v41
	s_add_i32 s26, s26, s1
	s_add_i32 s25, s25, s0
	v_permlane16_swap_b32_e32 v2, v4
	v_permlane16_swap_b32_e32 v3, v5
	v_addc_co_u32_e32 v7, vcc, 0, v7, vcc
	s_cmpk_gt_i32 s26, 0x1ff
	global_store_dwordx4 v[6:7], v[2:5], off offset:1024
	s_cbranch_scc0 .LBB0_44

; #define P_LSE WSP(float, OFF_LSE)
; DI unsigned pack2(float a, float b) { f2_t v = {a, b}; bf2_t r = __builtin_convertvector(v, bf2_t); return __builtin_bit_cast(unsigned, r); }
; #define BLO(u) __uint_as_float((u) << 16)
; #define BHI(u) __uint_as_float((u) & 0xffff0000u)
; DI int otid() { int t; asm volatile("v_mov_b32 %0, %1" : "=v"(t) : "v"((int)threadIdx.x)); __builtin_assume(t >= 0 && t < 256); return t; }
; DI float frcp(float x) { return __builtin_amdgcn_rcpf(x); }
; DI void combine_c(const Params& p) {
;   for (size_t u = (size_t)blockIdx.x * 256 + otid(); u < (size_t)32768 * 32; u += (size_t)gridDim.x * 256) {
;     const size_t t = u >> 5; const int h = (int)(u >> 3) & 3, ch = (int)u & 7;
;     const float* ls = P_LSE + t * 12 + h;
;     float l0 = ls[0], l1 = ls[4], l2 = ls[8];
;     float mx = fmaxf(l0, fmaxf(l1, l2));
;     float a0 = __builtin_amdgcn_exp2f(l0 - mx), a1 = __builtin_amdgcn_exp2f(l1 - mx), a2 = __builtin_amdgcn_exp2f(l2 - mx);
;     float inv = frcp(a0 + a1 + a2); a0 *= inv; a1 *= inv; a2 *= inv;
;     const bf16_t* row = P_PROJ + t * PW;
;     uint4 x0 = *(const uint4*)(row + C_CQ + h * 64 + ch * 8), x1 = *(const uint4*)(row + C_CQ + 256 + h * 64 + ch * 8),
;           x2 = *(const uint4*)(row + C_CQ + 512 + h * 64 + ch * 8);
;     bf16_t* gp = P_PROJ + t * PW + C_GATE + 512 + h * 64 + ch * 8;
;     uint4 gu = *(const uint4*)gp;
;     unsigned xa[4] = {x0.x, x0.y, x0.z, x0.w}, xb[4] = {x1.x, x1.y, x1.z, x1.w}, xc[4] = {x2.x, x2.y, x2.z, x2.w}, gg[4] = {gu.x, gu.y, gu.z, gu.w};
;     unsigned ov[4];
; #pragma unroll
;     for (int e = 0; e < 4; ++e) {
;       float ylo = a0 * BLO(xa[e]) + a1 * BLO(xb[e]) + a2 * BLO(xc[e]);
;       float yhi = a0 * BHI(xa[e]) + a1 * BHI(xb[e]) + a2 * BHI(xc[e]);
;       float glo = BLO(gg[e]), ghi = BHI(gg[e]);
;       ov[e] = pack2(ylo * glo * frcp(1.0f + __expf(-glo)), yhi * ghi * frcp(1.0f + __expf(-ghi)));
;     }
;     uint4 w; w.x = ov[0]; w.y = ov[1]; w.z = ov[2]; w.w = ov[3];
;     *(uint4*)gp = w;
;   }
; }
.LBB0_54:
	v_alignbit_b32 v11, v5, v4, 5
	v_mad_u64_u32 v[6:7], s[6:7], v11, 48, s[22:23]
	v_mov_b32_e32 v0, v7
	v_lshrrev_b32_e32 v12, 5, v5
	v_bfe_u32 v10, v4, 3, 2
	v_mad_u64_u32 v[8:9], s[6:7], v12, 48, v[0:1]
	v_mov_b32_e32 v7, v8
	v_lshlrev_b32_e32 v0, 2, v10
	v_lshl_add_u64 v[6:7], v[6:7], 0, v[0:1]
	global_load_dword v0, v[6:7], off
	global_load_dword v8, v[6:7], off offset:16
	s_nop 0
	global_load_dword v6, v[6:7], off offset:32
	v_lshl_add_u64 v[4:5], v[4:5], 0, s[12:13]
	s_waitcnt vmcnt(0)
	v_max3_f32 v7, v0, v8, v6
	v_sub_f32_e32 v0, v0, v7
	v_exp_f32_e32 v23, v0
	v_sub_f32_e32 v0, v8, v7
	v_exp_f32_e32 v22, v0
	v_sub_f32_e32 v0, v6, v7
	v_exp_f32_e32 v0, v0
	v_add_f32_e32 v6, v23, v22
	v_add_f32_e32 v6, v0, v6
	v_rcp_f32_e32 v24, v6
	v_mov_b64_e32 v[6:7], s[26:27]
	v_mad_u64_u32 v[6:7], s[6:7], v11, s4, v[6:7]
	v_mul_f32_e32 v26, v0, v24
	v_mov_b32_e32 v0, v7
	v_mad_u64_u32 v[8:9], s[6:7], v12, s4, v[0:1]
	v_mov_b32_e32 v7, v8
	v_lshlrev_b32_e32 v0, 7, v10
	v_lshl_add_u64 v[6:7], v[6:7], 0, v[0:1]
	v_and_b32_e32 v0, 56, v2
	v_lshlrev_b32_e32 v0, 1, v0
	v_lshl_add_u64 v[18:19], v[6:7], 0, v[0:1]
	v_add_co_u32_e32 v28, vcc, s85, v18
	global_load_dwordx4 v[6:9], v[18:19], off offset:1024
	global_load_dwordx4 v[10:13], v[18:19], off offset:1536
	global_load_dwordx4 v[14:17], v[18:19], off offset:2048
	v_addc_co_u32_e32 v29, vcc, 0, v19, vcc
	global_load_dwordx4 v[18:21], v[28:29], off offset:3584
	v_mul_f32_e32 v22, v22, v24
	v_mul_f32_e32 v23, v23, v24
	s_mov_b64 s[6:7], 0xfffff
	v_cmp_lt_u64_e32 vcc, s[6:7], v[4:5]
	v_lshl_add_u64 v[2:3], v[2:3], 0, s[24:25]
	s_or_b64 s[0:1], vcc, s[0:1]
	s_waitcnt vmcnt(3)
	v_lshlrev_b32_e32 v38, 16, v6
	s_waitcnt vmcnt(2)
	v_and_b32_e32 v39, 0xffff0000, v10
	v_lshlrev_b32_e32 v24, 16, v10
	v_and_b32_e32 v25, 0xffff0000, v6
	v_mul_f32_e32 v38, v23, v38
	v_mul_f32_e32 v39, v22, v39
	s_waitcnt vmcnt(0)
	v_lshlrev_b32_e32 v32, 16, v18
	v_mul_f32_e32 v0, 0xbfb8aa3b, v32
	v_exp_f32_e32 v0, v0
	v_and_b32_e32 v33, 0xffff0000, v18
	v_lshlrev_b32_e32 v18, 16, v19
	v_lshlrev_b32_e32 v30, 16, v14
	v_add_f32_e32 v0, 1.0, v0
	v_rcp_f32_e32 v40, v0
	v_mul_f32_e32 v0, 0xbfb8aa3b, v33
	v_exp_f32_e32 v0, v0
	v_and_b32_e32 v31, 0xffff0000, v14
	v_and_b32_e32 v19, 0xffff0000, v19
	v_fma_f32 v24, v22, v24, v38
	v_fma_f32 v25, v23, v25, v39
	v_add_f32_e32 v0, 1.0, v0
	v_rcp_f32_e32 v41, v0
	v_mul_f32_e32 v0, 0xbfb8aa3b, v18
	v_exp_f32_e32 v0, v0
	v_fma_f32 v24, v26, v30, v24
	v_fma_f32 v25, v26, v31, v25
	v_lshlrev_b32_e32 v36, 16, v20
	v_mul_f32_e32 v24, v24, v32
	v_mul_f32_e32 v25, v25, v33
	v_add_f32_e32 v0, 1.0, v0
	v_rcp_f32_e32 v30, v0
	v_mul_f32_e32 v0, 0xbfb8aa3b, v19
	v_exp_f32_e32 v0, v0
	v_mul_f32_e32 v24, v24, v40
	v_mul_f32_e32 v25, v25, v41
	v_lshlrev_b32_e32 v10, 16, v7
	v_cvt_pk_bf16_f32 v6, v24, v25
	v_add_f32_e32 v0, 1.0, v0
	v_rcp_f32_e32 v31, v0
	v_mul_f32_e32 v0, 0xbfb8aa3b, v36
	v_exp_f32_e32 v0, v0
	v_lshlrev_b32_e32 v24, 16, v11
	v_and_b32_e32 v11, 0xffff0000, v11
	v_and_b32_e32 v25, 0xffff0000, v7
	v_mul_f32_e32 v10, v23, v10
	v_mul_f32_e32 v11, v22, v11
	v_lshlrev_b32_e32 v14, 16, v15
	v_and_b32_e32 v15, 0xffff0000, v15
	v_fma_f32 v10, v22, v24, v10
	v_fma_f32 v11, v23, v25, v11
	v_and_b32_e32 v37, 0xffff0000, v20
	v_fma_f32 v10, v26, v14, v10
	v_fma_f32 v11, v26, v15, v11
	v_add_f32_e32 v0, 1.0, v0
	v_mul_f32_e32 v10, v10, v18
	v_mul_f32_e32 v11, v11, v19
	v_rcp_f32_e32 v18, v0
	v_mul_f32_e32 v0, 0xbfb8aa3b, v37
	v_exp_f32_e32 v0, v0
	v_mul_f32_e32 v10, v10, v30
	v_mul_f32_e32 v11, v11, v31
	v_lshlrev_b32_e32 v14, 16, v8
	v_and_b32_e32 v15, 0xffff0000, v12
	v_add_f32_e32 v0, 1.0, v0
	v_lshlrev_b32_e32 v20, 16, v21
	v_cvt_pk_bf16_f32 v7, v10, v11
	v_lshlrev_b32_e32 v10, 16, v12
	v_and_b32_e32 v11, 0xffff0000, v8
	v_rcp_f32_e32 v19, v0
	v_mul_f32_e32 v14, v23, v14
	v_mul_f32_e32 v15, v22, v15
	v_lshlrev_b32_e32 v34, 16, v16
	v_and_b32_e32 v35, 0xffff0000, v16
	v_fma_f32 v10, v22, v10, v14
	v_fma_f32 v11, v23, v11, v15
	v_mul_f32_e32 v0, 0xbfb8aa3b, v20
	v_fma_f32 v10, v26, v34, v10
	v_fma_f32 v11, v26, v35, v11
	v_exp_f32_e32 v0, v0
	v_mul_f32_e32 v10, v10, v36
	v_mul_f32_e32 v11, v11, v37
	v_lshlrev_b32_e32 v12, 16, v9
	v_mul_f32_e32 v10, v10, v18
	v_mul_f32_e32 v11, v11, v19
	v_and_b32_e32 v21, 0xffff0000, v21
	v_cvt_pk_bf16_f32 v8, v10, v11
	v_lshlrev_b32_e32 v10, 16, v13
	v_and_b32_e32 v13, 0xffff0000, v13
	v_and_b32_e32 v11, 0xffff0000, v9
	v_mul_f32_e32 v12, v23, v12
	v_mul_f32_e32 v13, v22, v13
	v_add_f32_e32 v0, 1.0, v0
	v_fma_f32 v10, v22, v10, v12
	v_fma_f32 v11, v23, v11, v13
	v_rcp_f32_e32 v12, v0
	v_mul_f32_e32 v0, 0xbfb8aa3b, v21
	v_exp_f32_e32 v0, v0
	v_lshlrev_b32_e32 v16, 16, v17
	v_and_b32_e32 v17, 0xffff0000, v17
	v_fma_f32 v10, v26, v16, v10
	v_fma_f32 v11, v26, v17, v11
	v_add_f32_e32 v0, 1.0, v0
	v_rcp_f32_e32 v13, v0
	v_mul_f32_e32 v10, v10, v20
	v_mul_f32_e32 v11, v11, v21
	s_nop 0
	v_mul_f32_e32 v10, v10, v12
	v_mul_f32_e32 v11, v11, v13
	s_nop 0
	v_cvt_pk_bf16_f32 v9, v10, v11
	global_store_dwordx4 v[28:29], v[6:9], off offset:3584
	s_andn2_b64 exec, exec, s[0:1]
	s_cbranch_execnz .LBB0_54
	s_or_b64 exec, exec, s[0:1]

; DI unsigned pack2(float a, float b) { f2_t v = {a, b}; bf2_t r = __builtin_convertvector(v, bf2_t); return __builtin_bit_cast(unsigned, r); }
; #define BLO(u) __uint_as_float((u) << 16)
; #define BHI(u) __uint_as_float((u) & 0xffff0000u)
; DI float frcp(float x) { return __builtin_amdgcn_rcpf(x); }
; template <int W, bool SINK>
; DI void attn_band_mfma(const bf16_t* Qb, size_t ldq, const bf16_t* Kb, const bf16_t* Vb, size_t ldk, int L, int i0,
;                        const float* lut_g, float sink2, bf16_t* outp, size_t ldo, float* lse_out, size_t ldl, char* smem) {
;     ...
;   const float ltot = half_swap_sum(l_run);
;   const float inv = frcp(ltot);
;   bf16_t* orow = outp + (size_t)qi * ldo;
;   if (!SINK && h == 0) lse_out[(size_t)qi * ldl] = m_run + __log2f(ltot);
; #pragma unroll
;   for (int db = 0; db < 2; ++db)
; #pragma unroll
;     for (int kp = 0; kp < 2; ++kp) {
;       uint2 w2[2];
; #pragma unroll
;       for (int gg = 0; gg < 2; ++gg) {
;         const int g4 = 2 * kp + gg;
;         float y[4];
;         if (SINK) {
;           uint2 u = *(const uint2*)(orow + 32 * db + 8 * g4 + 4 * h);
;           float g[4] = {BLO(u.x), BHI(u.x), BLO(u.y), BHI(u.y)};
; #pragma unroll
;           for (int e = 0; e < 4; ++e) { float ov = db == 0 ? o0[4 * g4 + e] : o1[4 * g4 + e]; y[e] = ov * inv * g[e] * frcp(1.0f + __expf(-g[e])); }
;         } else {
; #pragma unroll
;           for (int e = 0; e < 4; ++e) { float ov = db == 0 ? o0[4 * g4 + e] : o1[4 * g4 + e]; y[e] = ov * inv; }
;         }
;         w2[gg].x = pack2(y[0], y[1]); w2[gg].y = pack2(y[2], y[3]);
;       }
;       auto rx = __builtin_amdgcn_permlane32_swap(w2[0].x, w2[1].x, false, false);
;       auto ry = __builtin_amdgcn_permlane32_swap(w2[0].y, w2[1].y, false, false);
;       uint4 w; w.x = rx[0]; w.y = ry[0]; w.z = rx[1]; w.w = ry[1];
;       *(uint4*)(orow + 32 * db + 16 * kp + 8 * h) = w;
;     }
.LBB0_60:
	s_or_b64 exec, exec, s[0:1]
	v_rcp_f32_e32 v0, v0
	v_readlane_b32 s28, v255, 3
	v_readlane_b32 s29, v255, 4
	v_mul_f32_e32 v2, v32, v0
	v_mul_f32_e32 v3, v33, v0
	v_mul_f32_e32 v4, v34, v0
	v_mul_f32_e32 v5, v35, v0
	v_cvt_pk_bf16_f32 v2, v2, v3
	v_cvt_pk_bf16_f32 v3, v4, v5
	v_mul_f32_e32 v4, v36, v0
	v_mul_f32_e32 v5, v37, v0
	v_mul_f32_e32 v6, v38, v0
	v_mul_f32_e32 v7, v39, v0
	v_cvt_pk_bf16_f32 v4, v4, v5
	v_cvt_pk_bf16_f32 v5, v6, v7
	s_nop 0
	v_permlane32_swap_b32_e32 v2, v4
	v_permlane32_swap_b32_e32 v3, v5
	global_store_dwordx4 v[132:133], v[2:5], off offset:1024
	v_mul_f32_e32 v6, v46, v0
	v_mul_f32_e32 v7, v47, v0
	s_nop 0
	v_mul_f32_e32 v2, v40, v0
	v_mul_f32_e32 v3, v41, v0
	v_mul_f32_e32 v4, v42, v0
	v_mul_f32_e32 v5, v43, v0
	v_cvt_pk_bf16_f32 v2, v2, v3
	v_cvt_pk_bf16_f32 v3, v4, v5
	v_mul_f32_e32 v4, v44, v0
	v_mul_f32_e32 v5, v45, v0
	s_nop 0
	v_cvt_pk_bf16_f32 v4, v4, v5
	v_cvt_pk_bf16_f32 v5, v6, v7
	s_nop 0
	v_permlane32_swap_b32_e32 v2, v4
	v_permlane32_swap_b32_e32 v3, v5
	global_store_dwordx4 v[132:133], v[2:5], off offset:1056
	v_mul_f32_e32 v6, v22, v0
	v_mul_f32_e32 v7, v23, v0
	s_nop 0
	v_mul_f32_e32 v2, v16, v0
	v_mul_f32_e32 v3, v17, v0
	v_mul_f32_e32 v4, v18, v0
	v_mul_f32_e32 v5, v19, v0
	v_cvt_pk_bf16_f32 v2, v2, v3
	v_cvt_pk_bf16_f32 v3, v4, v5
	v_mul_f32_e32 v4, v20, v0
	v_mul_f32_e32 v5, v21, v0
	s_nop 0
	v_cvt_pk_bf16_f32 v4, v4, v5
	v_cvt_pk_bf16_f32 v5, v6, v7
	s_nop 0
	v_permlane32_swap_b32_e32 v2, v4
	v_permlane32_swap_b32_e32 v3, v5
	global_store_dwordx4 v[132:133], v[2:5], off offset:1088
	v_mul_f32_e32 v6, v24, v0
	v_mul_f32_e32 v7, v25, v0
	s_nop 0
	v_mul_f32_e32 v4, v28, v0
	v_mul_f32_e32 v5, v29, v0
	v_mul_f32_e32 v2, v26, v0
	v_mul_f32_e32 v3, v27, v0
	v_cvt_pk_bf16_f32 v8, v6, v7
	v_cvt_pk_bf16_f32 v2, v2, v3
	v_mul_f32_e32 v6, v30, v0
	v_mul_f32_e32 v7, v31, v0
	v_cvt_pk_bf16_f32 v3, v4, v5
	v_cvt_pk_bf16_f32 v4, v6, v7
	s_nop 0
	v_permlane32_swap_b32_e32 v8, v3
	v_permlane32_swap_b32_e32 v2, v4
	global_store_dword v[132:133], v8, off offset:1120

; template <int W, bool SINK>
; DI void attn_band_mfma(const bf16_t* Qb, size_t ldq, const bf16_t* Kb, const bf16_t* Vb, size_t ldk, int L, int i0,
;                        const float* lut_g, float sink2, bf16_t* outp, size_t ldo, float* lse_out, size_t ldl, char* smem) {
;     ...
;     const int offb = k0 + 4 * h - qi + W;
;     float pm = -1e30f;
; #pragma unroll
;     for (int i = 0; i < 16; ++i) {
;       int idx0 = offb + (i & 3) + 8 * (i >> 2), idx1 = idx0 + 32;
;       int c0 = min(max(idx0, 0), 2 * W), c1 = min(max(idx1, 0), 2 * W);
;       float b0 = sLut[c0], b1 = sLut[c1];
;       p0[i] = ((unsigned)idx0 <= (unsigned)(2 * W)) ? p0[i] + b0 : -1e30f;
;       p1[i] = ((unsigned)idx1 <= (unsigned)(2 * W)) ? p1[i] + b1 : -1e30f;
;       pm = fmaxf(pm, fmaxf(p0[i], p1[i]));
;     }
;     pm = half_swap_max(pm);
;     const bool has = pm > -1e29f;
;     float delta = 0.f;
;     if (has) { if (!seen) delta = pm; else if (pm > 8.0f) delta = pm; }
;     if (__any(delta != 0.f)) {
;       float alpha = seen ? __builtin_amdgcn_exp2f(-delta) : 1.0f;
;       l_run *= alpha; m_run += delta;
; #pragma unroll
;       for (int i = 0; i < 16; ++i) { o0[i] *= alpha; o1[i] *= alpha; p0[i] -= delta; p1[i] -= delta; }
;       negm = splat16(-m_run);
;     }
.LBB0_101:
	s_or_b64 exec, exec, s[26:27]
	v_cmp_gt_u32_e32 vcc, s17, v161
	s_waitcnt lgkmcnt(14)
	v_add_f32_e32 v66, v66, v160
	v_add_f32_e32 v67, v67, v163
	v_cndmask_b32_e32 v66, v202, v66, vcc
	v_cmp_gt_u32_e32 vcc, s17, v169
	s_waitcnt lgkmcnt(13)
	v_add_f32_e32 v68, v68, v156
	s_waitcnt lgkmcnt(12)
	v_add_f32_e32 v69, v69, v157
	v_cndmask_b32_e32 v67, v202, v67, vcc
	v_cmp_gt_u32_e32 vcc, s17, v167
	s_waitcnt lgkmcnt(11)
	v_add_f32_e32 v70, v70, v152
	s_waitcnt lgkmcnt(10)
	v_add_f32_e32 v71, v71, v153
	v_cndmask_b32_e32 v68, v202, v68, vcc
	v_cmp_gt_u32_e32 vcc, s17, v166
	v_max_f32_e32 v93, v2, v2
	v_max_f32_e32 v94, v3, v3
	v_cndmask_b32_e32 v69, v202, v69, vcc
	v_cmp_gt_u32_e32 vcc, s17, v165
	s_waitcnt lgkmcnt(9)
	v_add_f32_e32 v72, v72, v149
	v_max_f32_e32 v93, v93, v66
	v_cndmask_b32_e32 v70, v202, v70, vcc
	v_cmp_gt_u32_e32 vcc, s17, v164
	v_max_f32_e32 v94, v94, v67
	s_mov_b32 s26, 0xf149f2ca
	v_cndmask_b32_e32 v71, v202, v71, vcc
	v_cmp_gt_u32_e32 vcc, s17, v162
	s_waitcnt lgkmcnt(8)
	v_add_f32_e32 v73, v73, v150
	v_max3_f32 v93, v93, s26, v94
	v_cndmask_b32_e32 v72, v202, v72, vcc
	v_cmp_gt_u32_e32 vcc, s17, v159
	v_max_f32_e32 v94, v4, v4
	v_max_f32_e32 v95, v5, v5
	v_cndmask_b32_e32 v73, v202, v73, vcc
	v_cmp_gt_u32_e32 vcc, s17, v158
	s_waitcnt lgkmcnt(7)
	v_add_f32_e32 v74, v74, v88
	v_max_f32_e32 v94, v94, v68
	v_max_f32_e32 v95, v95, v69
	v_cndmask_b32_e32 v74, v202, v74, vcc
	v_cmp_gt_u32_e32 vcc, s17, v155
	s_waitcnt lgkmcnt(6)
	v_add_f32_e32 v75, v75, v89
	v_max3_f32 v93, v93, v94, v95
	v_max_f32_e32 v94, v6, v6
	v_max_f32_e32 v95, v7, v7
	v_cndmask_b32_e32 v75, v202, v75, vcc
	v_cmp_gt_u32_e32 vcc, s17, v154
	s_waitcnt lgkmcnt(5)
	v_add_f32_e32 v76, v76, v85
	v_max_f32_e32 v94, v94, v70
	v_max_f32_e32 v95, v95, v71
	v_cndmask_b32_e32 v76, v202, v76, vcc
	v_cmp_gt_u32_e32 vcc, s17, v151
	s_waitcnt lgkmcnt(4)
	v_add_f32_e32 v77, v77, v86
	v_max3_f32 v93, v93, v94, v95
	v_max_f32_e32 v94, v8, v8
	v_max_f32_e32 v95, v9, v9
	v_cndmask_b32_e32 v77, v202, v77, vcc
	v_cmp_gt_u32_e32 vcc, s17, v92
	s_waitcnt lgkmcnt(3)
	v_add_f32_e32 v78, v78, v83
	v_max_f32_e32 v94, v94, v72
	v_max_f32_e32 v95, v95, v73
	v_max_f32_e32 v88, v10, v10
	v_max_f32_e32 v89, v11, v11
	v_cndmask_b32_e32 v78, v202, v78, vcc
	v_cmp_gt_u32_e32 vcc, s17, v91
	s_waitcnt lgkmcnt(2)
	v_add_f32_e32 v79, v79, v84
	v_max3_f32 v93, v93, v94, v95
	v_max_f32_e32 v88, v88, v74
	v_max_f32_e32 v89, v89, v75
	v_max_f32_e32 v85, v12, v12
	v_max_f32_e32 v86, v13, v13
	v_cndmask_b32_e32 v79, v202, v79, vcc
	v_cmp_gt_u32_e32 vcc, s17, v90
	s_waitcnt lgkmcnt(1)
	v_add_f32_e32 v0, v80, v0
	v_max3_f32 v88, v93, v88, v89
	v_max_f32_e32 v85, v85, v76
	v_max_f32_e32 v86, v86, v77
	v_max_f32_e32 v83, v14, v14
	v_max_f32_e32 v84, v15, v15
	v_cndmask_b32_e32 v80, v202, v0, vcc
	v_cmp_gt_u32_e32 vcc, s17, v87
	s_waitcnt lgkmcnt(0)
	v_add_f32_e32 v81, v81, v82
	v_max3_f32 v85, v88, v85, v86
	v_max_f32_e32 v83, v83, v78
	v_max_f32_e32 v84, v84, v79
	v_max_f32_e32 v0, v64, v64
	v_cndmask_b32_e32 v81, v202, v81, vcc
	v_max_f32_e32 v82, v65, v65
	v_max3_f32 v83, v85, v83, v84
	v_max_f32_e32 v0, v0, v80
	v_max_f32_e32 v82, v82, v81
	v_max3_f32 v0, v83, v0, v82
	v_mov_b32_e32 v82, v0
	s_nop 1
	v_permlane32_swap_b32_e32 v0, v82
	v_max_f32_e32 v82, v82, v82
	v_max_f32_e32 v0, v0, v0
	v_max_f32_e32 v0, v0, v82
	v_cmp_lt_f32_e32 vcc, s19, v0
	s_nop 1
	v_cndmask_b32_e32 v0, 0, v0, vcc
	v_cmp_neq_f32_e32 vcc, 0, v0
	s_cbranch_vccz .LBB0_103
	v_exp_f32_e64 v48, -v0
	v_add_f32_e32 v131, v131, v0
	v_sub_f32_e32 v65, v65, v0
	v_sub_f32_e32 v64, v64, v0
	v_mul_f32_e32 v138, v138, v48
	v_mul_f32_e32 v46, v46, v48
	v_mul_f32_e32 v47, v47, v48
	v_mul_f32_e32 v44, v44, v48
	v_mul_f32_e32 v45, v45, v48
	v_mul_f32_e32 v42, v42, v48
	v_mul_f32_e32 v43, v43, v48
	v_mul_f32_e32 v40, v40, v48
	v_mul_f32_e32 v41, v41, v48
	v_mul_f32_e32 v38, v38, v48
	v_mul_f32_e32 v39, v39, v48
	v_mul_f32_e32 v36, v36, v48
	v_mul_f32_e32 v37, v37, v48
	v_mul_f32_e32 v34, v34, v48
	v_mul_f32_e32 v35, v35, v48
	v_mul_f32_e32 v32, v32, v48
	v_mul_f32_e32 v33, v33, v48
	v_mul_f32_e32 v30, v30, v48
	v_mul_f32_e32 v31, v31, v48
	v_mul_f32_e32 v28, v28, v48
	v_mul_f32_e32 v29, v29, v48
	v_mul_f32_e32 v26, v26, v48
	v_mul_f32_e32 v27, v27, v48
	v_mul_f32_e32 v24, v24, v48
	v_mul_f32_e32 v25, v25, v48
	v_mul_f32_e32 v22, v22, v48
	v_mul_f32_e32 v23, v23, v48
	v_mul_f32_e32 v20, v20, v48
	v_mul_f32_e32 v21, v21, v48
	v_mul_f32_e32 v18, v18, v48
	v_mul_f32_e32 v19, v19, v48
	v_mul_f32_e32 v16, v16, v48
	v_mul_f32_e32 v17, v17, v48
	v_xor_b32_e32 v48, 0x80000000, v131
	v_sub_f32_e32 v15, v15, v0
	v_sub_f32_e32 v14, v14, v0
	v_sub_f32_e32 v13, v13, v0
	v_sub_f32_e32 v12, v12, v0
	v_sub_f32_e32 v11, v11, v0
	v_sub_f32_e32 v10, v10, v0
	v_sub_f32_e32 v9, v9, v0
	v_sub_f32_e32 v8, v8, v0
	v_sub_f32_e32 v7, v7, v0
	v_sub_f32_e32 v6, v6, v0
	v_sub_f32_e32 v5, v5, v0
	v_sub_f32_e32 v4, v4, v0
	v_sub_f32_e32 v3, v3, v0
	v_sub_f32_e32 v2, v2, v0
	v_sub_f32_e32 v81, v81, v0
	v_sub_f32_e32 v80, v80, v0
	v_sub_f32_e32 v79, v79, v0
	v_sub_f32_e32 v78, v78, v0
	v_sub_f32_e32 v77, v77, v0
	v_sub_f32_e32 v76, v76, v0
	v_sub_f32_e32 v75, v75, v0
	v_sub_f32_e32 v74, v74, v0
	v_sub_f32_e32 v73, v73, v0
	v_sub_f32_e32 v72, v72, v0
	v_sub_f32_e32 v71, v71, v0
	v_sub_f32_e32 v70, v70, v0
	v_sub_f32_e32 v69, v69, v0
	v_sub_f32_e32 v68, v68, v0
	v_sub_f32_e32 v67, v67, v0
	v_sub_f32_e32 v66, v66, v0
	v_mov_b32_e32 v49, v48
	v_mov_b32_e32 v50, v48
	v_mov_b32_e32 v51, v48
	v_mov_b32_e32 v52, v48
	v_mov_b32_e32 v53, v48
	v_mov_b32_e32 v54, v48
	v_mov_b32_e32 v55, v48
	v_mov_b32_e32 v56, v48
	v_mov_b32_e32 v57, v48
	v_mov_b32_e32 v58, v48
	v_mov_b32_e32 v59, v48
	v_mov_b32_e32 v60, v48
	v_mov_b32_e32 v61, v48
	v_mov_b32_e32 v62, v48
	v_mov_b32_e32 v63, v48
; #define MFMA32(a, b, c) __builtin_amdgcn_mfma_f32_32x32x16_bf16((a), (b), (c), 0, 0, 0)
; template <int DB, int VLD> DI void pv_block(f32x16& o, unsigned vb, bf16x8 pb0, bf16x8 pb1, bf16x8 pb2, bf16x8 pb3) {
;   constexpr int RB = VLD * 2;
;   bf16x4 l0 = tr_read<0 * RB + 64 * DB>(vb), h0 = tr_read<8 * RB + 64 * DB>(vb);
;   bf16x4 l1 = tr_read<16 * RB + 64 * DB>(vb), h1 = tr_read<24 * RB + 64 * DB>(vb);
;   bf16x4 l2 = tr_read<32 * RB + 64 * DB>(vb), h2 = tr_read<40 * RB + 64 * DB>(vb);
;   bf16x4 l3 = tr_read<48 * RB + 64 * DB>(vb), h3 = tr_read<56 * RB + 64 * DB>(vb);
;   asm volatile("s_waitcnt lgkmcnt(0)" ::: "memory"); __builtin_amdgcn_sched_barrier(0);
;   o = MFMA32(__builtin_shufflevector(l0, h0, 0, 1, 2, 3, 4, 5, 6, 7), pb0, o);
;   o = MFMA32(__builtin_shufflevector(l1, h1, 0, 1, 2, 3, 4, 5, 6, 7), pb1, o);
;   o = MFMA32(__builtin_shufflevector(l2, h2, 0, 1, 2, 3, 4, 5, 6, 7), pb2, o);
;   o = MFMA32(__builtin_shufflevector(l3, h3, 0, 1, 2, 3, 4, 5, 6, 7), pb3, o);
; }
; template <int W, bool SINK>
; DI void attn_band_mfma(const bf16_t* Qb, size_t ldq, const bf16_t* Kb, const bf16_t* Vb, size_t ldk, int L, int i0,
;                        const float* lut_g, float sink2, bf16_t* outp, size_t ldo, float* lse_out, size_t ldl, char* smem) {
;     ...
;     float ls = 0.f;
; #pragma unroll
;     for (int i = 0; i < 16; ++i) { p0[i] = __builtin_amdgcn_exp2f(p0[i]); p1[i] = __builtin_amdgcn_exp2f(p1[i]); ls += p0[i] + p1[i]; }
;     l_run += ls;
;     bf16x8 pb0 = pack8(p0, 0), pb1 = pack8(p0, 8), pb2 = pack8(p1, 0), pb3 = pack8(p1, 8);
;     const unsigned vb = vb0 + cur * VBYTES;
;     pv_block<0, VLD>(o0, vb, pb0, pb1, pb2, pb3);
;     pv_block<1, VLD>(o1, vb, pb0, pb1, pb2, pb3);
.LBB0_103:
	v_exp_f32_e32 v84, v2
	v_exp_f32_e32 v85, v66
	v_exp_f32_e32 v0, v3
	v_exp_f32_e32 v66, v67
	v_exp_f32_e32 v86, v68
	v_add_f32_e32 v67, v85, v84
	v_exp_f32_e32 v68, v69
	v_add_f32_e32 v2, v66, v0
	v_add_f32_e32 v3, v67, v1
	v_exp_f32_e32 v67, v4
	v_add_f32_e32 v82, v2, v2
	v_add_f32_e32 v83, v2, v3
	v_exp_f32_e32 v82, v5
	s_mul_i32 s26, s37, 0x3000
	v_add_f32_e32 v69, v86, v67
	v_add_f32_e32 v2, v68, v82
	v_add_f32_e32 v3, v69, v83
	s_nop 0
	v_add_f32_e32 v4, v2, v2
	v_add_f32_e32 v5, v2, v3
	v_exp_f32_e32 v69, v6
	v_exp_f32_e32 v83, v70
	v_exp_f32_e32 v4, v7
	v_exp_f32_e32 v70, v71
	v_add_f32_e32 v71, v83, v69
	v_add_f32_e32 v2, v70, v4
	v_add_f32_e32 v3, v71, v5
	s_nop 0
	v_add_f32_e32 v6, v2, v2
	v_add_f32_e32 v7, v2, v3
	v_exp_f32_e32 v5, v8
	v_exp_f32_e32 v71, v72
	v_exp_f32_e32 v6, v9
	v_exp_f32_e32 v72, v73
	v_cvt_pk_bf16_f32 v4, v69, v4
	v_add_f32_e32 v73, v71, v5
	v_cvt_pk_bf16_f32 v5, v5, v6
	v_add_f32_e32 v2, v72, v6
	v_add_f32_e32 v3, v73, v7
	v_exp_f32_e32 v7, v10
	v_add_f32_e32 v8, v2, v2
	v_add_f32_e32 v9, v2, v3
	v_exp_f32_e32 v73, v74
	v_exp_f32_e32 v8, v11
	v_exp_f32_e32 v74, v75
	v_add_f32_e32 v75, v73, v7
	v_cvt_pk_bf16_f32 v6, v7, v8
	v_add_f32_e32 v2, v74, v8
	v_add_f32_e32 v3, v75, v9
	v_exp_f32_e32 v9, v12
	v_add_f32_e32 v10, v2, v2
	v_add_f32_e32 v11, v2, v3
	v_exp_f32_e32 v75, v76
	v_exp_f32_e32 v10, v13
	v_exp_f32_e32 v76, v77
	v_add_f32_e32 v77, v75, v9
	v_cvt_pk_bf16_f32 v7, v9, v10
	v_add_f32_e32 v2, v76, v10
	v_add_f32_e32 v3, v77, v11
	v_exp_f32_e32 v11, v14
	v_add_f32_e32 v12, v2, v2
	v_add_f32_e32 v13, v2, v3
	v_exp_f32_e32 v77, v78
	v_exp_f32_e32 v12, v15
	v_exp_f32_e32 v14, v79
	v_cvt_pk_bf16_f32 v10, v85, v66
	v_add_f32_e32 v15, v77, v11
	v_cvt_pk_bf16_f32 v8, v11, v12
	v_add_f32_e32 v2, v14, v12
	v_add_f32_e32 v3, v15, v13
	v_exp_f32_e32 v13, v64
	v_add_f32_e32 v78, v2, v2
	v_add_f32_e32 v79, v2, v3
	v_exp_f32_e32 v15, v80
	v_exp_f32_e32 v78, v65
	v_exp_f32_e32 v80, v81
	v_cvt_pk_bf16_f32 v11, v86, v68
	v_add_f32_e32 v81, v15, v13
	v_cvt_pk_bf16_f32 v9, v13, v78
	v_add_f32_e32 v2, v80, v78
	v_add_f32_e32 v3, v81, v79
	v_cvt_pk_bf16_f32 v12, v83, v70
	v_add_f32_e32 v2, v2, v3
	v_add_f32_e32 v138, v138, v2
	v_cvt_pk_bf16_f32 v2, v84, v0
	v_add_u32_e32 v0, s26, v139
	ds_read_b64_tr_b16 v[68:69], v0 offset:0
	v_cvt_pk_bf16_f32 v13, v71, v72
	ds_read_b64_tr_b16 v[70:71], v0 offset:0x600
	v_cvt_pk_bf16_f32 v64, v73, v74
	ds_read_b64_tr_b16 v[72:73], v0 offset:0xc00
	v_cvt_pk_bf16_f32 v65, v75, v76
	ds_read_b64_tr_b16 v[74:75], v0 offset:0x1200
	v_cvt_pk_bf16_f32 v66, v77, v14
	ds_read_b64_tr_b16 v[76:77], v0 offset:0x1800
	ds_read_b64_tr_b16 v[78:79], v0 offset:0x1e00
	v_cvt_pk_bf16_f32 v3, v67, v82
	v_cvt_pk_bf16_f32 v67, v15, v80
	ds_read_b64_tr_b16 v[80:81], v0 offset:0x2400
	ds_read_b64_tr_b16 v[82:83], v0 offset:0x2a00
	s_waitcnt lgkmcnt(0)
	s_nop 0
	v_mfma_f32_32x32x16_bf16 v[32:47], v[68:71], v[2:5], v[32:47]
	ds_read_b64_tr_b16 v[68:69], v0 offset:64
	ds_read_b64_tr_b16 v[70:71], v0 offset:0x640
	v_mfma_f32_32x32x16_bf16 v[32:47], v[72:75], v[6:9], v[32:47]
	ds_read_b64_tr_b16 v[72:73], v0 offset:0xc40
	ds_read_b64_tr_b16 v[74:75], v0 offset:0x1240
	v_mfma_f32_32x32x16_bf16 v[32:47], v[76:79], v[10:13], v[32:47]
	ds_read_b64_tr_b16 v[76:77], v0 offset:0x1840
	ds_read_b64_tr_b16 v[78:79], v0 offset:0x1e40
	v_mfma_f32_32x32x16_bf16 v[32:47], v[80:83], v[64:67], v[32:47]
	ds_read_b64_tr_b16 v[80:81], v0 offset:0x2440
	ds_read_b64_tr_b16 v[82:83], v0 offset:0x2a40
	s_waitcnt lgkmcnt(0)
	v_mfma_f32_32x32x16_bf16 v[16:31], v[68:71], v[2:5], v[16:31]
	v_mfma_f32_32x32x16_bf16 v[16:31], v[72:75], v[6:9], v[16:31]
	v_mfma_f32_32x32x16_bf16 v[16:31], v[76:79], v[10:13], v[16:31]
	v_mfma_f32_32x32x16_bf16 v[16:31], v[80:83], v[64:67], v[16:31]

; DI unsigned pack2(float a, float b) { f2_t v = {a, b}; bf2_t r = __builtin_convertvector(v, bf2_t); return __builtin_bit_cast(unsigned, r); }
; #define BLO(u) __uint_as_float((u) << 16)
; #define BHI(u) __uint_as_float((u) & 0xffff0000u)
; DI float frcp(float x) { return __builtin_amdgcn_rcpf(x); }
; template <int W, bool SINK>
; DI void attn_band_mfma(const bf16_t* Qb, size_t ldq, const bf16_t* Kb, const bf16_t* Vb, size_t ldk, int L, int i0,
;                        const float* lut_g, float sink2, bf16_t* outp, size_t ldo, float* lse_out, size_t ldl, char* smem) {
;     ...
;   const float ltot = half_swap_sum(l_run);
;   const float inv = frcp(ltot);
;   bf16_t* orow = outp + (size_t)qi * ldo;
;   if (!SINK && h == 0) lse_out[(size_t)qi * ldl] = m_run + __log2f(ltot);
; #pragma unroll
;   for (int db = 0; db < 2; ++db)
; #pragma unroll
;     for (int kp = 0; kp < 2; ++kp) {
;       uint2 w2[2];
; #pragma unroll
;       for (int gg = 0; gg < 2; ++gg) {
;         const int g4 = 2 * kp + gg;
;         float y[4];
;         if (SINK) {
;           uint2 u = *(const uint2*)(orow + 32 * db + 8 * g4 + 4 * h);
;           float g[4] = {BLO(u.x), BHI(u.x), BLO(u.y), BHI(u.y)};
; #pragma unroll
;           for (int e = 0; e < 4; ++e) { float ov = db == 0 ? o0[4 * g4 + e] : o1[4 * g4 + e]; y[e] = ov * inv * g[e] * frcp(1.0f + __expf(-g[e])); }
;         } else {
; #pragma unroll
;           for (int e = 0; e < 4; ++e) { float ov = db == 0 ? o0[4 * g4 + e] : o1[4 * g4 + e]; y[e] = ov * inv; }
;         }
;         w2[gg].x = pack2(y[0], y[1]); w2[gg].y = pack2(y[2], y[3]);
;       }
;       auto rx = __builtin_amdgcn_permlane32_swap(w2[0].x, w2[1].x, false, false);
;       auto ry = __builtin_amdgcn_permlane32_swap(w2[0].y, w2[1].y, false, false);
;       uint4 w; w.x = rx[0]; w.y = ry[0]; w.z = rx[1]; w.w = ry[1];
;       *(uint4*)(orow + 32 * db + 16 * kp + 8 * h) = w;
;     }
.LBB0_108:
	v_mov_b32_e32 v0, v138
	s_lshl_b32 s0, s30, 1
	s_nop 0
	v_permlane32_swap_b32_e32 v138, v0
	s_add_u32 s0, s28, s0
	v_add_f32_e32 v0, v138, v0
	s_addc_u32 s1, s29, 0
	v_rcp_f32_e32 v4, v0
	v_lshlrev_b32_e32 v0, 1, v132
	v_lshl_add_u64 v[2:3], s[0:1], 0, v[0:1]
	s_mov_b64 s[0:1], 0x2000
	v_lshl_add_u64 v[6:7], v[2:3], 0, s[0:1]
	v_lshlrev_b32_e32 v0, 1, v133
	v_lshl_add_u64 v[2:3], v[6:7], 0, v[0:1]
	v_lshlrev_b32_e32 v0, 1, v130
	v_lshl_add_u64 v[130:131], v[6:7], 0, v[0:1]
	global_load_dwordx2 v[6:7], v[2:3], off
	v_mul_f32_e32 v12, v32, v4
	v_mul_f32_e32 v13, v33, v4
	v_mul_f32_e32 v14, v36, v4
	v_mul_f32_e32 v15, v37, v4
	v_readlane_b32 s28, v255, 3
	s_mov_b64 s[0:1], 0
	v_readlane_b32 s29, v255, 4
	s_waitcnt vmcnt(0)
	v_lshlrev_b32_e32 v8, 16, v6
	v_mul_f32_e32 v0, 0xbfb8aa3b, v8
	v_exp_f32_e32 v0, v0
	v_and_b32_e32 v9, 0xffff0000, v6
	v_mul_f32_e32 v12, v12, v8
	v_mul_f32_e32 v13, v13, v9
	v_lshlrev_b32_e32 v6, 16, v7
	v_add_f32_e32 v0, 1.0, v0
	v_rcp_f32_e32 v10, v0
	v_mul_f32_e32 v0, 0xbfb8aa3b, v9
	v_exp_f32_e32 v0, v0
	v_and_b32_e32 v7, 0xffff0000, v7
	v_add_f32_e32 v0, 1.0, v0
	v_rcp_f32_e32 v11, v0
	v_mul_f32_e32 v0, 0xbfb8aa3b, v6
	v_exp_f32_e32 v0, v0
	v_mul_f32_e32 v8, v12, v10
	v_mul_f32_e32 v9, v13, v11
	v_mul_f32_e32 v12, v34, v4
	v_mul_f32_e32 v13, v35, v4
	v_add_f32_e32 v0, 1.0, v0
	v_mul_f32_e32 v12, v12, v6
	v_mul_f32_e32 v13, v13, v7
	v_cvt_pk_bf16_f32 v6, v8, v9
	global_load_dwordx2 v[8:9], v[2:3], off offset:16
	v_rcp_f32_e32 v10, v0
	v_mul_f32_e32 v0, 0xbfb8aa3b, v7
	v_exp_f32_e32 v0, v0
	s_nop 0
	v_add_f32_e32 v0, 1.0, v0
	v_rcp_f32_e32 v11, v0
	s_nop 0
	v_mul_f32_e32 v10, v12, v10
	v_mul_f32_e32 v11, v13, v11
	s_nop 0
	v_cvt_pk_bf16_f32 v7, v10, v11
	s_waitcnt vmcnt(0)
	v_lshlrev_b32_e32 v10, 16, v8
	v_mul_f32_e32 v0, 0xbfb8aa3b, v10
	v_exp_f32_e32 v0, v0
	v_and_b32_e32 v11, 0xffff0000, v8
	v_lshlrev_b32_e32 v8, 16, v9
	v_and_b32_e32 v9, 0xffff0000, v9
	v_add_f32_e32 v0, 1.0, v0
	v_rcp_f32_e32 v12, v0
	v_mul_f32_e32 v0, 0xbfb8aa3b, v11
	v_exp_f32_e32 v0, v0
	v_mul_f32_e32 v14, v14, v10
	v_mul_f32_e32 v15, v15, v11
	v_add_f32_e32 v0, 1.0, v0
	v_rcp_f32_e32 v13, v0
	v_mul_f32_e32 v0, 0xbfb8aa3b, v8
	v_exp_f32_e32 v0, v0
	v_mul_f32_e32 v10, v14, v12
	v_mul_f32_e32 v11, v15, v13
	v_mul_f32_e32 v14, v38, v4
	v_mul_f32_e32 v15, v39, v4
	v_add_f32_e32 v0, 1.0, v0
	v_rcp_f32_e32 v12, v0
	v_mul_f32_e32 v0, 0xbfb8aa3b, v9
	v_exp_f32_e32 v0, v0
	v_mul_f32_e32 v14, v14, v8
	v_mul_f32_e32 v15, v15, v9
	v_cvt_pk_bf16_f32 v8, v10, v11
	s_nop 1
	v_permlane32_swap_b32_e32 v6, v8
	v_add_f32_e32 v0, 1.0, v0
	v_rcp_f32_e32 v13, v0
	s_nop 0
	v_mul_f32_e32 v12, v14, v12
	v_mul_f32_e32 v13, v15, v13
	s_nop 0
	v_cvt_pk_bf16_f32 v9, v12, v13
	s_nop 1
	v_permlane32_swap_b32_e32 v7, v9
	global_store_dwordx4 v[130:131], v[6:9], off
	global_load_dwordx2 v[6:7], v[2:3], off offset:32
	v_mul_f32_e32 v12, v40, v4
	v_mul_f32_e32 v13, v41, v4
	v_mul_f32_e32 v14, v44, v4
	v_mul_f32_e32 v15, v45, v4
	s_waitcnt vmcnt(0)
	v_lshlrev_b32_e32 v8, 16, v6
	v_mul_f32_e32 v0, 0xbfb8aa3b, v8
	v_exp_f32_e32 v0, v0
	v_and_b32_e32 v9, 0xffff0000, v6
	v_mul_f32_e32 v12, v12, v8
	v_mul_f32_e32 v13, v13, v9
	v_lshlrev_b32_e32 v6, 16, v7
	v_add_f32_e32 v0, 1.0, v0
	v_rcp_f32_e32 v10, v0
	v_mul_f32_e32 v0, 0xbfb8aa3b, v9
	v_exp_f32_e32 v0, v0
	v_and_b32_e32 v7, 0xffff0000, v7
	v_add_f32_e32 v0, 1.0, v0
	v_rcp_f32_e32 v11, v0
	v_mul_f32_e32 v0, 0xbfb8aa3b, v6
	v_exp_f32_e32 v0, v0
	v_mul_f32_e32 v8, v12, v10
	v_mul_f32_e32 v9, v13, v11
	v_mul_f32_e32 v12, v42, v4
	v_mul_f32_e32 v13, v43, v4
	v_add_f32_e32 v0, 1.0, v0
	v_mul_f32_e32 v12, v12, v6
	v_mul_f32_e32 v13, v13, v7
	v_cvt_pk_bf16_f32 v6, v8, v9
	global_load_dwordx2 v[8:9], v[2:3], off offset:48
	v_rcp_f32_e32 v10, v0
	v_mul_f32_e32 v0, 0xbfb8aa3b, v7
	v_exp_f32_e32 v0, v0
	s_nop 0
	v_add_f32_e32 v0, 1.0, v0
	v_rcp_f32_e32 v11, v0
	s_nop 0
	v_mul_f32_e32 v10, v12, v10
	v_mul_f32_e32 v11, v13, v11
	s_nop 0
	v_cvt_pk_bf16_f32 v7, v10, v11
	s_waitcnt vmcnt(0)
	v_lshlrev_b32_e32 v10, 16, v8
	v_mul_f32_e32 v0, 0xbfb8aa3b, v10
	v_exp_f32_e32 v0, v0
	v_and_b32_e32 v11, 0xffff0000, v8
	v_lshlrev_b32_e32 v8, 16, v9
	v_and_b32_e32 v9, 0xffff0000, v9
	v_add_f32_e32 v0, 1.0, v0
	v_rcp_f32_e32 v12, v0
	v_mul_f32_e32 v0, 0xbfb8aa3b, v11
	v_exp_f32_e32 v0, v0
	v_mul_f32_e32 v14, v14, v10
	v_mul_f32_e32 v15, v15, v11
	v_add_f32_e32 v0, 1.0, v0
	v_rcp_f32_e32 v13, v0
	v_mul_f32_e32 v0, 0xbfb8aa3b, v8
	v_exp_f32_e32 v0, v0
	v_mul_f32_e32 v10, v14, v12
	v_mul_f32_e32 v11, v15, v13
	v_mul_f32_e32 v14, v46, v4
	v_mul_f32_e32 v15, v47, v4
	v_add_f32_e32 v0, 1.0, v0
	v_rcp_f32_e32 v12, v0
	v_mul_f32_e32 v0, 0xbfb8aa3b, v9
	v_exp_f32_e32 v0, v0
	v_mul_f32_e32 v14, v14, v8
	v_mul_f32_e32 v15, v15, v9
	v_cvt_pk_bf16_f32 v8, v10, v11
	s_nop 1
	v_permlane32_swap_b32_e32 v6, v8
	v_add_f32_e32 v0, 1.0, v0
	v_rcp_f32_e32 v13, v0
	s_nop 0
	v_mul_f32_e32 v12, v14, v12
	v_mul_f32_e32 v13, v15, v13
	s_nop 0
	v_cvt_pk_bf16_f32 v9, v12, v13
	s_nop 1
	v_permlane32_swap_b32_e32 v7, v9
	global_store_dwordx4 v[130:131], v[6:9], off offset:32
	global_load_dwordx2 v[6:7], v[2:3], off offset:64
	v_mul_f32_e32 v12, v16, v4
	v_mul_f32_e32 v13, v17, v4
	v_mul_f32_e32 v14, v20, v4
	v_mul_f32_e32 v15, v21, v4
	s_waitcnt vmcnt(0)
; DI unsigned pack2(float a, float b) { f2_t v = {a, b}; bf2_t r = __builtin_convertvector(v, bf2_t); return __builtin_bit_cast(unsigned, r); }
; #define BLO(u) __uint_as_float((u) << 16)
; #define BHI(u) __uint_as_float((u) & 0xffff0000u)
; DI float frcp(float x) { return __builtin_amdgcn_rcpf(x); }
; template <int W, bool SINK>
; DI void attn_band_mfma(const bf16_t* Qb, size_t ldq, const bf16_t* Kb, const bf16_t* Vb, size_t ldk, int L, int i0,
;                        const float* lut_g, float sink2, bf16_t* outp, size_t ldo, float* lse_out, size_t ldl, char* smem) {
;     ...
;       for (int gg = 0; gg < 2; ++gg) {
;         const int g4 = 2 * kp + gg;
;         float y[4];
;         if (SINK) {
;           uint2 u = *(const uint2*)(orow + 32 * db + 8 * g4 + 4 * h);
;           float g[4] = {BLO(u.x), BHI(u.x), BLO(u.y), BHI(u.y)};
; #pragma unroll
;           for (int e = 0; e < 4; ++e) { float ov = db == 0 ? o0[4 * g4 + e] : o1[4 * g4 + e]; y[e] = ov * inv * g[e] * frcp(1.0f + __expf(-g[e])); }
;         } else {
; #pragma unroll
;           for (int e = 0; e < 4; ++e) { float ov = db == 0 ? o0[4 * g4 + e] : o1[4 * g4 + e]; y[e] = ov * inv; }
;         }
;         w2[gg].x = pack2(y[0], y[1]); w2[gg].y = pack2(y[2], y[3]);
;       }
;       auto rx = __builtin_amdgcn_permlane32_swap(w2[0].x, w2[1].x, false, false);
;       auto ry = __builtin_amdgcn_permlane32_swap(w2[0].y, w2[1].y, false, false);
;       uint4 w; w.x = rx[0]; w.y = ry[0]; w.z = rx[1]; w.w = ry[1];
;       *(uint4*)(orow + 32 * db + 16 * kp + 8 * h) = w;
;     }
	v_lshlrev_b32_e32 v8, 16, v6
	v_mul_f32_e32 v0, 0xbfb8aa3b, v8
	v_exp_f32_e32 v0, v0
	v_and_b32_e32 v9, 0xffff0000, v6
	v_mul_f32_e32 v12, v12, v8
	v_mul_f32_e32 v13, v13, v9
	v_lshlrev_b32_e32 v6, 16, v7
	v_add_f32_e32 v0, 1.0, v0
	v_rcp_f32_e32 v10, v0
	v_mul_f32_e32 v0, 0xbfb8aa3b, v9
	v_exp_f32_e32 v0, v0
	v_and_b32_e32 v7, 0xffff0000, v7
	v_add_f32_e32 v0, 1.0, v0
	v_rcp_f32_e32 v11, v0
	v_mul_f32_e32 v0, 0xbfb8aa3b, v6
	v_exp_f32_e32 v0, v0
	v_mul_f32_e32 v8, v12, v10
	v_mul_f32_e32 v9, v13, v11
	v_mul_f32_e32 v12, v18, v4
	v_mul_f32_e32 v13, v19, v4
	v_add_f32_e32 v0, 1.0, v0
	v_mul_f32_e32 v12, v12, v6
	v_mul_f32_e32 v13, v13, v7
	v_cvt_pk_bf16_f32 v6, v8, v9
	global_load_dwordx2 v[8:9], v[2:3], off offset:80
	v_rcp_f32_e32 v10, v0
	v_mul_f32_e32 v0, 0xbfb8aa3b, v7
	v_exp_f32_e32 v0, v0
	s_nop 0
	v_add_f32_e32 v0, 1.0, v0
	v_rcp_f32_e32 v11, v0
	s_nop 0
	v_mul_f32_e32 v10, v12, v10
	v_mul_f32_e32 v11, v13, v11
	s_nop 0
	v_cvt_pk_bf16_f32 v7, v10, v11
	s_waitcnt vmcnt(0)
	v_lshlrev_b32_e32 v10, 16, v8
	v_mul_f32_e32 v0, 0xbfb8aa3b, v10
	v_exp_f32_e32 v0, v0
	v_and_b32_e32 v11, 0xffff0000, v8
	v_lshlrev_b32_e32 v8, 16, v9
	v_and_b32_e32 v9, 0xffff0000, v9
	v_add_f32_e32 v0, 1.0, v0
	v_rcp_f32_e32 v12, v0
	v_mul_f32_e32 v0, 0xbfb8aa3b, v11
	v_exp_f32_e32 v0, v0
	v_mul_f32_e32 v14, v14, v10
	v_mul_f32_e32 v15, v15, v11
	v_add_f32_e32 v0, 1.0, v0
	v_rcp_f32_e32 v13, v0
	v_mul_f32_e32 v0, 0xbfb8aa3b, v8
	v_exp_f32_e32 v0, v0
	v_mul_f32_e32 v10, v14, v12
	v_mul_f32_e32 v11, v15, v13
	v_mul_f32_e32 v14, v22, v4
	v_mul_f32_e32 v15, v23, v4
	v_add_f32_e32 v0, 1.0, v0
	v_rcp_f32_e32 v12, v0
	v_mul_f32_e32 v0, 0xbfb8aa3b, v9
	v_exp_f32_e32 v0, v0
	v_mul_f32_e32 v14, v14, v8
	v_mul_f32_e32 v15, v15, v9
	v_cvt_pk_bf16_f32 v8, v10, v11
	s_nop 1
	v_permlane32_swap_b32_e32 v6, v8
	v_add_f32_e32 v0, 1.0, v0
	v_rcp_f32_e32 v13, v0
	s_nop 0
	v_mul_f32_e32 v12, v14, v12
	v_mul_f32_e32 v13, v15, v13
	s_nop 0
	v_cvt_pk_bf16_f32 v9, v12, v13
	s_nop 1
	v_permlane32_swap_b32_e32 v7, v9
	global_store_dwordx4 v[130:131], v[6:9], off offset:64
	global_load_dwordx2 v[6:7], v[2:3], off offset:96
	s_nop 0
	global_load_dwordx2 v[2:3], v[2:3], off offset:112
	v_mul_f32_e32 v14, v28, v4
	v_mul_f32_e32 v15, v29, v4
	s_waitcnt vmcnt(0)
	v_and_b32_e32 v11, 0xffff0000, v2
	v_mul_f32_e32 v0, 0xbfb8aa3b, v11
	v_exp_f32_e32 v0, v0
	v_lshlrev_b32_e32 v10, 16, v2
	v_lshlrev_b32_e32 v2, 16, v7
	v_lshlrev_b32_e32 v8, 16, v3
	v_add_f32_e32 v0, 1.0, v0
	v_rcp_f32_e32 v13, v0
	v_mul_f32_e32 v0, 0xbfb8aa3b, v10
	v_exp_f32_e32 v0, v0
	v_mul_f32_e32 v14, v14, v10
	v_mul_f32_e32 v15, v15, v11
	v_and_b32_e32 v9, 0xffff0000, v3
	v_and_b32_e32 v3, 0xffff0000, v7
	v_add_f32_e32 v0, 1.0, v0
	v_rcp_f32_e32 v12, v0
	v_mul_f32_e32 v0, 0xbfb8aa3b, v2
	v_exp_f32_e32 v0, v0
	v_mul_f32_e32 v10, v14, v12
	v_mul_f32_e32 v11, v15, v13
	v_mul_f32_e32 v14, v26, v4
	v_mul_f32_e32 v15, v27, v4
	v_add_f32_e32 v0, 1.0, v0
	v_rcp_f32_e32 v12, v0
	v_mul_f32_e32 v0, 0xbfb8aa3b, v3
	v_exp_f32_e32 v0, v0
	v_mul_f32_e32 v14, v14, v2
	v_mul_f32_e32 v15, v15, v3
	v_add_f32_e32 v0, 1.0, v0
	v_rcp_f32_e32 v13, v0
	s_nop 0
	v_mul_f32_e32 v2, v14, v12
	v_mul_f32_e32 v3, v15, v13
	v_lshlrev_b32_e32 v12, 16, v6
	v_mul_f32_e32 v0, 0xbfb8aa3b, v12
	v_exp_f32_e32 v0, v0
	v_and_b32_e32 v13, 0xffff0000, v6
	v_cvt_pk_bf16_f32 v2, v2, v3
	v_mul_f32_e32 v3, 0xbfb8aa3b, v8
	v_add_f32_e32 v0, 1.0, v0
	v_rcp_f32_e32 v6, v0
	v_mul_f32_e32 v0, 0xbfb8aa3b, v13
	v_exp_f32_e32 v0, v0
	v_exp_f32_e32 v3, v3
	v_mul_f32_e32 v14, v24, v4
	v_mul_f32_e32 v15, v25, v4
	v_mul_f32_e32 v5, v31, v4
	v_mul_f32_e32 v4, v30, v4
	v_add_f32_e32 v0, 1.0, v0
	v_rcp_f32_e32 v7, v0
	v_mul_f32_e32 v14, v14, v12
	v_mul_f32_e32 v15, v15, v13
	v_add_f32_e32 v3, 1.0, v3
	v_mul_f32_e32 v4, v4, v8
	v_mul_f32_e32 v5, v5, v9
	v_mul_f32_e32 v6, v14, v6
	v_mul_f32_e32 v7, v15, v7
	s_nop 0
	v_cvt_pk_bf16_f32 v0, v6, v7
	v_rcp_f32_e32 v6, v3
	v_mul_f32_e32 v3, 0xbfb8aa3b, v9
	v_exp_f32_e32 v3, v3
	s_nop 0
	v_add_f32_e32 v3, 1.0, v3
	v_rcp_f32_e32 v7, v3
	v_cvt_pk_bf16_f32 v3, v10, v11
	s_nop 1
	v_permlane32_swap_b32_e32 v0, v3
	v_mul_f32_e32 v4, v4, v6
	v_mul_f32_e32 v5, v5, v7
	global_store_dword v[130:131], v0, off offset:96
	v_cvt_pk_bf16_f32 v4, v4, v5
	s_nop 1
	v_permlane32_swap_b32_e32 v2, v4

; template <int W, bool SINK>
; DI void attn_band_mfma(const bf16_t* Qb, size_t ldq, const bf16_t* Kb, const bf16_t* Vb, size_t ldk, int L, int i0,
;                        const float* lut_g, float sink2, bf16_t* outp, size_t ldo, float* lse_out, size_t ldl, char* smem) {
;     ...
;     if (__any(delta != 0.f)) {
;       float alpha = seen ? __builtin_amdgcn_exp2f(-delta) : 1.0f;
;       l_run *= alpha; m_run += delta;
; #pragma unroll
;       for (int i = 0; i < 16; ++i) { o0[i] *= alpha; o1[i] *= alpha; p0[i] -= delta; p1[i] -= delta; }
;       negm = splat16(-m_run);
;     }
;     seen = seen || has;
;     float ls = 0.f;
; #pragma unroll
;     for (int i = 0; i < 16; ++i) { p0[i] = __builtin_amdgcn_exp2f(p0[i]); p1[i] = __builtin_amdgcn_exp2f(p1[i]); ls += p0[i] + p1[i]; }
;     l_run += ls;
;     bf16x8 pb0 = pack8(p0, 0), pb1 = pack8(p0, 8), pb2 = pack8(p1, 0), pb3 = pack8(p1, 8);
;     const unsigned vb = vb0 + cur * VBYTES;
;     pv_block<0, VLD>(o0, vb, pb0, pb1, pb2, pb3);
;     pv_block<1, VLD>(o1, vb, pb0, pb1, pb2, pb3);
.LBB0_153:
	s_or_b64 exec, exec, s[34:35]
	v_cmp_neq_f32_e32 vcc, 0, v0
	s_cbranch_vccz .LBB0_155
	v_exp_f32_e64 v48, -v0
	v_add_f32_e32 v149, v149, v0
	v_sub_f32_e32 v65, v65, v0
	v_sub_f32_e32 v64, v64, v0
	v_cndmask_b32_e64 v48, 1.0, v48, s[28:29]
	v_mul_f32_e32 v152, v152, v48
	v_mul_f32_e32 v46, v46, v48
	v_mul_f32_e32 v47, v47, v48
	v_mul_f32_e32 v44, v44, v48
	v_mul_f32_e32 v45, v45, v48
	v_mul_f32_e32 v42, v42, v48
	v_mul_f32_e32 v43, v43, v48
	v_mul_f32_e32 v40, v40, v48
	v_mul_f32_e32 v41, v41, v48
	v_mul_f32_e32 v38, v38, v48
	v_mul_f32_e32 v39, v39, v48
	v_mul_f32_e32 v36, v36, v48
	v_mul_f32_e32 v37, v37, v48
	v_mul_f32_e32 v34, v34, v48
	v_mul_f32_e32 v35, v35, v48
	v_mul_f32_e32 v32, v32, v48
	v_mul_f32_e32 v33, v33, v48
	v_mul_f32_e32 v30, v30, v48
	v_mul_f32_e32 v31, v31, v48
	v_mul_f32_e32 v28, v28, v48
	v_mul_f32_e32 v29, v29, v48
	v_mul_f32_e32 v26, v26, v48
	v_mul_f32_e32 v27, v27, v48
	v_mul_f32_e32 v24, v24, v48
	v_mul_f32_e32 v25, v25, v48
	v_mul_f32_e32 v22, v22, v48
	v_mul_f32_e32 v23, v23, v48
	v_mul_f32_e32 v20, v20, v48
	v_mul_f32_e32 v21, v21, v48
	v_mul_f32_e32 v18, v18, v48
	v_mul_f32_e32 v19, v19, v48
	v_mul_f32_e32 v16, v16, v48
	v_mul_f32_e32 v17, v17, v48
	v_xor_b32_e32 v48, 0x80000000, v149
	v_sub_f32_e32 v15, v15, v0
	v_sub_f32_e32 v14, v14, v0
	v_sub_f32_e32 v13, v13, v0
	v_sub_f32_e32 v12, v12, v0
	v_sub_f32_e32 v11, v11, v0
	v_sub_f32_e32 v10, v10, v0
	v_sub_f32_e32 v9, v9, v0
	v_sub_f32_e32 v8, v8, v0
	v_sub_f32_e32 v7, v7, v0
	v_sub_f32_e32 v6, v6, v0
	v_sub_f32_e32 v5, v5, v0
	v_sub_f32_e32 v4, v4, v0
	v_sub_f32_e32 v3, v3, v0
	v_sub_f32_e32 v2, v2, v0
	v_sub_f32_e32 v81, v81, v0
	v_sub_f32_e32 v80, v80, v0
	v_sub_f32_e32 v79, v79, v0
	v_sub_f32_e32 v78, v78, v0
	v_sub_f32_e32 v77, v77, v0
	v_sub_f32_e32 v76, v76, v0
	v_sub_f32_e32 v75, v75, v0
	v_sub_f32_e32 v74, v74, v0
	v_sub_f32_e32 v73, v73, v0
	v_sub_f32_e32 v72, v72, v0
	v_sub_f32_e32 v71, v71, v0
	v_sub_f32_e32 v70, v70, v0
	v_sub_f32_e32 v69, v69, v0
	v_sub_f32_e32 v68, v68, v0
	v_sub_f32_e32 v67, v67, v0
	v_sub_f32_e32 v66, v66, v0
	v_mov_b32_e32 v49, v48
	v_mov_b32_e32 v50, v48
	v_mov_b32_e32 v51, v48
	v_mov_b32_e32 v52, v48
	v_mov_b32_e32 v53, v48
	v_mov_b32_e32 v54, v48
	v_mov_b32_e32 v55, v48
	v_mov_b32_e32 v56, v48
	v_mov_b32_e32 v57, v48
	v_mov_b32_e32 v58, v48
	v_mov_b32_e32 v59, v48
	v_mov_b32_e32 v60, v48
	v_mov_b32_e32 v61, v48
	v_mov_b32_e32 v62, v48
	v_mov_b32_e32 v63, v48
.LBB0_155:
	v_exp_f32_e32 v84, v2
	v_exp_f32_e32 v85, v66
	v_exp_f32_e32 v0, v3
	v_exp_f32_e32 v66, v67
	v_exp_f32_e32 v86, v68
	v_add_f32_e32 v67, v85, v84
	v_exp_f32_e32 v68, v69
	v_add_f32_e32 v2, v66, v0
	v_add_f32_e32 v3, v67, v1
	v_exp_f32_e32 v67, v4
	v_add_f32_e32 v82, v2, v2
	v_add_f32_e32 v83, v2, v3
	v_exp_f32_e32 v82, v5
	s_mul_i32 s34, s83, 0x3000
	v_add_f32_e32 v69, v86, v67
	s_or_b64 s[38:39], s[28:29], s[38:39]
	v_add_f32_e32 v2, v68, v82
	v_add_f32_e32 v3, v69, v83
	v_exp_f32_e32 v69, v6
	v_add_f32_e32 v4, v2, v2
	v_add_f32_e32 v5, v2, v3
	v_exp_f32_e32 v83, v70
	v_exp_f32_e32 v4, v7
	v_exp_f32_e32 v70, v71
	v_add_f32_e32 v71, v83, v69
	v_add_f32_e32 v2, v70, v4
	v_add_f32_e32 v3, v71, v5
	s_nop 0
	v_add_f32_e32 v6, v2, v2
	v_add_f32_e32 v7, v2, v3
	v_exp_f32_e32 v5, v8
	v_exp_f32_e32 v71, v72
	v_exp_f32_e32 v6, v9
	v_exp_f32_e32 v72, v73
	v_cvt_pk_bf16_f32 v4, v69, v4
	v_add_f32_e32 v73, v71, v5
	v_cvt_pk_bf16_f32 v5, v5, v6
	v_add_f32_e32 v2, v72, v6
	v_add_f32_e32 v3, v73, v7
	v_exp_f32_e32 v7, v10
	v_add_f32_e32 v8, v2, v2
	v_add_f32_e32 v9, v2, v3
	v_exp_f32_e32 v73, v74
	v_exp_f32_e32 v8, v11
	v_exp_f32_e32 v74, v75
	v_add_f32_e32 v75, v73, v7
	v_cvt_pk_bf16_f32 v6, v7, v8
	v_add_f32_e32 v2, v74, v8
	v_add_f32_e32 v3, v75, v9
	v_exp_f32_e32 v9, v12
	v_add_f32_e32 v10, v2, v2
	v_add_f32_e32 v11, v2, v3
	v_exp_f32_e32 v75, v76
	v_exp_f32_e32 v10, v13
	v_exp_f32_e32 v76, v77
	v_add_f32_e32 v77, v75, v9
	v_cvt_pk_bf16_f32 v7, v9, v10
	v_add_f32_e32 v2, v76, v10
	v_add_f32_e32 v3, v77, v11
	v_exp_f32_e32 v11, v14
	v_add_f32_e32 v12, v2, v2
	v_add_f32_e32 v13, v2, v3
	v_exp_f32_e32 v77, v78
	v_exp_f32_e32 v12, v15
	v_exp_f32_e32 v14, v79
	v_cvt_pk_bf16_f32 v10, v85, v66
	v_add_f32_e32 v15, v77, v11
	v_cvt_pk_bf16_f32 v8, v11, v12
	v_add_f32_e32 v2, v14, v12
	v_add_f32_e32 v3, v15, v13
	v_exp_f32_e32 v13, v64
	v_add_f32_e32 v78, v2, v2
	v_add_f32_e32 v79, v2, v3
	v_exp_f32_e32 v15, v80
	v_exp_f32_e32 v78, v65
	v_exp_f32_e32 v80, v81
	v_cvt_pk_bf16_f32 v11, v86, v68
	v_add_f32_e32 v81, v15, v13
	v_cvt_pk_bf16_f32 v9, v13, v78
	v_add_f32_e32 v2, v80, v78
	v_add_f32_e32 v3, v81, v79
	v_cvt_pk_bf16_f32 v12, v83, v70
	v_add_f32_e32 v2, v2, v3
	v_add_f32_e32 v152, v152, v2
	v_cvt_pk_bf16_f32 v2, v84, v0
	v_add_u32_e32 v0, s34, v144
	ds_read_b64_tr_b16 v[68:69], v0 offset:0
	v_cvt_pk_bf16_f32 v13, v71, v72
	ds_read_b64_tr_b16 v[70:71], v0 offset:0x600
	v_cvt_pk_bf16_f32 v64, v73, v74
	ds_read_b64_tr_b16 v[72:73], v0 offset:0xc00
	v_cvt_pk_bf16_f32 v65, v75, v76
	ds_read_b64_tr_b16 v[74:75], v0 offset:0x1200
	v_cvt_pk_bf16_f32 v66, v77, v14
	ds_read_b64_tr_b16 v[76:77], v0 offset:0x1800
	ds_read_b64_tr_b16 v[78:79], v0 offset:0x1e00
	v_cvt_pk_bf16_f32 v3, v67, v82
	v_cvt_pk_bf16_f32 v67, v15, v80
	ds_read_b64_tr_b16 v[80:81], v0 offset:0x2400
	ds_read_b64_tr_b16 v[82:83], v0 offset:0x2a00
	s_waitcnt lgkmcnt(0)
	s_nop 0
	v_mfma_f32_32x32x16_bf16 v[32:47], v[68:71], v[2:5], v[32:47]
	ds_read_b64_tr_b16 v[68:69], v0 offset:64
	ds_read_b64_tr_b16 v[70:71], v0 offset:0x640
	v_mfma_f32_32x32x16_bf16 v[32:47], v[72:75], v[6:9], v[32:47]
	ds_read_b64_tr_b16 v[72:73], v0 offset:0xc40
	ds_read_b64_tr_b16 v[74:75], v0 offset:0x1240
	v_mfma_f32_32x32x16_bf16 v[32:47], v[76:79], v[10:13], v[32:47]
	ds_read_b64_tr_b16 v[76:77], v0 offset:0x1840
	ds_read_b64_tr_b16 v[78:79], v0 offset:0x1e40
	v_mfma_f32_32x32x16_bf16 v[32:47], v[80:83], v[64:67], v[32:47]
	ds_read_b64_tr_b16 v[80:81], v0 offset:0x2440
	ds_read_b64_tr_b16 v[82:83], v0 offset:0x2a40
	s_waitcnt lgkmcnt(0)
	v_mfma_f32_32x32x16_bf16 v[16:31], v[68:71], v[2:5], v[16:31]
	s_andn2_b64 s[28:29], s[28:29], exec
	s_and_b64 s[34:35], s[38:39], exec
	s_or_b64 s[28:29], s[28:29], s[34:35]
	v_mfma_f32_32x32x16_bf16 v[16:31], v[72:75], v[6:9], v[16:31]
	v_mfma_f32_32x32x16_bf16 v[16:31], v[76:79], v[10:13], v[16:31]
	v_mfma_f32_32x32x16_bf16 v[16:31], v[80:83], v[64:67], v[16:31]

; DI unsigned pack2(float a, float b) { f2_t v = {a, b}; bf2_t r = __builtin_convertvector(v, bf2_t); return __builtin_bit_cast(unsigned, r); }
; #define BLO(u) __uint_as_float((u) << 16)
; #define BHI(u) __uint_as_float((u) & 0xffff0000u)
; DI float frcp(float x) { return __builtin_amdgcn_rcpf(x); }
; template <int DQK, bool FIXEDM>
; DI void attn_dense_mfma(const bf16_t* Qb, int ldq, const bf16_t* Kb, int ldk, const bf16_t* Vb, int ldv, bf16_t* gate_io, char* smem, bool store, float mbound) {
;     ...
;   if (!store) return;
;   const float inv = frcp(half_swap_sum(l_run));
;   bf16_t* grow = gate_io + (size_t)(wid * 32 + r) * PW;
; #pragma unroll
;   for (int db = 0; db < 2; ++db)
; #pragma unroll
;     for (int g4 = 0; g4 < 4; ++g4) {
;       bf16_t* gp = grow + 32 * db + 8 * g4 + 4 * h;
;       uint2 u = *(const uint2*)gp;
;       float g[4] = {BLO(u.x), BHI(u.x), BLO(u.y), BHI(u.y)};
;       float y[4];
; #pragma unroll
;       for (int e = 0; e < 4; ++e) { float ov = db == 0 ? o0[4 * g4 + e] : o1[4 * g4 + e]; y[e] = ov * inv * g[e] * frcp(1.0f + __expf(-g[e])); }
;       uint2 w; w.x = pack2(y[0], y[1]); w.y = pack2(y[2], y[3]);
;       *(uint2*)gp = w;
;     }
; DI void dense_item(const Params& p, int l, int combo, int qblk, char* smem, bool store) {
;     ...
;   const size_t t0 = (size_t)b * SEQ + qblk * 128;
;   bf16_t* gate_io = P_PROJ + t0 * PW + C_GATE + br * 256 + h * 64;
.LBB0_163:
	s_lshl_b32 s0, s31, 1
	s_add_u32 s6, s58, s0
	s_addc_u32 s7, s59, 0
	s_lshl_b32 s0, s30, 7
	s_and_b32 s0, s0, 0xffffff00
	s_ashr_i32 s1, s0, 31
	s_lshl_b64 s[0:1], s[0:1], 1
	s_add_u32 s0, s6, s0
	s_addc_u32 s1, s7, s1
	v_readlane_b32 s6, v255, 22
	s_add_u32 s0, s0, s6
	s_addc_u32 s1, s1, 0
	v_lshl_add_u64 v[36:37], v[162:163], 1, s[0:1]
	v_mov_b32_e32 v167, v1
	v_lshl_add_u64 v[38:39], v[166:167], 1, v[36:37]
	s_mov_b64 s[0:1], 0x6ca5a00
	v_lshl_add_u64 v[36:37], v[38:39], 0, s[0:1]
	s_mov_b32 s0, 0x6ca5000
	v_add_co_u32_e32 v38, vcc, s0, v38
	v_mul_f32_e32 v18, v18, v34
	v_mul_f32_e32 v19, v19, v34
	s_nop 0
	v_addc_co_u32_e32 v39, vcc, 0, v39, vcc
	global_load_dwordx2 v[40:41], v[38:39], off offset:2560
	v_mul_f32_e32 v20, v20, v34
	v_mul_f32_e32 v21, v21, v34
	v_mul_f32_e32 v22, v22, v34
	v_mul_f32_e32 v23, v23, v34
	v_mul_f32_e32 v24, v24, v34
	v_mul_f32_e32 v25, v25, v34
	v_mul_f32_e32 v2, v34, v2
	v_mul_f32_e32 v3, v34, v3
	v_mul_f32_e32 v4, v34, v4
	v_mul_f32_e32 v5, v34, v5
	v_mul_f32_e32 v6, v34, v6
	v_mul_f32_e32 v7, v34, v7
	v_mul_f32_e32 v8, v34, v8
	v_mul_f32_e32 v9, v34, v9
	v_readlane_b32 s0, v255, 33
	s_add_i32 s29, s29, s0
	s_cmpk_gt_i32 s29, 0xff
	s_waitcnt vmcnt(0)
	v_lshlrev_b32_e32 v42, 16, v40
	v_mul_f32_e32 v0, 0xbfb8aa3b, v42
	v_exp_f32_e32 v0, v0
	v_and_b32_e32 v43, 0xffff0000, v40
	v_lshlrev_b32_e32 v40, 16, v41
	v_and_b32_e32 v41, 0xffff0000, v41
	v_add_f32_e32 v0, 1.0, v0
	v_rcp_f32_e32 v44, v0
	v_mul_f32_e32 v0, 0xbfb8aa3b, v43
	v_exp_f32_e32 v0, v0
	v_mul_f32_e32 v18, v18, v42
	v_mul_f32_e32 v19, v19, v43
	v_mul_f32_e32 v20, v20, v40
	v_mul_f32_e32 v21, v21, v41
	v_add_f32_e32 v0, 1.0, v0
	v_rcp_f32_e32 v45, v0
	v_mul_f32_e32 v0, 0xbfb8aa3b, v40
	v_exp_f32_e32 v0, v0
	v_mul_f32_e32 v18, v18, v44
	v_mul_f32_e32 v19, v19, v45
	s_nop 0
	v_cvt_pk_bf16_f32 v18, v18, v19
	v_add_f32_e32 v0, 1.0, v0
	v_rcp_f32_e32 v42, v0
	v_mul_f32_e32 v0, 0xbfb8aa3b, v41
	v_exp_f32_e32 v0, v0
	s_nop 0
	v_add_f32_e32 v0, 1.0, v0
	v_rcp_f32_e32 v43, v0
	s_nop 0
	v_mul_f32_e32 v20, v20, v42
	v_mul_f32_e32 v21, v21, v43
	s_nop 0
	v_cvt_pk_bf16_f32 v19, v20, v21
	global_store_dwordx2 v[38:39], v[18:19], off offset:2560
	global_load_dwordx2 v[18:19], v[36:37], off offset:16
	s_waitcnt vmcnt(0)
	v_lshlrev_b32_e32 v20, 16, v18
	v_mul_f32_e32 v0, 0xbfb8aa3b, v20
	v_exp_f32_e32 v0, v0
	v_and_b32_e32 v21, 0xffff0000, v18
	v_lshlrev_b32_e32 v18, 16, v19
	v_and_b32_e32 v19, 0xffff0000, v19
	v_add_f32_e32 v0, 1.0, v0
	v_rcp_f32_e32 v38, v0
	v_mul_f32_e32 v0, 0xbfb8aa3b, v21
	v_exp_f32_e32 v0, v0
	v_mul_f32_e32 v22, v22, v20
	v_mul_f32_e32 v23, v23, v21
	v_mul_f32_e32 v24, v24, v18
	v_mul_f32_e32 v25, v25, v19
	v_add_f32_e32 v0, 1.0, v0
	v_rcp_f32_e32 v39, v0
	v_mul_f32_e32 v0, 0xbfb8aa3b, v18
	v_exp_f32_e32 v0, v0
	v_mul_f32_e32 v20, v22, v38
	v_mul_f32_e32 v21, v23, v39
	s_nop 0
	v_cvt_pk_bf16_f32 v20, v20, v21
	v_add_f32_e32 v0, 1.0, v0
	v_rcp_f32_e32 v22, v0
	v_mul_f32_e32 v0, 0xbfb8aa3b, v19
	v_exp_f32_e32 v0, v0
	s_nop 0
	v_add_f32_e32 v0, 1.0, v0
	v_rcp_f32_e32 v23, v0
	s_nop 0
	v_mul_f32_e32 v18, v24, v22
	v_mul_f32_e32 v19, v25, v23
	s_nop 0
	v_cvt_pk_bf16_f32 v21, v18, v19
	global_load_dwordx2 v[18:19], v[36:37], off offset:32
	v_mul_f32_e32 v24, v26, v34
	v_mul_f32_e32 v25, v27, v34
	global_store_dwordx2 v[36:37], v[20:21], off offset:16
	s_waitcnt vmcnt(1)
	v_lshlrev_b32_e32 v20, 16, v18
	v_mul_f32_e32 v0, 0xbfb8aa3b, v20
	v_exp_f32_e32 v0, v0
	v_and_b32_e32 v21, 0xffff0000, v18
	v_lshlrev_b32_e32 v18, 16, v19
	v_and_b32_e32 v19, 0xffff0000, v19
	v_add_f32_e32 v0, 1.0, v0
	v_rcp_f32_e32 v22, v0
	v_mul_f32_e32 v0, 0xbfb8aa3b, v21
	v_exp_f32_e32 v0, v0
	v_mul_f32_e32 v24, v24, v20
	v_mul_f32_e32 v25, v25, v21
	v_add_f32_e32 v0, 1.0, v0
	v_rcp_f32_e32 v23, v0
	v_mul_f32_e32 v0, 0xbfb8aa3b, v18
	v_exp_f32_e32 v0, v0
	v_mul_f32_e32 v20, v24, v22
	v_mul_f32_e32 v21, v25, v23
	v_mul_f32_e32 v24, v28, v34
	v_mul_f32_e32 v25, v29, v34
	v_add_f32_e32 v0, 1.0, v0
	v_rcp_f32_e32 v22, v0
	v_mul_f32_e32 v0, 0xbfb8aa3b, v19
	v_exp_f32_e32 v0, v0
	v_mul_f32_e32 v24, v24, v18
	v_mul_f32_e32 v25, v25, v19
	v_cvt_pk_bf16_f32 v20, v20, v21
	v_add_f32_e32 v0, 1.0, v0
	v_rcp_f32_e32 v23, v0
	s_nop 0
	v_mul_f32_e32 v18, v24, v22
	v_mul_f32_e32 v19, v25, v23
	s_nop 0
	v_cvt_pk_bf16_f32 v21, v18, v19
	global_load_dwordx2 v[18:19], v[36:37], off offset:48
	v_mul_f32_e32 v24, v30, v34
	v_mul_f32_e32 v25, v31, v34
	global_store_dwordx2 v[36:37], v[20:21], off offset:32
	s_waitcnt vmcnt(1)
; DI unsigned pack2(float a, float b) { f2_t v = {a, b}; bf2_t r = __builtin_convertvector(v, bf2_t); return __builtin_bit_cast(unsigned, r); }
; #define BLO(u) __uint_as_float((u) << 16)
; #define BHI(u) __uint_as_float((u) & 0xffff0000u)
; DI float frcp(float x) { return __builtin_amdgcn_rcpf(x); }
; template <int DQK, bool FIXEDM>
; DI void attn_dense_mfma(const bf16_t* Qb, int ldq, const bf16_t* Kb, int ldk, const bf16_t* Vb, int ldv, bf16_t* gate_io, char* smem, bool store, float mbound) {
;     ...
; #pragma unroll
;   for (int db = 0; db < 2; ++db)
; #pragma unroll
;     for (int g4 = 0; g4 < 4; ++g4) {
;       bf16_t* gp = grow + 32 * db + 8 * g4 + 4 * h;
;       uint2 u = *(const uint2*)gp;
;       float g[4] = {BLO(u.x), BHI(u.x), BLO(u.y), BHI(u.y)};
;       float y[4];
; #pragma unroll
;       for (int e = 0; e < 4; ++e) { float ov = db == 0 ? o0[4 * g4 + e] : o1[4 * g4 + e]; y[e] = ov * inv * g[e] * frcp(1.0f + __expf(-g[e])); }
;       uint2 w; w.x = pack2(y[0], y[1]); w.y = pack2(y[2], y[3]);
;       *(uint2*)gp = w;
;     }
; DI void run_phase(const Params& p, int ph, char* smem, bool never) {
;     ...
;       for (int w = lb; w < 256; w += nl) { const int k = w >> 6, ck = ((k & 1) << 1 | (k >> 1)) ^ 1; dense_item(p, l, xcd + 8 * ck, w & 63, smem, true); }
	v_lshlrev_b32_e32 v20, 16, v18
	v_mul_f32_e32 v0, 0xbfb8aa3b, v20
	v_exp_f32_e32 v0, v0
	v_and_b32_e32 v21, 0xffff0000, v18
	v_lshlrev_b32_e32 v18, 16, v19
	v_and_b32_e32 v19, 0xffff0000, v19
	v_add_f32_e32 v0, 1.0, v0
	v_rcp_f32_e32 v22, v0
	v_mul_f32_e32 v0, 0xbfb8aa3b, v21
	v_exp_f32_e32 v0, v0
	v_mul_f32_e32 v24, v24, v20
	v_mul_f32_e32 v25, v25, v21
	v_add_f32_e32 v0, 1.0, v0
	v_rcp_f32_e32 v23, v0
	v_mul_f32_e32 v0, 0xbfb8aa3b, v18
	v_exp_f32_e32 v0, v0
	v_mul_f32_e32 v20, v24, v22
	v_mul_f32_e32 v21, v25, v23
	v_mul_f32_e32 v24, v32, v34
	v_mul_f32_e32 v25, v33, v34
	v_add_f32_e32 v0, 1.0, v0
	v_rcp_f32_e32 v22, v0
	v_mul_f32_e32 v0, 0xbfb8aa3b, v19
	v_exp_f32_e32 v0, v0
	v_mul_f32_e32 v24, v24, v18
	v_mul_f32_e32 v25, v25, v19
	v_cvt_pk_bf16_f32 v20, v20, v21
	v_add_f32_e32 v0, 1.0, v0
	v_rcp_f32_e32 v23, v0
	s_nop 0
	v_mul_f32_e32 v18, v24, v22
	v_mul_f32_e32 v19, v25, v23
	s_nop 0
	v_cvt_pk_bf16_f32 v21, v18, v19
	global_load_dwordx2 v[18:19], v[36:37], off offset:64
	s_nop 0
	global_store_dwordx2 v[36:37], v[20:21], off offset:48
	s_waitcnt vmcnt(1)
	v_lshlrev_b32_e32 v20, 16, v18
	v_mul_f32_e32 v0, 0xbfb8aa3b, v20
	v_exp_f32_e32 v0, v0
	v_and_b32_e32 v21, 0xffff0000, v18
	v_lshlrev_b32_e32 v18, 16, v19
	v_and_b32_e32 v19, 0xffff0000, v19
	v_add_f32_e32 v0, 1.0, v0
	v_rcp_f32_e32 v22, v0
	v_mul_f32_e32 v0, 0xbfb8aa3b, v21
	v_exp_f32_e32 v0, v0
	v_mul_f32_e32 v2, v2, v20
	v_mul_f32_e32 v3, v3, v21
	v_mul_f32_e32 v4, v4, v18
	v_mul_f32_e32 v5, v5, v19
	v_add_f32_e32 v0, 1.0, v0
	v_rcp_f32_e32 v23, v0
	v_mul_f32_e32 v0, 0xbfb8aa3b, v18
	v_exp_f32_e32 v0, v0
	v_mul_f32_e32 v2, v2, v22
	v_mul_f32_e32 v3, v3, v23
	s_nop 0
	v_cvt_pk_bf16_f32 v2, v2, v3
	v_add_f32_e32 v0, 1.0, v0
	v_rcp_f32_e32 v20, v0
	v_mul_f32_e32 v0, 0xbfb8aa3b, v19
	v_exp_f32_e32 v0, v0
	s_nop 0
	v_add_f32_e32 v0, 1.0, v0
	v_rcp_f32_e32 v21, v0
	s_nop 0
	v_mul_f32_e32 v4, v4, v20
	v_mul_f32_e32 v5, v5, v21
	s_nop 0
	v_cvt_pk_bf16_f32 v3, v4, v5
	global_store_dwordx2 v[36:37], v[2:3], off offset:64
	global_load_dwordx2 v[2:3], v[36:37], off offset:80
	s_waitcnt vmcnt(0)
	v_lshlrev_b32_e32 v4, 16, v2
	v_mul_f32_e32 v0, 0xbfb8aa3b, v4
	v_exp_f32_e32 v0, v0
	v_and_b32_e32 v5, 0xffff0000, v2
	v_lshlrev_b32_e32 v2, 16, v3
	v_and_b32_e32 v3, 0xffff0000, v3
	v_add_f32_e32 v0, 1.0, v0
	v_rcp_f32_e32 v18, v0
	v_mul_f32_e32 v0, 0xbfb8aa3b, v5
	v_exp_f32_e32 v0, v0
	v_mul_f32_e32 v6, v6, v4
	v_mul_f32_e32 v7, v7, v5
	v_mul_f32_e32 v8, v8, v2
	v_mul_f32_e32 v9, v9, v3
	v_add_f32_e32 v0, 1.0, v0
	v_rcp_f32_e32 v19, v0
	v_mul_f32_e32 v0, 0xbfb8aa3b, v2
	v_exp_f32_e32 v0, v0
	v_mul_f32_e32 v4, v6, v18
	v_mul_f32_e32 v5, v7, v19
	s_nop 0
	v_cvt_pk_bf16_f32 v4, v4, v5
	v_add_f32_e32 v0, 1.0, v0
	v_rcp_f32_e32 v6, v0
	v_mul_f32_e32 v0, 0xbfb8aa3b, v3
	v_exp_f32_e32 v0, v0
	s_nop 0
	v_add_f32_e32 v0, 1.0, v0
	v_rcp_f32_e32 v7, v0
	s_nop 0
	v_mul_f32_e32 v2, v8, v6
	v_mul_f32_e32 v3, v9, v7
	s_nop 0
	v_cvt_pk_bf16_f32 v5, v2, v3
	global_load_dwordx2 v[2:3], v[36:37], off offset:96
	v_mul_f32_e32 v8, v34, v10
	v_mul_f32_e32 v9, v34, v11
	global_store_dwordx2 v[36:37], v[4:5], off offset:80
	v_mul_f32_e32 v10, v34, v14
	v_mul_f32_e32 v11, v34, v15
	s_waitcnt vmcnt(1)
	v_lshlrev_b32_e32 v4, 16, v2
	v_mul_f32_e32 v0, 0xbfb8aa3b, v4
	v_exp_f32_e32 v0, v0
	v_and_b32_e32 v5, 0xffff0000, v2
	v_lshlrev_b32_e32 v2, 16, v3
	v_and_b32_e32 v3, 0xffff0000, v3
	v_add_f32_e32 v0, 1.0, v0
	v_rcp_f32_e32 v6, v0
	v_mul_f32_e32 v0, 0xbfb8aa3b, v5
	v_exp_f32_e32 v0, v0
	v_mul_f32_e32 v8, v8, v4
	v_mul_f32_e32 v9, v9, v5
	v_add_f32_e32 v0, 1.0, v0
	v_rcp_f32_e32 v7, v0
	v_mul_f32_e32 v0, 0xbfb8aa3b, v2
	v_exp_f32_e32 v0, v0
	v_mul_f32_e32 v4, v8, v6
	v_mul_f32_e32 v5, v9, v7
	v_mul_f32_e32 v8, v34, v12
	v_mul_f32_e32 v9, v34, v13
	v_add_f32_e32 v0, 1.0, v0
	v_rcp_f32_e32 v6, v0
	v_mul_f32_e32 v0, 0xbfb8aa3b, v3
	v_exp_f32_e32 v0, v0
	v_mul_f32_e32 v8, v8, v2
	v_mul_f32_e32 v9, v9, v3
	v_cvt_pk_bf16_f32 v4, v4, v5
	v_add_f32_e32 v0, 1.0, v0
	v_rcp_f32_e32 v7, v0
	s_nop 0
	v_mul_f32_e32 v2, v8, v6
	v_mul_f32_e32 v3, v9, v7
	s_nop 0
	v_cvt_pk_bf16_f32 v5, v2, v3
	global_store_dwordx2 v[36:37], v[4:5], off offset:96
	global_load_dwordx2 v[4:5], v[36:37], off offset:112
	s_waitcnt vmcnt(0)
	v_and_b32_e32 v7, 0xffff0000, v4
	v_mul_f32_e32 v0, 0xbfb8aa3b, v7
	v_exp_f32_e32 v0, v0
	v_lshlrev_b32_e32 v6, 16, v4
	v_lshlrev_b32_e32 v2, 16, v5
	v_and_b32_e32 v3, 0xffff0000, v5
	v_add_f32_e32 v0, 1.0, v0
	v_rcp_f32_e32 v9, v0
	v_mul_f32_e32 v0, 0xbfb8aa3b, v6
	v_exp_f32_e32 v0, v0
	v_mul_f32_e32 v10, v10, v6
	v_mul_f32_e32 v11, v11, v7
	v_add_f32_e32 v0, 1.0, v0
	v_rcp_f32_e32 v8, v0
	v_mul_f32_e32 v0, 0xbfb8aa3b, v2
	v_exp_f32_e32 v0, v0
	v_mul_f32_e32 v6, v10, v8
	v_mul_f32_e32 v7, v11, v9
	v_mul_f32_e32 v8, v34, v16
	v_mul_f32_e32 v9, v34, v17
	v_add_f32_e32 v0, 1.0, v0
	v_rcp_f32_e32 v4, v0
	v_mul_f32_e32 v0, 0xbfb8aa3b, v3
	v_exp_f32_e32 v0, v0
	v_mul_f32_e32 v8, v8, v2
	v_mul_f32_e32 v9, v9, v3
	v_add_f32_e32 v0, 1.0, v0
	v_rcp_f32_e32 v5, v0
	s_nop 0
	v_mul_f32_e32 v2, v8, v4
	v_mul_f32_e32 v3, v9, v5
	v_cvt_pk_bf16_f32 v4, v6, v7
	v_cvt_pk_bf16_f32 v5, v2, v3
	global_store_dwordx2 v[36:37], v[4:5], off offset:112
	s_cbranch_scc1 .LBB0_203

; #define MFMA32(a, b, c) __builtin_amdgcn_mfma_f32_32x32x16_bf16((a), (b), (c), 0, 0, 0)
; template <int DB, int VLD> DI void pv_block(f32x16& o, unsigned vb, bf16x8 pb0, bf16x8 pb1, bf16x8 pb2, bf16x8 pb3) {
;   constexpr int RB = VLD * 2;
;   bf16x4 l0 = tr_read<0 * RB + 64 * DB>(vb), h0 = tr_read<8 * RB + 64 * DB>(vb);
;   bf16x4 l1 = tr_read<16 * RB + 64 * DB>(vb), h1 = tr_read<24 * RB + 64 * DB>(vb);
;   bf16x4 l2 = tr_read<32 * RB + 64 * DB>(vb), h2 = tr_read<40 * RB + 64 * DB>(vb);
;   bf16x4 l3 = tr_read<48 * RB + 64 * DB>(vb), h3 = tr_read<56 * RB + 64 * DB>(vb);
;   asm volatile("s_waitcnt lgkmcnt(0)" ::: "memory"); __builtin_amdgcn_sched_barrier(0);
;   o = MFMA32(__builtin_shufflevector(l0, h0, 0, 1, 2, 3, 4, 5, 6, 7), pb0, o);
;   o = MFMA32(__builtin_shufflevector(l1, h1, 0, 1, 2, 3, 4, 5, 6, 7), pb1, o);
;   o = MFMA32(__builtin_shufflevector(l2, h2, 0, 1, 2, 3, 4, 5, 6, 7), pb2, o);
;   o = MFMA32(__builtin_shufflevector(l3, h3, 0, 1, 2, 3, 4, 5, 6, 7), pb3, o);
; }
.Lattnb_loop:
	ds_read_b128 v[34:37], v191 offset:9216
	ds_read_b128 v[38:41], v191 offset:9248
	ds_read_b128 v[42:45], v191 offset:9280
	ds_read_b128 v[46:49], v191 offset:9312
	ds_read_b128 v[130:133], v191 offset:13824
	ds_read_b128 v[134:137], v191 offset:13856
	ds_read_b128 v[138:141], v191 offset:13888
	ds_read_b128 v[142:145], v191 offset:13920
	global_load_dwordx4 v[168:171], v164, s[26:27] offset:512
	global_load_dwordx4 v[172:175], v164, s[26:27] offset:528
	s_add_u32 s26, s26, 0x98000
	s_addc_u32 s27, s27, 0
	global_load_dwordx4 v[176:179], v165, s[36:37] offset:768
	global_load_dwordx4 v[180:183], v165, s[4:5] offset:768
	s_add_u32 s36, s36, 0x98000
	s_addc_u32 s37, s37, 0
	s_add_u32 s4, s4, 0x98000
	s_addc_u32 s5, s5, 0
	v_exp_f32_e32 v50, v50
	v_exp_f32_e32 v51, v51
	v_exp_f32_e32 v52, v52
	v_exp_f32_e32 v53, v53
	v_exp_f32_e32 v54, v54
	v_exp_f32_e32 v55, v55
	v_exp_f32_e32 v56, v56
	v_exp_f32_e32 v57, v57
	ds_read_b64_tr_b16 v[206:207], v192 offset:0
	ds_read_b64_tr_b16 v[208:209], v192 offset:1536
	ds_read_b64_tr_b16 v[210:211], v192 offset:3072
	ds_read_b64_tr_b16 v[212:213], v192 offset:4608
	v_exp_f32_e32 v58, v58
	v_exp_f32_e32 v59, v59
	v_exp_f32_e32 v60, v60
	v_exp_f32_e32 v61, v61
	v_exp_f32_e32 v62, v62
	v_exp_f32_e32 v63, v63
	v_exp_f32_e32 v64, v64
	v_exp_f32_e32 v65, v65
	ds_read_b64_tr_b16 v[214:215], v192 offset:6144
	ds_read_b64_tr_b16 v[216:217], v192 offset:7680
	ds_read_b64_tr_b16 v[218:219], v192 offset:9216
	s_waitcnt lgkmcnt(14)
	v_mfma_f32_32x32x16_bf16 v[82:97], v[34:37], v[114:117], 0
	v_exp_f32_e32 v66, v66
	v_exp_f32_e32 v67, v67
	v_exp_f32_e32 v68, v68
	s_waitcnt lgkmcnt(13)
	v_mfma_f32_32x32x16_bf16 v[82:97], v[38:41], v[118:121], v[82:97]
	v_exp_f32_e32 v69, v69
	v_exp_f32_e32 v70, v70
	v_exp_f32_e32 v71, v71
	s_waitcnt lgkmcnt(12)
	v_mfma_f32_32x32x16_bf16 v[82:97], v[42:45], v[122:125], v[82:97]
	v_exp_f32_e32 v72, v72
	v_exp_f32_e32 v73, v73
	v_exp_f32_e32 v74, v74
	s_waitcnt lgkmcnt(11)
	v_mfma_f32_32x32x16_bf16 v[82:97], v[46:49], v[126:129], v[82:97]
	v_exp_f32_e32 v75, v75
	v_exp_f32_e32 v76, v76
	v_exp_f32_e32 v77, v77
	s_waitcnt lgkmcnt(10)
	v_mfma_f32_32x32x16_bf16 v[98:113], v[130:133], v[114:117], 0
	v_exp_f32_e32 v78, v78
	v_exp_f32_e32 v79, v79
	v_exp_f32_e32 v80, v80
	s_waitcnt lgkmcnt(9)
	v_mfma_f32_32x32x16_bf16 v[98:113], v[134:137], v[118:121], v[98:113]
	v_exp_f32_e32 v81, v81
	ds_read_b64_tr_b16 v[220:221], v192 offset:10752
	v_cvt_pk_bf16_f32 v146, v50, v51
	v_cvt_pk_bf16_f32 v147, v52, v53
	v_cvt_pk_bf16_f32 v148, v54, v55
	v_cvt_pk_bf16_f32 v149, v56, v57
	s_waitcnt lgkmcnt(9)
	v_mfma_f32_32x32x16_bf16 v[98:113], v[138:141], v[122:125], v[98:113]
	v_cvt_pk_bf16_f32 v150, v58, v59
	v_cvt_pk_bf16_f32 v151, v60, v61
	v_cvt_pk_bf16_f32 v152, v62, v63
	v_cvt_pk_bf16_f32 v153, v64, v65
	v_add_f32_e32 v193, v193, v50
	v_add_f32_e32 v194, v194, v51
	s_waitcnt lgkmcnt(8)
	v_mfma_f32_32x32x16_bf16 v[98:113], v[142:145], v[126:129], v[98:113]
	v_cvt_pk_bf16_f32 v154, v66, v67
	v_cvt_pk_bf16_f32 v155, v68, v69
	s_waitcnt lgkmcnt(6)
	v_mfma_f32_32x32x16_bf16 v[18:33], v[206:209], v[146:149], v[18:33]
	ds_read_b64_tr_b16 v[206:207], v192 offset:64
	ds_read_b64_tr_b16 v[208:209], v192 offset:1600
	v_cvt_pk_bf16_f32 v156, v70, v71
	v_cvt_pk_bf16_f32 v157, v72, v73
	v_add_f32_e32 v195, v195, v52
	v_add_f32_e32 v196, v196, v53
	s_waitcnt lgkmcnt(6)
	v_mfma_f32_32x32x16_bf16 v[18:33], v[210:213], v[150:153], v[18:33]
	ds_read_b64_tr_b16 v[210:211], v192 offset:3136
	ds_read_b64_tr_b16 v[212:213], v192 offset:4672
	v_cvt_pk_bf16_f32 v158, v74, v75
	v_cvt_pk_bf16_f32 v159, v76, v77
	v_add_f32_e32 v193, v193, v54
	v_add_f32_e32 v194, v194, v55
	s_waitcnt lgkmcnt(6)
	v_mfma_f32_32x32x16_bf16 v[18:33], v[214:217], v[154:157], v[18:33]
	ds_read_b64_tr_b16 v[214:215], v192 offset:6208
	ds_read_b64_tr_b16 v[216:217], v192 offset:7744
	v_cvt_pk_bf16_f32 v160, v78, v79
	v_cvt_pk_bf16_f32 v161, v80, v81
	v_add_f32_e32 v195, v195, v56
	v_add_f32_e32 v196, v196, v57
	s_waitcnt lgkmcnt(6)
	v_mfma_f32_32x32x16_bf16 v[18:33], v[218:221], v[158:161], v[18:33]
	ds_read_b64_tr_b16 v[218:219], v192 offset:9280
	ds_read_b64_tr_b16 v[220:221], v192 offset:10816
	v_add_f32_e32 v193, v193, v58
	v_add_f32_e32 v194, v194, v59
	v_add_f32_e32 v195, v195, v60
	v_add_f32_e32 v196, v196, v61
	s_waitcnt lgkmcnt(6)
	v_mfma_f32_32x32x16_bf16 v[2:17], v[206:209], v[146:149], v[2:17]
	v_add_f32_e32 v193, v193, v62
	v_add_f32_e32 v194, v194, v63
	v_add_f32_e32 v195, v195, v64
	v_add_f32_e32 v196, v196, v65
	v_add_f32_e32 v193, v193, v66
	v_add_f32_e32 v194, v194, v67
	s_waitcnt lgkmcnt(4)
	v_mfma_f32_32x32x16_bf16 v[2:17], v[210:213], v[150:153], v[2:17]
	v_add_f32_e32 v195, v195, v68
	v_add_f32_e32 v196, v196, v69
	v_add_f32_e32 v193, v193, v70
	v_add_f32_e32 v194, v194, v71
	v_add_f32_e32 v195, v195, v72
	v_add_f32_e32 v196, v196, v73
	s_waitcnt lgkmcnt(2)
	v_mfma_f32_32x32x16_bf16 v[2:17], v[214:217], v[154:157], v[2:17]
	v_add_f32_e32 v193, v193, v74
	v_add_f32_e32 v194, v194, v75
	v_add_f32_e32 v195, v195, v76
	v_add_f32_e32 v196, v196, v77
	v_add_f32_e32 v193, v193, v78
	v_add_f32_e32 v194, v194, v79
	s_waitcnt lgkmcnt(0)
	v_mfma_f32_32x32x16_bf16 v[2:17], v[218:221], v[158:161], v[2:17]
	v_add_f32_e32 v195, v195, v80
	v_add_f32_e32 v196, v196, v81
	s_waitcnt vmcnt(3)
	ds_write_b128 v167, v[168:171] offset:0
	s_waitcnt vmcnt(2)
	ds_write_b128 v167, v[172:175] offset:16
	s_waitcnt vmcnt(1)
	ds_write_b128 v190, v[176:179] offset:12288
	s_waitcnt vmcnt(0)
	ds_write_b128 v190, v[180:183] offset:18432
	s_waitcnt lgkmcnt(0)
	s_barrier
; #define MFMA32(a, b, c) __builtin_amdgcn_mfma_f32_32x32x16_bf16((a), (b), (c), 0, 0, 0)
; template <int DB, int VLD> DI void pv_block(f32x16& o, unsigned vb, bf16x8 pb0, bf16x8 pb1, bf16x8 pb2, bf16x8 pb3) {
;   constexpr int RB = VLD * 2;
;   bf16x4 l0 = tr_read<0 * RB + 64 * DB>(vb), h0 = tr_read<8 * RB + 64 * DB>(vb);
;   bf16x4 l1 = tr_read<16 * RB + 64 * DB>(vb), h1 = tr_read<24 * RB + 64 * DB>(vb);
;   bf16x4 l2 = tr_read<32 * RB + 64 * DB>(vb), h2 = tr_read<40 * RB + 64 * DB>(vb);
;   bf16x4 l3 = tr_read<48 * RB + 64 * DB>(vb), h3 = tr_read<56 * RB + 64 * DB>(vb);
;   asm volatile("s_waitcnt lgkmcnt(0)" ::: "memory"); __builtin_amdgcn_sched_barrier(0);
;   o = MFMA32(__builtin_shufflevector(l0, h0, 0, 1, 2, 3, 4, 5, 6, 7), pb0, o);
;   o = MFMA32(__builtin_shufflevector(l1, h1, 0, 1, 2, 3, 4, 5, 6, 7), pb1, o);
;   o = MFMA32(__builtin_shufflevector(l2, h2, 0, 1, 2, 3, 4, 5, 6, 7), pb2, o);
;   o = MFMA32(__builtin_shufflevector(l3, h3, 0, 1, 2, 3, 4, 5, 6, 7), pb3, o);
; }
	ds_read_b128 v[34:37], v191 offset:0
	ds_read_b128 v[38:41], v191 offset:32
	ds_read_b128 v[42:45], v191 offset:64
	ds_read_b128 v[46:49], v191 offset:96
	ds_read_b128 v[130:133], v191 offset:4608
	ds_read_b128 v[134:137], v191 offset:4640
	ds_read_b128 v[138:141], v191 offset:4672
	ds_read_b128 v[142:145], v191 offset:4704
	global_load_dwordx4 v[168:171], v164, s[26:27] offset:512
	global_load_dwordx4 v[172:175], v164, s[26:27] offset:528
	s_add_u32 s26, s26, 0x98000
	s_addc_u32 s27, s27, 0
	global_load_dwordx4 v[176:179], v165, s[36:37] offset:768
	global_load_dwordx4 v[180:183], v165, s[4:5] offset:768
	s_add_u32 s36, s36, 0x98000
	s_addc_u32 s37, s37, 0
	s_add_u32 s4, s4, 0x98000
	s_addc_u32 s5, s5, 0
	v_exp_f32_e32 v82, v82
	v_exp_f32_e32 v83, v83
	v_exp_f32_e32 v84, v84
	v_exp_f32_e32 v85, v85
	v_exp_f32_e32 v86, v86
	v_exp_f32_e32 v87, v87
	v_exp_f32_e32 v88, v88
	v_exp_f32_e32 v89, v89
	ds_read_b64_tr_b16 v[206:207], v192 offset:12288
	ds_read_b64_tr_b16 v[208:209], v192 offset:13824
	ds_read_b64_tr_b16 v[210:211], v192 offset:15360
	ds_read_b64_tr_b16 v[212:213], v192 offset:16896
	v_exp_f32_e32 v90, v90
	v_exp_f32_e32 v91, v91
	v_exp_f32_e32 v92, v92
	v_exp_f32_e32 v93, v93
	v_exp_f32_e32 v94, v94
	v_exp_f32_e32 v95, v95
	v_exp_f32_e32 v96, v96
	v_exp_f32_e32 v97, v97
	ds_read_b64_tr_b16 v[214:215], v192 offset:18432
	ds_read_b64_tr_b16 v[216:217], v192 offset:19968
	ds_read_b64_tr_b16 v[218:219], v192 offset:21504
	s_waitcnt lgkmcnt(14)
	v_mfma_f32_32x32x16_bf16 v[50:65], v[34:37], v[114:117], 0
	v_exp_f32_e32 v98, v98
	v_exp_f32_e32 v99, v99
	v_exp_f32_e32 v100, v100
	s_waitcnt lgkmcnt(13)
	v_mfma_f32_32x32x16_bf16 v[50:65], v[38:41], v[118:121], v[50:65]
	v_exp_f32_e32 v101, v101
	v_exp_f32_e32 v102, v102
	v_exp_f32_e32 v103, v103
	s_waitcnt lgkmcnt(12)
	v_mfma_f32_32x32x16_bf16 v[50:65], v[42:45], v[122:125], v[50:65]
	v_exp_f32_e32 v104, v104
	v_exp_f32_e32 v105, v105
	v_exp_f32_e32 v106, v106
	s_waitcnt lgkmcnt(11)
	v_mfma_f32_32x32x16_bf16 v[50:65], v[46:49], v[126:129], v[50:65]
	v_exp_f32_e32 v107, v107
	v_exp_f32_e32 v108, v108
	v_exp_f32_e32 v109, v109
	s_waitcnt lgkmcnt(10)
	v_mfma_f32_32x32x16_bf16 v[66:81], v[130:133], v[114:117], 0
	v_exp_f32_e32 v110, v110
	v_exp_f32_e32 v111, v111
	v_exp_f32_e32 v112, v112
	s_waitcnt lgkmcnt(9)
	v_mfma_f32_32x32x16_bf16 v[66:81], v[134:137], v[118:121], v[66:81]
	v_exp_f32_e32 v113, v113
	ds_read_b64_tr_b16 v[220:221], v192 offset:23040
	v_cvt_pk_bf16_f32 v146, v82, v83
	v_cvt_pk_bf16_f32 v147, v84, v85
	v_cvt_pk_bf16_f32 v148, v86, v87
	v_cvt_pk_bf16_f32 v149, v88, v89
	s_waitcnt lgkmcnt(9)
	v_mfma_f32_32x32x16_bf16 v[66:81], v[138:141], v[122:125], v[66:81]
	v_cvt_pk_bf16_f32 v150, v90, v91
	v_cvt_pk_bf16_f32 v151, v92, v93
	v_cvt_pk_bf16_f32 v152, v94, v95
	v_cvt_pk_bf16_f32 v153, v96, v97
	v_add_f32_e32 v193, v193, v82
	v_add_f32_e32 v194, v194, v83
	s_waitcnt lgkmcnt(8)
	v_mfma_f32_32x32x16_bf16 v[66:81], v[142:145], v[126:129], v[66:81]
	v_cvt_pk_bf16_f32 v154, v98, v99
	v_cvt_pk_bf16_f32 v155, v100, v101
	s_waitcnt lgkmcnt(6)
	v_mfma_f32_32x32x16_bf16 v[18:33], v[206:209], v[146:149], v[18:33]
	ds_read_b64_tr_b16 v[206:207], v192 offset:12352
	ds_read_b64_tr_b16 v[208:209], v192 offset:13888
	v_cvt_pk_bf16_f32 v156, v102, v103
	v_cvt_pk_bf16_f32 v157, v104, v105
	v_add_f32_e32 v195, v195, v84
	v_add_f32_e32 v196, v196, v85
	s_waitcnt lgkmcnt(6)
	v_mfma_f32_32x32x16_bf16 v[18:33], v[210:213], v[150:153], v[18:33]
	ds_read_b64_tr_b16 v[210:211], v192 offset:15424
	ds_read_b64_tr_b16 v[212:213], v192 offset:16960
	v_cvt_pk_bf16_f32 v158, v106, v107
	v_cvt_pk_bf16_f32 v159, v108, v109
	v_add_f32_e32 v193, v193, v86
	v_add_f32_e32 v194, v194, v87
	s_waitcnt lgkmcnt(6)
	v_mfma_f32_32x32x16_bf16 v[18:33], v[214:217], v[154:157], v[18:33]
	ds_read_b64_tr_b16 v[214:215], v192 offset:18496
	ds_read_b64_tr_b16 v[216:217], v192 offset:20032
	v_cvt_pk_bf16_f32 v160, v110, v111
	v_cvt_pk_bf16_f32 v161, v112, v113
	v_add_f32_e32 v195, v195, v88
	v_add_f32_e32 v196, v196, v89
	s_waitcnt lgkmcnt(6)
	v_mfma_f32_32x32x16_bf16 v[18:33], v[218:221], v[158:161], v[18:33]
	ds_read_b64_tr_b16 v[218:219], v192 offset:21568
	ds_read_b64_tr_b16 v[220:221], v192 offset:23104
	v_add_f32_e32 v193, v193, v90
	v_add_f32_e32 v194, v194, v91
	v_add_f32_e32 v195, v195, v92
	v_add_f32_e32 v196, v196, v93
	s_waitcnt lgkmcnt(6)
	v_mfma_f32_32x32x16_bf16 v[2:17], v[206:209], v[146:149], v[2:17]
	v_add_f32_e32 v193, v193, v94
	v_add_f32_e32 v194, v194, v95
	v_add_f32_e32 v195, v195, v96
	v_add_f32_e32 v196, v196, v97
	v_add_f32_e32 v193, v193, v98
	v_add_f32_e32 v194, v194, v99
	s_waitcnt lgkmcnt(4)
	v_mfma_f32_32x32x16_bf16 v[2:17], v[210:213], v[150:153], v[2:17]
	v_add_f32_e32 v195, v195, v100
	v_add_f32_e32 v196, v196, v101
	v_add_f32_e32 v193, v193, v102
	v_add_f32_e32 v194, v194, v103
	v_add_f32_e32 v195, v195, v104
	v_add_f32_e32 v196, v196, v105
	s_waitcnt lgkmcnt(2)
	v_mfma_f32_32x32x16_bf16 v[2:17], v[214:217], v[154:157], v[2:17]
	v_add_f32_e32 v193, v193, v106
	v_add_f32_e32 v194, v194, v107
	v_add_f32_e32 v195, v195, v108
	v_add_f32_e32 v196, v196, v109
	v_add_f32_e32 v193, v193, v110
	v_add_f32_e32 v194, v194, v111
	s_waitcnt lgkmcnt(0)
	v_mfma_f32_32x32x16_bf16 v[2:17], v[218:221], v[158:161], v[2:17]
	v_add_f32_e32 v195, v195, v112
	v_add_f32_e32 v196, v196, v113
	s_waitcnt vmcnt(3)
	ds_write_b128 v167, v[168:171] offset:9216
	s_waitcnt vmcnt(2)
	ds_write_b128 v167, v[172:175] offset:9232
	s_waitcnt vmcnt(1)
	ds_write_b128 v190, v[176:179] offset:0
	s_waitcnt vmcnt(0)
	ds_write_b128 v190, v[180:183] offset:6144
	s_waitcnt lgkmcnt(0)
	s_barrier
	s_add_i32 s7, s7, 2
	s_cmpk_lt_u32 s7, 0x7e
	s_cbranch_scc1 .Lattnb_loop
; #define MFMA32(a, b, c) __builtin_amdgcn_mfma_f32_32x32x16_bf16((a), (b), (c), 0, 0, 0)
; template <int DB, int VLD> DI void pv_block(f32x16& o, unsigned vb, bf16x8 pb0, bf16x8 pb1, bf16x8 pb2, bf16x8 pb3) {
;   constexpr int RB = VLD * 2;
;   bf16x4 l0 = tr_read<0 * RB + 64 * DB>(vb), h0 = tr_read<8 * RB + 64 * DB>(vb);
;   bf16x4 l1 = tr_read<16 * RB + 64 * DB>(vb), h1 = tr_read<24 * RB + 64 * DB>(vb);
;   bf16x4 l2 = tr_read<32 * RB + 64 * DB>(vb), h2 = tr_read<40 * RB + 64 * DB>(vb);
;   bf16x4 l3 = tr_read<48 * RB + 64 * DB>(vb), h3 = tr_read<56 * RB + 64 * DB>(vb);
;   asm volatile("s_waitcnt lgkmcnt(0)" ::: "memory"); __builtin_amdgcn_sched_barrier(0);
;   o = MFMA32(__builtin_shufflevector(l0, h0, 0, 1, 2, 3, 4, 5, 6, 7), pb0, o);
;   o = MFMA32(__builtin_shufflevector(l1, h1, 0, 1, 2, 3, 4, 5, 6, 7), pb1, o);
;   o = MFMA32(__builtin_shufflevector(l2, h2, 0, 1, 2, 3, 4, 5, 6, 7), pb2, o);
;   o = MFMA32(__builtin_shufflevector(l3, h3, 0, 1, 2, 3, 4, 5, 6, 7), pb3, o);
; }
	ds_read_b128 v[34:37], v191 offset:9216
	ds_read_b128 v[38:41], v191 offset:9248
	ds_read_b128 v[42:45], v191 offset:9280
	ds_read_b128 v[46:49], v191 offset:9312
	ds_read_b128 v[130:133], v191 offset:13824
	ds_read_b128 v[134:137], v191 offset:13856
	ds_read_b128 v[138:141], v191 offset:13888
	ds_read_b128 v[142:145], v191 offset:13920
	global_load_dwordx4 v[176:179], v165, s[36:37] offset:768
	global_load_dwordx4 v[180:183], v165, s[4:5] offset:768
	s_add_u32 s36, s36, 0x98000
	s_addc_u32 s37, s37, 0
	s_add_u32 s4, s4, 0x98000
	s_addc_u32 s5, s5, 0
	v_exp_f32_e32 v50, v50
	v_exp_f32_e32 v51, v51
	v_exp_f32_e32 v52, v52
	v_exp_f32_e32 v53, v53
	v_exp_f32_e32 v54, v54
	v_exp_f32_e32 v55, v55
	v_exp_f32_e32 v56, v56
	v_exp_f32_e32 v57, v57
	ds_read_b64_tr_b16 v[206:207], v192 offset:0
	ds_read_b64_tr_b16 v[208:209], v192 offset:1536
	ds_read_b64_tr_b16 v[210:211], v192 offset:3072
	ds_read_b64_tr_b16 v[212:213], v192 offset:4608
	v_exp_f32_e32 v58, v58
	v_exp_f32_e32 v59, v59
	v_exp_f32_e32 v60, v60
	v_exp_f32_e32 v61, v61
	v_exp_f32_e32 v62, v62
	v_exp_f32_e32 v63, v63
	v_exp_f32_e32 v64, v64
	v_exp_f32_e32 v65, v65
	ds_read_b64_tr_b16 v[214:215], v192 offset:6144
	ds_read_b64_tr_b16 v[216:217], v192 offset:7680
	ds_read_b64_tr_b16 v[218:219], v192 offset:9216
	s_waitcnt lgkmcnt(14)
	v_mfma_f32_32x32x16_bf16 v[82:97], v[34:37], v[114:117], 0
	v_exp_f32_e32 v66, v66
	v_exp_f32_e32 v67, v67
	v_exp_f32_e32 v68, v68
	s_waitcnt lgkmcnt(13)
	v_mfma_f32_32x32x16_bf16 v[82:97], v[38:41], v[118:121], v[82:97]
	v_exp_f32_e32 v69, v69
	v_exp_f32_e32 v70, v70
	v_exp_f32_e32 v71, v71
	s_waitcnt lgkmcnt(12)
	v_mfma_f32_32x32x16_bf16 v[82:97], v[42:45], v[122:125], v[82:97]
	v_exp_f32_e32 v72, v72
	v_exp_f32_e32 v73, v73
	v_exp_f32_e32 v74, v74
	s_waitcnt lgkmcnt(11)
	v_mfma_f32_32x32x16_bf16 v[82:97], v[46:49], v[126:129], v[82:97]
	v_exp_f32_e32 v75, v75
	v_exp_f32_e32 v76, v76
	v_exp_f32_e32 v77, v77
	s_waitcnt lgkmcnt(10)
	v_mfma_f32_32x32x16_bf16 v[98:113], v[130:133], v[114:117], 0
	v_exp_f32_e32 v78, v78
	v_exp_f32_e32 v79, v79
	v_exp_f32_e32 v80, v80
	s_waitcnt lgkmcnt(9)
	v_mfma_f32_32x32x16_bf16 v[98:113], v[134:137], v[118:121], v[98:113]
	v_exp_f32_e32 v81, v81
	ds_read_b64_tr_b16 v[220:221], v192 offset:10752
	v_cvt_pk_bf16_f32 v146, v50, v51
	v_cvt_pk_bf16_f32 v147, v52, v53
	v_cvt_pk_bf16_f32 v148, v54, v55
	v_cvt_pk_bf16_f32 v149, v56, v57
	s_waitcnt lgkmcnt(9)
	v_mfma_f32_32x32x16_bf16 v[98:113], v[138:141], v[122:125], v[98:113]
	v_cvt_pk_bf16_f32 v150, v58, v59
	v_cvt_pk_bf16_f32 v151, v60, v61
	v_cvt_pk_bf16_f32 v152, v62, v63
	v_cvt_pk_bf16_f32 v153, v64, v65
	v_add_f32_e32 v193, v193, v50
	v_add_f32_e32 v194, v194, v51
	s_waitcnt lgkmcnt(8)
	v_mfma_f32_32x32x16_bf16 v[98:113], v[142:145], v[126:129], v[98:113]
	v_cvt_pk_bf16_f32 v154, v66, v67
	v_cvt_pk_bf16_f32 v155, v68, v69
	s_waitcnt lgkmcnt(6)
	v_mfma_f32_32x32x16_bf16 v[18:33], v[206:209], v[146:149], v[18:33]
	ds_read_b64_tr_b16 v[206:207], v192 offset:64
	ds_read_b64_tr_b16 v[208:209], v192 offset:1600
	v_cvt_pk_bf16_f32 v156, v70, v71
	v_cvt_pk_bf16_f32 v157, v72, v73
	v_add_f32_e32 v195, v195, v52
	v_add_f32_e32 v196, v196, v53
	s_waitcnt lgkmcnt(6)
	v_mfma_f32_32x32x16_bf16 v[18:33], v[210:213], v[150:153], v[18:33]
	ds_read_b64_tr_b16 v[210:211], v192 offset:3136
	ds_read_b64_tr_b16 v[212:213], v192 offset:4672
	v_cvt_pk_bf16_f32 v158, v74, v75
	v_cvt_pk_bf16_f32 v159, v76, v77
	v_add_f32_e32 v193, v193, v54
	v_add_f32_e32 v194, v194, v55
	s_waitcnt lgkmcnt(6)
	v_mfma_f32_32x32x16_bf16 v[18:33], v[214:217], v[154:157], v[18:33]
	ds_read_b64_tr_b16 v[214:215], v192 offset:6208
	ds_read_b64_tr_b16 v[216:217], v192 offset:7744
	v_cvt_pk_bf16_f32 v160, v78, v79
	v_cvt_pk_bf16_f32 v161, v80, v81
	v_add_f32_e32 v195, v195, v56
	v_add_f32_e32 v196, v196, v57
	s_waitcnt lgkmcnt(6)
	v_mfma_f32_32x32x16_bf16 v[18:33], v[218:221], v[158:161], v[18:33]
	ds_read_b64_tr_b16 v[218:219], v192 offset:9280
	ds_read_b64_tr_b16 v[220:221], v192 offset:10816
	v_add_f32_e32 v193, v193, v58
	v_add_f32_e32 v194, v194, v59
	v_add_f32_e32 v195, v195, v60
	v_add_f32_e32 v196, v196, v61
	s_waitcnt lgkmcnt(6)
	v_mfma_f32_32x32x16_bf16 v[2:17], v[206:209], v[146:149], v[2:17]
	v_add_f32_e32 v193, v193, v62
	v_add_f32_e32 v194, v194, v63
	v_add_f32_e32 v195, v195, v64
	v_add_f32_e32 v196, v196, v65
	v_add_f32_e32 v193, v193, v66
	v_add_f32_e32 v194, v194, v67
	s_waitcnt lgkmcnt(4)
	v_mfma_f32_32x32x16_bf16 v[2:17], v[210:213], v[150:153], v[2:17]
	v_add_f32_e32 v195, v195, v68
	v_add_f32_e32 v196, v196, v69
	v_add_f32_e32 v193, v193, v70
	v_add_f32_e32 v194, v194, v71
	v_add_f32_e32 v195, v195, v72
	v_add_f32_e32 v196, v196, v73
	s_waitcnt lgkmcnt(2)
	v_mfma_f32_32x32x16_bf16 v[2:17], v[214:217], v[154:157], v[2:17]
	v_add_f32_e32 v193, v193, v74
	v_add_f32_e32 v194, v194, v75
	v_add_f32_e32 v195, v195, v76
	v_add_f32_e32 v196, v196, v77
	v_add_f32_e32 v193, v193, v78
	v_add_f32_e32 v194, v194, v79
	s_waitcnt lgkmcnt(0)
	v_mfma_f32_32x32x16_bf16 v[2:17], v[218:221], v[158:161], v[2:17]
	v_add_f32_e32 v195, v195, v80
	v_add_f32_e32 v196, v196, v81
	s_waitcnt vmcnt(1)
	ds_write_b128 v190, v[176:179] offset:12288
	s_waitcnt vmcnt(0)
	ds_write_b128 v190, v[180:183] offset:18432
	s_waitcnt lgkmcnt(0)
	s_barrier
; DI float frcp(float x) { return __builtin_amdgcn_rcpf(x); }
; template <int DQK, bool FIXEDM>
; DI void attn_dense_mfma(const bf16_t* Qb, int ldq, const bf16_t* Kb, int ldk, const bf16_t* Vb, int ldv, bf16_t* gate_io, char* smem, bool store, float mbound) {
;     ...
;   if (!store) return;
;   const float inv = frcp(half_swap_sum(l_run));
	ds_read_b128 v[34:37], v191 offset:0
	ds_read_b128 v[38:41], v191 offset:32
	ds_read_b128 v[42:45], v191 offset:64
	ds_read_b128 v[46:49], v191 offset:96
	ds_read_b128 v[130:133], v191 offset:4608
	ds_read_b128 v[134:137], v191 offset:4640
	ds_read_b128 v[138:141], v191 offset:4672
	ds_read_b128 v[142:145], v191 offset:4704
	v_exp_f32_e32 v82, v82
	v_exp_f32_e32 v83, v83
	v_exp_f32_e32 v84, v84
	v_exp_f32_e32 v85, v85
	v_exp_f32_e32 v86, v86
	v_exp_f32_e32 v87, v87
	v_exp_f32_e32 v88, v88
	v_exp_f32_e32 v89, v89
	ds_read_b64_tr_b16 v[206:207], v192 offset:12288
	ds_read_b64_tr_b16 v[208:209], v192 offset:13824
	ds_read_b64_tr_b16 v[210:211], v192 offset:15360
	ds_read_b64_tr_b16 v[212:213], v192 offset:16896
	v_exp_f32_e32 v90, v90
	v_exp_f32_e32 v91, v91
	v_exp_f32_e32 v92, v92
	v_exp_f32_e32 v93, v93
	v_exp_f32_e32 v94, v94
	v_exp_f32_e32 v95, v95
	v_exp_f32_e32 v96, v96
	v_exp_f32_e32 v97, v97
	ds_read_b64_tr_b16 v[214:215], v192 offset:18432
	ds_read_b64_tr_b16 v[216:217], v192 offset:19968
	ds_read_b64_tr_b16 v[218:219], v192 offset:21504
	s_waitcnt lgkmcnt(14)
	v_mfma_f32_32x32x16_bf16 v[50:65], v[34:37], v[114:117], 0
	v_exp_f32_e32 v98, v98
	v_exp_f32_e32 v99, v99
	v_exp_f32_e32 v100, v100
	s_waitcnt lgkmcnt(13)
	v_mfma_f32_32x32x16_bf16 v[50:65], v[38:41], v[118:121], v[50:65]
	v_exp_f32_e32 v101, v101
	v_exp_f32_e32 v102, v102
	v_exp_f32_e32 v103, v103
	s_waitcnt lgkmcnt(12)
	v_mfma_f32_32x32x16_bf16 v[50:65], v[42:45], v[122:125], v[50:65]
	v_exp_f32_e32 v104, v104
	v_exp_f32_e32 v105, v105
	v_exp_f32_e32 v106, v106
	s_waitcnt lgkmcnt(11)
	v_mfma_f32_32x32x16_bf16 v[50:65], v[46:49], v[126:129], v[50:65]
	v_exp_f32_e32 v107, v107
	v_exp_f32_e32 v108, v108
	v_exp_f32_e32 v109, v109
	s_waitcnt lgkmcnt(10)
	v_mfma_f32_32x32x16_bf16 v[66:81], v[130:133], v[114:117], 0
	v_exp_f32_e32 v110, v110
	v_exp_f32_e32 v111, v111
	v_exp_f32_e32 v112, v112
	s_waitcnt lgkmcnt(9)
	v_mfma_f32_32x32x16_bf16 v[66:81], v[134:137], v[118:121], v[66:81]
	v_exp_f32_e32 v113, v113
	ds_read_b64_tr_b16 v[220:221], v192 offset:23040
	v_cvt_pk_bf16_f32 v146, v82, v83
	v_cvt_pk_bf16_f32 v147, v84, v85
	v_cvt_pk_bf16_f32 v148, v86, v87
	v_cvt_pk_bf16_f32 v149, v88, v89
	s_waitcnt lgkmcnt(9)
	v_mfma_f32_32x32x16_bf16 v[66:81], v[138:141], v[122:125], v[66:81]
	v_cvt_pk_bf16_f32 v150, v90, v91
	v_cvt_pk_bf16_f32 v151, v92, v93
	v_cvt_pk_bf16_f32 v152, v94, v95
	v_cvt_pk_bf16_f32 v153, v96, v97
	v_add_f32_e32 v193, v193, v82
	v_add_f32_e32 v194, v194, v83
	s_waitcnt lgkmcnt(8)
	v_mfma_f32_32x32x16_bf16 v[66:81], v[142:145], v[126:129], v[66:81]
	v_cvt_pk_bf16_f32 v154, v98, v99
	v_cvt_pk_bf16_f32 v155, v100, v101
	s_waitcnt lgkmcnt(6)
	v_mfma_f32_32x32x16_bf16 v[18:33], v[206:209], v[146:149], v[18:33]
	ds_read_b64_tr_b16 v[206:207], v192 offset:12352
	ds_read_b64_tr_b16 v[208:209], v192 offset:13888
	v_cvt_pk_bf16_f32 v156, v102, v103
	v_cvt_pk_bf16_f32 v157, v104, v105
	v_add_f32_e32 v195, v195, v84
	v_add_f32_e32 v196, v196, v85
	s_waitcnt lgkmcnt(6)
	v_mfma_f32_32x32x16_bf16 v[18:33], v[210:213], v[150:153], v[18:33]
	ds_read_b64_tr_b16 v[210:211], v192 offset:15424
	ds_read_b64_tr_b16 v[212:213], v192 offset:16960
	v_cvt_pk_bf16_f32 v158, v106, v107
	v_cvt_pk_bf16_f32 v159, v108, v109
	v_add_f32_e32 v193, v193, v86
	v_add_f32_e32 v194, v194, v87
	s_waitcnt lgkmcnt(6)
	v_mfma_f32_32x32x16_bf16 v[18:33], v[214:217], v[154:157], v[18:33]
	ds_read_b64_tr_b16 v[214:215], v192 offset:18496
	ds_read_b64_tr_b16 v[216:217], v192 offset:20032
	v_cvt_pk_bf16_f32 v160, v110, v111
	v_cvt_pk_bf16_f32 v161, v112, v113
	v_add_f32_e32 v195, v195, v88
	v_add_f32_e32 v196, v196, v89
	s_waitcnt lgkmcnt(6)
	v_mfma_f32_32x32x16_bf16 v[18:33], v[218:221], v[158:161], v[18:33]
	ds_read_b64_tr_b16 v[218:219], v192 offset:21568
	ds_read_b64_tr_b16 v[220:221], v192 offset:23104
	v_add_f32_e32 v193, v193, v90
	v_add_f32_e32 v194, v194, v91
	v_add_f32_e32 v195, v195, v92
	v_add_f32_e32 v196, v196, v93
	s_waitcnt lgkmcnt(6)
	v_mfma_f32_32x32x16_bf16 v[2:17], v[206:209], v[146:149], v[2:17]
	v_add_f32_e32 v193, v193, v94
	v_add_f32_e32 v194, v194, v95
	v_add_f32_e32 v195, v195, v96
	v_add_f32_e32 v196, v196, v97
	v_add_f32_e32 v193, v193, v98
	v_add_f32_e32 v194, v194, v99
	s_waitcnt lgkmcnt(4)
	v_mfma_f32_32x32x16_bf16 v[2:17], v[210:213], v[150:153], v[2:17]
	v_add_f32_e32 v195, v195, v100
	v_add_f32_e32 v196, v196, v101
	v_add_f32_e32 v193, v193, v102
	v_add_f32_e32 v194, v194, v103
	v_add_f32_e32 v195, v195, v104
	v_add_f32_e32 v196, v196, v105
	s_waitcnt lgkmcnt(2)
	v_mfma_f32_32x32x16_bf16 v[2:17], v[214:217], v[154:157], v[2:17]
	v_add_f32_e32 v193, v193, v106
	v_add_f32_e32 v194, v194, v107
	v_add_f32_e32 v195, v195, v108
	v_add_f32_e32 v196, v196, v109
	v_add_f32_e32 v193, v193, v110
	v_add_f32_e32 v194, v194, v111
	s_waitcnt lgkmcnt(0)
	v_mfma_f32_32x32x16_bf16 v[2:17], v[218:221], v[158:161], v[2:17]
	v_add_f32_e32 v195, v195, v112
	v_add_f32_e32 v196, v196, v113
	s_barrier
	v_add_f32_e32 v193, v193, v194
	v_add_f32_e32 v195, v195, v196
	v_add_f32_e32 v0, v193, v195
	v_mov_b32_e32 v34, v0
	s_nop 1
	v_permlane32_swap_b32_e32 v0, v34
	v_add_f32_e32 v0, v0, v34
	v_rcp_f32_e32 v34, v0
	s_movk_i32 s11, 0x2000
	v_mov_b32_e32 v190, 0x358637bd
	v_xor_b32_e32 v191, 16, v204
	v_xor_b32_e32 v192, 8, v204
	v_xor_b32_e32 v193, 4, v204
	v_xor_b32_e32 v194, 2, v204
	v_xor_b32_e32 v195, 1, v204
	s_nop 3
; DI int otid() { int t; asm volatile("v_mov_b32 %0, %1" : "=v"(t) : "v"((int)threadIdx.x)); __builtin_assume(t >= 0 && t < 256); return t; }
; #define KLOAD() do { _Pragma("unroll") for (int i = 0; i < NKC; ++i) rk[i] = *(const u32x4*)(kp + i * 8); kp += kstep; } while (0)
; #define VLOAD() do { rv[0] = *(const u32x4*)vp0; rv[1] = *(const u32x4*)vp1; vp0 += vstep; vp1 += vstep; } while (0)
; #define KSTORE(st) do { _Pragma("unroll") for (int i = 0; i < NKC; ++i) *(u32x4*)(sKc + (st) * KBYTES + kso + i * 16) = rk[i]; } while (0)
; #define VSTORE(st) do { *(u32x4*)(sVc + (st) * VBYTES + vso) = rv[0]; *(u32x4*)(sVc + (st) * VBYTES + vso + 32 * VLD * 2) = rv[1]; } while (0)
; template <int DQK, bool FIXEDM>
; DI void attn_dense_mfma(const bf16_t* Qb, int ldq, const bf16_t* Kb, int ldk, const bf16_t* Vb, int ldv, bf16_t* gate_io, char* smem, bool store, float mbound) {
;   constexpr int NS = DQK / 16, KLD = DQK + 8, VLD = 96, CPR = DQK / 8, NKC = (64 * CPR) / 256;
;   constexpr int KBYTES = 64 * KLD * 2, VBYTES = 64 * VLD * 2;
;   char* sKc = smem; char* sVc = smem + 2 * KBYTES;
;   const int tid = otid(), lane = tid & 63, wid = tid >> 6, r = lane & 31, h = lane >> 5;
;   bf16x8 qf[NS];
; #pragma unroll
;   for (int s = 0; s < NS; ++s) qf[s] = *(const bf16x8*)(Qb + (size_t)(wid * 32 + r) * ldq + 16 * s + 8 * h);
;   const bf16_t* kp = Kb + (size_t)(tid >> 2) * ldk + (tid & 3) * (NKC * 8);
;   const int kso = ((tid >> 2) * KLD + (tid & 3) * (NKC * 8)) * 2;
;   const bf16_t* vp0 = Vb + (size_t)(tid >> 3) * ldv + (tid & 7) * 8;
;   const bf16_t* vp1 = vp0 + (size_t)32 * ldv;
;   const int vso = ((tid >> 3) * VLD + (tid & 7) * 8) * 2;
;   const size_t kstep = (size_t)64 * ldk, vstep = (size_t)64 * ldv;
;   u32x4 rk[NKC], rv[2];
;     ...
;   const unsigned vb0 = (unsigned)(size_t)sVc + (unsigned)(((4 * h + ((lane & 15) >> 2)) * VLD + 16 * ((lane >> 4) & 1) + 4 * (lane & 3)) * 2);
;   f32x16 o0 = splat16(0.f), o1 = splat16(0.f), negm = splat16(FIXEDM ? -mbound : 0.f);
;   f32x16 pa0, pa1, pc0, pc1;
;   float m_run = 0.f, l_run = 0.f;
;   constexpr int NT = SEQ / 64;
;   __syncthreads();
;   KLOAD(); VLOAD(); KSTORE(0); VSTORE(0);
;   KLOAD(); KSTORE(1);
;   __syncthreads();
;   QKT(pa0, pa1, 0);
;   __syncthreads();
.LBB0_169:
	s_andn2_saveexec_b64 s[0:1], s[0:1]
	s_cbranch_execz .LBB0_186
	v_mov_b32 v148, v188
	s_movk_i32 s7, 0x60
	v_and_b32_e32 v28, 31, v148
	v_lshrrev_b32_e32 v0, 1, v148
	v_and_or_b32 v0, v0, s7, v28
	v_mul_u32_u24_e32 v162, 0x1300, v0
	v_bfe_u32 v42, v148, 5, 1
	v_lshlrev_b32_e32 v0, 1, v162
	s_nop 2
	v_lshl_add_u64 v[2:3], s[24:25], 0, v[0:1]
	v_lshlrev_b32_e32 v26, 4, v42
	v_mov_b32_e32 v27, v1
	v_lshrrev_b32_e32 v43, 2, v148
	v_lshlrev_b32_e32 v4, 4, v148
	v_lshl_add_u64 v[2:3], v[2:3], 0, v[26:27]
	v_mul_u32_u24_e32 v0, 0x1300, v43
	v_and_b32_e32 v27, 48, v4
	global_load_dwordx4 v[126:129], v[2:3], off
	global_load_dwordx4 v[122:125], v[2:3], off offset:32
	global_load_dwordx4 v[118:121], v[2:3], off offset:64
	global_load_dwordx4 v[114:117], v[2:3], off offset:96
	v_lshl_add_u64 v[2:3], v[0:1], 1, s[22:23]
	v_lshlrev_b32_e32 v4, 1, v27
	v_mov_b32_e32 v5, v1
	v_lshl_add_u64 v[64:65], v[2:3], 0, v[4:5]
	v_lshrrev_b32_e32 v29, 3, v148
	v_lshlrev_b32_e32 v4, 3, v148
	v_mul_u32_u24_e32 v146, 0x1300, v29
	v_mov_b32_e32 v147, v1
	v_and_b32_e32 v30, 56, v4
	v_lshl_add_u64 v[2:3], v[146:147], 1, s[22:23]
	v_lshlrev_b32_e32 v4, 1, v30
	v_lshl_add_u64 v[62:63], v[2:3], 0, v[4:5]
	s_mov_b32 s7, 0x4c000
	v_add_co_u32_e32 v14, vcc, s7, v62
	s_mov_b32 s7, 0x98000
	s_nop 0
	v_addc_co_u32_e32 v15, vcc, 0, v63, vcc
	s_mov_b64 s[4:5], 0x98200
	v_add_co_u32_e32 v18, vcc, s7, v64
	v_lshl_add_u64 v[22:23], v[64:65], 0, s[4:5]
	s_nop 0
	v_addc_co_u32_e32 v19, vcc, 0, v65, vcc
	s_barrier
	global_load_dwordx4 v[2:5], v[64:65], off offset:528
	global_load_dwordx4 v[6:9], v[64:65], off offset:512
	global_load_dwordx4 v[10:13], v[62:63], off offset:768
	s_nop 0
	global_load_dwordx4 v[14:17], v[14:15], off offset:768
	s_nop 0
	global_load_dwordx4 v[18:21], v[18:19], off offset:512
	s_nop 0
	global_load_dwordx4 v[22:25], v[22:23], off offset:16
	v_mul_u32_u24_e32 v31, 0x48, v43
	v_mul_u32_u24_e32 v28, 0x48, v28
	v_mul_u32_u24_e32 v29, 0x60, v29
	v_add_lshl_u32 v182, v31, v27, 1
	v_lshl_add_u32 v181, v28, 1, v26
	v_add_lshl_u32 v167, v29, v30, 1
	v_lshlrev_b32_e32 v166, 2, v42
	v_lshlrev_b32_e32 v45, 2, v148
	v_and_b32_e32 v44, 16, v148
	s_mov_b64 s[4:5], 0x130200
	s_waitcnt vmcnt(4)
	ds_write_b128 v182, v[6:9]
	ds_write_b128 v182, v[2:5] offset:16
	s_waitcnt vmcnt(3)
	ds_write_b128 v167, v[10:13] offset:18432
	s_waitcnt vmcnt(2)
	ds_write_b128 v167, v[14:17] offset:24576
	s_waitcnt vmcnt(1)
	ds_write_b128 v182, v[18:21] offset:9216
	s_waitcnt vmcnt(0)
	ds_write_b128 v182, v[22:25] offset:9232
	s_waitcnt lgkmcnt(0)
	s_barrier
	ds_read_b128 v[2:5], v181
	ds_read_b128 v[34:37], v181 offset:32
	s_waitcnt lgkmcnt(1)
	v_mfma_f32_32x32x16_bf16 v[2:17], v[2:5], v[126:129], 0
	ds_read_b128 v[18:21], v181 offset:4608
	ds_read_b128 v[38:41], v181 offset:4640
	s_waitcnt lgkmcnt(1)
	v_mfma_f32_32x32x16_bf16 v[18:33], v[18:21], v[126:129], 0
	v_mfma_f32_32x32x16_bf16 v[2:17], v[34:37], v[122:125], v[2:17]
	ds_read_b128 v[34:37], v181 offset:64
	s_waitcnt lgkmcnt(1)
	v_mfma_f32_32x32x16_bf16 v[18:33], v[38:41], v[122:125], v[18:33]
	v_and_or_b32 v39, v43, 3, v166
	v_and_b32_e32 v38, 12, v45
	v_mul_u32_u24_e32 v39, 0x60, v39
	v_or3_b32 v46, v39, v44, v38
	ds_read_b128 v[38:41], v181 offset:4672
	ds_read_b128 v[42:45], v181 offset:96
	v_lshlrev_b32_e32 v149, 1, v46
	ds_read_b128 v[46:49], v181 offset:4704
	s_waitcnt lgkmcnt(3)
	v_mfma_f32_32x32x16_bf16 v[2:17], v[34:37], v[118:121], v[2:17]
	v_add_co_u32_e32 v34, vcc, s7, v62
	s_mov_b32 s7, 0xe4000
	s_nop 0
	v_addc_co_u32_e32 v35, vcc, 0, v63, vcc
	v_add_co_u32_e32 v50, vcc, s7, v62
	s_mov_b32 s7, 0x130000
	s_nop 0
	v_addc_co_u32_e32 v51, vcc, 0, v63, vcc
	s_waitcnt lgkmcnt(2)
	v_mfma_f32_32x32x16_bf16 v[18:33], v[38:41], v[118:121], v[18:33]
	v_add_co_u32_e32 v38, vcc, s7, v64
	v_lshl_add_u64 v[36:37], v[64:65], 0, s[4:5]
	s_nop 0
	v_addc_co_u32_e32 v39, vcc, 0, v65, vcc
	s_waitcnt lgkmcnt(0)
	s_barrier
	global_load_dwordx4 v[130:133], v[38:39], off offset:512
	global_load_dwordx4 v[134:137], v[36:37], off offset:16
	s_nop 0
	global_load_dwordx4 v[34:37], v[34:35], off offset:768
	s_nop 0
	global_load_dwordx4 v[38:41], v[50:51], off offset:768
	v_mfma_f32_32x32x16_bf16 v[2:17], v[42:45], v[114:117], v[2:17]
	v_add_u32_e32 v180, 0x4800, v149
	ds_read_b128 v[94:97], v181 offset:9216
	ds_read_b128 v[90:93], v181 offset:9248
	ds_read_b128 v[86:89], v181 offset:13824
	ds_read_b128 v[82:85], v181 offset:13856
	ds_read_b128 v[98:101], v181 offset:9280
	ds_read_b128 v[102:105], v181 offset:9312
	ds_read_b128 v[74:77], v181 offset:13888
	ds_read_b128 v[66:69], v181 offset:13920
	s_mov_b64 s[4:5], 0x1c8200
	v_lshl_add_u64 v[106:107], v[64:65], 0, s[4:5]
	s_nop 0
	v_max_f32_e32 v43, v2, v2
	v_mfma_f32_32x32x16_bf16 v[18:33], v[46:49], v[114:117], v[18:33]
	s_nop 11
	v_max_f32_e32 v42, v18, v18
	v_max_f32_e32 v42, v43, v42
	v_max3_f32 v42, v42, v3, v19
	v_max3_f32 v42, v42, v4, v20
	v_max3_f32 v42, v42, v5, v21
	v_max3_f32 v42, v42, v6, v22
	v_max3_f32 v42, v42, v7, v23
	v_max3_f32 v42, v42, v8, v24
	v_max3_f32 v42, v42, v9, v25
	v_max3_f32 v42, v42, v10, v26
	v_max3_f32 v42, v42, v11, v27
	v_max3_f32 v42, v42, v12, v28
	v_max3_f32 v42, v42, v13, v29
	v_max3_f32 v42, v42, v14, v30
	v_max3_f32 v42, v42, v15, v31
	v_max3_f32 v42, v42, v16, v32
	v_max3_f32 v42, v42, v17, v33
	v_mov_b32_e32 v43, v42
	s_nop 1
	v_permlane32_swap_b32_e32 v42, v43
	v_max_f32_e32 v43, v43, v43
	v_max_f32_e32 v42, v42, v42
	v_max_f32_e32 v110, v42, v43
	v_sub_f32_e32 v5, v5, v110
	v_sub_f32_e32 v21, v21, v110
	v_sub_f32_e32 v22, v22, v110
	v_sub_f32_e32 v23, v23, v110
	v_sub_f32_e32 v44, v8, v110
	v_sub_f32_e32 v24, v24, v110
	v_sub_f32_e32 v9, v9, v110
; DI unsigned pack2(float a, float b) { f2_t v = {a, b}; bf2_t r = __builtin_convertvector(v, bf2_t); return __builtin_bit_cast(unsigned, r); }
; #define MFMA32(a, b, c) __builtin_amdgcn_mfma_f32_32x32x16_bf16((a), (b), (c), 0, 0, 0)
; DI bf16x8 pack8(const f32x16& p, int base) {
;   u32x4 w = {pack2(p[base + 0], p[base + 1]), pack2(p[base + 2], p[base + 3]), pack2(p[base + 4], p[base + 5]), pack2(p[base + 6], p[base + 7])};
;   return __builtin_bit_cast(bf16x8, w);
; }
; template <int DB, int VLD> DI void pv_block(f32x16& o, unsigned vb, bf16x8 pb0, bf16x8 pb1, bf16x8 pb2, bf16x8 pb3) {
;   constexpr int RB = VLD * 2;
;   bf16x4 l0 = tr_read<0 * RB + 64 * DB>(vb), h0 = tr_read<8 * RB + 64 * DB>(vb);
;   bf16x4 l1 = tr_read<16 * RB + 64 * DB>(vb), h1 = tr_read<24 * RB + 64 * DB>(vb);
;   bf16x4 l2 = tr_read<32 * RB + 64 * DB>(vb), h2 = tr_read<40 * RB + 64 * DB>(vb);
;   bf16x4 l3 = tr_read<48 * RB + 64 * DB>(vb), h3 = tr_read<56 * RB + 64 * DB>(vb);
;   asm volatile("s_waitcnt lgkmcnt(0)" ::: "memory"); __builtin_amdgcn_sched_barrier(0);
;   o = MFMA32(__builtin_shufflevector(l0, h0, 0, 1, 2, 3, 4, 5, 6, 7), pb0, o);
;   o = MFMA32(__builtin_shufflevector(l1, h1, 0, 1, 2, 3, 4, 5, 6, 7), pb1, o);
;   o = MFMA32(__builtin_shufflevector(l2, h2, 0, 1, 2, 3, 4, 5, 6, 7), pb2, o);
;   o = MFMA32(__builtin_shufflevector(l3, h3, 0, 1, 2, 3, 4, 5, 6, 7), pb3, o);
; }
	v_sub_f32_e32 v25, v25, v110
	v_sub_f32_e32 v45, v10, v110
	v_sub_f32_e32 v26, v26, v110
	v_sub_f32_e32 v27, v27, v110
	v_sub_f32_e32 v47, v12, v110
	v_sub_f32_e32 v28, v28, v110
	v_sub_f32_e32 v13, v13, v110
	v_sub_f32_e32 v29, v29, v110
	v_sub_f32_e32 v50, v16, v110
	v_exp_f32_e32 v10, v5
	v_exp_f32_e32 v5, v22
	v_exp_f32_e32 v12, v21
	v_exp_f32_e32 v21, v44
	v_exp_f32_e32 v22, v24
	v_exp_f32_e32 v16, v23
	v_exp_f32_e32 v108, v9
	v_exp_f32_e32 v9, v45
	v_exp_f32_e32 v23, v26
	v_exp_f32_e32 v112, v25
	v_exp_f32_e32 v140, v27
	v_sub_f32_e32 v2, v2, v110
	v_sub_f32_e32 v18, v18, v110
	v_sub_f32_e32 v19, v19, v110
	v_exp_f32_e32 v24, v47
	v_exp_f32_e32 v25, v28
	v_exp_f32_e32 v142, v13
	v_exp_f32_e32 v144, v29
	v_sub_f32_e32 v4, v4, v110
	v_sub_f32_e32 v20, v20, v110
	v_exp_f32_e32 v2, v2
	v_exp_f32_e32 v51, v18
	v_exp_f32_e32 v8, v19
	v_sub_f32_e32 v49, v15, v110
	v_exp_f32_e32 v4, v4
	v_exp_f32_e32 v52, v20
	v_sub_f32_e32 v43, v7, v110
	v_add_f32_e32 v109, v21, v22
	v_add_f32_e32 v139, v9, v23
	v_exp_f32_e32 v150, v49
	v_cvt_pk_bf16_f32 v49, v22, v112
	v_cvt_pk_bf16_f32 v70, v23, v140
	ds_read_b64_tr_b16 v[22:23], v180 offset:0
	v_sub_f32_e32 v46, v11, v110
	v_sub_f32_e32 v48, v14, v110
	v_exp_f32_e32 v14, v43
	v_add_f32_e32 v143, v24, v25
	v_cvt_pk_bf16_f32 v43, v24, v142
	v_cvt_pk_bf16_f32 v71, v25, v144
	ds_read_b64_tr_b16 v[24:25], v180 offset:0x600
	v_add_f32_e32 v7, v2, v51
	v_exp_f32_e32 v138, v46
	v_exp_f32_e32 v27, v50
	v_cvt_pk_bf16_f32 v46, v51, v8
	ds_read_b64_tr_b16 v[50:51], v180 offset:0xc00
	v_add_f32_e32 v11, v4, v52
	v_cvt_pk_bf16_f32 v47, v52, v12
	ds_read_b64_tr_b16 v[52:53], v180 offset:0x1200
	ds_read_b64_tr_b16 v[54:55], v180 offset:0x1800
	v_sub_f32_e32 v3, v3, v110
	v_sub_f32_e32 v42, v6, v110
	v_sub_f32_e32 v30, v30, v110
	v_sub_f32_e32 v31, v31, v110
	v_sub_f32_e32 v32, v32, v110
	v_sub_f32_e32 v17, v17, v110
	v_sub_f32_e32 v33, v33, v110
	ds_read_b64_tr_b16 v[56:57], v180 offset:0x1e00
	v_exp_f32_e32 v6, v3
	v_exp_f32_e32 v3, v42
	v_exp_f32_e32 v13, v48
	v_exp_f32_e32 v26, v30
	v_exp_f32_e32 v28, v32
	v_exp_f32_e32 v152, v31
	v_exp_f32_e32 v154, v17
	v_exp_f32_e32 v156, v33
	ds_read_b64_tr_b16 v[78:79], v180 offset:0x2400
	ds_read_b64_tr_b16 v[80:81], v180 offset:0x2a00
	s_waitcnt lgkmcnt(0)
	v_add_f32_e32 v15, v3, v5
	v_add_f32_e32 v155, v27, v28
	v_cvt_pk_bf16_f32 v18, v2, v6
	v_cvt_pk_bf16_f32 v19, v4, v10
	v_cvt_pk_bf16_f32 v20, v3, v14
	v_cvt_pk_bf16_f32 v21, v21, v108
	v_cvt_pk_bf16_f32 v42, v9, v138
	v_cvt_pk_bf16_f32 v44, v13, v150
	v_cvt_pk_bf16_f32 v45, v27, v154
	v_cvt_pk_bf16_f32 v48, v5, v16
	v_cvt_pk_bf16_f32 v72, v26, v152
	v_cvt_pk_bf16_f32 v73, v28, v156
	v_add_f32_e32 v151, v13, v26
	ds_read_b64_tr_b16 v[2:3], v180 offset:64
	ds_read_b64_tr_b16 v[4:5], v180 offset:0x640
	ds_read_b64_tr_b16 v[26:27], v180 offset:0xc40
	ds_read_b64_tr_b16 v[28:29], v180 offset:0x1240
	ds_read_b64_tr_b16 v[30:31], v180 offset:0x1840
	ds_read_b64_tr_b16 v[32:33], v180 offset:0x1e40
	ds_read_b64_tr_b16 v[58:59], v180 offset:0x2440
	ds_read_b64_tr_b16 v[60:61], v180 offset:0x2a40
	s_waitcnt lgkmcnt(0)
	v_mov_b32_e32 v9, v1
	v_add_f32_e32 v6, v6, v8
	v_add_f32_e32 v7, v7, v9
	s_mov_b32 s12, 0x1c8000
	v_add_f32_e32 v7, v6, v7
	v_add_f32_e32 v6, v6, v6
	v_mov_b32_e32 v13, v7
	v_add_f32_e32 v6, v10, v12
	v_add_f32_e32 v7, v11, v13
	s_waitcnt vmcnt(3)
	ds_write_b128 v182, v[130:133]
	s_waitcnt vmcnt(2)
	ds_write_b128 v182, v[134:137] offset:16
	v_add_f32_e32 v7, v6, v7
	v_add_f32_e32 v6, v6, v6
	v_mov_b32_e32 v17, v7
	v_add_f32_e32 v6, v14, v16
	v_add_f32_e32 v7, v15, v17
	s_waitcnt vmcnt(1)
	ds_write_b128 v167, v[34:37] offset:30720
	s_waitcnt vmcnt(0)
	ds_write_b128 v167, v[38:41] offset:36864
	v_add_f32_e32 v7, v6, v7
	v_add_f32_e32 v6, v6, v6
	v_mov_b32_e32 v113, v7
	v_add_f32_e32 v6, v108, v112
	v_add_f32_e32 v7, v109, v113
	s_waitcnt lgkmcnt(0)
	v_add_f32_e32 v7, v6, v7
	v_add_f32_e32 v6, v6, v6
	v_mov_b32_e32 v141, v7
	v_add_f32_e32 v6, v138, v140
	v_add_f32_e32 v7, v139, v141
	s_barrier
	v_add_f32_e32 v7, v6, v7
	v_add_f32_e32 v6, v6, v6
	v_mov_b32_e32 v145, v7
	v_add_f32_e32 v6, v142, v144
	v_add_f32_e32 v7, v143, v145
	s_nop 0
	v_add_f32_e32 v7, v6, v7
	v_add_f32_e32 v6, v6, v6
	v_mov_b32_e32 v153, v7
	v_add_f32_e32 v6, v150, v152
	v_add_f32_e32 v7, v151, v153
	v_mov_b32_e32 v242, 0x358637bd
	v_add_f32_e32 v7, v6, v7
	v_add_f32_e32 v6, v6, v6
	v_mov_b32_e32 v157, v7
	v_mfma_f32_32x32x16_bf16 v[2:17], v[2:5], v[18:21], 0
	v_add_f32_e64 v108, v154, v156
	v_add_f32_e64 v109, v155, v157
	v_mfma_f32_32x32x16_bf16 v[2:17], v[26:29], v[42:45], v[2:17]
	v_add_co_u32_e32 v26, vcc, s12, v64
	s_nop 1
	v_addc_co_u32_e32 v27, vcc, 0, v65, vcc
	global_load_dwordx4 v[142:145], v[26:27], off offset:512
	global_load_dwordx4 v[138:141], v[106:107], off offset:16
	v_add_co_u32_e32 v34, vcc, s7, v62
	v_mfma_f32_32x32x16_bf16 v[2:17], v[30:33], v[46:49], v[2:17]
	s_nop 0
	v_addc_co_u32_e32 v35, vcc, 0, v63, vcc
	s_mov_b32 s7, 0x17c000
	global_load_dwordx4 v[130:133], v[34:35], off offset:768
	v_add_co_u32_e32 v34, vcc, s7, v62
	v_mfma_f32_32x32x16_bf16 v[18:33], v[22:25], v[18:21], 0
	s_nop 0
	v_addc_co_u32_e32 v35, vcc, 0, v63, vcc
	global_load_dwordx4 v[134:137], v[34:35], off offset:768
	v_add_f32_e64 v34, v108, v109
	v_add_f32_e64 v35, v109, v108
	v_mov_b32_e32 v35, v110
	v_add_f32_e32 v154, 0, v34
	v_add_f32_e32 v155, 0, v35
	v_mfma_f32_32x32x16_bf16 v[18:33], v[50:53], v[42:45], v[18:33]
	v_xor_b32_e32 v50, 0x80000000, v155
	v_mov_b32_e32 v51, v50
	v_mov_b32_e32 v52, v50
	v_mov_b32_e32 v53, v50
	v_mov_b32_e32 v62, v50
	v_mov_b32_e32 v63, v50
	v_mov_b32_e32 v64, v50
	v_mfma_f32_32x32x16_bf16 v[18:33], v[54:57], v[46:49], v[18:33]
	v_mov_b32_e32 v54, v50
	v_mov_b32_e32 v55, v50
	v_mov_b32_e32 v56, v50
	v_mov_b32_e32 v57, v50
	v_mov_b32_e32 v65, v50
	v_mfma_f32_32x32x16_bf16 v[2:17], v[58:61], v[70:73], v[2:17]
	v_mov_b32_e32 v58, v50
	v_mov_b32_e32 v59, v50
	v_mov_b32_e32 v60, v50
	v_mov_b32_e32 v61, v50
	s_nop 1
	v_mfma_f32_32x32x16_bf16 v[34:49], v[94:97], v[126:129], v[50:65]
	v_mfma_f32_32x32x16_bf16 v[34:49], v[90:93], v[122:125], v[34:49]
	v_mfma_f32_32x32x16_bf16 v[34:49], v[98:101], v[118:121], v[34:49]
	v_mfma_f32_32x32x16_bf16 v[34:49], v[102:105], v[114:117], v[34:49]
	v_mov_b64_e32 v[112:113], v[64:65]
	v_mov_b64_e32 v[110:111], v[62:63]
	v_mov_b64_e32 v[108:109], v[60:61]
	v_mov_b64_e32 v[106:107], v[58:59]
	v_mov_b64_e32 v[104:105], v[56:57]
	v_mov_b64_e32 v[102:103], v[54:55]
	v_mov_b64_e32 v[100:101], v[52:53]
	v_mov_b64_e32 v[98:99], v[50:51]
	s_nop 3
	v_max_f32_e32 v52, v34, v34
	v_mfma_f32_32x32x16_bf16 v[18:33], v[78:81], v[70:73], v[18:33]
	v_mfma_f32_32x32x16_bf16 v[98:113], v[86:89], v[126:129], v[98:113]
	v_mfma_f32_32x32x16_bf16 v[98:113], v[82:85], v[122:125], v[98:113]
	v_mfma_f32_32x32x16_bf16 v[98:113], v[74:77], v[118:121], v[98:113]
	v_mfma_f32_32x32x16_bf16 v[98:113], v[66:69], v[114:117], v[98:113]
	s_nop 11
	v_max_f32_e32 v51, v98, v98
	v_max_f32_e32 v51, v52, v51
	v_max3_f32 v51, v51, v35, v99
	v_max3_f32 v51, v51, v36, v100
	v_max3_f32 v51, v51, v37, v101
	v_max3_f32 v51, v51, v38, v102
	v_max3_f32 v51, v51, v39, v103
	v_max3_f32 v51, v51, v40, v104
	v_max3_f32 v51, v51, v41, v105
	v_max3_f32 v51, v51, v42, v106
	v_max3_f32 v51, v51, v43, v107
	v_max3_f32 v51, v51, v44, v108
	v_max3_f32 v51, v51, v45, v109
	v_max3_f32 v51, v51, v46, v110
	v_max3_f32 v51, v51, v47, v111
	v_max3_f32 v51, v51, v48, v112
	v_max3_f32 v51, v51, v49, v113
	v_mov_b32_e32 v52, v51
	s_nop 1
	v_permlane32_swap_b32_e32 v51, v52
	v_max_f32_e32 v52, v52, v52
	v_max_f32_e32 v51, v51, v51
	v_max_f32_e32 v51, v51, v52
	v_cmp_lt_f32_e32 vcc, s19, v51
	s_cbranch_vccz .LBB0_172
	v_max_f32_e32 v50, v51, v51
	v_max_f32_e32 v50, 0, v50
	v_exp_f32_e64 v52, -v50
	v_add_f32_e64 v34, v34, -v50
	v_add_f32_e64 v35, v35, -v50
	v_add_f32_e64 v98, v98, -v50
	v_add_f32_e64 v99, v99, -v50
	v_add_f32_e64 v36, v36, -v50
	v_add_f32_e64 v37, v37, -v50
	v_mul_f32_e32 v32, v32, v52
	v_mul_f32_e32 v33, v33, v52
	v_mul_f32_e32 v30, v30, v52
	v_mul_f32_e32 v31, v31, v52
	v_mul_f32_e32 v28, v28, v52
	v_mul_f32_e32 v29, v29, v52
	v_mul_f32_e32 v26, v26, v52
	v_mul_f32_e32 v27, v27, v52
	v_mul_f32_e32 v24, v24, v52
	v_mul_f32_e32 v25, v25, v52
	v_mul_f32_e32 v22, v22, v52
	v_mul_f32_e32 v23, v23, v52
	v_mul_f32_e32 v20, v20, v52
	v_mul_f32_e32 v21, v21, v52
	v_mul_f32_e32 v18, v18, v52
	v_mul_f32_e32 v19, v19, v52
	v_mul_f32_e32 v16, v16, v52
	v_mul_f32_e32 v17, v17, v52
	v_mul_f32_e32 v14, v14, v52
	v_mul_f32_e32 v15, v15, v52
	v_mul_f32_e32 v12, v12, v52
	v_mul_f32_e32 v13, v13, v52
	v_mul_f32_e32 v10, v10, v52
	v_mul_f32_e32 v11, v11, v52
	v_mul_f32_e32 v8, v8, v52
	v_mul_f32_e32 v9, v9, v52
	v_mul_f32_e32 v6, v6, v52
	v_mul_f32_e32 v7, v7, v52
	v_mul_f32_e32 v4, v4, v52
	v_mul_f32_e32 v5, v5, v52
	v_mul_f32_e32 v2, v2, v52
	v_mul_f32_e32 v3, v3, v52
	v_mul_f32_e32 v52, v154, v52
	v_mul_f32_e32 v53, v155, v53
	v_add_f32_e32 v155, v155, v50
	v_xor_b32_e32 v66, 0x80000000, v155
	v_add_f32_e64 v100, v100, -v50
	v_add_f32_e64 v101, v101, -v50
	v_add_f32_e64 v38, v38, -v50
	v_add_f32_e64 v39, v39, -v50
	v_add_f32_e64 v102, v102, -v50
	v_add_f32_e64 v103, v103, -v50
	v_add_f32_e64 v40, v40, -v50
	v_add_f32_e64 v41, v41, -v50
	v_add_f32_e64 v104, v104, -v50
	v_add_f32_e64 v105, v105, -v50
	v_add_f32_e64 v42, v42, -v50
	v_add_f32_e64 v43, v43, -v50
	v_add_f32_e64 v106, v106, -v50
	v_add_f32_e64 v107, v107, -v50
	v_add_f32_e64 v44, v44, -v50
	v_add_f32_e64 v45, v45, -v50
	v_add_f32_e64 v108, v108, -v50
	v_add_f32_e64 v109, v109, -v50
	v_add_f32_e64 v46, v46, -v50
	v_add_f32_e64 v47, v47, -v50
	v_add_f32_e64 v110, v110, -v50
	v_add_f32_e64 v111, v111, -v50
	v_add_f32_e64 v48, v48, -v50
	v_add_f32_e64 v49, v49, -v50
	v_add_f32_e64 v112, v112, -v50
	v_add_f32_e64 v113, v113, -v50
	v_mov_b32_e32 v50, v66
	v_mov_b32_e32 v154, v52
	s_branch .LBB0_173

.LBB0_173:
	ds_read_b128 v[52:55], v181
	ds_read_b128 v[56:59], v181 offset:32
	v_mov_b32_e32 v67, v50
	v_mov_b32_e32 v68, v50
	v_mov_b32_e32 v69, v50
	v_mov_b32_e32 v70, v50
	v_mov_b32_e32 v71, v50
	v_mov_b32_e32 v72, v50
	v_mov_b32_e32 v73, v50
	v_mov_b32_e32 v74, v50
	v_mov_b32_e32 v75, v50
	v_mov_b32_e32 v76, v50
	v_mov_b32_e32 v77, v50
	v_mov_b32_e32 v78, v50
	v_mov_b32_e32 v79, v50
	v_mov_b32_e32 v80, v50
	v_mov_b32_e32 v81, v50
	v_exp_f32_e32 v176, v41
	v_exp_f32_e32 v41, v48
	s_waitcnt lgkmcnt(1)
	v_mfma_f32_32x32x16_bf16 v[82:97], v[52:55], v[126:129], v[66:81]
	ds_read_b128 v[52:55], v181 offset:64
	v_exp_f32_e32 v196, v113
	v_exp_f32_e32 v168, v37
	v_exp_f32_e32 v172, v39
	v_exp_f32_e32 v37, v40
	v_exp_f32_e32 v39, v44
	v_exp_f32_e32 v186, v109
	s_waitcnt lgkmcnt(1)
	v_mfma_f32_32x32x16_bf16 v[82:97], v[56:59], v[122:125], v[82:97]
	ds_read_b128 v[56:59], v181 offset:4608
	ds_read_b128 v[60:63], v181 offset:4640
	ds_read_b128 v[150:153], v181 offset:96
	v_exp_f32_e32 v40, v46
	v_exp_f32_e32 v192, v111
	v_exp_f32_e32 v198, v49
	v_add_u32_e32 v183, 0x7800, v149
	v_exp_f32_e32 v51, v98
	v_exp_f32_e32 v64, v35
	s_waitcnt lgkmcnt(2)
	v_mfma_f32_32x32x16_bf16 v[66:81], v[56:59], v[126:129], v[66:81]
	v_exp_f32_e32 v56, v108
	v_exp_f32_e32 v57, v110
	v_exp_f32_e32 v35, v36
	v_exp_f32_e32 v160, v99
	v_exp_f32_e32 v36, v38
	v_exp_f32_e32 v98, v102
	v_exp_f32_e32 v170, v103
	s_waitcnt lgkmcnt(1)
	v_mfma_f32_32x32x16_bf16 v[66:81], v[60:63], v[122:125], v[66:81]
	v_exp_f32_e32 v99, v104
	v_exp_f32_e32 v174, v105
	v_add_f32_e32 v187, v56, v39
	v_add_f32_e32 v193, v57, v40
	v_exp_f32_e32 v194, v47
	v_cvt_pk_bf16_f32 v47, v56, v186
	v_cvt_pk_bf16_f32 v48, v57, v192
	v_mfma_f32_32x32x16_bf16 v[82:97], v[52:55], v[118:121], v[82:97]
	ds_read_b128 v[52:55], v181 offset:4672
	ds_read_b128 v[156:159], v181 offset:4704
	v_exp_f32_e32 v65, v100
	v_exp_f32_e32 v38, v42
	v_exp_f32_e32 v100, v106
	v_exp_f32_e32 v178, v107
	v_add_f32_e32 v171, v98, v36
	v_add_f32_e32 v175, v99, v37
	s_waitcnt lgkmcnt(1)
	v_mfma_f32_32x32x16_bf16 v[66:81], v[52:55], v[118:121], v[66:81]
	v_exp_f32_e32 v52, v112
	v_exp_f32_e32 v190, v45
	v_cvt_pk_bf16_f32 v44, v98, v170
	v_cvt_pk_bf16_f32 v45, v99, v174
	v_add_f32_e32 v197, v52, v41
	v_cvt_pk_bf16_f32 v49, v52, v196
	ds_read_b64_tr_b16 v[52:53], v183 offset:0
	ds_read_b64_tr_b16 v[54:55], v183 offset:0x600
	ds_read_b64_tr_b16 v[56:57], v183 offset:0xc00
	v_mfma_f32_32x32x16_bf16 v[82:97], v[150:153], v[114:117], v[82:97]
	ds_read_b64_tr_b16 v[58:59], v183 offset:0x1200
	ds_read_b64_tr_b16 v[60:61], v183 offset:0x1800
	ds_read_b64_tr_b16 v[62:63], v183 offset:0x1e00
	ds_read_b64_tr_b16 v[98:99], v183 offset:0x2400
	v_exp_f32_e32 v34, v34
	v_exp_f32_e32 v164, v101
	v_add_f32_e32 v179, v100, v38
	s_waitcnt lgkmcnt(0)
	v_mfma_f32_32x32x16_bf16 v[66:81], v[156:159], v[114:117], v[66:81]
	v_exp_f32_e32 v184, v43
	v_cvt_pk_bf16_f32 v46, v100, v178
	ds_read_b64_tr_b16 v[100:101], v183 offset:0x2a00
	s_waitcnt lgkmcnt(0)
	s_mov_b64 s[4:5], 0x6f04200
	v_mov_b32_e32 v163, v1
	v_add_f32_e32 v161, v51, v34
	v_add_f32_e32 v165, v65, v35
	v_cvt_pk_bf16_f32 v34, v34, v64
	v_cvt_pk_bf16_f32 v35, v35, v168
	v_cvt_pk_bf16_f32 v36, v36, v172
	v_cvt_pk_bf16_f32 v37, v37, v176
	v_cvt_pk_bf16_f32 v38, v38, v184
	v_cvt_pk_bf16_f32 v39, v39, v190
	v_cvt_pk_bf16_f32 v40, v40, v194
	v_cvt_pk_bf16_f32 v41, v41, v198
	v_cvt_pk_bf16_f32 v42, v51, v160
	v_cvt_pk_bf16_f32 v43, v65, v164
	ds_read_b64_tr_b16 v[102:103], v183 offset:64
	ds_read_b64_tr_b16 v[104:105], v183 offset:0x640
	ds_read_b64_tr_b16 v[106:107], v183 offset:0xc40
	ds_read_b64_tr_b16 v[108:109], v183 offset:0x1240
	ds_read_b64_tr_b16 v[110:111], v183 offset:0x1840
	ds_read_b64_tr_b16 v[112:113], v183 offset:0x1e40
	ds_read_b64_tr_b16 v[150:151], v183 offset:0x2440
	ds_read_b64_tr_b16 v[152:153], v183 offset:0x2a40
	s_waitcnt lgkmcnt(0)
	v_mfma_f32_32x32x16_bf16 v[18:33], v[52:55], v[34:37], v[18:33]
	v_mov_b32_e32 v65, v1
	v_add_f32_e64 v64, v160, v64
	v_add_f32_e64 v65, v161, v65
	v_readlane_b32 s7, v255, 17
	v_add_f32_e32 v65, v64, v65
	v_add_f32_e32 v64, v64, v64
	v_mov_b32_e32 v169, v65
	v_add_f32_e32 v52, v164, v168
	v_add_f32_e32 v53, v165, v169
	s_add_u32 s22, s7, s6
	v_mfma_f32_32x32x16_bf16 v[2:17], v[102:105], v[34:37], v[2:17]
	v_add_f32_e32 v53, v52, v53
	v_add_f32_e32 v52, v52, v52
	v_mov_b32_e32 v173, v53
	v_add_f32_e32 v52, v170, v172
	v_add_f32_e32 v53, v171, v173
	v_readlane_b32 s6, v255, 18
	v_add_f32_e32 v53, v52, v53
	v_add_f32_e32 v52, v52, v52
	v_mov_b32_e32 v177, v53
	v_add_f32_e32 v52, v174, v176
	v_add_f32_e32 v53, v175, v177
	v_mfma_f32_32x32x16_bf16 v[18:33], v[56:59], v[38:41], v[18:33]
	v_add_f32_e32 v53, v52, v53
	v_add_f32_e32 v52, v52, v52
	v_mov_b32_e32 v185, v53
	v_add_f32_e32 v52, v178, v184
	v_add_f32_e32 v53, v179, v185
	s_addc_u32 s23, s6, 0
	v_add_f32_e32 v53, v52, v53
	v_add_f32_e32 v52, v52, v52
	v_mov_b32_e32 v191, v53
	v_add_f32_e32 v52, v186, v190
	v_add_f32_e32 v53, v187, v191
	v_mfma_f32_32x32x16_bf16 v[2:17], v[106:109], v[38:41], v[2:17]
	v_add_f32_e32 v53, v52, v53
	v_add_f32_e32 v52, v52, v52
	v_mov_b32_e32 v195, v53
	v_add_f32_e32 v52, v192, v194
	v_add_f32_e32 v53, v193, v195
	s_mov_b32 s6, 0
	v_add_f32_e32 v53, v52, v53
	v_add_f32_e32 v52, v52, v52
	v_mov_b32_e32 v199, v53
	v_add_f32_e32 v52, v196, v198
	v_add_f32_e32 v53, v197, v199
	v_mfma_f32_32x32x16_bf16 v[18:33], v[60:63], v[42:45], v[18:33]
	v_add_f32_e32 v51, v52, v53
	v_add_f32_e32 v154, v154, v51
	v_and_b32_e32 v51, 3, v148
	v_lshlrev_b32_e32 v52, 5, v51
	v_mov_b32_e32 v53, v1
	v_lshl_add_u64 v[156:157], v[0:1], 1, v[52:53]
	v_and_b32_e32 v0, 7, v148
	v_mfma_f32_32x32x16_bf16 v[2:17], v[110:113], v[42:45], v[2:17]
	v_lshlrev_b32_e32 v0, 4, v0
	v_lshl_add_u64 v[158:159], v[146:147], 1, v[0:1]
	v_mov_b32_e32 v51, v50
	v_mov_b32_e32 v52, v50
	v_mov_b32_e32 v53, v50
	v_mov_b32_e32 v54, v50
	v_mov_b32_e32 v55, v50
	v_mfma_f32_32x32x16_bf16 v[18:33], v[98:101], v[46:49], v[18:33]
	v_mov_b32_e32 v56, v50
	v_mov_b32_e32 v57, v50
	v_mov_b32_e32 v58, v50
	v_mov_b32_e32 v59, v50
	v_mov_b32_e32 v60, v50
	v_mov_b32_e32 v61, v50
	v_mov_b32_e32 v62, v50
	v_mfma_f32_32x32x16_bf16 v[2:17], v[150:153], v[46:49], v[2:17]
	v_mov_b32_e32 v63, v50
	v_mov_b32_e32 v64, v50
	v_mov_b32_e32 v65, v50
	s_waitcnt vmcnt(3)
	ds_write_b128 v182, v[142:145] offset:9216
	s_waitcnt vmcnt(2)
	ds_write_b128 v182, v[138:141] offset:9232
	s_waitcnt vmcnt(1)
	ds_write_b128 v167, v[130:133] offset:18432
	s_waitcnt vmcnt(0)
	ds_write_b128 v167, v[134:137] offset:24576
	s_waitcnt lgkmcnt(0)
	s_barrier
	s_branch .LBB0_175
.LBB0_174:
	ds_read_b128 v[146:149], v181 offset:4608
	ds_read_b128 v[150:153], v181
	ds_read_b128 v[168:171], v181 offset:32
	ds_read_b128 v[172:175], v181 offset:4640
	v_exp_f32_e32 v154, v98
	v_exp_f32_e32 v185, v67
	s_waitcnt lgkmcnt(2)
	v_mfma_f32_32x32x16_bf16 v[82:97], v[150:153], v[126:129], v[34:49]
	v_exp_f32_e32 v187, v68
	v_exp_f32_e32 v193, v69
	v_exp_f32_e32 v194, v102
	v_exp_f32_e32 v195, v70
	v_exp_f32_e32 v98, v71
	v_exp_f32_e32 v196, v104
	v_exp_f32_e32 v197, v72
	s_waitcnt lgkmcnt(1)
	v_mfma_f32_32x32x16_bf16 v[82:97], v[168:171], v[122:125], v[82:97]
	ds_read_b128 v[168:171], v181 offset:64
	ds_read_b128 v[150:153], v181 offset:4672
	v_exp_f32_e32 v104, v105
	v_exp_f32_e32 v102, v73
	v_exp_f32_e32 v105, v106
	v_exp_f32_e32 v199, v74
	v_exp_f32_e32 v106, v107
	v_exp_f32_e32 v160, v75
	s_waitcnt lgkmcnt(1)
	v_mfma_f32_32x32x16_bf16 v[82:97], v[168:171], v[118:121], v[82:97]
	ds_read_b128 v[168:171], v181 offset:96
	ds_read_b128 v[176:179], v181 offset:4704
	v_exp_f32_e32 v107, v108
	v_exp_f32_e32 v200, v76
	v_exp_f32_e32 v164, v77
	v_exp_f32_e32 v206, v78
	v_exp_f32_e32 v108, v79
	v_exp_f32_e32 v207, v80
	s_waitcnt lgkmcnt(1)
	v_mfma_f32_32x32x16_bf16 v[82:97], v[168:171], v[114:117], v[82:97]
	v_exp_f32_e32 v169, v66
	v_exp_f32_e32 v170, v81
	v_exp_f32_e32 v184, v99
	v_exp_f32_e32 v186, v100
	v_exp_f32_e32 v101, v101
	v_exp_f32_e32 v100, v103
	v_add_f32_e32 v191, v185, v184
	v_mfma_f32_32x32x16_bf16 v[66:81], v[146:149], v[126:129], v[34:49]
	v_exp_f32_e32 v201, v110
	v_exp_f32_e32 v110, v111
	v_exp_f32_e32 v111, v112
	v_cvt_pk_bf16_f32 v146, v154, v184
	v_add_f32_e32 v192, v187, v186
	v_cvt_pk_bf16_f32 v147, v186, v101
	v_add_f32_e32 v99, v195, v194
	v_mfma_f32_32x32x16_bf16 v[66:81], v[172:175], v[122:125], v[66:81]
	v_cvt_pk_bf16_f32 v172, v169, v185
	ds_read_b64_tr_b16 v[184:185], v183 offset:0
	v_cvt_pk_bf16_f32 v173, v187, v193
	ds_read_b64_tr_b16 v[186:187], v183 offset:0x600
	v_cvt_pk_bf16_f32 v148, v194, v100
	v_cvt_pk_bf16_f32 v174, v195, v98
	ds_read_b64_tr_b16 v[194:195], v183 offset:0xc00
	v_mfma_f32_32x32x16_bf16 v[66:81], v[150:153], v[118:121], v[66:81]
	v_add_f32_e32 v103, v197, v196
	v_cvt_pk_bf16_f32 v149, v196, v104
	v_cvt_pk_bf16_f32 v175, v197, v102
	ds_read_b64_tr_b16 v[196:197], v183 offset:0x1200
	v_exp_f32_e32 v168, v109
	v_add_f32_e32 v109, v206, v201
	v_add_f32_e32 v171, v207, v111
	s_waitcnt lgkmcnt(0)
	v_mfma_f32_32x32x16_bf16 v[66:81], v[176:179], v[114:117], v[66:81]
	v_cvt_pk_bf16_f32 v178, v206, v108
	v_cvt_pk_bf16_f32 v179, v207, v170
	ds_read_b64_tr_b16 v[206:207], v183 offset:0x1800
	ds_read_b64_tr_b16 v[208:209], v183 offset:0x1e00
	ds_read_b64_tr_b16 v[210:211], v183 offset:0x2400
	v_exp_f32_e32 v112, v113
	ds_read_b64_tr_b16 v[212:213], v183 offset:0x2a00
	s_waitcnt lgkmcnt(0)
	v_add_f32_e32 v190, v169, v154
	v_add_f32_e32 v198, v193, v101
	v_add_f32_e32 v161, v199, v105
	v_add_f32_e32 v165, v200, v107
	v_cvt_pk_bf16_f32 v150, v105, v106
	v_cvt_pk_bf16_f32 v151, v107, v168
	v_cvt_pk_bf16_f32 v152, v201, v110
	v_cvt_pk_bf16_f32 v153, v111, v112
	v_cvt_pk_bf16_f32 v176, v199, v160
	v_cvt_pk_bf16_f32 v177, v200, v164
	ds_read_b64_tr_b16 v[214:215], v183 offset:64
	ds_read_b64_tr_b16 v[216:217], v183 offset:0x640
	ds_read_b64_tr_b16 v[218:219], v183 offset:0xc40
	ds_read_b64_tr_b16 v[220:221], v183 offset:0x1240
	ds_read_b64_tr_b16 v[222:223], v183 offset:0x1840
	ds_read_b64_tr_b16 v[224:225], v183 offset:0x1e40
	ds_read_b64_tr_b16 v[226:227], v183 offset:0x2440
	ds_read_b64_tr_b16 v[228:229], v183 offset:0x2a40
	s_waitcnt lgkmcnt(0)
	v_mfma_f32_32x32x16_bf16 v[18:33], v[184:187], v[146:149], v[18:33]
	v_add_f32_e32 v101, 0, v190
	v_add_f32_e32 v101, v191, v101
	v_add_f32_e32 v101, v192, v101
	v_add_f32_e32 v101, v198, v101
	v_add_f32_e64 v98, v98, v100
	v_add_f32_e64 v99, v99, v101
	s_add_u32 s22, s22, 0x130000
	v_add_f32_e32 v99, v98, v99
	v_add_f32_e32 v98, v98, v98
	v_mfma_f32_32x32x16_bf16 v[2:17], v[214:217], v[146:149], v[2:17]
	v_mov_b32_e32 v105, v99
	v_add_f32_e64 v98, v102, v104
	v_add_f32_e64 v99, v103, v105
	s_addc_u32 s23, s23, 0
	v_add_f32_e32 v99, v98, v99
	v_add_f32_e32 v98, v98, v98
	v_mov_b32_e32 v107, v99
	v_add_f32_e32 v98, v160, v106
	v_add_f32_e32 v99, v161, v107
	s_add_i32 s6, s6, 2
	v_mfma_f32_32x32x16_bf16 v[18:33], v[194:197], v[150:153], v[18:33]
	v_add_f32_e32 v99, v98, v99
	v_add_f32_e32 v98, v98, v98
	v_mov_b32_e32 v169, v99
	v_add_f32_e32 v98, v164, v168
	v_add_f32_e32 v99, v165, v169
	s_cmpk_gt_u32 s6, 0x7b
	v_add_f32_e32 v99, v98, v99
	v_add_f32_e32 v98, v98, v98
	v_mov_b32_e32 v111, v99
	v_add_f32_e32 v98, v108, v110
	v_add_f32_e32 v99, v109, v111
	v_mfma_f32_32x32x16_bf16 v[2:17], v[218:221], v[150:153], v[2:17]
	v_add_f32_e32 v99, v98, v99
	v_add_f32_e32 v98, v98, v98
	v_mov_b32_e32 v113, v99
	v_add_f32_e32 v98, v170, v112
	v_add_f32_e32 v99, v171, v113
	s_mov_b64 s[4:5], 0x6f04200
	v_add_f32_e32 v98, v98, v99
	v_add_f32_e32 v154, v0, v98
	s_waitcnt vmcnt(3)
	ds_write_b128 v182, v[138:141] offset:9216
	s_waitcnt vmcnt(2)
	ds_write_b128 v182, v[142:145] offset:9232
	v_mfma_f32_32x32x16_bf16 v[18:33], v[206:209], v[172:175], v[18:33]
	s_waitcnt vmcnt(1)
	ds_write_b128 v167, v[130:133] offset:18432
	s_waitcnt vmcnt(0)
	ds_write_b128 v167, v[134:137] offset:24576
	s_waitcnt lgkmcnt(0)
	s_barrier
	v_mfma_f32_32x32x16_bf16 v[2:17], v[222:225], v[172:175], v[2:17]
	v_mfma_f32_32x32x16_bf16 v[18:33], v[210:213], v[176:179], v[18:33]
	v_mfma_f32_32x32x16_bf16 v[2:17], v[226:229], v[176:179], v[2:17]
	s_cbranch_scc1 .LBB0_180
.LBB0_175:
	v_lshl_add_u64 v[152:153], s[22:23], 0, v[156:157]
	v_add_co_u32_e32 v36, vcc, s21, v152
	v_lshl_add_u64 v[34:35], v[152:153], 0, s[4:5]
	v_lshl_add_u64 v[150:151], s[22:23], 0, v[158:159]
	v_addc_co_u32_e32 v37, vcc, 0, v153, vcc
	s_mov_b32 s7, 0x6e6c000
	global_load_dwordx4 v[134:137], v[36:37], off offset:512
	global_load_dwordx4 v[130:133], v[34:35], off offset:16
	v_add_co_u32_e32 v34, vcc, s7, v150
	s_mov_b32 s7, 0x6eb8000
	s_nop 0
	v_addc_co_u32_e32 v35, vcc, 0, v151, vcc
	v_add_co_u32_e32 v36, vcc, s7, v150
	v_max_f32_e32 v0, v66, v66
	s_nop 0
	v_addc_co_u32_e32 v37, vcc, 0, v151, vcc
	global_load_dwordx4 v[138:141], v[34:35], off offset:768
	global_load_dwordx4 v[142:145], v[36:37], off offset:768
	v_max_f32_e32 v34, v82, v82
	v_max_f32_e32 v0, v34, v0
	v_max3_f32 v0, v0, v83, v67
	v_max3_f32 v0, v0, v84, v68
	v_max3_f32 v0, v0, v85, v69
	v_max3_f32 v0, v0, v86, v70
	v_max3_f32 v0, v0, v87, v71
	v_max3_f32 v0, v0, v88, v72
	v_max3_f32 v0, v0, v89, v73
	v_max3_f32 v0, v0, v90, v74
	v_max3_f32 v0, v0, v91, v75
	v_max3_f32 v0, v0, v92, v76
	v_max3_f32 v0, v0, v93, v77
	v_max3_f32 v0, v0, v94, v78
	v_max3_f32 v0, v0, v95, v79
	v_max3_f32 v0, v0, v96, v80
	v_max3_f32 v0, v0, v97, v81
	v_mov_b32_e32 v34, v0
	s_nop 1
	v_permlane32_swap_b32_e32 v0, v34
	v_max_f32_e32 v34, v34, v34
	v_max_f32_e32 v0, v0, v0
	v_max_f32_e32 v0, v0, v34
	v_cmp_lt_f32_e32 vcc, s19, v0
	s_cbranch_vccz .LBB0_177
	v_max_f32_e32 v0, v0, v0
	v_max_f32_e32 v0, 0, v0
	v_exp_f32_e64 v34, -v0
	v_add_f32_e32 v155, v155, v0
	v_add_f32_e64 v82, v82, -v0
	v_add_f32_e64 v83, v83, -v0
	v_add_f32_e64 v66, v66, -v0
	v_add_f32_e64 v67, v67, -v0
	v_mul_f32_e32 v154, v154, v34
	v_mul_f32_e32 v32, v32, v34
	v_mul_f32_e32 v33, v33, v34
	v_mul_f32_e32 v30, v30, v34
	v_mul_f32_e32 v31, v31, v34
	v_mul_f32_e32 v28, v28, v34
	v_mul_f32_e32 v29, v29, v34
	v_mul_f32_e32 v26, v26, v34
	v_mul_f32_e32 v27, v27, v34
	v_mul_f32_e32 v24, v24, v34
	v_mul_f32_e32 v25, v25, v34
	v_mul_f32_e32 v22, v22, v34
	v_mul_f32_e32 v23, v23, v34
	v_mul_f32_e32 v20, v20, v34
	v_mul_f32_e32 v21, v21, v34
	v_mul_f32_e32 v18, v18, v34
	v_mul_f32_e32 v19, v19, v34
	v_mul_f32_e32 v16, v16, v34
	v_mul_f32_e32 v17, v17, v34
	v_mul_f32_e32 v14, v14, v34
	v_mul_f32_e32 v15, v15, v34
	v_mul_f32_e32 v12, v12, v34
	v_mul_f32_e32 v13, v13, v34
	v_mul_f32_e32 v10, v10, v34
	v_mul_f32_e32 v11, v11, v34
	v_mul_f32_e32 v8, v8, v34
	v_mul_f32_e32 v9, v9, v34
	v_mul_f32_e32 v6, v6, v34
	v_mul_f32_e32 v7, v7, v34
	v_mul_f32_e32 v4, v4, v34
	v_mul_f32_e32 v5, v5, v34
	v_mul_f32_e32 v2, v2, v34
	v_mul_f32_e32 v3, v3, v34
	v_xor_b32_e32 v34, 0x80000000, v155
	v_add_f32_e64 v84, v84, -v0
	v_add_f32_e64 v85, v85, -v0
	v_add_f32_e64 v68, v68, -v0
	v_add_f32_e64 v69, v69, -v0
	v_add_f32_e64 v86, v86, -v0
	v_add_f32_e64 v87, v87, -v0
	v_add_f32_e64 v70, v70, -v0
	v_add_f32_e64 v71, v71, -v0
	v_add_f32_e64 v88, v88, -v0
	v_add_f32_e64 v89, v89, -v0
	v_add_f32_e64 v72, v72, -v0
	v_add_f32_e64 v73, v73, -v0
	v_add_f32_e64 v90, v90, -v0
	v_add_f32_e64 v91, v91, -v0
	v_add_f32_e64 v74, v74, -v0
	v_add_f32_e64 v75, v75, -v0
	v_add_f32_e64 v92, v92, -v0
	v_add_f32_e64 v93, v93, -v0
	v_add_f32_e64 v76, v76, -v0
	v_add_f32_e64 v77, v77, -v0
	v_add_f32_e64 v94, v94, -v0
	v_add_f32_e64 v95, v95, -v0
	v_add_f32_e64 v78, v78, -v0
	v_add_f32_e64 v79, v79, -v0
	v_add_f32_e64 v96, v96, -v0
	v_add_f32_e64 v97, v97, -v0
	v_add_f32_e64 v80, v80, -v0
	v_add_f32_e64 v81, v81, -v0
	v_mov_b32_e32 v35, v34
	v_mov_b32_e32 v36, v34
	v_mov_b32_e32 v37, v34
	v_mov_b32_e32 v38, v34
	v_mov_b32_e32 v39, v34
	v_mov_b32_e32 v40, v34
	v_mov_b32_e32 v41, v34
	v_mov_b32_e32 v42, v34
	v_mov_b32_e32 v43, v34
	v_mov_b32_e32 v44, v34
	v_mov_b32_e32 v45, v34
	v_mov_b32_e32 v46, v34
	v_mov_b32_e32 v47, v34
	v_mov_b32_e32 v48, v34
	v_mov_b32_e32 v49, v34
	v_mov_b32_e32 v50, v34
	v_mov_b32_e32 v51, v34
	v_mov_b32_e32 v52, v34
	v_mov_b32_e32 v53, v34
	v_mov_b32_e32 v54, v34
	v_mov_b32_e32 v55, v34
	v_mov_b32_e32 v56, v34
	v_mov_b32_e32 v57, v34
	v_mov_b32_e32 v58, v34
	v_mov_b32_e32 v59, v34
	v_mov_b32_e32 v60, v34
	v_mov_b32_e32 v61, v34
	v_mov_b32_e32 v62, v34
	v_mov_b32_e32 v63, v34
	v_mov_b32_e32 v64, v34
	v_mov_b32_e32 v65, v34
	s_branch .LBB0_178

.LBB0_178:
	ds_read_b128 v[146:149], v181 offset:13824
	ds_read_b128 v[168:171], v181 offset:9216
	ds_read_b128 v[172:175], v181 offset:9248
	ds_read_b128 v[184:187], v181 offset:13856
	v_exp_f32_e32 v177, v66
	v_exp_f32_e32 v164, v67
	s_waitcnt lgkmcnt(2)
	v_mfma_f32_32x32x16_bf16 v[98:113], v[168:171], v[126:129], v[34:49]
	ds_read_b128 v[168:171], v181 offset:9280
	ds_read_b128 v[194:197], v181 offset:13888
	v_exp_f32_e32 v190, v84
	v_exp_f32_e32 v191, v68
	v_exp_f32_e32 v192, v86
	v_exp_f32_e32 v193, v70
	v_exp_f32_e32 v86, v87
	v_exp_f32_e32 v84, v71
	s_waitcnt lgkmcnt(3)
	v_mfma_f32_32x32x16_bf16 v[98:113], v[172:175], v[122:125], v[98:113]
	v_exp_f32_e32 v87, v88
	v_exp_f32_e32 v198, v72
	v_exp_f32_e32 v88, v89
	v_exp_f32_e32 v89, v90
	v_exp_f32_e32 v199, v74
	v_exp_f32_e32 v90, v91
	v_exp_f32_e32 v172, v75
	s_waitcnt lgkmcnt(1)
	v_mfma_f32_32x32x16_bf16 v[98:113], v[168:171], v[118:121], v[98:113]
	ds_read_b128 v[168:171], v181 offset:9312
	ds_read_b128 v[206:209], v181 offset:13920
	v_exp_f32_e32 v91, v92
	v_exp_f32_e32 v200, v76
	v_exp_f32_e32 v174, v77
	v_exp_f32_e32 v210, v78
	v_exp_f32_e32 v92, v79
	v_exp_f32_e32 v211, v80
	s_waitcnt lgkmcnt(1)
	v_mfma_f32_32x32x16_bf16 v[98:113], v[168:171], v[114:117], v[98:113]
	v_exp_f32_e32 v169, v82
	v_exp_f32_e32 v82, v69
	v_exp_f32_e32 v170, v73
	v_exp_f32_e32 v178, v81
	v_exp_f32_e32 v201, v94
	v_exp_f32_e32 v94, v95
	v_exp_f32_e32 v95, v96
	v_mfma_f32_32x32x16_bf16 v[66:81], v[146:149], v[126:129], v[34:49]
	v_exp_f32_e32 v176, v93
	v_add_f32_e32 v93, v210, v201
	v_add_f32_e32 v179, v211, v95
	v_exp_f32_e32 v0, v83
	v_exp_f32_e32 v168, v85
	v_exp_f32_e32 v96, v97
	s_mov_b64 s[4:5], 0x6f9c200
	v_mfma_f32_32x32x16_bf16 v[66:81], v[184:187], v[122:125], v[66:81]
	v_lshl_add_u64 v[160:161], v[152:153], 0, s[4:5]
	v_add_f32_e32 v165, v177, v169
	v_add_f32_e32 v83, v191, v190
	v_add_f32_e32 v85, v193, v192
	v_add_f32_e32 v171, v198, v87
	v_add_f32_e32 v173, v199, v89
	v_add_f32_e32 v175, v200, v91
	v_mfma_f32_32x32x16_bf16 v[66:81], v[194:197], v[118:121], v[66:81]
	v_cvt_pk_bf16_f32 v146, v169, v0
	v_cvt_pk_bf16_f32 v147, v190, v168
	v_cvt_pk_bf16_f32 v148, v192, v86
	v_cvt_pk_bf16_f32 v149, v87, v88
	v_cvt_pk_bf16_f32 v184, v89, v90
	v_cvt_pk_bf16_f32 v185, v91, v176
	v_cvt_pk_bf16_f32 v186, v201, v94
	s_waitcnt lgkmcnt(0)
	v_mfma_f32_32x32x16_bf16 v[66:81], v[206:209], v[114:117], v[66:81]
	v_cvt_pk_bf16_f32 v208, v210, v92
	v_cvt_pk_bf16_f32 v209, v211, v178
	ds_read_b64_tr_b16 v[210:211], v180 offset:0
	ds_read_b64_tr_b16 v[212:213], v180 offset:0x600
	ds_read_b64_tr_b16 v[214:215], v180 offset:0xc00
	ds_read_b64_tr_b16 v[216:217], v180 offset:0x1200
	ds_read_b64_tr_b16 v[218:219], v180 offset:0x1800
	ds_read_b64_tr_b16 v[220:221], v180 offset:0x1e00
	ds_read_b64_tr_b16 v[222:223], v180 offset:0x2400
	ds_read_b64_tr_b16 v[224:225], v180 offset:0x2a00
	s_waitcnt lgkmcnt(0)
	v_cvt_pk_bf16_f32 v187, v95, v96
	v_cvt_pk_bf16_f32 v194, v177, v164
	v_cvt_pk_bf16_f32 v195, v191, v82
	v_cvt_pk_bf16_f32 v196, v193, v84
	v_cvt_pk_bf16_f32 v197, v198, v170
	v_cvt_pk_bf16_f32 v206, v199, v172
	v_cvt_pk_bf16_f32 v207, v200, v174
	ds_read_b64_tr_b16 v[226:227], v180 offset:64
	ds_read_b64_tr_b16 v[228:229], v180 offset:0x640
	ds_read_b64_tr_b16 v[230:231], v180 offset:0xc40
	ds_read_b64_tr_b16 v[232:233], v180 offset:0x1240
	ds_read_b64_tr_b16 v[234:235], v180 offset:0x1840
	ds_read_b64_tr_b16 v[236:237], v180 offset:0x1e40
	ds_read_b64_tr_b16 v[238:239], v180 offset:0x2440
	ds_read_b64_tr_b16 v[240:241], v180 offset:0x2a40
	s_waitcnt lgkmcnt(0)
	s_mov_b32 s4, 0x6f9c000
	s_waitcnt vmcnt(3)
	ds_write_b128 v182, v[134:137]
	s_waitcnt vmcnt(2)
	ds_write_b128 v182, v[130:133] offset:16
	s_waitcnt vmcnt(1)
	ds_write_b128 v167, v[138:141] offset:30720
	s_waitcnt vmcnt(0)
	ds_write_b128 v167, v[142:145] offset:36864
	v_add_co_u32_e32 v130, vcc, s4, v152
	s_waitcnt lgkmcnt(0)
	s_nop 0
	v_addc_co_u32_e32 v131, vcc, 0, v153, vcc
	s_barrier
	global_load_dwordx4 v[138:141], v[130:131], off offset:512
	global_load_dwordx4 v[142:145], v[160:161], off offset:16
	v_add_co_u32_e32 v130, vcc, s21, v150
	s_mov_b32 s7, 0x6f50000
	s_nop 0
	v_addc_co_u32_e32 v131, vcc, 0, v151, vcc
	v_add_co_u32_e32 v134, vcc, s7, v150
	v_mfma_f32_32x32x16_bf16 v[2:17], v[226:229], v[146:149], v[2:17]
	s_nop 0
	v_addc_co_u32_e32 v135, vcc, 0, v151, vcc
	global_load_dwordx4 v[130:133], v[130:131], off offset:768
	s_nop 0
	global_load_dwordx4 v[134:137], v[134:135], off offset:768
	v_add_f32_e64 v150, v164, v0
	v_add_f32_e64 v151, v165, v1
	v_add_f32_e32 v151, v150, v151
	v_add_f32_e32 v150, v150, v150
	v_mov_b32_e32 v169, v151
	v_add_f32_e32 v82, v82, v168
	v_add_f32_e32 v83, v83, v169
	v_mfma_f32_32x32x16_bf16 v[18:33], v[210:213], v[146:149], v[18:33]
	v_add_f32_e32 v83, v82, v83
	v_add_f32_e32 v82, v82, v82
	v_mov_b32_e32 v87, v83
	v_add_f32_e32 v82, v84, v86
	v_add_f32_e32 v83, v85, v87
	s_nop 0
	v_add_f32_e32 v83, v82, v83
	v_add_f32_e32 v82, v82, v82
	v_mov_b32_e32 v89, v83
	v_add_f32_e32 v82, v170, v88
	v_add_f32_e32 v83, v171, v89
	v_mfma_f32_32x32x16_bf16 v[2:17], v[230:233], v[184:187], v[2:17]
	v_add_f32_e32 v83, v82, v83
	v_add_f32_e32 v82, v82, v82
	v_mov_b32_e32 v91, v83
	v_add_f32_e32 v82, v172, v90
	v_add_f32_e32 v83, v173, v91
	s_nop 0
	v_add_f32_e32 v83, v82, v83
	v_add_f32_e32 v82, v82, v82
	v_mov_b32_e32 v177, v83
	v_add_f32_e32 v82, v174, v176
	v_add_f32_e32 v83, v175, v177
	v_mfma_f32_32x32x16_bf16 v[18:33], v[214:217], v[184:187], v[18:33]
	v_add_f32_e32 v83, v82, v83
	v_add_f32_e32 v82, v82, v82
	v_mov_b32_e32 v95, v83
	v_add_f32_e32 v82, v92, v94
	v_add_f32_e32 v83, v93, v95
	s_nop 0
	v_add_f32_e32 v83, v82, v83
	v_add_f32_e32 v82, v82, v82
	v_mov_b32_e32 v97, v83
	v_add_f32_e32 v82, v178, v96
	v_add_f32_e32 v83, v179, v97
	v_mfma_f32_32x32x16_bf16 v[2:17], v[234:237], v[194:197], v[2:17]
	v_add_f32_e32 v0, v82, v83
	v_max_f32_e32 v82, v66, v66
	v_max_f32_e32 v83, v98, v98
	v_max_f32_e32 v82, v83, v82
	v_max3_f32 v82, v82, v99, v67
	v_max3_f32 v82, v82, v100, v68
	v_max3_f32 v82, v82, v101, v69
	v_max3_f32 v82, v82, v102, v70
	v_mfma_f32_32x32x16_bf16 v[18:33], v[218:221], v[194:197], v[18:33]
	v_max3_f32 v82, v82, v103, v71
	v_max3_f32 v82, v82, v104, v72
	v_max3_f32 v82, v82, v105, v73
	v_max3_f32 v82, v82, v106, v74
	v_max3_f32 v82, v82, v107, v75
	v_max3_f32 v82, v82, v108, v76
	v_max3_f32 v82, v82, v109, v77
	v_max3_f32 v82, v82, v110, v78
	v_mfma_f32_32x32x16_bf16 v[2:17], v[238:241], v[206:209], v[2:17]
	v_max3_f32 v82, v82, v111, v79
	v_max3_f32 v82, v82, v112, v80
	v_max3_f32 v82, v82, v113, v81
	v_mov_b32_e32 v83, v82
	s_nop 1
	v_permlane32_swap_b32_e32 v82, v83
	v_max_f32_e32 v83, v83, v83
	v_mfma_f32_32x32x16_bf16 v[18:33], v[222:225], v[206:209], v[18:33]
	v_max_f32_e32 v82, v82, v82
	v_max_f32_e32 v82, v82, v83
	v_add_f32_e32 v0, v154, v0
	v_cmp_lt_f32_e32 vcc, s19, v82
	s_cbranch_vccz .LBB0_174
	v_max_f32_e32 v34, v82, v82
	v_max_f32_e32 v34, 0, v34
	v_exp_f32_e64 v36, -v34
	v_add_f32_e32 v155, v155, v34
	v_add_f32_e64 v98, v98, -v34
	v_add_f32_e64 v99, v99, -v34
	v_add_f32_e64 v66, v66, -v34
	v_add_f32_e64 v67, v67, -v34
	v_add_f32_e64 v100, v100, -v34
	v_add_f32_e64 v101, v101, -v34
	v_add_f32_e64 v68, v68, -v34
	v_add_f32_e64 v69, v69, -v34
	v_add_f32_e64 v102, v102, -v34
	v_add_f32_e64 v103, v103, -v34
	v_add_f32_e64 v70, v70, -v34
	v_add_f32_e64 v71, v71, -v34
	v_add_f32_e64 v104, v104, -v34
	v_add_f32_e64 v105, v105, -v34
	v_add_f32_e64 v72, v72, -v34
	v_add_f32_e64 v73, v73, -v34
	v_add_f32_e64 v106, v106, -v34
	v_add_f32_e64 v107, v107, -v34
	v_add_f32_e64 v74, v74, -v34
	v_add_f32_e64 v75, v75, -v34
	v_add_f32_e64 v108, v108, -v34
	v_add_f32_e64 v109, v109, -v34
	v_add_f32_e64 v76, v76, -v34
	v_add_f32_e64 v77, v77, -v34
	v_add_f32_e64 v110, v110, -v34
	v_add_f32_e64 v111, v111, -v34
	v_add_f32_e64 v78, v78, -v34
	v_add_f32_e64 v79, v79, -v34
	v_add_f32_e64 v112, v112, -v34
	v_add_f32_e64 v113, v113, -v34
	v_add_f32_e64 v80, v80, -v34
	v_add_f32_e64 v81, v81, -v34
	v_xor_b32_e32 v34, 0x80000000, v155
	v_mul_f32_e32 v0, v0, v36
	v_mul_f32_e32 v32, v32, v36
	v_mul_f32_e32 v33, v33, v36
	v_mul_f32_e32 v30, v30, v36
	v_mul_f32_e32 v31, v31, v36
	v_mul_f32_e32 v28, v28, v36
	v_mul_f32_e32 v29, v29, v36
	v_mul_f32_e32 v26, v26, v36
	v_mul_f32_e32 v27, v27, v36
	v_mul_f32_e32 v24, v24, v36
	v_mul_f32_e32 v25, v25, v36
	v_mul_f32_e32 v22, v22, v36
	v_mul_f32_e32 v23, v23, v36
	v_mul_f32_e32 v20, v20, v36
	v_mul_f32_e32 v21, v21, v36
	v_mul_f32_e32 v18, v18, v36
	v_mul_f32_e32 v19, v19, v36
	v_mul_f32_e32 v16, v16, v36
	v_mul_f32_e32 v17, v17, v36
	v_mul_f32_e32 v14, v14, v36
	v_mul_f32_e32 v15, v15, v36
	v_mul_f32_e32 v12, v12, v36
	v_mul_f32_e32 v13, v13, v36
	v_mul_f32_e32 v10, v10, v36
	v_mul_f32_e32 v11, v11, v36
	v_mul_f32_e32 v8, v8, v36
	v_mul_f32_e32 v9, v9, v36
	v_mul_f32_e32 v6, v6, v36
	v_mul_f32_e32 v7, v7, v36
	v_mul_f32_e32 v4, v4, v36
	v_mul_f32_e32 v5, v5, v36
	v_mul_f32_e32 v2, v2, v36
	v_mul_f32_e32 v3, v3, v36
	v_mov_b32_e32 v35, v34
	v_mov_b32_e32 v36, v34
	v_mov_b32_e32 v37, v34
	v_mov_b32_e32 v38, v34
	v_mov_b32_e32 v39, v34
	v_mov_b32_e32 v40, v34
	v_mov_b32_e32 v41, v34
	v_mov_b32_e32 v42, v34
	v_mov_b32_e32 v43, v34
	v_mov_b32_e32 v44, v34
	v_mov_b32_e32 v45, v34
	v_mov_b32_e32 v46, v34
	v_mov_b32_e32 v47, v34
	v_mov_b32_e32 v48, v34
	v_mov_b32_e32 v49, v34
	v_mov_b32_e32 v50, v34
	v_mov_b32_e32 v51, v34
	v_mov_b32_e32 v52, v34
	v_mov_b32_e32 v53, v34
	v_mov_b32_e32 v54, v34
	v_mov_b32_e32 v55, v34
	v_mov_b32_e32 v56, v34
	v_mov_b32_e32 v57, v34
	v_mov_b32_e32 v58, v34
	v_mov_b32_e32 v59, v34
	v_mov_b32_e32 v60, v34
	v_mov_b32_e32 v61, v34
	v_mov_b32_e32 v62, v34
	v_mov_b32_e32 v63, v34
	v_mov_b32_e32 v64, v34
	v_mov_b32_e32 v65, v34
	s_branch .LBB0_174
.LBB0_180:
	v_lshl_add_u64 v[50:51], s[22:23], 0, v[158:159]
	v_add_co_u32_e32 v52, vcc, 0x6e6c000, v50
	v_max_f32_e32 v0, v66, v66
	s_nop 0
	v_addc_co_u32_e32 v53, vcc, 0, v51, vcc
	v_add_co_u32_e32 v50, vcc, 0x6eb8000, v50
	s_nop 1
	v_addc_co_u32_e32 v51, vcc, 0, v51, vcc
	global_load_dwordx4 v[98:101], v[52:53], off offset:768
	global_load_dwordx4 v[102:105], v[50:51], off offset:768
	v_max_f32_e32 v50, v82, v82
	v_max_f32_e32 v0, v50, v0
	v_max3_f32 v0, v0, v83, v67
	v_max3_f32 v0, v0, v84, v68
	v_max3_f32 v0, v0, v85, v69
	v_max3_f32 v0, v0, v86, v70
	v_max3_f32 v0, v0, v87, v71
	v_max3_f32 v0, v0, v88, v72
	v_max3_f32 v0, v0, v89, v73
	v_max3_f32 v0, v0, v90, v74
	v_max3_f32 v0, v0, v91, v75
	v_max3_f32 v0, v0, v92, v76
	v_max3_f32 v0, v0, v93, v77
	v_max3_f32 v0, v0, v94, v78
	v_max3_f32 v0, v0, v95, v79
	v_max3_f32 v0, v0, v96, v80
	v_max3_f32 v0, v0, v97, v81
	v_mov_b32_e32 v50, v0
	s_nop 1
	v_permlane32_swap_b32_e32 v0, v50
	v_max_f32_e32 v50, v50, v50
	v_max_f32_e32 v0, v0, v0
	v_max_f32_e32 v0, v0, v50
	v_cmp_lt_f32_e32 vcc, s19, v0
	s_cbranch_vccz .LBB0_182
	v_max_f32_e32 v0, v0, v0
	v_max_f32_e32 v0, 0, v0
	v_exp_f32_e64 v34, -v0
	v_add_f32_e64 v82, v82, -v0
	v_add_f32_e64 v83, v83, -v0
	v_add_f32_e64 v66, v66, -v0
	v_add_f32_e64 v67, v67, -v0
	v_add_f32_e64 v84, v84, -v0
	v_add_f32_e64 v85, v85, -v0
	v_add_f32_e64 v68, v68, -v0
	v_add_f32_e64 v69, v69, -v0
	v_add_f32_e64 v86, v86, -v0
	v_add_f32_e64 v87, v87, -v0
	v_add_f32_e64 v70, v70, -v0
	v_add_f32_e64 v71, v71, -v0
	v_add_f32_e64 v88, v88, -v0
	v_add_f32_e64 v89, v89, -v0
	v_add_f32_e64 v72, v72, -v0
	v_add_f32_e64 v73, v73, -v0
	v_add_f32_e64 v90, v90, -v0
	v_add_f32_e64 v91, v91, -v0
	v_add_f32_e64 v74, v74, -v0
	v_add_f32_e64 v75, v75, -v0
	v_add_f32_e64 v92, v92, -v0
	v_add_f32_e64 v93, v93, -v0
	v_add_f32_e64 v76, v76, -v0
	v_add_f32_e64 v77, v77, -v0
	v_add_f32_e64 v94, v94, -v0
	v_add_f32_e64 v95, v95, -v0
	v_add_f32_e64 v78, v78, -v0
	v_add_f32_e64 v79, v79, -v0
	v_add_f32_e64 v96, v96, -v0
	v_add_f32_e64 v97, v97, -v0
	v_add_f32_e64 v80, v80, -v0
	v_add_f32_e64 v81, v81, -v0
	v_add_f32_e32 v0, v155, v0
	v_mul_f32_e32 v154, v154, v34
	v_mul_f32_e32 v32, v32, v34
	v_mul_f32_e32 v33, v33, v34
	v_mul_f32_e32 v30, v30, v34
	v_mul_f32_e32 v31, v31, v34
	v_mul_f32_e32 v28, v28, v34
	v_mul_f32_e32 v29, v29, v34
	v_mul_f32_e32 v26, v26, v34
	v_mul_f32_e32 v27, v27, v34
	v_mul_f32_e32 v24, v24, v34
	v_mul_f32_e32 v25, v25, v34
	v_mul_f32_e32 v22, v22, v34
	v_mul_f32_e32 v23, v23, v34
	v_mul_f32_e32 v20, v20, v34
	v_mul_f32_e32 v21, v21, v34
	v_mul_f32_e32 v18, v18, v34
	v_mul_f32_e32 v19, v19, v34
	v_mul_f32_e32 v16, v16, v34
	v_mul_f32_e32 v17, v17, v34
	v_mul_f32_e32 v14, v14, v34
	v_mul_f32_e32 v15, v15, v34
	v_mul_f32_e32 v12, v12, v34
	v_mul_f32_e32 v13, v13, v34
	v_mul_f32_e32 v10, v10, v34
	v_mul_f32_e32 v11, v11, v34
	v_mul_f32_e32 v8, v8, v34
	v_mul_f32_e32 v9, v9, v34
	v_mul_f32_e32 v6, v6, v34
	v_mul_f32_e32 v7, v7, v34
	v_mul_f32_e32 v4, v4, v34
	v_mul_f32_e32 v5, v5, v34
	v_mul_f32_e32 v2, v2, v34
	v_mul_f32_e32 v3, v3, v34
	v_xor_b32_e32 v34, 0x80000000, v0
	v_mov_b32_e32 v35, v34
	v_mov_b32_e32 v36, v34
	v_mov_b32_e32 v37, v34
	v_mov_b32_e32 v38, v34
	v_mov_b32_e32 v39, v34
	v_mov_b32_e32 v40, v34
	v_mov_b32_e32 v41, v34
	v_mov_b32_e32 v42, v34
	v_mov_b32_e32 v43, v34
	v_mov_b32_e32 v44, v34
	v_mov_b32_e32 v45, v34
	v_mov_b32_e32 v46, v34
	v_mov_b32_e32 v47, v34
	v_mov_b32_e32 v48, v34
	v_mov_b32_e32 v49, v34
	v_mov_b32_e32 v190, 0x358637bd
	s_branch .LBB0_183

.LBB0_183:
	ds_read_b128 v[106:109], v181 offset:9216
	ds_read_b128 v[110:113], v181 offset:9248
	ds_read_b128 v[130:133], v181 offset:13824
	ds_read_b128 v[134:137], v181 offset:13856
	ds_read_b128 v[138:141], v181 offset:9280
	ds_read_b128 v[142:145], v181 offset:9312
	s_waitcnt lgkmcnt(5)
	v_mfma_f32_32x32x16_bf16 v[50:65], v[106:109], v[126:129], v[34:49]
	ds_read_b128 v[106:109], v181 offset:13888
	ds_read_b128 v[146:149], v181 offset:13920
	v_exp_f32_e32 v96, v96
	v_exp_f32_e32 v150, v82
	v_exp_f32_e32 v151, v66
	v_exp_f32_e32 v0, v83
	v_exp_f32_e32 v82, v67
	v_exp_f32_e32 v67, v84
	s_waitcnt lgkmcnt(5)
	v_mfma_f32_32x32x16_bf16 v[34:49], v[130:133], v[126:129], v[34:49]
	v_exp_f32_e32 v152, v68
	v_exp_f32_e32 v66, v85
	v_exp_f32_e32 v68, v69
	v_exp_f32_e32 v153, v70
	v_exp_f32_e32 v70, v87
	v_exp_f32_e32 v84, v71
	v_exp_f32_e32 v71, v88
	v_mfma_f32_32x32x16_bf16 v[50:65], v[110:113], v[122:125], v[50:65]
	v_exp_f32_e32 v110, v86
	v_exp_f32_e32 v86, v73
	v_exp_f32_e32 v73, v90
	v_exp_f32_e32 v90, v77
	v_exp_f32_e32 v77, v78
	v_exp_f32_e32 v78, v81
	v_exp_f32_e32 v111, v92
	s_waitcnt lgkmcnt(4)
	v_mfma_f32_32x32x16_bf16 v[34:49], v[134:137], v[122:125], v[34:49]
	v_exp_f32_e32 v122, v80
	v_exp_f32_e32 v92, v79
	v_exp_f32_e32 v88, v75
	v_exp_f32_e32 v75, v94
	v_add_f32_e32 v79, v122, v96
	v_exp_f32_e32 v94, v95
	v_exp_f32_e32 v80, v97
	s_waitcnt lgkmcnt(3)
	v_mfma_f32_32x32x16_bf16 v[50:65], v[138:141], v[118:121], v[50:65]
	v_exp_f32_e32 v138, v72
	v_exp_f32_e32 v72, v89
	v_exp_f32_e32 v139, v74
	v_exp_f32_e32 v140, v76
	v_exp_f32_e32 v74, v91
	v_exp_f32_e32 v76, v93
	v_xor_b32_e32 v191, 16, v204
	s_waitcnt lgkmcnt(1)
	v_mfma_f32_32x32x16_bf16 v[34:49], v[106:109], v[118:121], v[34:49]
	v_cvt_pk_bf16_f32 v121, v122, v78
	ds_read_b64_tr_b16 v[122:123], v180 offset:0
	ds_read_b64_tr_b16 v[124:125], v180 offset:0x600
	ds_read_b64_tr_b16 v[126:127], v180 offset:0xc00
	ds_read_b64_tr_b16 v[128:129], v180 offset:0x1200
	ds_read_b64_tr_b16 v[130:131], v180 offset:0x1800
	ds_read_b64_tr_b16 v[132:133], v180 offset:0x1e00
	v_mfma_f32_32x32x16_bf16 v[50:65], v[142:145], v[114:117], v[50:65]
	ds_read_b64_tr_b16 v[134:135], v180 offset:0x2400
	ds_read_b64_tr_b16 v[136:137], v180 offset:0x2a00
	s_waitcnt lgkmcnt(0)
	v_xor_b32_e32 v192, 8, v204
	v_xor_b32_e32 v193, 4, v204
	v_xor_b32_e32 v194, 2, v204
	v_xor_b32_e32 v195, 1, v204
	s_waitcnt lgkmcnt(0)
	v_mfma_f32_32x32x16_bf16 v[34:49], v[146:149], v[114:117], v[34:49]
	v_add_f32_e32 v83, v151, v150
	v_add_f32_e32 v69, v152, v67
	v_add_f32_e32 v85, v153, v110
	v_add_f32_e32 v87, v138, v71
	v_add_f32_e32 v89, v139, v73
	v_add_f32_e32 v91, v140, v111
	v_add_f32_e32 v93, v77, v75
	v_cvt_pk_bf16_f32 v106, v150, v0
	v_cvt_pk_bf16_f32 v107, v67, v66
	v_cvt_pk_bf16_f32 v108, v110, v70
	v_cvt_pk_bf16_f32 v109, v71, v72
	v_cvt_pk_bf16_f32 v110, v73, v74
	v_cvt_pk_bf16_f32 v111, v111, v76
	v_cvt_pk_bf16_f32 v112, v75, v94
	v_cvt_pk_bf16_f32 v113, v96, v80
	v_cvt_pk_bf16_f32 v114, v151, v82
	v_cvt_pk_bf16_f32 v115, v152, v68
	v_cvt_pk_bf16_f32 v116, v153, v84
	v_cvt_pk_bf16_f32 v117, v138, v86
	v_cvt_pk_bf16_f32 v118, v139, v88
	v_cvt_pk_bf16_f32 v119, v140, v90
	v_cvt_pk_bf16_f32 v120, v77, v92
	ds_read_b64_tr_b16 v[138:139], v180 offset:64
	ds_read_b64_tr_b16 v[140:141], v180 offset:0x640
	ds_read_b64_tr_b16 v[142:143], v180 offset:0xc40
	ds_read_b64_tr_b16 v[144:145], v180 offset:0x1240
	ds_read_b64_tr_b16 v[146:147], v180 offset:0x1840
	ds_read_b64_tr_b16 v[148:149], v180 offset:0x1e40
	ds_read_b64_tr_b16 v[150:151], v180 offset:0x2440
	ds_read_b64_tr_b16 v[152:153], v180 offset:0x2a40
	s_waitcnt lgkmcnt(0)
	v_max_f32_e32 v67, v34, v34
	v_max_f32_e32 v71, v50, v50
	v_max_f32_e32 v67, v71, v67
	v_max3_f32 v67, v67, v51, v35
	v_max3_f32 v67, v67, v52, v36
	v_max3_f32 v67, v67, v53, v37
	v_max3_f32 v67, v67, v54, v38
	v_max3_f32 v67, v67, v55, v39
	v_max3_f32 v67, v67, v56, v40
	v_max3_f32 v67, v67, v57, v41
	v_max3_f32 v67, v67, v58, v42
	v_mfma_f32_32x32x16_bf16 v[18:33], v[122:125], v[106:109], v[18:33]
	v_max3_f32 v67, v67, v59, v43
	v_max3_f32 v67, v67, v60, v44
	v_max3_f32 v67, v67, v61, v45
	v_max3_f32 v67, v67, v62, v46
	v_max3_f32 v67, v67, v63, v47
	v_add_f32_e32 v82, v82, v0
	v_add_f32_e32 v83, v83, v1
	v_max3_f32 v67, v67, v64, v48
	v_mfma_f32_32x32x16_bf16 v[2:17], v[138:141], v[106:109], v[2:17]
	v_add_f32_e32 v83, v82, v83
	v_add_f32_e32 v82, v82, v82
	v_max3_f32 v96, v67, v65, v49
	v_mov_b32_e32 v67, v83
	v_add_f32_e32 v66, v68, v66
	v_add_f32_e32 v67, v69, v67
	s_waitcnt vmcnt(1)
	ds_write_b128 v167, v[98:101] offset:30720
	s_waitcnt vmcnt(0)
	ds_write_b128 v167, v[102:105] offset:36864
	v_add_f32_e32 v67, v66, v67
	v_add_f32_e32 v66, v66, v66
	v_mov_b32_e32 v71, v67
	v_mfma_f32_32x32x16_bf16 v[18:33], v[126:129], v[110:113], v[18:33]
	v_add_f32_e64 v66, v84, v70
	v_add_f32_e64 v67, v85, v71
	s_waitcnt lgkmcnt(0)
	v_add_f32_e32 v67, v66, v67
	v_add_f32_e32 v66, v66, v66
	v_mov_b32_e32 v73, v67
	v_add_f32_e32 v66, v86, v72
	v_add_f32_e32 v67, v87, v73
	s_barrier
	v_add_f32_e32 v67, v66, v67
	v_add_f32_e32 v66, v66, v66
	v_mfma_f32_32x32x16_bf16 v[2:17], v[142:145], v[110:113], v[2:17]
	v_mov_b32_e32 v75, v67
	v_add_f32_e64 v66, v88, v74
	v_add_f32_e64 v67, v89, v75
	v_add_f32_e32 v67, v66, v67
	v_add_f32_e32 v66, v66, v66
	v_mov_b32_e32 v77, v67
	v_add_f32_e32 v66, v90, v76
	v_add_f32_e32 v67, v91, v77
	v_mfma_f32_32x32x16_bf16 v[18:33], v[130:133], v[114:117], v[18:33]
	v_add_f32_e32 v67, v66, v67
	v_add_f32_e32 v66, v66, v66
	v_mov_b32_e32 v95, v67
	v_add_f32_e32 v66, v92, v94
	v_add_f32_e32 v67, v93, v95
	s_nop 0
	v_add_f32_e32 v67, v66, v67
	v_add_f32_e32 v66, v66, v66
	v_mov_b32_e32 v81, v67
	v_add_f32_e32 v66, v78, v80
	v_add_f32_e32 v67, v79, v81
	v_mfma_f32_32x32x16_bf16 v[2:17], v[146:149], v[114:117], v[2:17]
	v_add_f32_e32 v0, v66, v67
	v_add_f32_e32 v66, v154, v0
	v_mov_b32_e32 v0, v96
	s_nop 1
	v_permlane32_swap_b32_e32 v96, v0
	v_max_f32_e32 v0, v0, v0
	v_max_f32_e32 v67, v96, v96
	v_mfma_f32_32x32x16_bf16 v[18:33], v[134:137], v[118:121], v[18:33]
	v_max_f32_e32 v0, v67, v0
	v_cmp_lt_f32_e32 vcc, s19, v0
	v_mfma_f32_32x32x16_bf16 v[2:17], v[150:153], v[118:121], v[2:17]
	s_cbranch_vccz .LBB0_185
; DI float frcp(float x) { return __builtin_amdgcn_rcpf(x); }
; template <int DQK, bool FIXEDM>
; DI void attn_dense_mfma(const bf16_t* Qb, int ldq, const bf16_t* Kb, int ldk, const bf16_t* Vb, int ldv, bf16_t* gate_io, char* smem, bool store, float mbound) {
;     ...
;   const float inv = frcp(half_swap_sum(l_run));
	v_max_f32_e32 v0, v0, v0
	v_max_f32_e32 v0, 0, v0
	v_exp_f32_e64 v68, -v0
	v_add_f32_e64 v50, v50, -v0
	v_add_f32_e64 v51, v51, -v0
	v_add_f32_e64 v34, v34, -v0
	v_add_f32_e64 v35, v35, -v0
	v_add_f32_e64 v52, v52, -v0
	v_add_f32_e64 v53, v53, -v0
	s_nop 4
	v_mul_f32_e32 v16, v16, v68
	v_mul_f32_e32 v17, v17, v68
	v_mul_f32_e32 v14, v14, v68
	v_mul_f32_e32 v15, v15, v68
	v_mul_f32_e32 v12, v12, v68
	v_mul_f32_e32 v13, v13, v68
	v_mul_f32_e32 v10, v10, v68
	v_mul_f32_e32 v11, v11, v68
	v_mul_f32_e32 v8, v8, v68
	v_mul_f32_e32 v9, v9, v68
	v_mul_f32_e32 v6, v6, v68
	v_mul_f32_e32 v7, v7, v68
	v_mul_f32_e32 v4, v4, v68
	v_mul_f32_e32 v5, v5, v68
	v_mul_f32_e32 v2, v2, v68
	v_mul_f32_e32 v3, v3, v68
	v_add_f32_e64 v36, v36, -v0
	v_add_f32_e64 v37, v37, -v0
	v_add_f32_e64 v54, v54, -v0
	v_add_f32_e64 v55, v55, -v0
	v_add_f32_e64 v38, v38, -v0
	v_add_f32_e64 v39, v39, -v0
	v_add_f32_e64 v56, v56, -v0
	v_add_f32_e64 v57, v57, -v0
	v_add_f32_e64 v40, v40, -v0
	v_add_f32_e64 v41, v41, -v0
	v_add_f32_e64 v58, v58, -v0
	v_add_f32_e64 v59, v59, -v0
	v_add_f32_e64 v42, v42, -v0
	v_add_f32_e64 v43, v43, -v0
	v_add_f32_e64 v60, v60, -v0
	v_add_f32_e64 v61, v61, -v0
	v_add_f32_e64 v44, v44, -v0
	v_add_f32_e64 v45, v45, -v0
	v_add_f32_e64 v62, v62, -v0
	v_add_f32_e64 v63, v63, -v0
	v_add_f32_e64 v46, v46, -v0
	v_add_f32_e64 v47, v47, -v0
	v_add_f32_e64 v64, v64, -v0
	v_add_f32_e64 v65, v65, -v0
	v_add_f32_e64 v48, v48, -v0
	v_add_f32_e64 v49, v49, -v0
	v_mul_f32_e32 v32, v32, v68
	v_mul_f32_e32 v33, v33, v68
	v_mul_f32_e32 v30, v30, v68
	v_mul_f32_e32 v31, v31, v68
	v_mul_f32_e32 v28, v28, v68
	v_mul_f32_e32 v29, v29, v68
	v_mul_f32_e32 v26, v26, v68
	v_mul_f32_e32 v27, v27, v68
	v_mul_f32_e32 v24, v24, v68
	v_mul_f32_e32 v25, v25, v68
	v_mul_f32_e32 v22, v22, v68
	v_mul_f32_e32 v23, v23, v68
	v_mul_f32_e32 v20, v20, v68
	v_mul_f32_e32 v21, v21, v68
	v_mul_f32_e32 v18, v18, v68
	v_mul_f32_e32 v19, v19, v68
	v_mul_f32_e32 v66, v66, v68
.LBB0_185:
	v_exp_f32_e32 v67, v50
	v_exp_f32_e32 v70, v34
	v_exp_f32_e32 v0, v51
	v_exp_f32_e32 v50, v35
	v_exp_f32_e32 v71, v36
	v_add_f32_e32 v51, v70, v67
	v_add_f32_e32 v34, v50, v0
	v_add_f32_e32 v35, v51, v1
	s_nop 0
	v_add_f32_e32 v68, v34, v34
	v_add_f32_e32 v69, v34, v35
	v_exp_f32_e32 v51, v52
	v_exp_f32_e32 v68, v53
	v_exp_f32_e32 v52, v37
	v_add_f32_e32 v53, v71, v51
	v_add_f32_e32 v34, v52, v68
	v_add_f32_e32 v35, v53, v69
	s_nop 0
	v_add_f32_e32 v36, v34, v34
	v_add_f32_e32 v37, v34, v35
	v_exp_f32_e32 v53, v54
	v_exp_f32_e32 v69, v38
	v_exp_f32_e32 v36, v55
	v_exp_f32_e32 v54, v39
	v_add_f32_e32 v55, v69, v53
	v_add_f32_e32 v34, v54, v36
	v_add_f32_e32 v35, v55, v37
	s_nop 0
	v_add_f32_e32 v38, v34, v34
	v_add_f32_e32 v39, v34, v35
	v_exp_f32_e32 v37, v56
	v_exp_f32_e32 v55, v40
	v_exp_f32_e32 v38, v57
	v_exp_f32_e32 v56, v41
	v_cvt_pk_bf16_f32 v36, v53, v36
	v_add_f32_e32 v57, v55, v37
	v_cvt_pk_bf16_f32 v37, v37, v38
	v_add_f32_e32 v34, v56, v38
	v_add_f32_e32 v35, v57, v39
	v_exp_f32_e32 v39, v58
	v_add_f32_e32 v40, v34, v34
	v_add_f32_e32 v41, v34, v35
	v_exp_f32_e32 v57, v42
	v_exp_f32_e32 v40, v59
	v_exp_f32_e32 v58, v43
	v_add_f32_e32 v59, v57, v39
	v_cvt_pk_bf16_f32 v38, v39, v40
	v_add_f32_e32 v34, v58, v40
	v_add_f32_e32 v35, v59, v41
	v_exp_f32_e32 v41, v60
	v_add_f32_e32 v42, v34, v34
	v_add_f32_e32 v43, v34, v35
	v_exp_f32_e32 v59, v44
	v_exp_f32_e32 v42, v61
	v_exp_f32_e32 v60, v45
	v_add_f32_e32 v61, v59, v41
	v_cvt_pk_bf16_f32 v39, v41, v42
	v_add_f32_e32 v34, v60, v42
	v_add_f32_e32 v35, v61, v43
	v_exp_f32_e32 v43, v62
	v_add_f32_e32 v44, v34, v34
	v_add_f32_e32 v45, v34, v35
	v_exp_f32_e32 v61, v46
	v_exp_f32_e32 v44, v63
	v_exp_f32_e32 v62, v47
	v_cvt_pk_bf16_f32 v42, v70, v50
	v_add_f32_e32 v63, v61, v43
	v_cvt_pk_bf16_f32 v40, v43, v44
	v_add_f32_e32 v34, v62, v44
	v_add_f32_e32 v35, v63, v45
	v_exp_f32_e32 v45, v64
	v_add_f32_e32 v46, v34, v34
	v_add_f32_e32 v47, v34, v35
	v_exp_f32_e32 v63, v48
	v_exp_f32_e32 v46, v65
	v_exp_f32_e32 v64, v49
	v_cvt_pk_bf16_f32 v43, v71, v52
	v_add_f32_e32 v65, v63, v45
	v_cvt_pk_bf16_f32 v41, v45, v46
	v_add_f32_e32 v34, v64, v46
	v_add_f32_e32 v35, v65, v47
	v_cvt_pk_bf16_f32 v44, v69, v54
	v_add_f32_e32 v72, v34, v35
	v_cvt_pk_bf16_f32 v35, v51, v68
	ds_read_b64_tr_b16 v[50:51], v183 offset:0
	ds_read_b64_tr_b16 v[52:53], v183 offset:0x600
	v_cvt_pk_bf16_f32 v45, v55, v56
	ds_read_b64_tr_b16 v[54:55], v183 offset:0xc00
	v_cvt_pk_bf16_f32 v46, v57, v58
	ds_read_b64_tr_b16 v[56:57], v183 offset:0x1200
	v_cvt_pk_bf16_f32 v47, v59, v60
	ds_read_b64_tr_b16 v[58:59], v183 offset:0x1800
	v_cvt_pk_bf16_f32 v48, v61, v62
	ds_read_b64_tr_b16 v[60:61], v183 offset:0x1e00
	v_cvt_pk_bf16_f32 v49, v63, v64
	ds_read_b64_tr_b16 v[62:63], v183 offset:0x2400
	ds_read_b64_tr_b16 v[64:65], v183 offset:0x2a00
	s_waitcnt lgkmcnt(0)
	v_cvt_pk_bf16_f32 v34, v67, v0
	s_nop 1
	v_mfma_f32_32x32x16_bf16 v[18:33], v[50:53], v[34:37], v[18:33]
	ds_read_b64_tr_b16 v[50:51], v183 offset:64
	ds_read_b64_tr_b16 v[52:53], v183 offset:0x640
	v_mfma_f32_32x32x16_bf16 v[18:33], v[54:57], v[38:41], v[18:33]
	ds_read_b64_tr_b16 v[54:55], v183 offset:0xc40
	ds_read_b64_tr_b16 v[56:57], v183 offset:0x1240
	v_mfma_f32_32x32x16_bf16 v[18:33], v[58:61], v[42:45], v[18:33]
	ds_read_b64_tr_b16 v[58:59], v183 offset:0x1840
	ds_read_b64_tr_b16 v[60:61], v183 offset:0x1e40
	v_mfma_f32_32x32x16_bf16 v[18:33], v[62:65], v[46:49], v[18:33]
	ds_read_b64_tr_b16 v[62:63], v183 offset:0x2440
	ds_read_b64_tr_b16 v[64:65], v183 offset:0x2a40
	s_waitcnt lgkmcnt(0)
	v_mfma_f32_32x32x16_bf16 v[2:17], v[50:53], v[34:37], v[2:17]
	v_add_f32_e32 v0, v66, v72
	v_mov_b32_e32 v34, v0
	s_nop 1
	v_permlane32_swap_b32_e32 v0, v34
	v_add_f32_e32 v0, v0, v34
	v_rcp_f32_e32 v34, v0
	v_mfma_f32_32x32x16_bf16 v[2:17], v[54:57], v[38:41], v[2:17]
	s_barrier
	v_mfma_f32_32x32x16_bf16 v[2:17], v[58:61], v[42:45], v[2:17]
	v_mfma_f32_32x32x16_bf16 v[2:17], v[62:65], v[46:49], v[2:17]

; #define BLO(u) __uint_as_float((u) << 16)
; #define BHI(u) __uint_as_float((u) & 0xffff0000u)
; DI void mla_item(const Params& p, int l, int item, char* smem) {
;     ...
;     for (int rep = 0; rep < 3; ++rep) {
;       const int u = rep * 256 + tid, tl = u / 6, slot = u - tl * 6;
;       const size_t t = (size_t)it * 128 + tl; const int pos = (int)(t & (SEQ - 1));
;       bf16_t* hp = P_PROJ + t * PW + (slot < 4 ? C_BQ + slot * 64 : C_BK + (slot - 4) * 64);
;       const float* g = (slot < 4 ? p.gq_g : p.gk_g) + l * 64;
;       uint4 q[8];
; #pragma unroll
;       for (int c = 0; c < 8; ++c) q[c] = *(const uint4*)(hp + c * 8);
;       float ss = 0.f;
; #pragma unroll
;       for (int c = 0; c < 8; ++c) {
;         float f;
;         f = BLO(q[c].x); ss += f * f; f = BHI(q[c].x); ss += f * f; f = BLO(q[c].y); ss += f * f; f = BHI(q[c].y); ss += f * f;
;         f = BLO(q[c].z); ss += f * f; f = BHI(q[c].z); ss += f * f; f = BLO(q[c].w); ss += f * f; f = BHI(q[c].w); ss += f * f;
;       }
;       float sc = rsqrtf(ss * (1.0f / 64.0f) + 1e-6f);
.LBB0_213:
	v_mul_hi_u32 v0, v159, s33
	v_lshrrev_b32_e32 v0, 2, v0
	s_movk_i32 s0, 0x180
	v_mul_lo_u32 v2, v0, s0
	v_mul_lo_u32 v0, v0, 6
	v_sub_u32_e32 v3, v157, v0
	v_add_u32_e32 v0, s6, v157
	v_mul_hi_u32 v80, v0, s33
	v_lshrrev_b32_e32 v0, 2, v80
	v_lshl_add_u64 v[82:83], s[22:23], 0, v[0:1]
	v_mov_b64_e32 v[4:5], s[12:13]
	v_sub_u32_e32 v2, v158, v2
	v_add_u32_e32 v3, s6, v3
	v_mad_u64_u32 v[4:5], s[0:1], v82, s4, v[4:5]
	v_mad_u32_u24 v5, v83, s4, v5
	v_cmp_gt_i32_e32 vcc, 4, v3
	v_ashrrev_i32_e32 v3, 31, v2
	v_lshl_add_u64 v[34:35], v[2:3], 1, v[4:5]
	v_mov_b32_e32 v0, s45
	v_mov_b32_e32 v2, s75
	v_cndmask_b32_e32 v53, v0, v2, vcc
	v_mov_b32_e32 v0, s44
	v_mov_b32_e32 v2, s74
	v_cndmask_b32_e32 v52, v0, v2, vcc
	global_load_dwordx4 v[2:5], v[34:35], off offset:48
	global_load_dwordx4 v[6:9], v[34:35], off offset:32
	global_load_dwordx4 v[10:13], v[34:35], off offset:16
	global_load_dwordx4 v[14:17], v[34:35], off
	global_load_dwordx4 v[18:21], v[34:35], off offset:112
	global_load_dwordx4 v[22:25], v[34:35], off offset:96
	global_load_dwordx4 v[26:29], v[34:35], off offset:80
	global_load_dwordx4 v[30:33], v[34:35], off offset:64
	v_lshlrev_b32_e32 v0, 1, v82
	v_and_b32_e32 v0, 0x3f80, v0
	v_lshl_add_u64 v[52:53], v[52:53], 0, s[94:95]
	s_waitcnt vmcnt(16)
	v_lshl_add_u64 v[98:99], s[58:59], 0, v[0:1]
	v_lshl_add_u64 v[96:97], v[98:99], 0, s[28:29]
	v_lshl_add_u64 v[94:95], v[98:99], 0, s[34:35]
	s_addk_i32 s6, 0x100
	v_add_u32_e32 v158, 0x4000, v158
	v_add_u32_e32 v159, 0x100, v159
	s_cmpk_eq_i32 s6, 0x300
	s_waitcnt vmcnt(7)
	v_lshlrev_b32_e32 v92, 16, v2
	s_waitcnt vmcnt(6)
	v_lshlrev_b32_e32 v114, 16, v6
	s_waitcnt vmcnt(5)
	v_lshlrev_b32_e32 v90, 16, v10
	s_waitcnt vmcnt(4)
	v_lshlrev_b32_e32 v110, 16, v14
	v_and_b32_e32 v111, 0xffff0000, v14
	v_lshlrev_b32_e32 v106, 16, v15
	v_and_b32_e32 v107, 0xffff0000, v15
	v_lshlrev_b32_e32 v102, 16, v16
	v_and_b32_e32 v103, 0xffff0000, v16
	v_lshlrev_b32_e32 v100, 16, v17
	v_and_b32_e32 v101, 0xffff0000, v17
	v_and_b32_e32 v91, 0xffff0000, v10
	v_lshlrev_b32_e32 v86, 16, v11
	v_and_b32_e32 v87, 0xffff0000, v11
	v_lshlrev_b32_e32 v76, 16, v12
	v_and_b32_e32 v77, 0xffff0000, v12
	v_lshlrev_b32_e32 v72, 16, v13
	v_and_b32_e32 v73, 0xffff0000, v13
	v_and_b32_e32 v115, 0xffff0000, v6
	v_lshlrev_b32_e32 v112, 16, v7
	v_and_b32_e32 v113, 0xffff0000, v7
	v_lshlrev_b32_e32 v108, 16, v8
	v_and_b32_e32 v109, 0xffff0000, v8
	v_lshlrev_b32_e32 v104, 16, v9
	v_and_b32_e32 v105, 0xffff0000, v9
	v_and_b32_e32 v93, 0xffff0000, v2
	v_lshlrev_b32_e32 v88, 16, v3
	v_and_b32_e32 v89, 0xffff0000, v3
	v_lshlrev_b32_e32 v78, 16, v4
	v_and_b32_e32 v79, 0xffff0000, v4
	v_lshlrev_b32_e32 v74, 16, v5
	v_and_b32_e32 v75, 0xffff0000, v5
	s_waitcnt vmcnt(0)
	v_lshlrev_b32_e32 v64, 16, v30
	v_and_b32_e32 v65, 0xffff0000, v30
	v_lshlrev_b32_e32 v60, 16, v31
	v_and_b32_e32 v61, 0xffff0000, v31
	v_lshlrev_b32_e32 v56, 16, v32
	v_and_b32_e32 v57, 0xffff0000, v32
	v_lshlrev_b32_e32 v54, 16, v33
	v_and_b32_e32 v55, 0xffff0000, v33
	v_lshlrev_b32_e32 v46, 16, v26
	v_and_b32_e32 v47, 0xffff0000, v26
	v_lshlrev_b32_e32 v40, 16, v27
	v_and_b32_e32 v41, 0xffff0000, v27
	v_lshlrev_b32_e32 v38, 16, v28
	v_and_b32_e32 v39, 0xffff0000, v28
	v_lshlrev_b32_e32 v36, 16, v29
	v_and_b32_e32 v37, 0xffff0000, v29
	v_lshlrev_b32_e32 v68, 16, v22
	v_and_b32_e32 v69, 0xffff0000, v22
	v_lshlrev_b32_e32 v66, 16, v23
	v_and_b32_e32 v67, 0xffff0000, v23
	v_lshlrev_b32_e32 v62, 16, v24
	v_and_b32_e32 v63, 0xffff0000, v24
	v_lshlrev_b32_e32 v58, 16, v25
	v_and_b32_e32 v59, 0xffff0000, v25
	v_lshlrev_b32_e32 v50, 16, v18
	v_and_b32_e32 v51, 0xffff0000, v18
	v_lshlrev_b32_e32 v49, 16, v19
	v_and_b32_e32 v48, 0xffff0000, v19
	v_lshlrev_b32_e32 v45, 16, v20
	v_and_b32_e32 v44, 0xffff0000, v20
	v_lshlrev_b32_e32 v43, 16, v21
	v_and_b32_e32 v42, 0xffff0000, v21
	global_load_dwordx4 v[2:5], v0, s[88:89] offset:16
	global_load_dwordx4 v[18:21], v0, s[88:89]
	global_load_dwordx4 v[6:9], v0, s[88:89] offset:80
	global_load_dwordx4 v[22:25], v0, s[88:89] offset:64
	global_load_dwordx4 v[10:13], v[52:53], off offset:16
	global_load_dwordx4 v[26:29], v[52:53], off
	global_load_dwordx4 v[14:17], v[52:53], off offset:80
	global_load_dwordx4 v[30:33], v[52:53], off offset:64
	v_mul_f32_e32 v148, v110, v110
	v_mul_f32_e32 v149, v111, v111
	v_mul_f32_e32 v144, v106, v106
	v_mul_f32_e32 v145, v107, v107
	v_add_f32_e32 v148, v149, v148
	v_add_f32_e32 v144, v144, v148
	v_mul_f32_e32 v140, v102, v102
	v_mul_f32_e32 v141, v103, v103
	v_add_f32_e32 v144, v145, v144
	v_add_f32_e32 v140, v140, v144
	v_mul_f32_e32 v126, v100, v100
	v_mul_f32_e32 v127, v101, v101
	v_add_f32_e32 v140, v141, v140
	v_add_f32_e32 v126, v126, v140
	v_mul_f32_e32 v150, v90, v90
	v_mul_f32_e32 v151, v91, v91
	v_add_f32_e32 v126, v127, v126
	v_add_f32_e32 v126, v150, v126
	v_mul_f32_e32 v146, v86, v86
	v_mul_f32_e32 v147, v87, v87
	v_add_f32_e32 v126, v151, v126
	v_add_f32_e32 v126, v146, v126
	v_mul_f32_e32 v142, v76, v76
	v_mul_f32_e32 v143, v77, v77
	v_add_f32_e32 v126, v147, v126
	v_add_f32_e32 v126, v142, v126
	v_mul_f32_e32 v138, v72, v72
	v_mul_f32_e32 v139, v73, v73
	v_add_f32_e32 v126, v143, v126
	v_add_f32_e32 v126, v138, v126
	v_mul_f32_e32 v134, v114, v114
	v_mul_f32_e32 v135, v115, v115
	v_add_f32_e32 v126, v139, v126
	v_add_f32_e32 v126, v134, v126
	v_mul_f32_e32 v130, v112, v112
	v_mul_f32_e32 v131, v113, v113
	v_add_f32_e32 v126, v135, v126
	v_add_f32_e32 v126, v130, v126
	v_mul_f32_e32 v124, v108, v108
	v_mul_f32_e32 v125, v109, v109
	v_add_f32_e32 v126, v131, v126
	v_add_f32_e32 v124, v124, v126
	v_mul_f32_e32 v120, v104, v104
	v_mul_f32_e32 v121, v105, v105
	v_add_f32_e32 v124, v125, v124
; #define P_ROPE WSP(float, OFF_ROPE)
; DI unsigned pack2(float a, float b) { f2_t v = {a, b}; bf2_t r = __builtin_convertvector(v, bf2_t); return __builtin_bit_cast(unsigned, r); }
; DI void mla_item(const Params& p, int l, int item, char* smem) {
;     ...
; #pragma unroll
;       for (int c = 0; c < 8; ++c) {
;         float f;
;         f = BLO(q[c].x); ss += f * f; f = BHI(q[c].x); ss += f * f; f = BLO(q[c].y); ss += f * f; f = BHI(q[c].y); ss += f * f;
;         f = BLO(q[c].z); ss += f * f; f = BHI(q[c].z); ss += f * f; f = BLO(q[c].w); ss += f * f; f = BHI(q[c].w); ss += f * f;
;       }
;       float sc = rsqrtf(ss * (1.0f / 64.0f) + 1e-6f);
;       if (slot < 4) sc *= QS64;
; #pragma unroll
;       for (int pi = 0; pi < 4; ++pi) {
;         const int c = (pi & 1) + (pi >> 1) * 4;
;         const float* tab = P_ROPE + ((pi >> 1) ? (pos & 63) : (pos >> 6)) * 32 + (pi & 1) * 8;
;         const float4 c0 = *(const float4*)(tab), c1 = *(const float4*)(tab + 4), s0 = *(const float4*)(tab + 16), s1 = *(const float4*)(tab + 20);
;         const float cs[8] = {c0.x, c0.y, c0.z, c0.w, c1.x, c1.y, c1.z, c1.w}, sn[8] = {s0.x, s0.y, s0.z, s0.w, s1.x, s1.y, s1.z, s1.w};
;         const float4 ga0 = *(const float4*)(g + c * 8), ga1 = *(const float4*)(g + c * 8 + 4), gb0 = *(const float4*)(g + c * 8 + 16), gb1 = *(const float4*)(g + c * 8 + 20);
;         const float ga[8] = {ga0.x, ga0.y, ga0.z, ga0.w, ga1.x, ga1.y, ga1.z, ga1.w}, gb[8] = {gb0.x, gb0.y, gb0.z, gb0.w, gb1.x, gb1.y, gb1.z, gb1.w};
;         const unsigned ua[4] = {q[c].x, q[c].y, q[c].z, q[c].w}, ub[4] = {q[c + 2].x, q[c + 2].y, q[c + 2].z, q[c + 2].w};
;         unsigned oa[4], ob[4];
; #pragma unroll
;         for (int e = 0; e < 4; ++e) {
;           const float x1l = BLO(ua[e]) * sc * ga[2 * e], x1h = BHI(ua[e]) * sc * ga[2 * e + 1];
;           const float x2l = BLO(ub[e]) * sc * gb[2 * e], x2h = BHI(ub[e]) * sc * gb[2 * e + 1];
;           oa[e] = pack2(x1l * cs[2 * e] - x2l * sn[2 * e], x1h * cs[2 * e + 1] - x2h * sn[2 * e + 1]);
;           ob[e] = pack2(x1l * sn[2 * e] + x2l * cs[2 * e], x1h * sn[2 * e + 1] + x2h * cs[2 * e + 1]);
;         }
;         uint4 wa, wb; wa.x = oa[0]; wa.y = oa[1]; wa.z = oa[2]; wa.w = oa[3]; wb.x = ob[0]; wb.y = ob[1]; wb.z = ob[2]; wb.w = ob[3];
;         *(uint4*)(hp + c * 8) = wa; *(uint4*)(hp + (c + 2) * 8) = wb;
;       }
	v_add_f32_e32 v120, v120, v124
	v_mul_f32_e32 v136, v92, v92
	v_mul_f32_e32 v137, v93, v93
	v_add_f32_e32 v120, v121, v120
	v_add_f32_e32 v120, v136, v120
	v_mul_f32_e32 v132, v88, v88
	v_mul_f32_e32 v133, v89, v89
	v_add_f32_e32 v120, v137, v120
	v_add_f32_e32 v120, v132, v120
	v_mul_f32_e32 v128, v78, v78
	v_mul_f32_e32 v129, v79, v79
	v_add_f32_e32 v120, v133, v120
	v_add_f32_e32 v120, v128, v120
	v_mul_f32_e32 v122, v74, v74
	v_mul_f32_e32 v123, v75, v75
	v_add_f32_e32 v120, v129, v120
	v_add_f32_e32 v120, v122, v120
	v_mul_f32_e32 v172, v64, v64
	v_mul_f32_e32 v173, v65, v65
	v_add_f32_e32 v120, v123, v120
	v_add_f32_e32 v120, v172, v120
	v_mul_f32_e32 v168, v60, v60
	v_mul_f32_e32 v169, v61, v61
	v_add_f32_e32 v120, v173, v120
	v_add_f32_e32 v120, v168, v120
	v_mul_f32_e32 v164, v56, v56
	v_mul_f32_e32 v165, v57, v57
	v_add_f32_e32 v120, v169, v120
	v_add_f32_e32 v120, v164, v120
	v_mul_f32_e32 v160, v54, v54
	v_mul_f32_e32 v161, v55, v55
	v_add_f32_e32 v120, v165, v120
	v_add_f32_e32 v120, v160, v120
	v_mul_f32_e32 v182, v46, v46
	v_mul_f32_e32 v183, v47, v47
	v_add_f32_e32 v120, v161, v120
	v_add_f32_e32 v120, v182, v120
	v_mul_f32_e32 v180, v40, v40
	v_mul_f32_e32 v181, v41, v41
	v_add_f32_e32 v120, v183, v120
	v_add_f32_e32 v120, v180, v120
	v_mul_f32_e32 v178, v38, v38
	v_mul_f32_e32 v179, v39, v39
	v_add_f32_e32 v120, v181, v120
	v_add_f32_e32 v120, v178, v120
	v_mul_f32_e32 v176, v36, v36
	v_mul_f32_e32 v177, v37, v37
	v_add_f32_e32 v120, v179, v120
	v_add_f32_e32 v120, v176, v120
	v_mul_f32_e32 v174, v68, v68
	v_mul_f32_e32 v175, v69, v69
	v_add_f32_e32 v120, v177, v120
	v_add_f32_e32 v120, v174, v120
	v_mul_f32_e32 v170, v66, v66
	v_mul_f32_e32 v171, v67, v67
	v_add_f32_e32 v120, v175, v120
	v_add_f32_e32 v120, v170, v120
	v_mul_f32_e32 v166, v62, v62
	v_mul_f32_e32 v167, v63, v63
	v_add_f32_e32 v120, v171, v120
	v_add_f32_e32 v120, v166, v120
	v_mul_f32_e32 v162, v58, v58
	v_mul_f32_e32 v163, v59, v59
	v_add_f32_e32 v120, v167, v120
	v_add_f32_e32 v120, v162, v120
	v_mul_f32_e32 v184, v50, v50
	v_mul_f32_e32 v185, v51, v51
	v_add_f32_e32 v120, v163, v120
	v_add_f32_e32 v120, v184, v120
	v_mul_f32_e32 v70, v48, v48
	v_mul_f32_e32 v71, v49, v49
	v_add_f32_e32 v120, v185, v120
	v_add_f32_e32 v71, v71, v120
	v_mul_f32_e32 v116, v44, v44
	v_mul_f32_e32 v117, v45, v45
	v_add_f32_e32 v70, v70, v71
	v_add_f32_e32 v70, v117, v70
	v_mul_f32_e32 v118, v42, v42
	v_mul_f32_e32 v119, v43, v43
	v_add_f32_e32 v70, v116, v70
	v_add_f32_e32 v70, v119, v70
	v_add_f32_e32 v70, v118, v70
	v_fmamk_f32 v70, v70, 0x3c800000, v190
	v_cmp_gt_f32_e64 s[0:1], s3, v70
	v_mul_f32_e32 v71, 0x4b800000, v70
	v_lshlrev_b32_e32 v0, 5, v80
	v_cndmask_b32_e64 v70, v70, v71, s[0:1]
	v_rsq_f32_e32 v70, v70
	v_and_b32_e32 v0, 0x1f80, v0
	v_lshl_add_u64 v[84:85], s[58:59], 0, v[0:1]
	v_lshl_add_u64 v[82:83], v[84:85], 0, s[28:29]
	v_mul_f32_e32 v71, 0x45800000, v70
	v_cndmask_b32_e64 v70, v70, v71, s[0:1]
	v_mul_f32_e32 v71, 0x3e38aa3b, v70
	v_cndmask_b32_e32 v70, v70, v71, vcc
	v_mul_f32_e32 v110, v70, v110
	v_mul_f32_e32 v111, v70, v111
	s_waitcnt vmcnt(2)
	v_mul_f32_e32 v110, v26, v110
	v_mul_f32_e32 v111, v27, v111
	v_mul_f32_e32 v26, v70, v114
	v_mul_f32_e32 v27, v70, v115
	s_waitcnt vmcnt(0)
	v_mul_f32_e32 v30, v30, v26
	v_mul_f32_e32 v31, v31, v27
	v_mul_f32_e32 v90, v70, v90
	v_mul_f32_e32 v91, v70, v91
	v_mul_f32_e32 v26, v22, v30
	v_mul_f32_e32 v27, v23, v31
	v_mul_f32_e32 v22, v22, v110
	v_mul_f32_e32 v23, v23, v111
	v_fma_f32 v26, v18, v110, -v26
	v_fma_f32 v27, v19, v111, -v27
	v_fma_f32 v18, v18, v30, v22
	v_fma_f32 v19, v19, v31, v23
	v_mul_f32_e32 v22, v70, v106
	v_mul_f32_e32 v23, v70, v107
	v_mul_f32_e32 v22, v28, v22
	v_mul_f32_e32 v23, v29, v23
	v_mul_f32_e32 v28, v70, v112
	v_mul_f32_e32 v29, v70, v113
	v_mul_f32_e32 v28, v32, v28
	v_mul_f32_e32 v29, v33, v29
	v_cvt_pk_bf16_f32 v18, v18, v19
	v_mul_f32_e32 v30, v24, v28
	v_mul_f32_e32 v31, v25, v29
	v_cvt_pk_bf16_f32 v26, v26, v27
	v_fma_f32 v30, v20, v22, -v30
	v_fma_f32 v31, v21, v23, -v31
	v_mul_f32_e32 v22, v24, v22
	v_mul_f32_e32 v23, v25, v23
	v_cvt_pk_bf16_f32 v27, v30, v31
	v_fma_f32 v20, v20, v28, v22
	v_fma_f32 v21, v21, v29, v23
	v_mul_f32_e32 v64, v70, v64
	v_mul_f32_e32 v65, v70, v65
	v_cvt_pk_bf16_f32 v19, v20, v21
	v_mul_f32_e32 v20, v70, v102
	v_mul_f32_e32 v21, v70, v103
	v_mul_f32_e32 v10, v10, v20
	v_mul_f32_e32 v11, v11, v21
	v_mul_f32_e32 v20, v70, v108
	v_mul_f32_e32 v21, v70, v109
	v_mul_f32_e32 v14, v14, v20
	v_mul_f32_e32 v15, v15, v21
	v_lshl_add_u64 v[80:81], v[84:85], 0, s[34:35]
	v_mul_f32_e32 v20, v6, v14
	v_mul_f32_e32 v21, v7, v15
	v_mul_f32_e32 v6, v6, v10
	v_mul_f32_e32 v7, v7, v11
	v_fma_f32 v20, v2, v10, -v20
	v_fma_f32 v21, v3, v11, -v21
	v_fma_f32 v2, v2, v14, v6
	v_fma_f32 v3, v3, v15, v7
	v_mul_f32_e32 v6, v70, v104
	v_mul_f32_e32 v7, v70, v105
	v_cvt_pk_bf16_f32 v28, v20, v21
	v_cvt_pk_bf16_f32 v20, v2, v3
	v_mul_f32_e32 v2, v70, v100
	v_mul_f32_e32 v3, v70, v101
	v_mul_f32_e32 v6, v16, v6
	v_mul_f32_e32 v7, v17, v7
	v_mul_f32_e32 v2, v12, v2
	v_mul_f32_e32 v3, v13, v3
	v_mul_f32_e32 v10, v8, v6
	v_mul_f32_e32 v11, v9, v7
	v_mul_f32_e32 v46, v70, v46
	v_mul_f32_e32 v47, v70, v47
	v_fma_f32 v10, v4, v2, -v10
	v_fma_f32 v11, v5, v3, -v11
	v_mul_f32_e32 v2, v8, v2
	v_mul_f32_e32 v3, v9, v3
	v_cvt_pk_bf16_f32 v29, v10, v11
	v_fma_f32 v2, v4, v6, v2
	v_fma_f32 v3, v5, v7, v3
	s_nop 0
	v_cvt_pk_bf16_f32 v21, v2, v3
	v_add_co_u32_e32 v2, vcc, s7, v98
	global_store_dwordx4 v[34:35], v[26:29], off
	global_store_dwordx4 v[34:35], v[18:21], off offset:32
	v_addc_co_u32_e32 v3, vcc, 0, v99, vcc
	global_load_dwordx4 v[18:21], v[2:3], off offset:32
	global_load_dwordx4 v[6:9], v[96:97], off offset:16
	global_load_dwordx4 v[22:25], v[2:3], off offset:96
	s_nop 0
	global_load_dwordx4 v[2:5], v[94:95], off offset:16
	global_load_dwordx4 v[14:17], v[52:53], off offset:48
	global_load_dwordx4 v[30:33], v[52:53], off offset:32
	global_load_dwordx4 v[10:13], v[52:53], off offset:112
	global_load_dwordx4 v[26:29], v[52:53], off offset:96
	s_waitcnt vmcnt(2)
; #define P_ROPE WSP(float, OFF_ROPE)
; DI unsigned pack2(float a, float b) { f2_t v = {a, b}; bf2_t r = __builtin_convertvector(v, bf2_t); return __builtin_bit_cast(unsigned, r); }
; #define BLO(u) __uint_as_float((u) << 16)
; #define BHI(u) __uint_as_float((u) & 0xffff0000u)
; DI void mla_item(const Params& p, int l, int item, char* smem) {
;     ...
;       for (int pi = 0; pi < 4; ++pi) {
;         const int c = (pi & 1) + (pi >> 1) * 4;
;         const float* tab = P_ROPE + ((pi >> 1) ? (pos & 63) : (pos >> 6)) * 32 + (pi & 1) * 8;
;         const float4 c0 = *(const float4*)(tab), c1 = *(const float4*)(tab + 4), s0 = *(const float4*)(tab + 16), s1 = *(const float4*)(tab + 20);
;         const float cs[8] = {c0.x, c0.y, c0.z, c0.w, c1.x, c1.y, c1.z, c1.w}, sn[8] = {s0.x, s0.y, s0.z, s0.w, s1.x, s1.y, s1.z, s1.w};
;         const float4 ga0 = *(const float4*)(g + c * 8), ga1 = *(const float4*)(g + c * 8 + 4), gb0 = *(const float4*)(g + c * 8 + 16), gb1 = *(const float4*)(g + c * 8 + 20);
;         const float ga[8] = {ga0.x, ga0.y, ga0.z, ga0.w, ga1.x, ga1.y, ga1.z, ga1.w}, gb[8] = {gb0.x, gb0.y, gb0.z, gb0.w, gb1.x, gb1.y, gb1.z, gb1.w};
;         const unsigned ua[4] = {q[c].x, q[c].y, q[c].z, q[c].w}, ub[4] = {q[c + 2].x, q[c + 2].y, q[c + 2].z, q[c + 2].w};
;         unsigned oa[4], ob[4];
; #pragma unroll
;         for (int e = 0; e < 4; ++e) {
;           const float x1l = BLO(ua[e]) * sc * ga[2 * e], x1h = BHI(ua[e]) * sc * ga[2 * e + 1];
;           const float x2l = BLO(ub[e]) * sc * gb[2 * e], x2h = BHI(ub[e]) * sc * gb[2 * e + 1];
;           oa[e] = pack2(x1l * cs[2 * e] - x2l * sn[2 * e], x1h * cs[2 * e + 1] - x2h * sn[2 * e + 1]);
;           ob[e] = pack2(x1l * sn[2 * e] + x2l * cs[2 * e], x1h * sn[2 * e + 1] + x2h * cs[2 * e + 1]);
;         }
;         uint4 wa, wb; wa.x = oa[0]; wa.y = oa[1]; wa.z = oa[2]; wa.w = oa[3]; wb.x = ob[0]; wb.y = ob[1]; wb.z = ob[2]; wb.w = ob[3];
;         *(uint4*)(hp + c * 8) = wa; *(uint4*)(hp + (c + 2) * 8) = wb;
;       }
	v_mul_f32_e32 v30, v90, v30
	v_mul_f32_e32 v31, v91, v31
	v_mul_f32_e32 v90, v70, v92
	v_mul_f32_e32 v91, v70, v93
	s_waitcnt vmcnt(0)
	v_mul_f32_e32 v90, v90, v26
	v_mul_f32_e32 v91, v91, v27
	s_nop 0
	v_mul_f32_e32 v26, v22, v90
	v_mul_f32_e32 v27, v23, v91
	s_nop 0
	v_fma_f32 v26, v18, v30, -v26
	v_fma_f32 v27, v19, v31, -v27
	v_mul_f32_e32 v18, v18, v90
	v_mul_f32_e32 v19, v19, v91
	v_cvt_pk_bf16_f32 v26, v26, v27
	v_fma_f32 v18, v22, v30, v18
	v_fma_f32 v19, v23, v31, v19
	v_mul_f32_e32 v30, v70, v88
	v_mul_f32_e32 v31, v70, v89
	v_mul_f32_e32 v22, v70, v86
	v_mul_f32_e32 v23, v70, v87
	v_mul_f32_e32 v28, v30, v28
	v_mul_f32_e32 v29, v31, v29
	v_mul_f32_e32 v22, v22, v32
	v_mul_f32_e32 v23, v23, v33
	v_mul_f32_e32 v30, v24, v28
	v_mul_f32_e32 v31, v25, v29
	v_cvt_pk_bf16_f32 v18, v18, v19
	v_fma_f32 v30, v20, v22, -v30
	v_fma_f32 v31, v21, v23, -v31
	v_mul_f32_e32 v20, v20, v28
	v_mul_f32_e32 v21, v21, v29
	v_cvt_pk_bf16_f32 v27, v30, v31
	v_fma_f32 v20, v24, v22, v20
	v_fma_f32 v21, v25, v23, v21
	s_nop 0
	v_cvt_pk_bf16_f32 v19, v20, v21
	v_mul_f32_e32 v20, v70, v76
	v_mul_f32_e32 v21, v70, v77
	v_mul_f32_e32 v14, v20, v14
	v_mul_f32_e32 v15, v21, v15
	v_mul_f32_e32 v20, v70, v78
	v_mul_f32_e32 v21, v70, v79
	v_mul_f32_e32 v10, v20, v10
	v_mul_f32_e32 v11, v21, v11
	s_nop 0
	v_mul_f32_e32 v20, v2, v10
	v_mul_f32_e32 v21, v3, v11
	s_nop 0
	v_fma_f32 v20, v6, v14, -v20
	v_fma_f32 v21, v7, v15, -v21
	v_mul_f32_e32 v6, v6, v10
	v_mul_f32_e32 v7, v7, v11
	v_cvt_pk_bf16_f32 v28, v20, v21
	v_fma_f32 v2, v2, v14, v6
	v_fma_f32 v3, v3, v15, v7
	v_mul_f32_e32 v6, v70, v74
	v_mul_f32_e32 v7, v70, v75
	v_cvt_pk_bf16_f32 v20, v2, v3
	v_mul_f32_e32 v2, v70, v72
	v_mul_f32_e32 v3, v70, v73
	v_mul_f32_e32 v6, v6, v12
	v_mul_f32_e32 v7, v7, v13
	v_mul_f32_e32 v2, v2, v16
	v_mul_f32_e32 v3, v3, v17
	v_mul_f32_e32 v10, v4, v6
	v_mul_f32_e32 v11, v5, v7
	v_mul_f32_e32 v6, v8, v6
	v_mul_f32_e32 v7, v9, v7
	v_fma_f32 v10, v8, v2, -v10
	v_fma_f32 v11, v9, v3, -v11
	v_fma_f32 v2, v4, v2, v6
	v_fma_f32 v3, v5, v3, v7
	v_cvt_pk_bf16_f32 v29, v10, v11
	v_cvt_pk_bf16_f32 v21, v2, v3
	global_store_dwordx4 v[34:35], v[26:29], off offset:16
	global_store_dwordx4 v[34:35], v[18:21], off offset:48
	global_load_dwordx4 v[2:5], v0, s[88:89] offset:16
	global_load_dwordx4 v[6:9], v0, s[88:89]
	global_load_dwordx4 v[10:13], v0, s[88:89] offset:80
	global_load_dwordx4 v[14:17], v0, s[88:89] offset:64
	s_nop 0
	global_load_dwordx4 v[18:21], v[52:53], off offset:144
	global_load_dwordx4 v[22:25], v[52:53], off offset:128
	global_load_dwordx4 v[26:29], v[52:53], off offset:208
	global_load_dwordx4 v[30:33], v[52:53], off offset:192
	s_waitcnt vmcnt(2)
	v_mul_f32_e32 v64, v64, v22
	v_mul_f32_e32 v65, v65, v23
	v_mul_f32_e32 v22, v70, v68
	v_mul_f32_e32 v23, v70, v69
	s_waitcnt vmcnt(0)
	v_mul_f32_e32 v30, v22, v30
	v_mul_f32_e32 v31, v23, v31
	s_nop 0
	v_mul_f32_e32 v22, v14, v30
	v_mul_f32_e32 v23, v15, v31
	s_nop 0
	v_fma_f32 v22, v6, v64, -v22
	v_fma_f32 v23, v7, v65, -v23
	v_mul_f32_e32 v6, v6, v30
	v_mul_f32_e32 v7, v7, v31
	v_cvt_pk_bf16_f32 v22, v22, v23
	v_fma_f32 v6, v14, v64, v6
	v_fma_f32 v7, v15, v65, v7
	v_mul_f32_e32 v14, v70, v60
	v_mul_f32_e32 v15, v70, v61
	v_mul_f32_e32 v14, v14, v24
	v_mul_f32_e32 v15, v15, v25
	v_mul_f32_e32 v24, v70, v66
	v_mul_f32_e32 v25, v70, v67
	v_mul_f32_e32 v24, v24, v32
	v_mul_f32_e32 v25, v25, v33
	v_cvt_pk_bf16_f32 v6, v6, v7
	v_mul_f32_e32 v30, v16, v24
	v_mul_f32_e32 v31, v17, v25
	s_nop 0
	v_fma_f32 v30, v8, v14, -v30
	v_fma_f32 v31, v9, v15, -v31
	v_mul_f32_e32 v8, v8, v24
	v_mul_f32_e32 v9, v9, v25
	v_cvt_pk_bf16_f32 v23, v30, v31
	v_fma_f32 v8, v16, v14, v8
	v_fma_f32 v9, v17, v15, v9
	v_mul_f32_e32 v14, v70, v62
	v_mul_f32_e32 v15, v70, v63
	v_cvt_pk_bf16_f32 v7, v8, v9
	v_mul_f32_e32 v8, v70, v56
	v_mul_f32_e32 v9, v70, v57
	v_mul_f32_e32 v14, v14, v26
	v_mul_f32_e32 v15, v15, v27
	v_mul_f32_e32 v8, v8, v18
	v_mul_f32_e32 v9, v9, v19
	v_mul_f32_e32 v16, v10, v14
	v_mul_f32_e32 v17, v11, v15
	s_nop 0
	v_fma_f32 v16, v2, v8, -v16
	v_fma_f32 v17, v3, v9, -v17
	v_mul_f32_e32 v2, v2, v14
	v_mul_f32_e32 v3, v3, v15
	v_cvt_pk_bf16_f32 v24, v16, v17
	v_fma_f32 v2, v10, v8, v2
	v_fma_f32 v3, v11, v9, v3
	v_mul_f32_e32 v10, v70, v58
	v_mul_f32_e32 v11, v70, v59
	v_cvt_pk_bf16_f32 v8, v2, v3
	v_mul_f32_e32 v2, v70, v54
	v_mul_f32_e32 v3, v70, v55
	v_mul_f32_e32 v10, v10, v28
	v_mul_f32_e32 v11, v11, v29
	v_mul_f32_e32 v2, v2, v20
	v_mul_f32_e32 v3, v3, v21
	v_mul_f32_e32 v14, v12, v10
	v_mul_f32_e32 v15, v13, v11
	s_nop 0
	v_fma_f32 v14, v4, v2, -v14
	v_fma_f32 v15, v5, v3, -v15
	v_mul_f32_e32 v4, v4, v10
	v_mul_f32_e32 v5, v5, v11
	v_cvt_pk_bf16_f32 v25, v14, v15
	v_fma_f32 v2, v12, v2, v4
	v_fma_f32 v3, v13, v3, v5
	v_add_co_u32_e32 v10, vcc, s7, v84
	v_cvt_pk_bf16_f32 v9, v2, v3
	global_store_dwordx4 v[34:35], v[22:25], off offset:64
	global_store_dwordx4 v[34:35], v[6:9], off offset:96
	v_addc_co_u32_e32 v11, vcc, 0, v85, vcc
	global_load_dwordx4 v[2:5], v[10:11], off offset:32
	global_load_dwordx4 v[6:9], v[82:83], off offset:16
	s_nop 0
	global_load_dwordx4 v[10:13], v[10:11], off offset:96
	s_nop 0
	global_load_dwordx4 v[14:17], v[80:81], off offset:16
	global_load_dwordx4 v[18:21], v[52:53], off offset:176
	global_load_dwordx4 v[22:25], v[52:53], off offset:160
	global_load_dwordx4 v[26:29], v[52:53], off offset:240
	global_load_dwordx4 v[30:33], v[52:53], off offset:224
	s_waitcnt vmcnt(2)
	v_mul_f32_e32 v46, v46, v22
	v_mul_f32_e32 v47, v47, v23
	v_mul_f32_e32 v22, v70, v50
	v_mul_f32_e32 v23, v70, v51
	s_waitcnt vmcnt(0)
; #define P_ROPE WSP(float, OFF_ROPE)
; DI unsigned pack2(float a, float b) { f2_t v = {a, b}; bf2_t r = __builtin_convertvector(v, bf2_t); return __builtin_bit_cast(unsigned, r); }
; #define BLO(u) __uint_as_float((u) << 16)
; #define BHI(u) __uint_as_float((u) & 0xffff0000u)
; DI void mla_item(const Params& p, int l, int item, char* smem) {
;     ...
;       for (int pi = 0; pi < 4; ++pi) {
;         const int c = (pi & 1) + (pi >> 1) * 4;
;         const float* tab = P_ROPE + ((pi >> 1) ? (pos & 63) : (pos >> 6)) * 32 + (pi & 1) * 8;
;         const float4 c0 = *(const float4*)(tab), c1 = *(const float4*)(tab + 4), s0 = *(const float4*)(tab + 16), s1 = *(const float4*)(tab + 20);
;         const float cs[8] = {c0.x, c0.y, c0.z, c0.w, c1.x, c1.y, c1.z, c1.w}, sn[8] = {s0.x, s0.y, s0.z, s0.w, s1.x, s1.y, s1.z, s1.w};
;         const float4 ga0 = *(const float4*)(g + c * 8), ga1 = *(const float4*)(g + c * 8 + 4), gb0 = *(const float4*)(g + c * 8 + 16), gb1 = *(const float4*)(g + c * 8 + 20);
;         const float ga[8] = {ga0.x, ga0.y, ga0.z, ga0.w, ga1.x, ga1.y, ga1.z, ga1.w}, gb[8] = {gb0.x, gb0.y, gb0.z, gb0.w, gb1.x, gb1.y, gb1.z, gb1.w};
;         const unsigned ua[4] = {q[c].x, q[c].y, q[c].z, q[c].w}, ub[4] = {q[c + 2].x, q[c + 2].y, q[c + 2].z, q[c + 2].w};
;         unsigned oa[4], ob[4];
; #pragma unroll
;         for (int e = 0; e < 4; ++e) {
;           const float x1l = BLO(ua[e]) * sc * ga[2 * e], x1h = BHI(ua[e]) * sc * ga[2 * e + 1];
;           const float x2l = BLO(ub[e]) * sc * gb[2 * e], x2h = BHI(ub[e]) * sc * gb[2 * e + 1];
;           oa[e] = pack2(x1l * cs[2 * e] - x2l * sn[2 * e], x1h * cs[2 * e + 1] - x2h * sn[2 * e + 1]);
;           ob[e] = pack2(x1l * sn[2 * e] + x2l * cs[2 * e], x1h * sn[2 * e + 1] + x2h * cs[2 * e + 1]);
;         }
;         uint4 wa, wb; wa.x = oa[0]; wa.y = oa[1]; wa.z = oa[2]; wa.w = oa[3]; wb.x = ob[0]; wb.y = ob[1]; wb.z = ob[2]; wb.w = ob[3];
;         *(uint4*)(hp + c * 8) = wa; *(uint4*)(hp + (c + 2) * 8) = wb;
;       }
;     }
;     if (tid < 128) {
	v_mul_f32_e32 v30, v22, v30
	v_mul_f32_e32 v31, v23, v31
	s_nop 0
	v_mul_f32_e32 v22, v10, v30
	v_mul_f32_e32 v23, v11, v31
	s_nop 0
	v_fma_f32 v22, v2, v46, -v22
	v_fma_f32 v23, v3, v47, -v23
	v_mul_f32_e32 v2, v2, v30
	v_mul_f32_e32 v3, v3, v31
	v_cvt_pk_bf16_f32 v22, v22, v23
	v_fma_f32 v2, v10, v46, v2
	v_fma_f32 v3, v11, v47, v3
	v_mul_f32_e32 v10, v70, v40
	v_mul_f32_e32 v11, v70, v41
	v_mul_f32_e32 v10, v10, v24
	v_mul_f32_e32 v11, v11, v25
	v_mul_f32_e32 v24, v70, v48
	v_mul_f32_e32 v25, v70, v49
	v_pk_mul_f32 v[24:25], v[24:25], v[32:33] op_sel:[1,0] op_sel_hi:[0,1]
	v_mul_f32_e32 v30, v12, v24
	v_mul_f32_e32 v31, v13, v25
	v_cvt_pk_bf16_f32 v2, v2, v3
	v_fma_f32 v30, v4, v10, -v30
	v_fma_f32 v31, v5, v11, -v31
	v_mul_f32_e32 v4, v4, v24
	v_mul_f32_e32 v5, v5, v25
	v_cvt_pk_bf16_f32 v23, v30, v31
	v_fma_f32 v4, v12, v10, v4
	v_fma_f32 v5, v13, v11, v5
	v_mul_f32_e32 v10, v70, v44
	v_mul_f32_e32 v11, v70, v45
	v_cvt_pk_bf16_f32 v3, v4, v5
	v_mul_f32_e32 v4, v70, v38
	v_mul_f32_e32 v5, v70, v39
	v_pk_mul_f32 v[10:11], v[10:11], v[26:27] op_sel:[1,0] op_sel_hi:[0,1]
	v_mul_f32_e32 v4, v4, v18
	v_mul_f32_e32 v5, v5, v19
	v_mul_f32_e32 v12, v14, v10
	v_mul_f32_e32 v13, v15, v11
	s_nop 0
	v_fma_f32 v12, v6, v4, -v12
	v_fma_f32 v13, v7, v5, -v13
	v_mul_f32_e32 v6, v6, v10
	v_mul_f32_e32 v7, v7, v11
	v_mul_f32_e32 v10, v70, v42
	v_mul_f32_e32 v11, v70, v43
	v_fma_f32 v4, v14, v4, v6
	v_fma_f32 v5, v15, v5, v7
	v_mul_f32_e32 v6, v70, v36
	v_mul_f32_e32 v7, v70, v37
	v_pk_mul_f32 v[10:11], v[10:11], v[28:29] op_sel:[1,0] op_sel_hi:[0,1]
	v_cvt_pk_bf16_f32 v24, v12, v13
	v_mul_f32_e32 v6, v6, v20
	v_mul_f32_e32 v7, v7, v21
	v_mul_f32_e32 v12, v16, v10
	v_mul_f32_e32 v13, v17, v11
	v_cvt_pk_bf16_f32 v4, v4, v5
	v_fma_f32 v12, v8, v6, -v12
	v_fma_f32 v13, v9, v7, -v13
	v_mul_f32_e32 v8, v8, v10
	v_mul_f32_e32 v9, v9, v11
	v_cvt_pk_bf16_f32 v25, v12, v13
	v_fma_f32 v6, v16, v6, v8
	v_fma_f32 v7, v17, v7, v9
	s_nop 0
	v_cvt_pk_bf16_f32 v5, v6, v7
	global_store_dwordx4 v[34:35], v[22:25], off offset:80
	global_store_dwordx4 v[34:35], v[2:5], off offset:112
	s_cbranch_scc0 .LBB0_213
	s_movk_i32 s4, 0x2600
	v_cmp_gt_u32_e32 vcc, s93, v157
	s_and_saveexec_b64 s[0:1], vcc
	s_cbranch_execz .LBB0_216
; #define P_ROPE WSP(float, OFF_ROPE)
; DI unsigned pack2(float a, float b) { f2_t v = {a, b}; bf2_t r = __builtin_convertvector(v, bf2_t); return __builtin_bit_cast(unsigned, r); }
; #define BLO(u) __uint_as_float((u) << 16)
; #define BHI(u) __uint_as_float((u) & 0xffff0000u)
; DI void mla_item(const Params& p, int l, int item, char* smem) {
;     ...
;     if (tid < 128) {
;       const size_t t = (size_t)it * 128 + tid; const int pos = (int)(t & (SEQ - 1));
;       const bf16_t* src = P_PROJ + t * PW + C_AKR;
;       uint4 q[4];
; #pragma unroll
;       for (int c = 0; c < 4; ++c) q[c] = *(const uint4*)(src + c * 8);
;       uint4 w[4];
; #pragma unroll
;       for (int c = 0; c < 2; ++c) {
;         const float* tab = P_ROPE + pos * 32 + c * 8;
;         const float4 c0 = *(const float4*)(tab), c1 = *(const float4*)(tab + 4), s0 = *(const float4*)(tab + 16), s1 = *(const float4*)(tab + 20);
;         const float cs[8] = {c0.x, c0.y, c0.z, c0.w, c1.x, c1.y, c1.z, c1.w}, sn[8] = {s0.x, s0.y, s0.z, s0.w, s1.x, s1.y, s1.z, s1.w};
;         const unsigned ua[4] = {q[c].x, q[c].y, q[c].z, q[c].w}, ub[4] = {q[c + 2].x, q[c + 2].y, q[c + 2].z, q[c + 2].w};
;         unsigned oa[4], ob[4];
; #pragma unroll
;         for (int e = 0; e < 4; ++e) {
;           const float x1l = BLO(ua[e]), x1h = BHI(ua[e]), x2l = BLO(ub[e]), x2h = BHI(ub[e]);
;           oa[e] = pack2(x1l * cs[2 * e] - x2l * sn[2 * e], x1h * cs[2 * e + 1] - x2h * sn[2 * e + 1]);
;           ob[e] = pack2(x1l * sn[2 * e] + x2l * cs[2 * e], x1h * sn[2 * e + 1] + x2h * cs[2 * e + 1]);
;         }
;         w[c].x = oa[0]; w[c].y = oa[1]; w[c].z = oa[2]; w[c].w = oa[3];
;         w[c + 2].x = ob[0]; w[c + 2].y = ob[1]; w[c + 2].z = ob[2]; w[c + 2].w = ob[3];
;       }
; #pragma unroll
;       for (int h = 0; h < 4; ++h)
; #pragma unroll
;         for (int c = 0; c < 4; ++c) *(uint4*)(P_KA + t * 384 + h * 96 + 64 + c * 8) = w[c];
;     }
	v_or_b32_e32 v0, s22, v157
	v_mov_b64_e32 v[2:3], s[58:59]
	v_mad_u64_u32 v[34:35], s[6:7], v0, s4, v[2:3]
	v_mov_b32_e32 v2, 0x2600
	v_mad_u32_u24 v35, s23, v2, v35
	s_mov_b64 s[6:7], 0x6ca6500
	v_add_co_u32_e32 v2, vcc, 0x6ca6000, v34
	v_lshl_add_u64 v[10:11], v[34:35], 0, s[6:7]
	s_nop 0
	v_addc_co_u32_e32 v3, vcc, 0, v35, vcc
	global_load_dwordx4 v[18:21], v[2:3], off offset:1280
	s_nop 0
	global_load_dwordx4 v[2:5], v[10:11], off offset:48
	global_load_dwordx4 v[6:9], v[10:11], off offset:16
	global_load_dwordx4 v[22:25], v[10:11], off offset:32
	v_lshlrev_b32_e32 v10, 7, v0
	v_and_b32_e32 v48, 0xfff80, v10
	global_load_dwordx4 v[10:13], v48, s[88:89] offset:48
	global_load_dwordx4 v[26:29], v48, s[88:89] offset:32
	global_load_dwordx4 v[36:39], v48, s[88:89] offset:16
	global_load_dwordx4 v[40:43], v48, s[88:89]
	global_load_dwordx4 v[14:17], v48, s[88:89] offset:112
	global_load_dwordx4 v[30:33], v48, s[88:89] offset:96
	global_load_dwordx4 v[44:47], v48, s[88:89] offset:80
	s_nop 0
	global_load_dwordx4 v[48:51], v48, s[88:89] offset:64
	s_movk_i32 s6, 0xdd00
	s_waitcnt vmcnt(11)
	v_lshlrev_b32_e32 v52, 16, v18
	v_and_b32_e32 v53, 0xffff0000, v18
	s_waitcnt vmcnt(8)
	v_lshlrev_b32_e32 v54, 16, v22
	v_and_b32_e32 v55, 0xffff0000, v22
	s_waitcnt vmcnt(0)
	v_mul_f32_e32 v56, v48, v54
	v_mul_f32_e32 v57, v49, v55
	v_mul_f32_e32 v48, v48, v52
	v_mul_f32_e32 v49, v49, v53
	v_fma_f32 v56, v40, v52, -v56
	v_fma_f32 v57, v41, v53, -v57
	v_fma_f32 v40, v40, v54, v48
	v_fma_f32 v41, v41, v55, v49
	v_lshlrev_b32_e32 v48, 16, v23
	v_and_b32_e32 v49, 0xffff0000, v23
	v_cvt_pk_bf16_f32 v22, v40, v41
	v_lshlrev_b32_e32 v40, 16, v19
	v_and_b32_e32 v41, 0xffff0000, v19
	v_mul_f32_e32 v52, v50, v48
	v_mul_f32_e32 v53, v51, v49
	v_cvt_pk_bf16_f32 v18, v56, v57
	v_fma_f32 v52, v42, v40, -v52
	v_fma_f32 v53, v43, v41, -v53
	v_mul_f32_e32 v40, v50, v40
	v_mul_f32_e32 v41, v51, v41
	v_cvt_pk_bf16_f32 v19, v52, v53
	v_fma_f32 v40, v42, v48, v40
	v_fma_f32 v41, v43, v49, v41
	v_lshlrev_b32_e32 v42, 16, v24
	v_and_b32_e32 v43, 0xffff0000, v24
	v_cvt_pk_bf16_f32 v23, v40, v41
	v_lshlrev_b32_e32 v40, 16, v20
	v_and_b32_e32 v41, 0xffff0000, v20
	v_mul_f32_e32 v48, v44, v42
	v_mul_f32_e32 v49, v45, v43
	s_nop 0
	v_fma_f32 v48, v36, v40, -v48
	v_fma_f32 v49, v37, v41, -v49
	v_mul_f32_e32 v40, v44, v40
	v_mul_f32_e32 v41, v45, v41
	v_cvt_pk_bf16_f32 v20, v48, v49
	v_fma_f32 v36, v36, v42, v40
	v_fma_f32 v37, v37, v43, v41
	v_lshlrev_b32_e32 v40, 16, v25
	v_and_b32_e32 v41, 0xffff0000, v25
	v_cvt_pk_bf16_f32 v24, v36, v37
	v_lshlrev_b32_e32 v36, 16, v21
	v_and_b32_e32 v37, 0xffff0000, v21
	v_mul_f32_e32 v42, v46, v40
	v_mul_f32_e32 v43, v47, v41
	s_nop 0
	v_fma_f32 v42, v38, v36, -v42
	v_fma_f32 v43, v39, v37, -v43
	v_mul_f32_e32 v36, v46, v36
	v_mul_f32_e32 v37, v47, v37
	v_cvt_pk_bf16_f32 v21, v42, v43
	v_fma_f32 v36, v38, v40, v36
	v_fma_f32 v37, v39, v41, v37
	v_lshlrev_b32_e32 v38, 16, v2
	v_cvt_pk_bf16_f32 v25, v36, v37
	v_lshlrev_b32_e32 v36, 16, v6
	v_and_b32_e32 v37, 0xffff0000, v6
	v_and_b32_e32 v39, 0xffff0000, v2
	v_mul_f32_e32 v40, v30, v38
	v_mul_f32_e32 v41, v31, v39
	v_mul_f32_e32 v30, v30, v36
	v_mul_f32_e32 v31, v31, v37
	v_fma_f32 v40, v26, v36, -v40
	v_fma_f32 v41, v27, v37, -v41
	v_fma_f32 v26, v26, v38, v30
	v_fma_f32 v27, v27, v39, v31
	v_lshlrev_b32_e32 v30, 16, v3
	v_and_b32_e32 v31, 0xffff0000, v3
	v_cvt_pk_bf16_f32 v6, v26, v27
	v_lshlrev_b32_e32 v26, 16, v7
	v_and_b32_e32 v27, 0xffff0000, v7
	v_mul_f32_e32 v36, v32, v30
	v_mul_f32_e32 v37, v33, v31
	v_cvt_pk_bf16_f32 v2, v40, v41
	v_fma_f32 v36, v28, v26, -v36
	v_fma_f32 v37, v29, v27, -v37
	v_mul_f32_e32 v26, v32, v26
	v_mul_f32_e32 v27, v33, v27
	v_cvt_pk_bf16_f32 v3, v36, v37
	v_fma_f32 v26, v28, v30, v26
	v_fma_f32 v27, v29, v31, v27
	v_lshlrev_b32_e32 v28, 16, v4
	v_cvt_pk_bf16_f32 v7, v26, v27
	v_lshlrev_b32_e32 v26, 16, v8
	v_and_b32_e32 v27, 0xffff0000, v8
	v_and_b32_e32 v29, 0xffff0000, v4
	v_mul_f32_e32 v30, v14, v28
	v_mul_f32_e32 v31, v15, v29
	v_mul_f32_e32 v14, v14, v26
	v_mul_f32_e32 v15, v15, v27
	v_fma_f32 v30, v10, v26, -v30
	v_fma_f32 v31, v11, v27, -v31
	v_fma_f32 v10, v10, v28, v14
	v_fma_f32 v11, v11, v29, v15
	v_lshlrev_b32_e32 v14, 16, v5
	v_and_b32_e32 v15, 0xffff0000, v5
	v_cvt_pk_bf16_f32 v8, v10, v11
	v_lshlrev_b32_e32 v10, 16, v9
	v_and_b32_e32 v11, 0xffff0000, v9
	v_mul_f32_e32 v26, v16, v14
	v_mul_f32_e32 v27, v17, v15
	v_cvt_pk_bf16_f32 v4, v30, v31
	v_fma_f32 v26, v12, v10, -v26
	v_fma_f32 v27, v13, v11, -v27
	v_mul_f32_e32 v10, v16, v10
	v_mul_f32_e32 v11, v17, v11
	v_cvt_pk_bf16_f32 v5, v26, v27
	v_fma_f32 v10, v12, v14, v10
	v_fma_f32 v11, v13, v15, v11
	v_mov_b32_e32 v12, 0xffffdd00
	v_cvt_pk_bf16_f32 v9, v10, v11
	v_mad_u64_u32 v[10:11], s[6:7], v0, s6, v[34:35]
	v_mad_i32_i24 v11, s23, v12, v11
	s_mov_b32 s6, 0x1b4a4000
	v_sub_u32_e32 v0, v11, v0
	v_add_co_u32_e32 v10, vcc, s6, v10
	s_nop 1
	v_addc_co_u32_e32 v11, vcc, 0, v0, vcc
	global_store_dwordx4 v[10:11], v[18:21], off offset:128
	global_store_dwordx4 v[10:11], v[2:5], off offset:144
	global_store_dwordx4 v[10:11], v[22:25], off offset:160
	global_store_dwordx4 v[10:11], v[6:9], off offset:176
	global_store_dwordx4 v[10:11], v[18:21], off offset:320
	global_store_dwordx4 v[10:11], v[2:5], off offset:336
	global_store_dwordx4 v[10:11], v[22:25], off offset:352
	global_store_dwordx4 v[10:11], v[6:9], off offset:368
	global_store_dwordx4 v[10:11], v[18:21], off offset:512
	global_store_dwordx4 v[10:11], v[2:5], off offset:528
	global_store_dwordx4 v[10:11], v[22:25], off offset:544
	global_store_dwordx4 v[10:11], v[6:9], off offset:560
	global_store_dwordx4 v[10:11], v[18:21], off offset:704
	global_store_dwordx4 v[10:11], v[2:5], off offset:720
	global_store_dwordx4 v[10:11], v[22:25], off offset:736
	global_store_dwordx4 v[10:11], v[6:9], off offset:752

; DI int otid() { int t; asm volatile("v_mov_b32 %0, %1" : "=v"(t) : "v"((int)threadIdx.x)); __builtin_assume(t >= 0 && t < 256); return t; }
; #define GLOAD(ko) do { \
;     _Pragma("unroll") for (int i = 0; i < 4; ++i) ra[i] = *(const u32x4*)(ap + (size_t)(32 * i) * lda + (ko)); \
;     _Pragma("unroll") for (int i = 0; i < NB; ++i) rb[i] = *(const u32x4*)(bp + (size_t)(bstride * i) * ldb + (ko)); } while (0)
; #define GSTORE(st) do { \
;     _Pragma("unroll") for (int i = 0; i < 4; ++i) *(u32x4*)(sA + (st) * GST + so + 32 * i * 64) = ra[i]; \
;     _Pragma("unroll") for (int i = 0; i < NB; ++i) *(u32x4*)(sB + (st) * GST + so + 32 * i * 64) = rb[i]; } while (0)
;   constexpr int NB = NT;
;   const int tid = otid(), lane = tid & 63, wid = tid >> 6;
;   const int wm = wid >> 1, wn = wid & 1, fr = lane & 15, fq = lane >> 4;
;   u32x4 ra[4], rb[NB];
;   const int nk = K >> 6;
;   const bf16_t* ap = A + (size_t)(tid >> 3) * lda + (tid & 7) * 8;
;   const bf16_t* bp = Bt + (size_t)(tid >> 3) * ldb + (tid & 7) * 8;
;   const int so = (tid >> 3) * 64 + (((tid & 7) ^ ((tid >> 4) & 7)) * 8);
;   const int fsw = fr >> 1;
;     ...
;   __syncthreads();
;   GLOAD(0); GSTORE(0);
;   if (nk > 1) GLOAD(64);
;   __syncthreads();
;   for (int kt = 0; kt < nk; ++kt) {
;     const int cur = kt & 1;
;     if (kt + 1 < nk) { GSTORE(cur ^ 1); if (kt + 2 < nk) GLOAD((kt + 2) * 64); }
; DI void mla_item(const Params& p, int l, int item, char* smem) {
;     ...
;     const int it = item - 768; const int mt = it & 255, h = it >> 8;
;     const bf16_t* A = P_PROJ + (size_t)mt * 128 * PW + C_AKV;
;     __syncthreads();
;     row_scales(A, PW, 128, sRow);
;     f32x4 acc[4][4]; zero_acc<4>(acc);
;     gemm_mainloop<4>(acc, A, PW, P_WKVT + ((size_t)l * 512 + h * 128) * 128, 128, 128, sA, sB);
.LBB0_220:
	s_or_b64 exec, exec, s[22:23]
	v_mov_b32 v52, v188
	s_add_i32 s7, s27, 0xfffffd00
	v_lshrrev_b32_e32 v4, 3, v52
	v_mul_u32_u24_e32 v0, 0x2600, v4
	s_waitcnt lgkmcnt(0)
	v_lshl_add_u64 v[2:3], s[0:1], 0, v[0:1]
	v_lshlrev_b32_e32 v0, 4, v52
	s_lshr_b32 s7, s7, 8
	v_and_b32_e32 v0, 0x70, v0
	s_lshl_b32 s11, s7, 7
	v_lshl_add_u64 v[34:35], v[2:3], 0, v[0:1]
	s_mov_b32 s0, 0x4c000
	s_add_i32 s12, s11, s24
	s_mov_b32 s13, s95
	v_add_co_u32_e32 v38, vcc, s0, v34
	s_lshl_b64 s[12:13], s[12:13], 8
	v_readlane_b32 s11, v253, 14
	v_addc_co_u32_e32 v39, vcc, 0, v35, vcc
	s_mov_b32 s0, 0x98000
	s_add_u32 s12, s11, s12
	v_readlane_b32 s11, v253, 15
	v_add_co_u32_e32 v40, vcc, s0, v34
	s_addc_u32 s13, s11, s13
	v_lshlrev_b32_e32 v36, 7, v4
	v_mov_b32_e32 v37, v1
	v_addc_co_u32_e32 v41, vcc, 0, v35, vcc
	s_mov_b32 s0, 0xe4000
	v_lshl_add_u64 v[18:19], v[36:37], 1, s[12:13]
	v_add_co_u32_e32 v42, vcc, s0, v34
	v_lshl_add_u64 v[44:45], v[18:19], 0, v[0:1]
	s_nop 0
	v_addc_co_u32_e32 v43, vcc, 0, v35, vcc
	s_movk_i32 s11, 0x2000
	v_add_co_u32_e32 v46, vcc, s11, v44
	s_nop 1
	v_addc_co_u32_e32 v47, vcc, 0, v45, vcc
	v_add_co_u32_e32 v48, vcc, s2, v44
	s_barrier
	global_load_dwordx4 v[2:5], v[34:35], off
	global_load_dwordx4 v[6:9], v[38:39], off
	global_load_dwordx4 v[18:21], v[44:45], off
	global_load_dwordx4 v[22:25], v[46:47], off
	v_addc_co_u32_e32 v49, vcc, 0, v45, vcc
	v_add_co_u32_e32 v50, vcc, s42, v44
	global_load_dwordx4 v[10:13], v[40:41], off
	global_load_dwordx4 v[14:17], v[42:43], off
	global_load_dwordx4 v[26:29], v[48:49], off
	v_addc_co_u32_e32 v51, vcc, 0, v45, vcc
	global_load_dwordx4 v[30:33], v[50:51], off
	v_lshrrev_b32_e32 v53, 4, v52
	v_xor_b32_e32 v37, v53, v52
	v_lshlrev_b32_e32 v0, 4, v37
	s_movk_i32 s0, 0x70
	v_and_or_b32 v0, v0, s0, v36
	v_and_b32_e32 v36, 15, v52
	v_bfe_u32 v54, v52, 4, 2
	v_cmp_eq_u32_e32 vcc, 0, v152
	s_lshl_b32 s0, s7, 6
	s_mul_i32 s1, s7, 0x60
	s_movk_i32 s7, 0x300
	s_waitcnt vmcnt(7)
	ds_write_b128 v0, v[2:5]
	s_waitcnt vmcnt(6)
	ds_write_b128 v0, v[6:9] offset:4096
	s_waitcnt vmcnt(3)
	ds_write_b128 v0, v[10:13] offset:8192
	s_waitcnt vmcnt(2)
	ds_write_b128 v0, v[14:17] offset:12288
	ds_write_b128 v0, v[18:21] offset:32768
	ds_write_b128 v0, v[22:25] offset:36864
	s_waitcnt vmcnt(1)
	ds_write_b128 v0, v[26:29] offset:40960
	s_waitcnt vmcnt(0)
	ds_write_b128 v0, v[30:33] offset:45056
	global_load_dwordx4 v[2:5], v[34:35], off offset:128
	global_load_dwordx4 v[6:9], v[38:39], off offset:128
	global_load_dwordx4 v[10:13], v[40:41], off offset:128
	global_load_dwordx4 v[14:17], v[42:43], off offset:128
	global_load_dwordx4 v[18:21], v[44:45], off offset:128
	global_load_dwordx4 v[22:25], v[46:47], off offset:128
	global_load_dwordx4 v[26:29], v[48:49], off offset:128
	global_load_dwordx4 v[30:33], v[50:51], off offset:128
	v_lshrrev_b32_e32 v35, 1, v52
	v_bfe_u32 v34, v52, 1, 3
	v_and_or_b32 v35, v35, 64, v36
	v_bitop3_b32 v36, v53, v34, 3 bitop3:0x6c
	v_lshlrev_b32_e32 v70, 7, v35
	v_lshlrev_b32_e32 v35, 7, v52
	v_lshlrev_b32_e32 v36, 4, v36
	v_and_b32_e32 v82, 0x2780, v35
	s_waitcnt lgkmcnt(0)
	s_barrier
	v_or_b32_e32 v98, v36, v82
	v_bitop3_b32 v34, v54, v34, 4 bitop3:0x36
	v_lshlrev_b32_e32 v83, 4, v34
	v_or_b32_e32 v99, v83, v70
	v_or_b32_e32 v106, v83, v82
	s_waitcnt vmcnt(7)
	ds_write_b128 v0, v[2:5] offset:16384
	s_waitcnt vmcnt(6)
	ds_write_b128 v0, v[6:9] offset:20480
	s_waitcnt vmcnt(5)
	ds_write_b128 v0, v[10:13] offset:24576
	s_waitcnt vmcnt(4)
	ds_write_b128 v0, v[14:17] offset:28672
	s_waitcnt vmcnt(3)
	ds_write_b128 v0, v[18:21] offset:49152
	s_waitcnt vmcnt(2)
	ds_write_b128 v0, v[22:25] offset:53248
	s_waitcnt vmcnt(1)
	ds_write_b128 v0, v[26:29] offset:57344
	s_waitcnt vmcnt(0)
	ds_write_b128 v0, v[30:33] offset:61440
	v_or_b32_e32 v0, v36, v70
	ds_read_b128 v[2:5], v0
	ds_read_b128 v[6:9], v0 offset:2048
	ds_read_b128 v[10:13], v0 offset:4096
	ds_read_b128 v[14:17], v0 offset:6144
	ds_read_b128 v[18:21], v98 offset:32768
	ds_read_b128 v[22:25], v98 offset:34816
	ds_read_b128 v[26:29], v98 offset:36864
	ds_read_b128 v[30:33], v98 offset:38912
	s_waitcnt lgkmcnt(3)
	v_mfma_f32_16x16x32_bf16 v[34:37], v[18:21], v[2:5], 0
	s_waitcnt lgkmcnt(2)
	v_mfma_f32_16x16x32_bf16 v[38:41], v[22:25], v[2:5], 0
	s_waitcnt lgkmcnt(1)
	v_mfma_f32_16x16x32_bf16 v[42:45], v[26:29], v[2:5], 0
	s_waitcnt lgkmcnt(0)
	v_mfma_f32_16x16x32_bf16 v[2:5], v[30:33], v[2:5], 0
	v_mfma_f32_16x16x32_bf16 v[46:49], v[18:21], v[6:9], 0
	v_mfma_f32_16x16x32_bf16 v[50:53], v[22:25], v[6:9], 0
	v_mfma_f32_16x16x32_bf16 v[54:57], v[26:29], v[6:9], 0
	v_mfma_f32_16x16x32_bf16 v[6:9], v[30:33], v[6:9], 0
	v_mfma_f32_16x16x32_bf16 v[58:61], v[18:21], v[10:13], 0
	v_mfma_f32_16x16x32_bf16 v[62:65], v[22:25], v[10:13], 0
	v_mfma_f32_16x16x32_bf16 v[66:69], v[26:29], v[10:13], 0
	v_mfma_f32_16x16x32_bf16 v[10:13], v[30:33], v[10:13], 0
	v_mfma_f32_16x16x32_bf16 v[18:21], v[18:21], v[14:17], 0
	v_mfma_f32_16x16x32_bf16 v[22:25], v[22:25], v[14:17], 0
	v_mfma_f32_16x16x32_bf16 v[26:29], v[26:29], v[14:17], 0
	v_mfma_f32_16x16x32_bf16 v[14:17], v[30:33], v[14:17], 0
	ds_read_b128 v[30:33], v99
	ds_read_b128 v[70:73], v99 offset:2048
	ds_read_b128 v[74:77], v99 offset:4096
	ds_read_b128 v[78:81], v99 offset:6144
	ds_read_b128 v[82:85], v106 offset:32768
	ds_read_b128 v[86:89], v106 offset:34816
	ds_read_b128 v[90:93], v106 offset:36864
	ds_read_b128 v[94:97], v106 offset:38912
	s_waitcnt lgkmcnt(0)
	v_mfma_f32_16x16x32_bf16 v[34:37], v[82:85], v[30:33], v[34:37]
	s_barrier
; DI unsigned pack2(float a, float b) { f2_t v = {a, b}; bf2_t r = __builtin_convertvector(v, bf2_t); return __builtin_bit_cast(unsigned, r); }
; DI void mla_item(const Params& p, int l, int item, char* smem) {
;     ...
; #pragma unroll
;     for (int mi = 0; mi < 4; ++mi)
; #pragma unroll
;       for (int np = 0; np < 2; ++np) {
;         int rl = wm * 64 + mi * 16 + fr; size_t t = (size_t)mt * 128 + rl; float s = sRow[rl];
;         int d = (2 * np + (fq & 1)) * 16 + (fq >> 1) * 8;
;         uint2 a, b;
;         a.x = pack2(acc[mi][2 * np][0] * s, acc[mi][2 * np][1] * s); a.y = pack2(acc[mi][2 * np][2] * s, acc[mi][2 * np][3] * s);
;         b.x = pack2(acc[mi][2 * np + 1][0] * s, acc[mi][2 * np + 1][1] * s); b.y = pack2(acc[mi][2 * np + 1][2] * s, acc[mi][2 * np + 1][3] * s);
;         const uint4 w = widen16(a, b);
;         if (wn == 0) *(uint4*)(P_KA + t * 384 + h * 96 + d) = w;
;         else *(uint4*)(P_VA + t * 256 + h * 64 + d) = w;
;       }
	v_mfma_f32_16x16x32_bf16 v[38:41], v[86:89], v[30:33], v[38:41]
	v_mfma_f32_16x16x32_bf16 v[42:45], v[90:93], v[30:33], v[42:45]
	v_mfma_f32_16x16x32_bf16 v[2:5], v[94:97], v[30:33], v[2:5]
	v_mfma_f32_16x16x32_bf16 v[30:33], v[82:85], v[70:73], v[46:49]
	v_mfma_f32_16x16x32_bf16 v[46:49], v[86:89], v[70:73], v[50:53]
	v_mfma_f32_16x16x32_bf16 v[50:53], v[90:93], v[70:73], v[54:57]
	v_mfma_f32_16x16x32_bf16 v[6:9], v[94:97], v[70:73], v[6:9]
	v_mfma_f32_16x16x32_bf16 v[54:57], v[82:85], v[74:77], v[58:61]
	v_mfma_f32_16x16x32_bf16 v[58:61], v[86:89], v[74:77], v[62:65]
	v_mfma_f32_16x16x32_bf16 v[62:65], v[90:93], v[74:77], v[66:69]
	v_mfma_f32_16x16x32_bf16 v[10:13], v[94:97], v[74:77], v[10:13]
	v_mfma_f32_16x16x32_bf16 v[18:21], v[82:85], v[78:81], v[18:21]
	v_mfma_f32_16x16x32_bf16 v[22:25], v[86:89], v[78:81], v[22:25]
	v_mfma_f32_16x16x32_bf16 v[26:29], v[90:93], v[78:81], v[26:29]
	v_mfma_f32_16x16x32_bf16 v[14:17], v[94:97], v[78:81], v[14:17]
	ds_read_b128 v[66:69], v0 offset:16384
	ds_read_b128 v[70:73], v0 offset:18432
	ds_read_b128 v[74:77], v0 offset:20480
	ds_read_b128 v[78:81], v0 offset:22528
	ds_read_b128 v[82:85], v98 offset:49152
	ds_read_b128 v[86:89], v98 offset:51200
	ds_read_b128 v[90:93], v98 offset:53248
	ds_read_b128 v[94:97], v98 offset:55296
	s_waitcnt lgkmcnt(3)
	v_mfma_f32_16x16x32_bf16 v[34:37], v[82:85], v[66:69], v[34:37]
	s_waitcnt lgkmcnt(2)
	v_mfma_f32_16x16x32_bf16 v[38:41], v[86:89], v[66:69], v[38:41]
	s_waitcnt lgkmcnt(1)
	v_mfma_f32_16x16x32_bf16 v[42:45], v[90:93], v[66:69], v[42:45]
	s_waitcnt lgkmcnt(0)
	v_mfma_f32_16x16x32_bf16 v[2:5], v[94:97], v[66:69], v[2:5]
	v_mfma_f32_16x16x32_bf16 v[30:33], v[82:85], v[70:73], v[30:33]
	v_mfma_f32_16x16x32_bf16 v[66:69], v[86:89], v[70:73], v[46:49]
	v_mfma_f32_16x16x32_bf16 v[50:53], v[90:93], v[70:73], v[50:53]
	v_mfma_f32_16x16x32_bf16 v[6:9], v[94:97], v[70:73], v[6:9]
	v_mfma_f32_16x16x32_bf16 v[54:57], v[82:85], v[74:77], v[54:57]
	v_mfma_f32_16x16x32_bf16 v[58:61], v[86:89], v[74:77], v[58:61]
	v_mfma_f32_16x16x32_bf16 v[62:65], v[90:93], v[74:77], v[62:65]
	v_mfma_f32_16x16x32_bf16 v[10:13], v[94:97], v[74:77], v[10:13]
	v_mfma_f32_16x16x32_bf16 v[70:73], v[82:85], v[78:81], v[18:21]
	v_mfma_f32_16x16x32_bf16 v[74:77], v[86:89], v[78:81], v[22:25]
	v_mfma_f32_16x16x32_bf16 v[82:85], v[90:93], v[78:81], v[26:29]
	v_mfma_f32_16x16x32_bf16 v[78:81], v[94:97], v[78:81], v[14:17]
	s_nop 2
	ds_read_b128 v[14:17], v99 offset:16384
	ds_read_b128 v[18:21], v99 offset:18432
	ds_read_b128 v[86:89], v99 offset:20480
	ds_read_b128 v[90:93], v99 offset:22528
	ds_read_b128 v[94:97], v106 offset:49152
	ds_read_b128 v[98:101], v106 offset:51200
	ds_read_b128 v[102:105], v106 offset:53248
	ds_read_b128 v[106:109], v106 offset:55296
	s_waitcnt lgkmcnt(0)
	s_barrier
	v_mfma_f32_16x16x32_bf16 v[46:49], v[94:97], v[18:21], v[30:33]
	v_mfma_f32_16x16x32_bf16 v[30:33], v[94:97], v[86:89], v[54:57]
	v_mfma_f32_16x16x32_bf16 v[22:25], v[102:105], v[86:89], v[62:65]
	s_nop 1
	v_lshl_or_b32 v54, v155, 6, v156
	v_or_b32_e32 v0, s6, v54
	v_mul_hi_u32_u24_e32 v55, 0x300, v0
	v_mov_b32_e32 v65, 0x10000
	v_mfma_f32_16x16x32_bf16 v[114:117], v[98:101], v[14:17], v[38:41]
	v_mfma_f32_16x16x32_bf16 v[38:41], v[102:105], v[18:21], v[50:53]
	s_nop 2
	v_lshl_add_u32 v53, v54, 2, v65
	v_mfma_f32_16x16x32_bf16 v[26:29], v[98:101], v[86:89], v[58:61]
	v_lshlrev_b32_e32 v52, 2, v153
	v_lshlrev_b64 v[50:51], 9, v[0:1]
	s_nop 0
	ds_read_b32 v60, v53
	v_mfma_f32_16x16x32_bf16 v[110:113], v[94:97], v[14:17], v[34:37]
	v_mul_u32_u24_e32 v61, 0x300, v0
	v_and_b32_e32 v0, 16, v154
	v_and_or_b32 v64, v52, 8, v0
	v_mov_b32_e32 v0, 0x1cca4000
	v_mfma_f32_16x16x32_bf16 v[118:121], v[102:105], v[14:17], v[42:45]
	s_waitcnt lgkmcnt(0)
	s_nop 1
	v_mul_f32_e32 v52, v110, v60
	v_mul_f32_e32 v53, v111, v60
	s_nop 0
	v_cvt_pk_bf16_f32 v56, v52, v53
	v_mul_f32_e32 v52, v112, v60
	v_mul_f32_e32 v53, v113, v60
	v_mfma_f32_16x16x32_bf16 v[122:125], v[106:109], v[14:17], v[2:5]
	v_cvt_pk_bf16_f32 v57, v52, v53
	v_mul_f32_e32 v52, v114, v60
	v_mul_f32_e32 v53, v115, v60
	s_nop 0
	v_cvt_pk_bf16_f32 v58, v52, v53
	v_mul_f32_e32 v52, v116, v60
	v_mul_f32_e32 v53, v117, v60
	s_nop 0
	v_permlane16_swap_b32_e32 v56, v58
	v_cvt_pk_bf16_f32 v59, v52, v53
	v_mov_b32_e32 v52, 0x1b4a4000
	v_cndmask_b32_e32 v0, v0, v52, vcc
	v_cndmask_b32_e32 v53, v51, v55, vcc
	v_cndmask_b32_e32 v52, v50, v61, vcc
	v_mov_b32_e32 v50, s0
	v_mov_b32_e32 v51, s1
	v_cndmask_b32_e32 v55, v50, v51, vcc
	v_lshl_add_u64 v[50:51], s[58:59], 0, v[0:1]
	v_lshl_add_u64 v[52:53], v[50:51], 0, v[52:53]
	v_lshlrev_b32_e32 v0, 1, v55
	v_lshl_add_u64 v[62:63], v[52:53], 0, v[0:1]
	v_lshlrev_b32_e32 v52, 1, v64
	v_mov_b32_e32 v53, v1
	v_permlane16_swap_b32_e32 v57, v59
	v_lshl_add_u64 v[62:63], v[62:63], 0, v[52:53]
	global_store_dwordx4 v[62:63], v[56:59], off
	v_or_b32_e32 v55, 16, v54
	v_mfma_f32_16x16x32_bf16 v[42:45], v[98:101], v[18:21], v[66:69]
	v_mul_f32_e64 v56, v118, v60
	v_mul_f32_e64 v57, v119, v60
	v_mul_f32_e32 v58, v120, v60
	v_mul_f32_e32 v59, v121, v60
	v_cvt_pk_bf16_f32 v56, v56, v57
	v_cvt_pk_bf16_f32 v57, v58, v59
	v_mul_f32_e32 v58, v122, v60
	v_mul_f32_e32 v59, v123, v60
	v_mul_f32_e32 v61, v125, v60
	v_mul_f32_e32 v60, v124, v60
	v_cvt_pk_bf16_f32 v58, v58, v59
	v_cvt_pk_bf16_f32 v59, v60, v61
	s_nop 0
	v_permlane16_swap_b32_e32 v56, v58
	v_permlane16_swap_b32_e32 v57, v59
	global_store_dwordx4 v[62:63], v[56:59], off offset:64
	v_mfma_f32_16x16x32_bf16 v[34:37], v[106:109], v[18:21], v[6:9]
	s_nop 0
	v_or_b32_e32 v56, s6, v55
	v_lshl_add_u32 v55, v55, 2, v65
	ds_read_b32 v60, v55
	v_mov_b32_e32 v57, v1
	v_lshlrev_b64 v[58:59], 9, v[56:57]
	v_mad_u64_u32 v[56:57], s[0:1], v56, s7, 0
	s_waitcnt lgkmcnt(0)
; DI unsigned pack2(float a, float b) { f2_t v = {a, b}; bf2_t r = __builtin_convertvector(v, bf2_t); return __builtin_bit_cast(unsigned, r); }
; DI void mla_item(const Params& p, int l, int item, char* smem) {
;     ...
; #pragma unroll
;     for (int mi = 0; mi < 4; ++mi)
; #pragma unroll
;       for (int np = 0; np < 2; ++np) {
;         int rl = wm * 64 + mi * 16 + fr; size_t t = (size_t)mt * 128 + rl; float s = sRow[rl];
;         int d = (2 * np + (fq & 1)) * 16 + (fq >> 1) * 8;
;         uint2 a, b;
;         a.x = pack2(acc[mi][2 * np][0] * s, acc[mi][2 * np][1] * s); a.y = pack2(acc[mi][2 * np][2] * s, acc[mi][2 * np][3] * s);
;         b.x = pack2(acc[mi][2 * np + 1][0] * s, acc[mi][2 * np + 1][1] * s); b.y = pack2(acc[mi][2 * np + 1][2] * s, acc[mi][2 * np + 1][3] * s);
;         const uint4 w = widen16(a, b);
;         if (wn == 0) *(uint4*)(P_KA + t * 384 + h * 96 + d) = w;
;         else *(uint4*)(P_VA + t * 256 + h * 64 + d) = w;
;       }
	v_mul_f32_e32 v46, v46, v60
	v_mul_f32_e32 v47, v47, v60
	v_mul_f32_e32 v48, v48, v60
	v_mul_f32_e32 v49, v49, v60
	v_mul_f32_e32 v42, v42, v60
	v_mul_f32_e32 v43, v43, v60
	v_cvt_pk_bf16_f32 v46, v46, v47
	v_cvt_pk_bf16_f32 v47, v48, v49
	v_cvt_pk_bf16_f32 v48, v42, v43
	v_mul_f32_e32 v42, v44, v60
	v_mul_f32_e32 v43, v45, v60
	v_mul_f32_e32 v38, v38, v60
	v_mul_f32_e32 v39, v39, v60
	v_cvt_pk_bf16_f32 v49, v42, v43
	v_cndmask_b32_e32 v43, v59, v57, vcc
	v_cndmask_b32_e32 v42, v58, v56, vcc
	v_mul_f32_e32 v40, v40, v60
	v_mul_f32_e32 v41, v41, v60
	v_mul_f32_e32 v34, v34, v60
	v_mul_f32_e32 v35, v35, v60
	v_lshl_add_u64 v[42:43], v[50:51], 0, v[42:43]
	v_cvt_pk_bf16_f32 v38, v38, v39
	v_cvt_pk_bf16_f32 v39, v40, v41
	v_cvt_pk_bf16_f32 v40, v34, v35
	v_mul_f32_e32 v34, v36, v60
	v_mul_f32_e32 v35, v37, v60
	v_lshl_add_u64 v[42:43], v[42:43], 0, v[0:1]
	v_cvt_pk_bf16_f32 v41, v34, v35
	v_lshl_add_u64 v[42:43], v[42:43], 0, v[52:53]
	v_permlane16_swap_b32_e32 v38, v40
	v_permlane16_swap_b32_e32 v39, v41
	v_or_b32_e32 v36, 32, v54
	global_store_dwordx4 v[42:43], v[38:41], off offset:64
	v_mfma_f32_16x16x32_bf16 v[18:21], v[106:109], v[86:89], v[10:13]
	v_or_b32_e32 v34, s6, v36
	v_lshl_add_u32 v38, v36, 2, v65
	ds_read_b32 v38, v38
	v_mov_b32_e32 v35, v1
	v_lshlrev_b64 v[36:37], 9, v[34:35]
	v_mad_u64_u32 v[34:35], s[0:1], v34, s7, 0
	s_waitcnt lgkmcnt(0)
	v_mul_f32_e32 v30, v30, v38
	v_mul_f32_e32 v31, v31, v38
	v_mul_f32_e32 v32, v32, v38
	v_mul_f32_e32 v33, v33, v38
	v_mul_f32_e32 v26, v26, v38
	v_mul_f32_e32 v27, v27, v38
	v_cvt_pk_bf16_f32 v30, v30, v31
	v_cvt_pk_bf16_f32 v31, v32, v33
	v_cvt_pk_bf16_f32 v32, v26, v27
	v_mul_f32_e32 v26, v28, v38
	v_mul_f32_e32 v27, v29, v38
	v_mul_f32_e32 v22, v22, v38
	v_mul_f32_e32 v23, v23, v38
	v_cvt_pk_bf16_f32 v33, v26, v27
	v_cndmask_b32_e32 v27, v37, v35, vcc
	v_cndmask_b32_e32 v26, v36, v34, vcc
	v_mul_f32_e32 v24, v24, v38
	v_mul_f32_e32 v25, v25, v38
	v_mul_f32_e32 v18, v18, v38
	v_mul_f32_e32 v19, v19, v38
	v_lshl_add_u64 v[26:27], v[50:51], 0, v[26:27]
	v_cvt_pk_bf16_f32 v22, v22, v23
	v_cvt_pk_bf16_f32 v23, v24, v25
	v_cvt_pk_bf16_f32 v24, v18, v19
	v_mul_f32_e32 v18, v20, v38
	v_mul_f32_e32 v19, v21, v38
	v_lshl_add_u64 v[26:27], v[26:27], 0, v[0:1]
	v_cvt_pk_bf16_f32 v25, v18, v19
	v_permlane16_swap_b32_e32 v46, v48
	v_permlane16_swap_b32_e32 v47, v49
	v_lshl_add_u64 v[26:27], v[26:27], 0, v[52:53]
	v_permlane16_swap_b32_e32 v22, v24
	v_permlane16_swap_b32_e32 v23, v25
	v_or_b32_e32 v20, 48, v54
	global_store_dwordx4 v[42:43], v[46:49], off
	global_store_dwordx4 v[26:27], v[22:25], off offset:64
	v_or_b32_e32 v18, s6, v20
	v_mov_b32_e32 v19, v1
	v_lshl_add_u32 v24, v20, 2, v65
	v_lshlrev_b64 v[20:21], 9, v[18:19]
	v_mad_u64_u32 v[22:23], s[0:1], v18, s7, 0
	ds_read_b32 v18, v24
	v_mfma_f32_16x16x32_bf16 v[14:17], v[94:97], v[90:93], v[70:73]
	v_permlane16_swap_b32_e32 v30, v32
	v_permlane16_swap_b32_e32 v31, v33
	v_mfma_f32_16x16x32_bf16 v[10:13], v[98:101], v[90:93], v[74:77]
	s_waitcnt lgkmcnt(0)
	s_nop 3
	v_mul_f32_e32 v14, v14, v18
	v_mul_f32_e32 v15, v15, v18
	v_mul_f32_e32 v16, v16, v18
	v_mul_f32_e32 v17, v17, v18
	v_cvt_pk_bf16_f32 v14, v14, v15
	v_mfma_f32_16x16x32_bf16 v[6:9], v[102:105], v[90:93], v[82:85]
	v_cvt_pk_bf16_f32 v15, v16, v17
	v_mul_f32_e32 v10, v10, v18
	v_mul_f32_e32 v11, v11, v18
	global_store_dwordx4 v[26:27], v[30:33], off
	v_mfma_f32_16x16x32_bf16 v[2:5], v[106:109], v[90:93], v[78:81]
	v_cvt_pk_bf16_f32 v16, v10, v11
	v_mul_f32_e32 v10, v12, v18
	v_mul_f32_e32 v11, v13, v18
	s_nop 1
	v_mul_f32_e32 v6, v6, v18
	v_mul_f32_e32 v7, v7, v18
	v_cvt_pk_bf16_f32 v17, v10, v11
	v_cndmask_b32_e32 v11, v21, v23, vcc
	v_cndmask_b32_e32 v10, v20, v22, vcc
	v_mul_f32_e32 v8, v8, v18
	v_mul_f32_e32 v9, v9, v18
	v_mul_f32_e32 v2, v2, v18
	v_mul_f32_e32 v3, v3, v18
	v_lshl_add_u64 v[10:11], v[50:51], 0, v[10:11]
	v_cvt_pk_bf16_f32 v6, v6, v7
	v_cvt_pk_bf16_f32 v7, v8, v9
	v_cvt_pk_bf16_f32 v8, v2, v3
	v_mul_f32_e32 v2, v4, v18
	v_mul_f32_e32 v3, v5, v18
	v_lshl_add_u64 v[10:11], v[10:11], 0, v[0:1]
	v_cvt_pk_bf16_f32 v9, v2, v3
	v_permlane16_swap_b32_e32 v14, v16
	v_permlane16_swap_b32_e32 v15, v17
	v_lshl_add_u64 v[10:11], v[10:11], 0, v[52:53]
	v_permlane16_swap_b32_e32 v6, v8
	v_permlane16_swap_b32_e32 v7, v9
	global_store_dwordx4 v[10:11], v[14:17], off
	global_store_dwordx4 v[10:11], v[6:9], off offset:64
	s_mov_b64 s[0:1], 0

; #define BLO(u) __uint_as_float((u) << 16)
; #define BHI(u) __uint_as_float((u) & 0xffff0000u)
; DI int otid() { int t; asm volatile("v_mov_b32 %0, %1" : "=v"(t) : "v"((int)threadIdx.x)); __builtin_assume(t >= 0 && t < 256); return t; }
; DI void row_scales(const bf16_t* A, int lda, int K, float* sRow) {
;   const int row = otid() >> 1, half = otid() & 1;
;   const int per = K >> 1;
;   const bf16_t* a = A + (size_t)row * lda + half * per;
;   float ss = 0.f;
;   for (int c = 0; c < per; c += 8) {
;     uint4 u = *(const uint4*)(a + c);
;     float f;
;     f = BLO(u.x); ss += f * f; f = BHI(u.x); ss += f * f; f = BLO(u.y); ss += f * f; f = BHI(u.y); ss += f * f;
;     f = BLO(u.z); ss += f * f; f = BHI(u.z); ss += f * f; f = BLO(u.w); ss += f * f; f = BHI(u.w); ss += f * f;
;   }
;   ss += __shfl_xor(ss, 1);
;   if (half == 0) sRow[row] = rsqrtf(ss / (float)K + 1e-6f);
; }
; DI void mla_item(const Params& p, int l, int item, char* smem) {
;   bf16_t* sA = (bf16_t*)smem; bf16_t* sB = sA + 2 * GST; float* sRow = (float*)(sB + 2 * GST);
;   const int lane = otid() & 63, wid = otid() >> 6, wm = wid >> 1, wn = wid & 1, fr = lane & 15, fq = lane >> 4;
;   if (item < 768) {
;     const int mt = item & 255, nt = item >> 8;
;     const bf16_t* A = P_PROJ + (size_t)mt * 128 * PW + C_AQ;
;     __syncthreads();
;     row_scales(A, PW, 256, sRow);
;     f32x4 acc[4][4]; zero_acc<4>(acc);
;     gemm_mainloop<4>(acc, A, PW, P_WQT + ((size_t)l * 384 + nt * 128) * 256, 256, 256, sA, sB);
.LBB0_223:
	global_load_dwordx4 v[6:9], v[2:3], off offset:16
	global_load_dwordx4 v[10:13], v[2:3], off
	global_load_dwordx4 v[14:17], v[2:3], off offset:-16
	global_load_dwordx4 v[18:21], v[2:3], off offset:-32
	s_add_i32 s0, s0, 32
	v_lshl_add_u64 v[2:3], v[2:3], 0, 64
	s_cmpk_gt_u32 s0, 0x77
	s_waitcnt vmcnt(0)
	v_lshlrev_b32_e32 v22, 16, v18
	v_fmac_f32_e32 v0, v22, v22
	v_lshlrev_b32_e32 v23, 16, v19
	v_and_b32_e32 v22, 0xffff0000, v18
	v_mul_f32_e32 v22, v22, v22
	v_mul_f32_e32 v23, v23, v23
	v_lshlrev_b32_e32 v18, 16, v20
	v_add_f32_e32 v0, v22, v0
	v_and_b32_e32 v19, 0xffff0000, v19
	v_add_f32_e32 v0, v23, v0
	v_mul_f32_e32 v18, v18, v18
	v_mul_f32_e32 v19, v19, v19
	s_nop 0
	v_add_f32_e32 v0, v19, v0
	v_add_f32_e32 v0, v18, v0
	v_lshlrev_b32_e32 v19, 16, v21
	v_and_b32_e32 v18, 0xffff0000, v20
	v_mul_f32_e32 v18, v18, v18
	v_mul_f32_e32 v19, v19, v19
	s_nop 0
	v_add_f32_e32 v0, v18, v0
	v_add_f32_e32 v0, v19, v0
	v_and_b32_e32 v18, 0xffff0000, v21
	v_fmac_f32_e32 v0, v18, v18
	v_lshlrev_b32_e32 v18, 16, v14
	v_fmac_f32_e32 v0, v18, v18
	v_lshlrev_b32_e32 v19, 16, v15
	v_and_b32_e32 v18, 0xffff0000, v14
	v_mul_f32_e32 v18, v18, v18
	v_mul_f32_e32 v19, v19, v19
	v_lshlrev_b32_e32 v14, 16, v16
	v_add_f32_e32 v0, v18, v0
	v_and_b32_e32 v15, 0xffff0000, v15
	v_add_f32_e32 v0, v19, v0
	v_mul_f32_e32 v14, v14, v14
	v_mul_f32_e32 v15, v15, v15
	s_nop 0
	v_add_f32_e32 v0, v15, v0
	v_add_f32_e32 v0, v14, v0
	v_lshlrev_b32_e32 v15, 16, v17
	v_and_b32_e32 v14, 0xffff0000, v16
	v_mul_f32_e32 v14, v14, v14
	v_mul_f32_e32 v15, v15, v15
	s_nop 0
	v_add_f32_e32 v0, v14, v0
	v_add_f32_e32 v0, v15, v0
	v_and_b32_e32 v14, 0xffff0000, v17
	v_fmac_f32_e32 v0, v14, v14
	v_lshlrev_b32_e32 v14, 16, v10
	v_fmac_f32_e32 v0, v14, v14
	v_lshlrev_b32_e32 v15, 16, v11
	v_and_b32_e32 v14, 0xffff0000, v10
	v_mul_f32_e32 v14, v14, v14
	v_mul_f32_e32 v15, v15, v15
	v_lshlrev_b32_e32 v10, 16, v12
	v_add_f32_e32 v0, v14, v0
	v_and_b32_e32 v11, 0xffff0000, v11
	v_add_f32_e32 v0, v15, v0
	v_mul_f32_e32 v10, v10, v10
	v_mul_f32_e32 v11, v11, v11
	s_nop 0
	v_add_f32_e32 v0, v11, v0
	v_add_f32_e32 v0, v10, v0
	v_lshlrev_b32_e32 v11, 16, v13
	v_and_b32_e32 v10, 0xffff0000, v12
	v_mul_f32_e32 v10, v10, v10
	v_mul_f32_e32 v11, v11, v11
	s_nop 0
	v_add_f32_e32 v0, v10, v0
	v_add_f32_e32 v0, v11, v0
	v_and_b32_e32 v10, 0xffff0000, v13
	v_fmac_f32_e32 v0, v10, v10
	v_lshlrev_b32_e32 v10, 16, v6
	v_fmac_f32_e32 v0, v10, v10
	v_lshlrev_b32_e32 v11, 16, v7
	v_and_b32_e32 v10, 0xffff0000, v6
	v_mul_f32_e32 v10, v10, v10
	v_mul_f32_e32 v11, v11, v11
	v_lshlrev_b32_e32 v6, 16, v8
	v_add_f32_e32 v0, v10, v0
	v_and_b32_e32 v7, 0xffff0000, v7
	v_add_f32_e32 v0, v11, v0
	v_mul_f32_e32 v6, v6, v6
	v_mul_f32_e32 v7, v7, v7
	s_nop 0
	v_add_f32_e32 v0, v7, v0
	v_add_f32_e32 v0, v6, v0
	v_lshlrev_b32_e32 v7, 16, v9
	v_and_b32_e32 v6, 0xffff0000, v8
	v_mul_f32_e32 v6, v6, v6
	v_mul_f32_e32 v7, v7, v7
	s_nop 0
	v_add_f32_e32 v0, v6, v0
	v_add_f32_e32 v0, v7, v0
	v_and_b32_e32 v6, 0xffff0000, v9
	v_fmac_f32_e32 v0, v6, v6
	s_cbranch_scc0 .LBB0_223
	v_cmp_lt_i32_e32 vcc, v195, v189
	s_nop 1
	v_cndmask_b32_e32 v2, v204, v195, vcc
	v_lshlrev_b32_e32 v2, 2, v2
	ds_bpermute_b32 v2, v2, v0
	v_cmp_eq_u32_e32 vcc, 0, v5
	s_and_saveexec_b64 s[0:1], vcc
	s_cbranch_execz .LBB0_226
	s_waitcnt lgkmcnt(0)
	v_add_f32_e32 v0, v0, v2
	v_fmamk_f32 v0, v0, 0x3b800000, v190
	v_mul_f32_e32 v2, 0x4b800000, v0
	v_cmp_gt_f32_e32 vcc, s3, v0
	s_nop 1
	v_cndmask_b32_e32 v0, v0, v2, vcc
	v_rsq_f32_e32 v0, v0
	s_nop 0
	v_mul_f32_e32 v2, 0x45800000, v0
	v_cndmask_b32_e32 v0, v0, v2, vcc
	v_mov_b32_e32 v2, 0x10000
	v_lshl_add_u32 v2, v4, 2, v2
	ds_write_b32 v2, v0
.LBB0_226:
	s_or_b64 exec, exec, s[0:1]
	s_lshl_b32 s1, s27, 7
	s_and_b32 s7, s1, 0x7f80
	s_ashr_i32 s0, s27, 8
	s_mul_i32 s1, s7, 0x2600
	s_add_u32 s12, s58, s1
	s_addc_u32 s13, s59, 0
	s_lshl_b32 s6, s0, 7
	s_ashr_i32 s1, s6, 31
	s_add_u32 s22, s25, s6
	v_mov_b32 v18, v188
	s_addc_u32 s23, 0, s1
	v_lshrrev_b32_e32 v20, 3, v18
	v_mul_u32_u24_e32 v0, 0x2600, v20
	s_lshl_b64 s[22:23], s[22:23], 9
	v_readlane_b32 s1, v253, 16
	s_waitcnt lgkmcnt(0)
	v_lshl_add_u64 v[2:3], s[12:13], 0, v[0:1]
	v_lshlrev_b32_e32 v0, 4, v18
	s_add_u32 s22, s1, s22
	v_readlane_b32 s1, v253, 17
	v_and_b32_e32 v0, 0x70, v0
	s_addc_u32 s23, s1, s23
	v_lshl_add_u64 v[16:17], v[2:3], 0, v[0:1]
	v_lshlrev_b32_e32 v2, 9, v20
	v_mov_b32_e32 v3, v1
	s_mov_b32 s1, 0x6ca6000
	v_lshl_add_u64 v[8:9], s[22:23], 0, v[2:3]
	v_add_co_u32_e32 v2, vcc, s1, v16
	s_mov_b32 s1, 0x6cf2000
	s_nop 0
	v_addc_co_u32_e32 v3, vcc, 0, v17, vcc
	v_lshl_add_u64 v[8:9], v[8:9], 0, v[0:1]
	s_barrier
; DI int otid() { int t; asm volatile("v_mov_b32 %0, %1" : "=v"(t) : "v"((int)threadIdx.x)); __builtin_assume(t >= 0 && t < 256); return t; }
; #define GLOAD(ko) do { \
;     _Pragma("unroll") for (int i = 0; i < 4; ++i) ra[i] = *(const u32x4*)(ap + (size_t)(32 * i) * lda + (ko)); \
;     _Pragma("unroll") for (int i = 0; i < NB; ++i) rb[i] = *(const u32x4*)(bp + (size_t)(bstride * i) * ldb + (ko)); } while (0)
; #define GSTORE(st) do { \
;     _Pragma("unroll") for (int i = 0; i < 4; ++i) *(u32x4*)(sA + (st) * GST + so + 32 * i * 64) = ra[i]; \
;     _Pragma("unroll") for (int i = 0; i < NB; ++i) *(u32x4*)(sB + (st) * GST + so + 32 * i * 64) = rb[i]; } while (0)
;   constexpr int NB = NT;
;   const int tid = otid(), lane = tid & 63, wid = tid >> 6;
;   const int wm = wid >> 1, wn = wid & 1, fr = lane & 15, fq = lane >> 4;
;   u32x4 ra[4], rb[NB];
;   const int nk = K >> 6;
;   const bf16_t* ap = A + (size_t)(tid >> 3) * lda + (tid & 7) * 8;
;   const bf16_t* bp = Bt + (size_t)(tid >> 3) * ldb + (tid & 7) * 8;
;   const int so = (tid >> 3) * 64 + (((tid & 7) ^ ((tid >> 4) & 7)) * 8);
;   const int fsw = fr >> 1;
;     ...
;   __syncthreads();
;   GLOAD(0); GSTORE(0);
;   if (nk > 1) GLOAD(64);
;   __syncthreads();
;   for (int kt = 0; kt < nk; ++kt) {
;     const int cur = kt & 1;
;     if (kt + 1 < nk) { GSTORE(cur ^ 1); if (kt + 2 < nk) GLOAD((kt + 2) * 64); }
;     if (LOWREG) {
;       const bf16_t* cA = sA + cur * GST; const bf16_t* cB = sB + cur * GST;
; #pragma nounroll
;       for (int ks = 0; ks < 2; ++ks) {
;         bf16x8 af[4], bfr[NT];
; #pragma unroll
;         for (int mi = 0; mi < 4; ++mi) af[mi] = *(const bf16x8*)(cA + (wm * 64 + mi * 16 + fr) * 64 + (((ks * 4 + fq) ^ fsw) * 8));
; #pragma unroll
;         for (int ni = 0; ni < NT; ++ni) bfr[ni] = *(const bf16x8*)(cB + (wn * NT * 16 + ni * 16 + fr) * 64 + (((ks * 4 + fq) ^ fsw) * 8));
; #pragma unroll
;         for (int mi = 0; mi < 4; ++mi)
; #pragma unroll
;           for (int ni = 0; ni < NT; ++ni) acc[mi][ni] = __builtin_amdgcn_mfma_f32_16x16x32_bf16(bfr[ni], af[mi], acc[mi][ni], 0, 0, 0);
;       }
;     } else GCOMPUTE(cur);
;     __syncthreads();
;   }
	global_load_dwordx4 v[22:25], v[2:3], off offset:512
	global_load_dwordx4 v[38:41], v[8:9], off
	v_add_co_u32_e32 v2, vcc, s1, v16
	s_mov_b32 s1, 0x6d3e000
	s_nop 0
	v_addc_co_u32_e32 v3, vcc, 0, v17, vcc
	v_add_co_u32_e32 v4, vcc, s1, v16
	s_mov_b32 s1, 0x6d8a000
	s_nop 0
	v_addc_co_u32_e32 v5, vcc, 0, v17, vcc
	v_add_co_u32_e32 v6, vcc, s1, v16
	global_load_dwordx4 v[26:29], v[2:3], off offset:512
	global_load_dwordx4 v[30:33], v[4:5], off offset:512
	v_addc_co_u32_e32 v7, vcc, 0, v17, vcc
	v_add_co_u32_e32 v10, vcc, s2, v8
	s_mov_b32 s1, 0x8000
	s_nop 0
	v_addc_co_u32_e32 v11, vcc, 0, v9, vcc
	global_load_dwordx4 v[34:37], v[6:7], off offset:512
	global_load_dwordx4 v[42:45], v[10:11], off
	v_add_co_u32_e32 v12, vcc, s1, v8
	v_lshrrev_b32_e32 v0, 4, v18
	s_nop 0
	v_addc_co_u32_e32 v13, vcc, 0, v9, vcc
	v_add_co_u32_e32 v14, vcc, s80, v8
	global_load_dwordx4 v[46:49], v[12:13], off
	s_nop 0
	v_addc_co_u32_e32 v15, vcc, 0, v9, vcc
	global_load_dwordx4 v[50:53], v[14:15], off
	v_lshlrev_b32_e32 v19, 7, v18
	v_xor_b32_e32 v54, v0, v18
	v_and_b32_e32 v123, 0x2780, v19
	v_lshlrev_b32_e32 v19, 4, v54
	s_mov_b64 s[12:13], 0x6ca6200
	v_and_b32_e32 v54, 0x70, v19
	v_lshl_add_u64 v[16:17], v[16:17], 0, s[12:13]
	v_lshl_or_b32 v20, v20, 7, v54
	global_load_dwordx4 v[54:57], v[16:17], off offset:128
	global_load_dwordx4 v[58:61], v[2:3], off offset:640
	global_load_dwordx4 v[62:65], v[4:5], off offset:640
	global_load_dwordx4 v[66:69], v[6:7], off offset:640
	global_load_dwordx4 v[70:73], v[8:9], off offset:128
	global_load_dwordx4 v[74:77], v[10:11], off offset:128
	global_load_dwordx4 v[78:81], v[12:13], off offset:128
	global_load_dwordx4 v[82:85], v[14:15], off offset:128
	v_bfe_u32 v122, v18, 1, 3
	v_bitop3_b32 v0, v0, v122, 3 bitop3:0x6c
	v_lshlrev_b32_e32 v0, 4, v0
	v_or_b32_e32 v19, v0, v123
	v_and_b32_e32 v21, 15, v18
	v_lshrrev_b32_e32 v86, 1, v18
	v_and_or_b32 v21, v86, 64, v21
	v_bfe_u32 v18, v18, 4, 2
	v_lshlrev_b32_e32 v126, 7, v21
	v_bitop3_b32 v18, v18, v122, 4 bitop3:0x36
	v_or_b32_e32 v0, v0, v126
	v_lshlrev_b32_e32 v18, 4, v18
	v_or_b32_e32 v21, v18, v123
	v_or_b32_e32 v18, v18, v126
	s_cmp_lt_i32 s0, 2
	s_mov_b64 s[0:1], -1
	s_waitcnt vmcnt(15)
	ds_write_b128 v20, v[22:25]
	s_waitcnt vmcnt(13)
	ds_write_b128 v20, v[26:29] offset:4096
	s_waitcnt vmcnt(12)
	ds_write_b128 v20, v[30:33] offset:8192
	s_waitcnt vmcnt(11)
	ds_write_b128 v20, v[34:37] offset:12288
	ds_write_b128 v20, v[38:41] offset:32768
	s_waitcnt vmcnt(10)
	ds_write_b128 v20, v[42:45] offset:36864
	s_waitcnt vmcnt(9)
	ds_write_b128 v20, v[46:49] offset:40960
	s_waitcnt vmcnt(8)
	ds_write_b128 v20, v[50:53] offset:45056
	s_waitcnt lgkmcnt(0)
	s_barrier
	ds_read_b128 v[22:25], v19 offset:32768
	ds_read_b128 v[34:37], v19 offset:34816
	ds_read_b128 v[42:45], v19 offset:36864
	ds_read_b128 v[50:53], v19 offset:38912
	ds_read_b128 v[26:29], v0
	ds_read_b128 v[86:89], v0 offset:2048
	ds_read_b128 v[102:105], v0 offset:4096
	ds_read_b128 v[118:121], v0 offset:6144
	ds_read_b128 v[122:125], v21 offset:32768
	ds_read_b128 v[126:129], v21 offset:34816
	ds_read_b128 v[130:133], v21 offset:36864
	ds_read_b128 v[134:137], v21 offset:38912
	s_waitcnt lgkmcnt(7)
	v_mfma_f32_16x16x32_bf16 v[30:33], v[22:25], v[26:29], 0
	ds_read_b128 v[138:141], v18 offset:6144
	v_mfma_f32_16x16x32_bf16 v[38:41], v[34:37], v[26:29], 0
	v_mfma_f32_16x16x32_bf16 v[46:49], v[42:45], v[26:29], 0
	v_mfma_f32_16x16x32_bf16 v[26:29], v[50:53], v[26:29], 0
	s_waitcnt lgkmcnt(7)
	v_mfma_f32_16x16x32_bf16 v[90:93], v[22:25], v[86:89], 0
	v_mfma_f32_16x16x32_bf16 v[94:97], v[34:37], v[86:89], 0
	v_mfma_f32_16x16x32_bf16 v[98:101], v[42:45], v[86:89], 0
	v_mfma_f32_16x16x32_bf16 v[86:89], v[50:53], v[86:89], 0
	s_waitcnt lgkmcnt(6)
	v_mfma_f32_16x16x32_bf16 v[106:109], v[22:25], v[102:105], 0
	v_mfma_f32_16x16x32_bf16 v[110:113], v[34:37], v[102:105], 0
	v_mfma_f32_16x16x32_bf16 v[114:117], v[42:45], v[102:105], 0
	v_mfma_f32_16x16x32_bf16 v[102:105], v[50:53], v[102:105], 0
	s_waitcnt lgkmcnt(5)
	v_mfma_f32_16x16x32_bf16 v[22:25], v[22:25], v[118:121], 0
	v_mfma_f32_16x16x32_bf16 v[34:37], v[34:37], v[118:121], 0
	v_mfma_f32_16x16x32_bf16 v[42:45], v[42:45], v[118:121], 0
	v_mfma_f32_16x16x32_bf16 v[50:53], v[50:53], v[118:121], 0
	ds_read_b128 v[118:121], v18
	s_waitcnt lgkmcnt(0)
	v_mfma_f32_16x16x32_bf16 v[30:33], v[122:125], v[118:121], v[30:33]
	v_mfma_f32_16x16x32_bf16 v[38:41], v[126:129], v[118:121], v[38:41]
	v_mfma_f32_16x16x32_bf16 v[46:49], v[130:133], v[118:121], v[46:49]
	v_mfma_f32_16x16x32_bf16 v[26:29], v[134:137], v[118:121], v[26:29]
	ds_read_b128 v[118:121], v18 offset:2048
	s_waitcnt lgkmcnt(0)
	v_mfma_f32_16x16x32_bf16 v[90:93], v[122:125], v[118:121], v[90:93]
	v_mfma_f32_16x16x32_bf16 v[94:97], v[126:129], v[118:121], v[94:97]
	v_mfma_f32_16x16x32_bf16 v[98:101], v[130:133], v[118:121], v[98:101]
	v_mfma_f32_16x16x32_bf16 v[86:89], v[134:137], v[118:121], v[86:89]
	ds_read_b128 v[118:121], v18 offset:4096
	s_waitcnt vmcnt(7)
	ds_write_b128 v20, v[54:57] offset:16384
	s_waitcnt vmcnt(6)
	ds_write_b128 v20, v[58:61] offset:20480
	s_waitcnt vmcnt(5)
	ds_write_b128 v20, v[62:65] offset:24576
	s_waitcnt vmcnt(4)
	ds_write_b128 v20, v[66:69] offset:28672
	s_waitcnt vmcnt(3)
	ds_write_b128 v20, v[70:73] offset:49152
	s_waitcnt vmcnt(2)
	ds_write_b128 v20, v[74:77] offset:53248
	s_waitcnt vmcnt(1)
	ds_write_b128 v20, v[78:81] offset:57344
	s_waitcnt vmcnt(0)
	ds_write_b128 v20, v[82:85] offset:61440
	s_waitcnt lgkmcnt(8)
	v_mfma_f32_16x16x32_bf16 v[54:57], v[130:133], v[118:121], v[114:117]
	global_load_dwordx4 v[62:65], v[14:15], off offset:256
	global_load_dwordx4 v[66:69], v[12:13], off offset:256
	global_load_dwordx4 v[70:73], v[10:11], off offset:256
	global_load_dwordx4 v[74:77], v[8:9], off offset:256
	v_mfma_f32_16x16x32_bf16 v[58:61], v[134:137], v[118:121], v[102:105]
	global_load_dwordx4 v[78:81], v[6:7], off offset:768
	global_load_dwordx4 v[82:85], v[4:5], off offset:768
	s_nop 0
	global_load_dwordx4 v[102:105], v[2:3], off offset:768
	global_load_dwordx4 v[114:117], v[16:17], off offset:256
	s_waitcnt lgkmcnt(0)
	s_barrier
; DI int otid() { int t; asm volatile("v_mov_b32 %0, %1" : "=v"(t) : "v"((int)threadIdx.x)); __builtin_assume(t >= 0 && t < 256); return t; }
; #define GLOAD(ko) do { \
;     _Pragma("unroll") for (int i = 0; i < 4; ++i) ra[i] = *(const u32x4*)(ap + (size_t)(32 * i) * lda + (ko)); \
;     _Pragma("unroll") for (int i = 0; i < NB; ++i) rb[i] = *(const u32x4*)(bp + (size_t)(bstride * i) * ldb + (ko)); } while (0)
; #define GSTORE(st) do { \
;     _Pragma("unroll") for (int i = 0; i < 4; ++i) *(u32x4*)(sA + (st) * GST + so + 32 * i * 64) = ra[i]; \
;     _Pragma("unroll") for (int i = 0; i < NB; ++i) *(u32x4*)(sB + (st) * GST + so + 32 * i * 64) = rb[i]; } while (0)
;   constexpr int NB = NT;
;   const int tid = otid(), lane = tid & 63, wid = tid >> 6;
;   const int wm = wid >> 1, wn = wid & 1, fr = lane & 15, fq = lane >> 4;
;   u32x4 ra[4], rb[NB];
;   const int nk = K >> 6;
;   const bf16_t* ap = A + (size_t)(tid >> 3) * lda + (tid & 7) * 8;
;   const bf16_t* bp = Bt + (size_t)(tid >> 3) * ldb + (tid & 7) * 8;
;   const int so = (tid >> 3) * 64 + (((tid & 7) ^ ((tid >> 4) & 7)) * 8);
;   const int fsw = fr >> 1;
;     ...
;   __syncthreads();
;   GLOAD(0); GSTORE(0);
;   if (nk > 1) GLOAD(64);
;   __syncthreads();
;   for (int kt = 0; kt < nk; ++kt) {
;     const int cur = kt & 1;
;     if (kt + 1 < nk) { GSTORE(cur ^ 1); if (kt + 2 < nk) GLOAD((kt + 2) * 64); }
;     if (LOWREG) {
;       const bf16_t* cA = sA + cur * GST; const bf16_t* cB = sB + cur * GST;
; #pragma nounroll
;       for (int ks = 0; ks < 2; ++ks) {
;         bf16x8 af[4], bfr[NT];
; #pragma unroll
;         for (int mi = 0; mi < 4; ++mi) af[mi] = *(const bf16x8*)(cA + (wm * 64 + mi * 16 + fr) * 64 + (((ks * 4 + fq) ^ fsw) * 8));
; #pragma unroll
;         for (int ni = 0; ni < NT; ++ni) bfr[ni] = *(const bf16x8*)(cB + (wn * NT * 16 + ni * 16 + fr) * 64 + (((ks * 4 + fq) ^ fsw) * 8));
; #pragma unroll
;         for (int mi = 0; mi < 4; ++mi)
; #pragma unroll
;           for (int ni = 0; ni < NT; ++ni) acc[mi][ni] = __builtin_amdgcn_mfma_f32_16x16x32_bf16(bfr[ni], af[mi], acc[mi][ni], 0, 0, 0);
;       }
;     } else GCOMPUTE(cur);
;     __syncthreads();
;   }
	v_mfma_f32_16x16x32_bf16 v[106:109], v[122:125], v[118:121], v[106:109]
	v_mfma_f32_16x16x32_bf16 v[110:113], v[126:129], v[118:121], v[110:113]
	ds_read_b128 v[118:121], v19 offset:49152
	v_mfma_f32_16x16x32_bf16 v[34:37], v[126:129], v[138:141], v[34:37]
	ds_read_b128 v[126:129], v19 offset:51200
	v_mfma_f32_16x16x32_bf16 v[42:45], v[130:133], v[138:141], v[42:45]
	ds_read_b128 v[130:133], v19 offset:53248
	v_mfma_f32_16x16x32_bf16 v[50:53], v[134:137], v[138:141], v[50:53]
	ds_read_b128 v[134:137], v19 offset:55296
	v_mfma_f32_16x16x32_bf16 v[22:25], v[122:125], v[138:141], v[22:25]
	ds_read_b128 v[122:125], v0 offset:16384
	ds_read_b128 v[138:141], v18 offset:22528
	s_waitcnt lgkmcnt(1)
	v_mfma_f32_16x16x32_bf16 v[30:33], v[118:121], v[122:125], v[30:33]
	v_mfma_f32_16x16x32_bf16 v[38:41], v[126:129], v[122:125], v[38:41]
	v_mfma_f32_16x16x32_bf16 v[46:49], v[130:133], v[122:125], v[46:49]
	v_mfma_f32_16x16x32_bf16 v[26:29], v[134:137], v[122:125], v[26:29]
	ds_read_b128 v[122:125], v0 offset:18432
	s_waitcnt lgkmcnt(0)
	v_mfma_f32_16x16x32_bf16 v[90:93], v[118:121], v[122:125], v[90:93]
	v_mfma_f32_16x16x32_bf16 v[94:97], v[126:129], v[122:125], v[94:97]
	v_mfma_f32_16x16x32_bf16 v[98:101], v[130:133], v[122:125], v[98:101]
	v_mfma_f32_16x16x32_bf16 v[86:89], v[134:137], v[122:125], v[86:89]
	ds_read_b128 v[122:125], v0 offset:20480
	s_waitcnt lgkmcnt(0)
	v_mfma_f32_16x16x32_bf16 v[106:109], v[118:121], v[122:125], v[106:109]
	v_mfma_f32_16x16x32_bf16 v[110:113], v[126:129], v[122:125], v[110:113]
	v_mfma_f32_16x16x32_bf16 v[54:57], v[130:133], v[122:125], v[54:57]
	v_mfma_f32_16x16x32_bf16 v[58:61], v[134:137], v[122:125], v[58:61]
	ds_read_b128 v[122:125], v0 offset:22528
	s_waitcnt lgkmcnt(0)
	v_mfma_f32_16x16x32_bf16 v[22:25], v[118:121], v[122:125], v[22:25]
	ds_read_b128 v[118:121], v21 offset:49152
	v_mfma_f32_16x16x32_bf16 v[34:37], v[126:129], v[122:125], v[34:37]
	ds_read_b128 v[126:129], v21 offset:51200
	v_mfma_f32_16x16x32_bf16 v[42:45], v[130:133], v[122:125], v[42:45]
	ds_read_b128 v[130:133], v21 offset:53248
	v_mfma_f32_16x16x32_bf16 v[50:53], v[134:137], v[122:125], v[50:53]
	ds_read_b128 v[134:137], v21 offset:55296
	ds_read_b128 v[122:125], v18 offset:16384
	s_waitcnt lgkmcnt(0)
	v_mfma_f32_16x16x32_bf16 v[30:33], v[118:121], v[122:125], v[30:33]
	v_mfma_f32_16x16x32_bf16 v[38:41], v[126:129], v[122:125], v[38:41]
	v_mfma_f32_16x16x32_bf16 v[46:49], v[130:133], v[122:125], v[46:49]
	v_mfma_f32_16x16x32_bf16 v[26:29], v[134:137], v[122:125], v[26:29]
	ds_read_b128 v[122:125], v18 offset:18432
	s_waitcnt lgkmcnt(0)
	v_mfma_f32_16x16x32_bf16 v[90:93], v[118:121], v[122:125], v[90:93]
	v_mfma_f32_16x16x32_bf16 v[94:97], v[126:129], v[122:125], v[94:97]
	v_mfma_f32_16x16x32_bf16 v[98:101], v[130:133], v[122:125], v[98:101]
	v_mfma_f32_16x16x32_bf16 v[86:89], v[134:137], v[122:125], v[86:89]
	ds_read_b128 v[122:125], v18 offset:20480
	s_waitcnt vmcnt(0)
	ds_write_b128 v20, v[114:117]
	ds_write_b128 v20, v[102:105] offset:4096
	ds_write_b128 v20, v[82:85] offset:8192
	ds_write_b128 v20, v[78:81] offset:12288
	ds_write_b128 v20, v[74:77] offset:32768
	ds_write_b128 v20, v[70:73] offset:36864
	ds_write_b128 v20, v[66:69] offset:40960
	ds_write_b128 v20, v[62:65] offset:45056
	global_load_dwordx4 v[62:65], v[14:15], off offset:384
	s_nop 0
	global_load_dwordx4 v[12:15], v[12:13], off offset:384
	s_nop 0
	global_load_dwordx4 v[66:69], v[10:11], off offset:384
	s_nop 0
	global_load_dwordx4 v[8:11], v[8:9], off offset:384
	s_nop 0
	global_load_dwordx4 v[70:73], v[6:7], off offset:896
	s_nop 0
	global_load_dwordx4 v[4:7], v[4:5], off offset:896
	s_nop 0
	global_load_dwordx4 v[74:77], v[2:3], off offset:896
	global_load_dwordx4 v[78:81], v[16:17], off offset:384
	s_waitcnt lgkmcnt(8)
	v_mfma_f32_16x16x32_bf16 v[106:109], v[118:121], v[122:125], v[106:109]
	s_waitcnt lgkmcnt(0)
	s_barrier
	v_mfma_f32_16x16x32_bf16 v[110:113], v[126:129], v[122:125], v[110:113]
	ds_read_b128 v[82:85], v19 offset:32768
	ds_read_b128 v[102:105], v0
	ds_read_b128 v[114:117], v19 offset:34816
	v_mfma_f32_16x16x32_bf16 v[54:57], v[130:133], v[122:125], v[54:57]
	v_mfma_f32_16x16x32_bf16 v[58:61], v[134:137], v[122:125], v[58:61]
	ds_read_b128 v[122:125], v19 offset:38912
	v_mfma_f32_16x16x32_bf16 v[22:25], v[118:121], v[138:141], v[22:25]
	ds_read_b128 v[118:121], v19 offset:36864
	s_waitcnt lgkmcnt(3)
	v_mfma_f32_16x16x32_bf16 v[30:33], v[82:85], v[102:105], v[30:33]
	s_waitcnt lgkmcnt(2)
	v_mfma_f32_16x16x32_bf16 v[38:41], v[114:117], v[102:105], v[38:41]
	s_waitcnt lgkmcnt(0)
	v_mfma_f32_16x16x32_bf16 v[46:49], v[118:121], v[102:105], v[46:49]
	v_mfma_f32_16x16x32_bf16 v[26:29], v[122:125], v[102:105], v[26:29]
	ds_read_b128 v[102:105], v0 offset:2048
	s_waitcnt lgkmcnt(0)
	v_mfma_f32_16x16x32_bf16 v[90:93], v[82:85], v[102:105], v[90:93]
	v_mfma_f32_16x16x32_bf16 v[94:97], v[114:117], v[102:105], v[94:97]
	v_mfma_f32_16x16x32_bf16 v[98:101], v[118:121], v[102:105], v[98:101]
	v_mfma_f32_16x16x32_bf16 v[86:89], v[122:125], v[102:105], v[86:89]
	ds_read_b128 v[102:105], v0 offset:4096
	s_waitcnt lgkmcnt(0)
	v_mfma_f32_16x16x32_bf16 v[106:109], v[82:85], v[102:105], v[106:109]
	v_mfma_f32_16x16x32_bf16 v[110:113], v[114:117], v[102:105], v[110:113]
	v_mfma_f32_16x16x32_bf16 v[54:57], v[118:121], v[102:105], v[54:57]
	v_mfma_f32_16x16x32_bf16 v[58:61], v[122:125], v[102:105], v[58:61]
	ds_read_b128 v[102:105], v0 offset:6144
	v_mfma_f32_16x16x32_bf16 v[34:37], v[126:129], v[138:141], v[34:37]
	v_mfma_f32_16x16x32_bf16 v[42:45], v[130:133], v[138:141], v[42:45]
	v_mfma_f32_16x16x32_bf16 v[50:53], v[134:137], v[138:141], v[50:53]
	s_waitcnt lgkmcnt(0)
; DI int otid() { int t; asm volatile("v_mov_b32 %0, %1" : "=v"(t) : "v"((int)threadIdx.x)); __builtin_assume(t >= 0 && t < 256); return t; }
; #define GLOAD(ko) do { \
;     _Pragma("unroll") for (int i = 0; i < 4; ++i) ra[i] = *(const u32x4*)(ap + (size_t)(32 * i) * lda + (ko)); \
;     _Pragma("unroll") for (int i = 0; i < NB; ++i) rb[i] = *(const u32x4*)(bp + (size_t)(bstride * i) * ldb + (ko)); } while (0)
; #define GSTORE(st) do { \
;     _Pragma("unroll") for (int i = 0; i < 4; ++i) *(u32x4*)(sA + (st) * GST + so + 32 * i * 64) = ra[i]; \
;     _Pragma("unroll") for (int i = 0; i < NB; ++i) *(u32x4*)(sB + (st) * GST + so + 32 * i * 64) = rb[i]; } while (0)
;   constexpr int NB = NT;
;   const int tid = otid(), lane = tid & 63, wid = tid >> 6;
;   const int wm = wid >> 1, wn = wid & 1, fr = lane & 15, fq = lane >> 4;
;   u32x4 ra[4], rb[NB];
;   const int nk = K >> 6;
;   const bf16_t* ap = A + (size_t)(tid >> 3) * lda + (tid & 7) * 8;
;   const bf16_t* bp = Bt + (size_t)(tid >> 3) * ldb + (tid & 7) * 8;
;   const int so = (tid >> 3) * 64 + (((tid & 7) ^ ((tid >> 4) & 7)) * 8);
;   const int fsw = fr >> 1;
;     ...
;   __syncthreads();
;   GLOAD(0); GSTORE(0);
;   if (nk > 1) GLOAD(64);
;   __syncthreads();
;   for (int kt = 0; kt < nk; ++kt) {
;     const int cur = kt & 1;
;     if (kt + 1 < nk) { GSTORE(cur ^ 1); if (kt + 2 < nk) GLOAD((kt + 2) * 64); }
;     if (LOWREG) {
;       const bf16_t* cA = sA + cur * GST; const bf16_t* cB = sB + cur * GST;
; #pragma nounroll
;       for (int ks = 0; ks < 2; ++ks) {
;         bf16x8 af[4], bfr[NT];
; #pragma unroll
;         for (int mi = 0; mi < 4; ++mi) af[mi] = *(const bf16x8*)(cA + (wm * 64 + mi * 16 + fr) * 64 + (((ks * 4 + fq) ^ fsw) * 8));
; #pragma unroll
;         for (int ni = 0; ni < NT; ++ni) bfr[ni] = *(const bf16x8*)(cB + (wn * NT * 16 + ni * 16 + fr) * 64 + (((ks * 4 + fq) ^ fsw) * 8));
; #pragma unroll
;         for (int mi = 0; mi < 4; ++mi)
; #pragma unroll
;           for (int ni = 0; ni < NT; ++ni) acc[mi][ni] = __builtin_amdgcn_mfma_f32_16x16x32_bf16(bfr[ni], af[mi], acc[mi][ni], 0, 0, 0);
;       }
;     } else GCOMPUTE(cur);
;     __syncthreads();
;   }
; DI void mla_item(const Params& p, int l, int item, char* smem) {
;     ...
;     if (nt < 2) {
	v_mfma_f32_16x16x32_bf16 v[22:25], v[82:85], v[102:105], v[22:25]
	ds_read_b128 v[82:85], v21 offset:32768
	v_mfma_f32_16x16x32_bf16 v[34:37], v[114:117], v[102:105], v[34:37]
	ds_read_b128 v[114:117], v21 offset:34816
	v_mfma_f32_16x16x32_bf16 v[42:45], v[118:121], v[102:105], v[42:45]
	ds_read_b128 v[118:121], v21 offset:36864
	v_mfma_f32_16x16x32_bf16 v[50:53], v[122:125], v[102:105], v[50:53]
	ds_read_b128 v[122:125], v21 offset:38912
	ds_read_b128 v[102:105], v18
	s_waitcnt lgkmcnt(0)
	v_mfma_f32_16x16x32_bf16 v[30:33], v[82:85], v[102:105], v[30:33]
	v_mfma_f32_16x16x32_bf16 v[38:41], v[114:117], v[102:105], v[38:41]
	v_mfma_f32_16x16x32_bf16 v[46:49], v[118:121], v[102:105], v[46:49]
	v_mfma_f32_16x16x32_bf16 v[26:29], v[122:125], v[102:105], v[26:29]
	ds_read_b128 v[102:105], v18 offset:2048
	s_waitcnt lgkmcnt(0)
	v_mfma_f32_16x16x32_bf16 v[90:93], v[82:85], v[102:105], v[90:93]
	v_mfma_f32_16x16x32_bf16 v[94:97], v[114:117], v[102:105], v[94:97]
	v_mfma_f32_16x16x32_bf16 v[98:101], v[118:121], v[102:105], v[98:101]
	v_mfma_f32_16x16x32_bf16 v[86:89], v[122:125], v[102:105], v[86:89]
	ds_read_b128 v[102:105], v18 offset:4096
	s_waitcnt lgkmcnt(0)
	v_mfma_f32_16x16x32_bf16 v[106:109], v[82:85], v[102:105], v[106:109]
	v_mfma_f32_16x16x32_bf16 v[110:113], v[114:117], v[102:105], v[110:113]
	v_mfma_f32_16x16x32_bf16 v[54:57], v[118:121], v[102:105], v[54:57]
	v_mfma_f32_16x16x32_bf16 v[58:61], v[122:125], v[102:105], v[58:61]
	ds_read_b128 v[102:105], v18 offset:6144
	s_waitcnt vmcnt(0)
	ds_write_b128 v20, v[78:81] offset:16384
	ds_write_b128 v20, v[74:77] offset:20480
	ds_write_b128 v20, v[4:7] offset:24576
	ds_write_b128 v20, v[70:73] offset:28672
	ds_write_b128 v20, v[8:11] offset:49152
	ds_write_b128 v20, v[66:69] offset:53248
	ds_write_b128 v20, v[12:15] offset:57344
	ds_write_b128 v20, v[62:65] offset:61440
	s_waitcnt lgkmcnt(8)
	v_mfma_f32_16x16x32_bf16 v[6:9], v[118:121], v[102:105], v[42:45]
	s_waitcnt lgkmcnt(0)
	s_barrier
	ds_read_b128 v[10:13], v19 offset:49152
	ds_read_b128 v[42:45], v19 offset:51200
	v_mfma_f32_16x16x32_bf16 v[14:17], v[122:125], v[102:105], v[50:53]
	ds_read_b128 v[62:65], v19 offset:55296
	ds_read_b128 v[78:81], v0 offset:20480
	s_nop 0
	ds_read_b128 v[50:53], v19 offset:53248
	v_mfma_f32_16x16x32_bf16 v[2:5], v[114:117], v[102:105], v[34:37]
	s_nop 2
	ds_read_b128 v[34:37], v0 offset:16384
	s_waitcnt lgkmcnt(0)
	v_mfma_f32_16x16x32_bf16 v[30:33], v[10:13], v[34:37], v[30:33]
	v_mfma_f32_16x16x32_bf16 v[38:41], v[42:45], v[34:37], v[38:41]
	v_mfma_f32_16x16x32_bf16 v[46:49], v[50:53], v[34:37], v[46:49]
	v_mfma_f32_16x16x32_bf16 v[26:29], v[62:65], v[34:37], v[26:29]
	ds_read_b128 v[34:37], v0 offset:18432
	v_mfma_f32_16x16x32_bf16 v[22:25], v[82:85], v[102:105], v[22:25]
	v_mfma_f32_16x16x32_bf16 v[82:85], v[10:13], v[78:81], v[106:109]
	s_nop 2
	ds_read_b128 v[104:107], v21 offset:51200
	s_waitcnt lgkmcnt(1)
	v_mfma_f32_16x16x32_bf16 v[66:69], v[10:13], v[34:37], v[90:93]
	v_mfma_f32_16x16x32_bf16 v[90:93], v[50:53], v[78:81], v[54:57]
	s_nop 2
	ds_read_b128 v[54:57], v0 offset:22528
	v_mfma_f32_16x16x32_bf16 v[70:73], v[42:45], v[34:37], v[94:97]
	v_mfma_f32_16x16x32_bf16 v[74:77], v[50:53], v[34:37], v[98:101]
	v_mfma_f32_16x16x32_bf16 v[34:37], v[62:65], v[34:37], v[86:89]
	s_nop 1
	ds_read_b128 v[96:99], v21 offset:49152
	v_lshl_or_b32 v0, v155, 6, v156
	v_or_b32_e32 v94, s7, v0
	v_mfma_f32_16x16x32_bf16 v[86:89], v[42:45], v[78:81], v[110:113]
	s_waitcnt lgkmcnt(1)
	v_mfma_f32_16x16x32_bf16 v[100:103], v[62:65], v[54:57], v[14:17]
	s_nop 0
	ds_read_b128 v[108:111], v21 offset:53248
	ds_read_b128 v[112:115], v21 offset:55296
	ds_read_b128 v[14:17], v18 offset:16384
	v_mfma_f32_16x16x32_bf16 v[78:81], v[62:65], v[78:81], v[58:61]
	v_mfma_f32_16x16x32_bf16 v[6:9], v[50:53], v[54:57], v[6:9]
	s_waitcnt lgkmcnt(0)
	v_mfma_f32_16x16x32_bf16 v[50:53], v[96:99], v[14:17], v[30:33]
	v_mfma_f32_16x16x32_bf16 v[58:61], v[104:107], v[14:17], v[38:41]
	v_mfma_f32_16x16x32_bf16 v[38:41], v[108:111], v[14:17], v[46:49]
	v_mfma_f32_16x16x32_bf16 v[26:29], v[112:115], v[14:17], v[26:29]
	ds_read_b128 v[14:17], v18 offset:18432
	v_mfma_f32_16x16x32_bf16 v[10:13], v[10:13], v[54:57], v[22:25]
	v_mfma_f32_16x16x32_bf16 v[2:5], v[42:45], v[54:57], v[2:5]
	s_waitcnt lgkmcnt(0)
	v_mfma_f32_16x16x32_bf16 v[54:57], v[104:107], v[14:17], v[70:73]
	v_mfma_f32_16x16x32_bf16 v[46:49], v[108:111], v[14:17], v[74:77]
	v_mfma_f32_16x16x32_bf16 v[42:45], v[112:115], v[14:17], v[34:37]
	s_nop 1
	ds_read_b128 v[72:75], v18 offset:22528
	ds_read_b128 v[34:37], v18 offset:20480
	v_mfma_f32_16x16x32_bf16 v[62:65], v[96:99], v[14:17], v[66:69]
	s_waitcnt lgkmcnt(0)
	s_barrier
	v_mfma_f32_16x16x32_bf16 v[22:25], v[96:99], v[34:37], v[82:85]
	v_or_b32_e32 v66, 16, v0
	v_or_b32_e32 v67, 32, v0
	v_or_b32_e32 v68, 48, v0
	v_mfma_f32_16x16x32_bf16 v[14:17], v[104:107], v[34:37], v[86:89]
	v_mov_b32_e32 v69, 0x10000
	v_lshl_add_u32 v95, v0, 2, v69
	v_or_b32_e32 v83, s7, v68
	v_mfma_f32_16x16x32_bf16 v[30:33], v[108:111], v[34:37], v[90:93]
	v_or_b32_e32 v89, s7, v66
	v_or_b32_e32 v88, s7, v67
	v_mfma_f32_16x16x32_bf16 v[34:37], v[112:115], v[34:37], v[78:81]
	v_and_b32_e32 v90, 16, v154
	v_lshl_add_u32 v93, v66, 2, v69
	v_lshl_add_u32 v92, v67, 2, v69
	v_mfma_f32_16x16x32_bf16 v[18:21], v[96:99], v[72:75], v[10:13]
	v_lshl_add_u32 v91, v68, 2, v69
	v_mfma_f32_16x16x32_bf16 v[10:13], v[104:107], v[72:75], v[2:5]
	v_mfma_f32_16x16x32_bf16 v[2:5], v[108:111], v[72:75], v[6:9]
	v_mfma_f32_16x16x32_bf16 v[6:9], v[112:115], v[72:75], v[100:103]
	s_cbranch_scc1 .LBB0_228
; #define P_ROPE WSP(float, OFF_ROPE)
; DI unsigned pack2(float a, float b) { f2_t v = {a, b}; bf2_t r = __builtin_convertvector(v, bf2_t); return __builtin_bit_cast(unsigned, r); }
; DI void mla_item(const Params& p, int l, int item, char* smem) {
;     ...
; #pragma unroll
;       for (int mi = 0; mi < 4; ++mi)
; #pragma unroll
;         for (int np = 0; np < 2; ++np) {
;           int rl = wm * 64 + mi * 16 + fr; size_t t = (size_t)mt * 128 + rl; float s = sRow[rl] * QS96;
;           int pos = (int)(t & (SEQ - 1)); int h = wn * 2 + np;
;           const float* cs = P_ROPE + pos * 32 + fq * 4;
;           float o1[4], o2[4];
; #pragma unroll
;           for (int j = 0; j < 4; ++j) {
;             float x1 = acc[mi][np * 2][j] * s, x2 = acc[mi][np * 2 + 1][j] * s; float c = cs[j], sn = cs[16 + j];
;             o1[j] = x1 * c - x2 * sn; o2[j] = x1 * sn + x2 * c;
;           }
;           uint2 a; a.x = pack2(o1[0], o1[1]); a.y = pack2(o1[2], o1[3]);
;           uint2 b; b.x = pack2(o2[0], o2[1]); b.y = pack2(o2[2], o2[3]);
;           *(uint4*)(P_QA + t * 384 + h * 96 + 64 + (fq & 1) * 16 + (fq >> 1) * 8) = widen16(a, b);
;         }
	ds_read_b32 v0, v95
	s_movk_i32 s7, 0x300
	s_mov_b32 s12, 0x19ca4000
	s_waitcnt lgkmcnt(0)
	v_mul_f32_e32 v82, 0x3e16c740, v0
	v_lshlrev_b32_e32 v0, 7, v94
	v_and_b32_e32 v0, 0xfe780, v0
	v_lshl_add_u64 v[66:67], s[88:89], 0, v[0:1]
	v_lshlrev_b32_e32 v0, 4, v153
	v_and_b32_e32 v0, 48, v0
	v_lshl_add_u64 v[70:71], v[66:67], 0, v[0:1]
	global_load_dwordx4 v[66:69], v[70:71], off
	v_mul_f32_e32 v76, v58, v82
	v_mul_f32_e32 v77, v59, v82
	global_load_dwordx4 v[70:73], v[70:71], off offset:64
	v_mul_f32_e32 v74, v50, v82
	v_mul_f32_e32 v75, v51, v82
	v_mul_f32_e32 v80, v60, v82
	v_mul_f32_e32 v81, v61, v82
	s_waitcnt vmcnt(0)
	v_mul_f32_e32 v78, v76, v70
	v_mul_f32_e32 v79, v77, v71
	s_nop 0
	v_fma_f32 v78, v74, v66, -v78
	v_fma_f32 v79, v75, v67, -v79
	v_mul_f32_e32 v74, v74, v70
	v_mul_f32_e32 v75, v75, v71
	v_mul_f32_e32 v84, v80, v72
	v_mul_f32_e32 v85, v81, v73
	v_fma_f32 v74, v66, v76, v74
	v_fma_f32 v75, v67, v77, v75
	v_mul_f32_e32 v76, v52, v82
	v_mul_f32_e32 v77, v53, v82
	s_nop 0
	v_fma_f32 v86, v76, v68, -v84
	v_fma_f32 v87, v77, v69, -v85
	v_mul_f32_e32 v76, v76, v72
	v_mul_f32_e32 v77, v77, v73
	v_cvt_pk_bf16_f32 v84, v78, v79
	v_fma_f32 v76, v80, v68, v76
	v_fma_f32 v77, v81, v69, v77
	v_cvt_pk_bf16_f32 v85, v86, v87
	v_cvt_pk_bf16_f32 v86, v74, v75
	v_mov_b64_e32 v[74:75], s[58:59]
	v_mul_u32_u24_e32 v78, 0xc0, v152
	v_cvt_pk_bf16_f32 v87, v76, v77
	v_mad_u64_u32 v[76:77], s[0:1], v94, s7, v[74:75]
	v_lshlrev_b32_e32 v80, 1, v78
	v_mov_b32_e32 v81, v1
	v_lshl_add_u64 v[96:97], v[76:77], 0, v[80:81]
	v_lshlrev_b32_e32 v76, 1, v90
	v_mov_b32_e32 v77, v1
	v_lshlrev_b32_e32 v78, 3, v153
	v_and_b32_e32 v78, 16, v78
	v_mov_b32_e32 v79, v1
	v_lshl_add_u64 v[96:97], v[96:97], 0, v[76:77]
	v_lshl_add_u64 v[96:97], v[96:97], 0, v[78:79]
	v_add_co_u32_e32 v96, vcc, s12, v96
	v_permlane16_swap_b32_e32 v84, v86
	v_permlane16_swap_b32_e32 v85, v87
	v_addc_co_u32_e32 v97, vcc, 0, v97, vcc
	global_store_dwordx4 v[96:97], v[84:87], off offset:128
	s_nop 1
	v_mul_f32_e32 v86, v26, v82
	v_mul_f32_e32 v87, v27, v82
	v_mul_f32_e32 v84, v38, v82
	v_mul_f32_e32 v85, v39, v82
	v_mul_f32_e32 v98, v86, v70
	v_mul_f32_e32 v99, v87, v71
	v_mul_f32_e32 v70, v84, v70
	v_mul_f32_e32 v71, v85, v71
	v_fma_f32 v98, v84, v66, -v98
	v_fma_f32 v99, v85, v67, -v99
	v_mul_f32_e32 v84, v28, v82
	v_mul_f32_e32 v85, v29, v82
	v_fma_f32 v70, v66, v86, v70
	v_fma_f32 v71, v67, v87, v71
	v_mul_f32_e32 v66, v40, v82
	v_mul_f32_e32 v67, v41, v82
	v_mul_f32_e32 v86, v84, v72
	v_mul_f32_e32 v87, v85, v73
	s_nop 0
	v_fma_f32 v86, v66, v68, -v86
	v_fma_f32 v87, v67, v69, -v87
	v_mul_f32_e32 v66, v66, v72
	v_mul_f32_e32 v67, v67, v73
	s_nop 0
	v_fma_f32 v72, v84, v68, v66
	v_fma_f32 v73, v85, v69, v67
	v_cvt_pk_bf16_f32 v66, v98, v99
	v_cvt_pk_bf16_f32 v67, v86, v87
	v_cvt_pk_bf16_f32 v68, v70, v71
	v_cvt_pk_bf16_f32 v69, v72, v73
	s_nop 0
	v_permlane16_swap_b32_e32 v66, v68
	v_permlane16_swap_b32_e32 v67, v69
	global_store_dwordx4 v[96:97], v[66:69], off offset:320
	ds_read_b32 v66, v93
	s_nop 0
	v_lshlrev_b32_e32 v67, 7, v89
	v_and_b32_e32 v68, 0xfff80, v67
	v_mov_b32_e32 v69, v1
	v_lshl_add_u64 v[68:69], s[88:89], 0, v[68:69]
	v_lshl_add_u64 v[72:73], v[68:69], 0, v[0:1]
	global_load_dwordx4 v[68:71], v[72:73], off
	global_load_dwordx4 v[84:87], v[72:73], off offset:64
	s_waitcnt lgkmcnt(0)
	v_mul_f32_e32 v66, 0x3e16c740, v66
	v_mul_f32_e32 v98, v54, v66
	v_mul_f32_e32 v99, v55, v66
	v_mul_f32_e32 v96, v62, v66
	v_mul_f32_e32 v97, v63, v66
	v_mul_f32_e32 v100, v56, v66
	v_mul_f32_e32 v101, v57, v66
	s_waitcnt vmcnt(0)
	v_mul_f32_e32 v72, v98, v84
	v_mul_f32_e32 v73, v99, v85
	s_nop 0
	v_fma_f32 v72, v96, v68, -v72
	v_fma_f32 v73, v97, v69, -v73
	v_mul_f32_e32 v96, v96, v84
	v_mul_f32_e32 v97, v97, v85
	v_mul_f32_e32 v102, v100, v86
	v_mul_f32_e32 v103, v101, v87
	v_fma_f32 v98, v68, v98, v96
	v_fma_f32 v99, v69, v99, v97
	v_mul_f32_e32 v96, v64, v66
	v_mul_f32_e32 v97, v65, v66
	v_cvt_pk_bf16_f32 v98, v98, v99
	v_fma_f32 v102, v96, v70, -v102
	v_fma_f32 v103, v97, v71, -v103
	v_mul_f32_e32 v96, v96, v86
	v_mul_f32_e32 v97, v97, v87
	s_nop 0
	v_fma_f32 v100, v100, v70, v96
	v_fma_f32 v101, v101, v71, v97
	v_cvt_pk_bf16_f32 v96, v72, v73
	v_mad_u64_u32 v[72:73], s[0:1], v89, s7, v[74:75]
	v_lshl_add_u64 v[72:73], v[72:73], 0, v[80:81]
	v_lshl_add_u64 v[72:73], v[72:73], 0, v[76:77]
	v_lshl_add_u64 v[72:73], v[72:73], 0, v[78:79]
	v_cvt_pk_bf16_f32 v97, v102, v103
	v_cvt_pk_bf16_f32 v99, v100, v101
	v_add_co_u32_e32 v72, vcc, s12, v72
	v_permlane16_swap_b32_e32 v96, v98
	v_permlane16_swap_b32_e32 v97, v99
	v_addc_co_u32_e32 v73, vcc, 0, v73, vcc
	global_store_dwordx4 v[72:73], v[96:99], off offset:128
	s_nop 1
	v_mul_f32_e32 v96, v46, v66
	v_mul_f32_e32 v97, v47, v66
	v_mul_f32_e32 v98, v42, v66
	v_mul_f32_e32 v99, v43, v66
	s_nop 0
	v_mul_f32_e32 v100, v98, v84
	v_mul_f32_e32 v101, v99, v85
	v_mul_f32_e32 v84, v96, v84
	v_mul_f32_e32 v85, v97, v85
	v_fma_f32 v100, v96, v68, -v100
	v_fma_f32 v101, v97, v69, -v101
	v_fma_f32 v68, v68, v98, v84
	v_fma_f32 v69, v69, v99, v85
	v_mul_f32_e32 v84, v48, v66
	v_mul_f32_e32 v85, v49, v66
	v_mul_f32_e32 v67, v45, v66
	v_mul_f32_e32 v66, v44, v66
	v_cvt_pk_bf16_f32 v68, v68, v69
	v_mul_f32_e32 v96, v66, v86
	v_mul_f32_e32 v97, v67, v87
	s_nop 0
	v_fma_f32 v96, v84, v70, -v96
	v_fma_f32 v97, v85, v71, -v97
	v_mul_f32_e32 v84, v84, v86
	v_mul_f32_e32 v85, v85, v87
	s_nop 0
	v_fma_f32 v70, v66, v70, v84
	v_fma_f32 v71, v67, v71, v85
	v_cvt_pk_bf16_f32 v66, v100, v101
	v_cvt_pk_bf16_f32 v67, v96, v97
	v_cvt_pk_bf16_f32 v69, v70, v71
	v_permlane16_swap_b32_e32 v66, v68
	s_nop 0
	v_permlane16_swap_b32_e32 v67, v69
	global_store_dwordx4 v[72:73], v[66:69], off offset:320
	ds_read_b32 v66, v92
	s_nop 0
	v_lshlrev_b32_e32 v67, 7, v88
	v_and_b32_e32 v68, 0xfff80, v67
	v_mov_b32_e32 v69, v1
	v_lshl_add_u64 v[68:69], s[88:89], 0, v[68:69]
	v_lshl_add_u64 v[72:73], v[68:69], 0, v[0:1]
	global_load_dwordx4 v[68:71], v[72:73], off
	global_load_dwordx4 v[84:87], v[72:73], off offset:64
	s_waitcnt lgkmcnt(0)
; #define P_ROPE WSP(float, OFF_ROPE)
; DI unsigned pack2(float a, float b) { f2_t v = {a, b}; bf2_t r = __builtin_convertvector(v, bf2_t); return __builtin_bit_cast(unsigned, r); }
; DI void mla_item(const Params& p, int l, int item, char* smem) {
;     ...
; #pragma unroll
;       for (int mi = 0; mi < 4; ++mi)
; #pragma unroll
;         for (int np = 0; np < 2; ++np) {
;           int rl = wm * 64 + mi * 16 + fr; size_t t = (size_t)mt * 128 + rl; float s = sRow[rl] * QS96;
;           int pos = (int)(t & (SEQ - 1)); int h = wn * 2 + np;
;           const float* cs = P_ROPE + pos * 32 + fq * 4;
;           float o1[4], o2[4];
; #pragma unroll
;           for (int j = 0; j < 4; ++j) {
;             float x1 = acc[mi][np * 2][j] * s, x2 = acc[mi][np * 2 + 1][j] * s; float c = cs[j], sn = cs[16 + j];
;             o1[j] = x1 * c - x2 * sn; o2[j] = x1 * sn + x2 * c;
;           }
;           uint2 a; a.x = pack2(o1[0], o1[1]); a.y = pack2(o1[2], o1[3]);
;           uint2 b; b.x = pack2(o2[0], o2[1]); b.y = pack2(o2[2], o2[3]);
;           *(uint4*)(P_QA + t * 384 + h * 96 + 64 + (fq & 1) * 16 + (fq >> 1) * 8) = widen16(a, b);
;         }
	v_mul_f32_e32 v66, 0x3e16c740, v66
	v_mul_f32_e32 v98, v14, v66
	v_mul_f32_e32 v99, v15, v66
	v_mul_f32_e32 v96, v22, v66
	v_mul_f32_e32 v97, v23, v66
	v_mul_f32_e32 v100, v16, v66
	v_mul_f32_e32 v101, v17, v66
	s_waitcnt vmcnt(0)
	v_mul_f32_e32 v72, v98, v84
	v_mul_f32_e32 v73, v99, v85
	s_nop 0
	v_fma_f32 v72, v96, v68, -v72
	v_fma_f32 v73, v97, v69, -v73
	v_mul_f32_e32 v96, v96, v84
	v_mul_f32_e32 v97, v97, v85
	v_mul_f32_e32 v102, v100, v86
	v_mul_f32_e32 v103, v101, v87
	v_fma_f32 v98, v68, v98, v96
	v_fma_f32 v99, v69, v99, v97
	v_mul_f32_e32 v96, v24, v66
	v_mul_f32_e32 v97, v25, v66
	v_cvt_pk_bf16_f32 v98, v98, v99
	v_fma_f32 v102, v96, v70, -v102
	v_fma_f32 v103, v97, v71, -v103
	v_mul_f32_e32 v96, v96, v86
	v_mul_f32_e32 v97, v97, v87
	s_nop 0
	v_fma_f32 v100, v100, v70, v96
	v_fma_f32 v101, v101, v71, v97
	v_cvt_pk_bf16_f32 v96, v72, v73
	v_mad_u64_u32 v[72:73], s[0:1], v88, s7, v[74:75]
	v_lshl_add_u64 v[72:73], v[72:73], 0, v[80:81]
	v_lshl_add_u64 v[72:73], v[72:73], 0, v[76:77]
	v_lshl_add_u64 v[72:73], v[72:73], 0, v[78:79]
	v_cvt_pk_bf16_f32 v97, v102, v103
	v_cvt_pk_bf16_f32 v99, v100, v101
	v_add_co_u32_e32 v72, vcc, s12, v72
	v_permlane16_swap_b32_e32 v96, v98
	v_permlane16_swap_b32_e32 v97, v99
	v_addc_co_u32_e32 v73, vcc, 0, v73, vcc
	global_store_dwordx4 v[72:73], v[96:99], off offset:128
	v_mad_u64_u32 v[74:75], s[0:1], v83, s7, v[74:75]
	s_nop 0
	v_mul_f32_e32 v96, v30, v66
	v_mul_f32_e32 v97, v31, v66
	v_mul_f32_e32 v98, v34, v66
	v_mul_f32_e32 v99, v35, v66
	v_lshl_add_u64 v[74:75], v[74:75], 0, v[80:81]
	v_mul_f32_e32 v100, v98, v84
	v_mul_f32_e32 v101, v99, v85
	v_mul_f32_e32 v84, v96, v84
	v_mul_f32_e32 v85, v97, v85
	v_fma_f32 v100, v96, v68, -v100
	v_fma_f32 v101, v97, v69, -v101
	v_fma_f32 v68, v68, v98, v84
	v_fma_f32 v69, v69, v99, v85
	v_mul_f32_e32 v84, v32, v66
	v_mul_f32_e32 v85, v33, v66
	v_mul_f32_e32 v67, v37, v66
	v_mul_f32_e32 v66, v36, v66
	v_cvt_pk_bf16_f32 v68, v68, v69
	v_mul_f32_e32 v96, v66, v86
	v_mul_f32_e32 v97, v67, v87
	v_lshl_add_u64 v[74:75], v[74:75], 0, v[76:77]
	v_fma_f32 v96, v84, v70, -v96
	v_fma_f32 v97, v85, v71, -v97
	v_mul_f32_e32 v84, v84, v86
	v_mul_f32_e32 v85, v85, v87
	v_lshl_add_u64 v[74:75], v[74:75], 0, v[78:79]
	v_fma_f32 v70, v66, v70, v84
	v_fma_f32 v71, v67, v71, v85
	v_cvt_pk_bf16_f32 v66, v100, v101
	v_cvt_pk_bf16_f32 v67, v96, v97
	v_cvt_pk_bf16_f32 v69, v70, v71
	v_permlane16_swap_b32_e32 v66, v68
	s_nop 0
	v_permlane16_swap_b32_e32 v67, v69
	global_store_dwordx4 v[72:73], v[66:69], off offset:320
	ds_read_b32 v66, v91
	v_add_co_u32_e32 v76, vcc, s12, v74
	v_mov_b32_e32 v67, v1
	s_nop 0
	v_addc_co_u32_e32 v77, vcc, 0, v75, vcc
	s_waitcnt lgkmcnt(0)
	v_mul_f32_e32 v82, 0x3e16c740, v66
	v_lshlrev_b32_e32 v66, 7, v83
	v_and_b32_e32 v66, 0xfff80, v66
	v_lshl_add_u64 v[66:67], s[88:89], 0, v[66:67]
	v_lshl_add_u64 v[70:71], v[66:67], 0, v[0:1]
	global_load_dwordx4 v[66:69], v[70:71], off
	v_mul_f32_e32 v86, v10, v82
	v_mul_f32_e32 v87, v11, v82
	global_load_dwordx4 v[70:73], v[70:71], off offset:64
	v_mul_f32_e32 v84, v18, v82
	v_mul_f32_e32 v85, v19, v82
	v_mul_f32_e32 v98, v12, v82
	v_mul_f32_e32 v99, v13, v82
	v_mul_f32_e32 v80, v6, v82
	v_mul_f32_e32 v81, v7, v82
	v_mul_f32_e32 v78, v2, v82
	v_mul_f32_e32 v79, v3, v82
	s_mov_b64 s[0:1], 0x19ca4140
	s_waitcnt vmcnt(0)
	v_mul_f32_e32 v96, v86, v70
	v_mul_f32_e32 v97, v87, v71
	s_nop 0
	v_fma_f32 v96, v84, v66, -v96
	v_fma_f32 v97, v85, v67, -v97
	v_mul_f32_e32 v84, v84, v70
	v_mul_f32_e32 v85, v85, v71
	v_mul_f32_e32 v100, v98, v72
	v_mul_f32_e32 v101, v99, v73
	v_fma_f32 v86, v66, v86, v84
	v_fma_f32 v87, v67, v87, v85
	v_mul_f32_e32 v84, v20, v82
	v_mul_f32_e32 v85, v21, v82
	v_cvt_pk_bf16_f32 v86, v86, v87
	v_fma_f32 v100, v84, v68, -v100
	v_fma_f32 v101, v85, v69, -v101
	v_mul_f32_e32 v84, v84, v72
	v_mul_f32_e32 v85, v85, v73
	s_nop 0
	v_fma_f32 v98, v98, v68, v84
	v_fma_f32 v99, v99, v69, v85
	v_cvt_pk_bf16_f32 v84, v96, v97
	v_cvt_pk_bf16_f32 v85, v100, v101
	v_cvt_pk_bf16_f32 v87, v98, v99
	v_permlane16_swap_b32_e32 v84, v86
	s_nop 0
	v_permlane16_swap_b32_e32 v85, v87
	global_store_dwordx4 v[76:77], v[84:87], off offset:128
	s_nop 1
	v_mul_f32_e32 v84, v80, v70
	v_mul_f32_e32 v85, v81, v71
	v_mul_f32_e32 v70, v78, v70
	v_mul_f32_e32 v71, v79, v71
	v_fma_f32 v84, v78, v66, -v84
	v_fma_f32 v85, v79, v67, -v85
	v_mul_f32_e32 v78, v8, v82
	v_mul_f32_e32 v79, v9, v82
	v_fma_f32 v70, v66, v80, v70
	v_fma_f32 v71, v67, v81, v71
	v_mul_f32_e32 v66, v4, v82
	v_mul_f32_e32 v67, v5, v82
	v_mul_f32_e32 v80, v78, v72
	v_mul_f32_e32 v81, v79, v73
	v_cvt_pk_bf16_f32 v0, v84, v85
	v_fma_f32 v80, v66, v68, -v80
	v_fma_f32 v81, v67, v69, -v81
	v_mul_f32_e32 v66, v66, v72
	v_mul_f32_e32 v67, v67, v73
	s_nop 0
	v_fma_f32 v68, v78, v68, v66
	v_fma_f32 v69, v79, v69, v67
	v_cvt_pk_bf16_f32 v66, v80, v81
	v_cvt_pk_bf16_f32 v67, v70, v71
	v_cvt_pk_bf16_f32 v68, v68, v69
	s_nop 0
	v_permlane16_swap_b32_e32 v0, v67
	v_permlane16_swap_b32_e32 v66, v68
	v_lshl_add_u64 v[70:71], v[74:75], 0, s[0:1]
	s_mov_b64 s[0:1], 0
	global_store_dword v[76:77], v0, off offset:320
; DI unsigned pack2(float a, float b) { f2_t v = {a, b}; bf2_t r = __builtin_convertvector(v, bf2_t); return __builtin_bit_cast(unsigned, r); }
; DI void mla_item(const Params& p, int l, int item, char* smem) {
;     ...
;     if (nt < 2) {
; #pragma unroll
;       for (int mi = 0; mi < 4; ++mi)
; #pragma unroll
;         for (int np = 0; np < 2; ++np) {
;           int rl = wm * 64 + mi * 16 + fr; size_t t = (size_t)mt * 128 + rl; float s = sRow[rl] * QS96;
;           int c = nt * 128 + wn * 64 + (2 * np + (fq & 1)) * 16 + (fq >> 1) * 8; int h = c >> 6, d = c & 63;
;           uint2 a, b;
;           a.x = pack2(acc[mi][2 * np][0] * s, acc[mi][2 * np][1] * s); a.y = pack2(acc[mi][2 * np][2] * s, acc[mi][2 * np][3] * s);
;           b.x = pack2(acc[mi][2 * np + 1][0] * s, acc[mi][2 * np + 1][1] * s); b.y = pack2(acc[mi][2 * np + 1][2] * s, acc[mi][2 * np + 1][3] * s);
;           *(uint4*)(P_QA + t * 384 + h * 96 + d) = widen16(a, b);
;         }
.LBB0_228:
	s_andn2_b64 vcc, exec, s[0:1]
	s_cbranch_vccnz .LBB0_208
	ds_read_b32 v66, v95
	v_lshlrev_b32_e32 v67, 2, v153
	v_lshl_or_b32 v68, v152, 6, s6
	v_and_or_b32 v67, v67, 8, v90
	v_ashrrev_i32_e32 v68, 6, v68
	s_waitcnt lgkmcnt(0)
	v_mul_f32_e32 v66, 0x3e16c740, v66
	v_mul_f32_e32 v50, v50, v66
	v_mul_f32_e32 v51, v51, v66
	v_mul_f32_e32 v52, v52, v66
	v_mul_f32_e32 v53, v53, v66
	s_movk_i32 s6, 0x60
	v_cvt_pk_bf16_f32 v50, v50, v51
	v_cvt_pk_bf16_f32 v51, v52, v53
	v_mul_f32_e32 v52, v58, v66
	v_mul_f32_e32 v53, v59, v66
	v_mul_f32_e32 v58, v60, v66
	v_mul_f32_e32 v59, v61, v66
	v_readlane_b32 s0, v253, 40
	v_mul_lo_u32 v60, v68, s6
	v_mul_u32_u24_e32 v0, 0x300, v94
	v_readlane_b32 s1, v253, 41
	v_ashrrev_i32_e32 v61, 31, v60
	v_mul_f32_e32 v38, v38, v66
	v_mul_f32_e32 v39, v39, v66
	v_mul_f32_e32 v40, v40, v66
	v_mul_f32_e32 v41, v41, v66
	v_mul_f32_e32 v26, v26, v66
	v_mul_f32_e32 v27, v27, v66
	ds_read_b32 v69, v93
	ds_read_b32 v70, v92
	ds_read_b32 v71, v91
	v_cvt_pk_bf16_f32 v52, v52, v53
	v_cvt_pk_bf16_f32 v53, v58, v59
	v_lshl_add_u64 v[58:59], s[0:1], 0, v[0:1]
	v_lshlrev_b64 v[60:61], 1, v[60:61]
	v_cvt_pk_bf16_f32 v38, v38, v39
	v_cvt_pk_bf16_f32 v39, v40, v41
	v_cvt_pk_bf16_f32 v40, v26, v27
	v_mul_f32_e32 v26, v28, v66
	v_mul_f32_e32 v27, v29, v66
	v_lshl_add_u64 v[58:59], v[58:59], 0, v[60:61]
	v_lshlrev_b32_e32 v0, 1, v67
	v_cvt_pk_bf16_f32 v41, v26, v27
	v_lshl_add_u64 v[58:59], v[58:59], 0, v[0:1]
	v_permlane16_swap_b32_e32 v38, v40
	v_permlane16_swap_b32_e32 v39, v41
	global_store_dwordx4 v[58:59], v[38:41], off offset:64
	v_permlane16_swap_b32_e32 v50, v52
	s_waitcnt lgkmcnt(2)
	v_mul_f32_e32 v40, 0x3e16c740, v69
	v_permlane16_swap_b32_e32 v51, v53
	v_mul_u32_u24_e32 v38, 0x300, v89
	v_mov_b32_e32 v39, v1
	v_mul_f32_e32 v26, v62, v40
	v_mul_f32_e32 v27, v63, v40
	v_mul_f32_e32 v28, v64, v40
	v_mul_f32_e32 v29, v65, v40
	global_store_dwordx4 v[58:59], v[50:53], off
	v_cvt_pk_bf16_f32 v26, v26, v27
	v_cvt_pk_bf16_f32 v27, v28, v29
	v_mul_f32_e32 v28, v54, v40
	v_mul_f32_e32 v29, v55, v40
	v_mul_f32_e32 v50, v56, v40
	v_mul_f32_e32 v51, v57, v40
	v_lshl_add_u64 v[38:39], s[0:1], 0, v[38:39]
	v_cvt_pk_bf16_f32 v28, v28, v29
	v_cvt_pk_bf16_f32 v29, v50, v51
	v_lshl_add_u64 v[38:39], v[38:39], 0, v[60:61]
	v_permlane16_swap_b32_e32 v26, v28
	v_permlane16_swap_b32_e32 v27, v29
	v_lshl_add_u64 v[38:39], v[38:39], 0, v[0:1]
	global_store_dwordx4 v[38:39], v[26:29], off
	s_nop 1
	v_mul_f32_e32 v26, v46, v40
	v_mul_f32_e32 v27, v47, v40
	v_mul_f32_e32 v28, v48, v40
	v_mul_f32_e32 v29, v49, v40
	v_cvt_pk_bf16_f32 v26, v26, v27
	v_cvt_pk_bf16_f32 v27, v28, v29
	v_mul_f32_e32 v28, v42, v40
	v_mul_f32_e32 v29, v43, v40
	v_mul_f32_e32 v41, v45, v40
	v_mul_f32_e32 v40, v44, v40
	v_cvt_pk_bf16_f32 v28, v28, v29
	v_cvt_pk_bf16_f32 v29, v40, v41
	s_nop 0
	v_permlane16_swap_b32_e32 v26, v28
	v_permlane16_swap_b32_e32 v27, v29
	global_store_dwordx4 v[38:39], v[26:29], off offset:64
	s_waitcnt lgkmcnt(1)
	s_nop 0
	v_mul_f32_e32 v28, 0x3e16c740, v70
	v_mul_f32_e32 v22, v22, v28
	v_mul_f32_e32 v23, v23, v28
	v_mul_f32_e32 v24, v24, v28
	v_mul_f32_e32 v25, v25, v28
	v_mul_f32_e32 v14, v14, v28
	v_mul_f32_e32 v15, v15, v28
	v_mul_u32_u24_e32 v26, 0x300, v88
	v_mov_b32_e32 v27, v1
	v_cvt_pk_bf16_f32 v22, v22, v23
	v_cvt_pk_bf16_f32 v23, v24, v25
	v_cvt_pk_bf16_f32 v24, v14, v15
	v_mul_f32_e32 v14, v16, v28
	v_mul_f32_e32 v15, v17, v28
	s_nop 0
	v_permlane16_swap_b32_e32 v22, v24
	v_cvt_pk_bf16_f32 v25, v14, v15
	v_lshl_add_u64 v[14:15], s[0:1], 0, v[26:27]
	v_lshl_add_u64 v[14:15], v[14:15], 0, v[60:61]
	v_permlane16_swap_b32_e32 v23, v25
	v_lshl_add_u64 v[26:27], v[14:15], 0, v[0:1]
	v_mul_f32_e32 v14, v30, v28
	v_mul_f32_e32 v15, v31, v28
	v_mul_f32_e32 v16, v32, v28
	v_mul_f32_e32 v17, v33, v28
	global_store_dwordx4 v[26:27], v[22:25], off
	v_cvt_pk_bf16_f32 v14, v14, v15
	v_cvt_pk_bf16_f32 v15, v16, v17
	v_mul_f32_e32 v16, v34, v28
	v_mul_f32_e32 v17, v35, v28
	v_mul_f32_e32 v22, v36, v28
	v_mul_f32_e32 v23, v37, v28
	v_cvt_pk_bf16_f32 v16, v16, v17
	v_cvt_pk_bf16_f32 v17, v22, v23
	s_nop 0
	v_permlane16_swap_b32_e32 v14, v16
	v_permlane16_swap_b32_e32 v15, v17
	s_waitcnt lgkmcnt(0)
	v_mul_f32_e32 v24, 0x3e16c740, v71
	global_store_dwordx4 v[26:27], v[14:17], off offset:64
	v_mul_f32_e32 v10, v10, v24
	v_mul_f32_e32 v11, v11, v24
	v_mul_u32_u24_e32 v22, 0x300, v83
	v_mul_f32_e32 v14, v18, v24
	v_mul_f32_e32 v15, v19, v24
	v_mul_f32_e32 v16, v20, v24
	v_mul_f32_e32 v17, v21, v24
	v_mov_b32_e32 v23, v1
	v_cvt_pk_bf16_f32 v14, v14, v15
	v_cvt_pk_bf16_f32 v15, v16, v17
	v_cvt_pk_bf16_f32 v16, v10, v11
	v_mul_f32_e32 v10, v12, v24
	v_mul_f32_e32 v11, v13, v24
	v_mul_f32_e32 v2, v2, v24
	v_mul_f32_e32 v3, v3, v24
	v_cvt_pk_bf16_f32 v17, v10, v11
	v_lshl_add_u64 v[10:11], s[0:1], 0, v[22:23]
	v_lshl_add_u64 v[10:11], v[10:11], 0, v[60:61]
	v_lshl_add_u64 v[10:11], v[10:11], 0, v[0:1]
	v_cvt_pk_bf16_f32 v0, v2, v3
	v_mul_f32_e32 v2, v4, v24
	v_mul_f32_e32 v3, v5, v24
	v_permlane16_swap_b32_e32 v14, v16
	v_cvt_pk_bf16_f32 v66, v2, v3
	v_mul_f32_e32 v2, v6, v24
	v_mul_f32_e32 v3, v7, v24
	v_permlane16_swap_b32_e32 v15, v17
	v_cvt_pk_bf16_f32 v67, v2, v3
	v_mul_f32_e32 v2, v8, v24
	v_mul_f32_e32 v3, v9, v24
	s_nop 0
	v_permlane16_swap_b32_e32 v0, v67
	v_cvt_pk_bf16_f32 v68, v2, v3
	s_nop 1
	v_permlane16_swap_b32_e32 v66, v68
	v_lshl_add_u64 v[70:71], v[10:11], 0, 64
	global_store_dwordx4 v[10:11], v[14:17], off
	global_store_dword v[10:11], v0, off offset:64
	s_branch .LBB0_208

; #define BLOADG(kt) do { \
;     _Pragma("unroll") for (int i = 0; i < 2; ++i) ra[i] = *(const u32x4*)(ap + (size_t)(64 * i) * lda + (kt) * 32); \
;     _Pragma("unroll") for (int i = 0; i < 4; ++i) rb[i] = *(const u32x4*)(bp + (size_t)((i & 1) * s1 + (i >> 1) * s2) * ldb + (kt) * 32); } while (0)
; #define BSTOREG(st) do { \
;     _Pragma("unroll") for (int i = 0; i < 2; ++i) *(u32x4*)(sA + (st) * BGA + so + 64 * i * 32) = ra[i]; \
;     _Pragma("unroll") for (int i = 0; i < 4; ++i) *(u32x4*)(sB + (st) * BGB + so + 64 * i * 32) = rb[i]; } while (0)
;     ...
;   for (int kt = 0; kt < nk; ++kt) {
;     const int cur = kt & 1;
;     if (kt + 1 < nk) { BSTOREG(cur ^ 1); if (kt + 2 < nk) BLOADG(kt + 2); }
;     const bf16_t* cA = sA + cur * BGA + (wm * 64) * 32 + fo; const bf16_t* cB = sB + cur * BGB + (wn * 128) * 32 + fo;
;     bf16x8 af[4];
; #pragma unroll
;     for (int mi = 0; mi < 4; ++mi) af[mi] = *(const bf16x8*)(cA + mi * 16 * 32);
; #pragma unroll
;     for (int nh = 0; nh < 2; ++nh) {
;       bf16x8 bfr[4];
; #pragma unroll
;       for (int ni = 0; ni < 4; ++ni) bfr[ni] = *(const bf16x8*)(cB + (nh * 4 + ni) * 16 * 32);
; #pragma unroll
;       for (int mi = 0; mi < 4; ++mi)
; #pragma unroll
;         for (int ni = 0; ni < 4; ++ni) acc[mi][nh * 4 + ni] = __builtin_amdgcn_mfma_f32_16x16x32_bf16(bfr[ni], af[mi], acc[mi][nh * 4 + ni], 0, 0, 0);
;     }
;     __syncthreads();
;   }
.LBB0_238:
	s_and_b32 s27, s26, 1
	s_lshl_b32 s28, s27, 13
	s_lshl_b32 s27, s27, 14
	s_xor_b32 s29, s28, 0x2000
	s_xor_b32 s30, s27, 0x4000
	v_add_u32_e32 v154, s29, v164
	v_or_b32_e32 v0, s28, v163
	v_or_b32_e32 v165, s27, v162
	v_add_u32_e32 v155, s30, v164
	s_waitcnt vmcnt(4)
	ds_write_b128 v154, v[118:121]
	ds_write_b128 v154, v[114:117] offset:4096
	s_waitcnt vmcnt(3)
	ds_write_b128 v155, v[110:113] offset:16384
	s_waitcnt vmcnt(2)
	ds_write_b128 v155, v[106:109] offset:20480
	s_waitcnt vmcnt(1)
	ds_write_b128 v155, v[90:93] offset:24576
	s_waitcnt vmcnt(0)
	ds_write_b128 v155, v[94:97] offset:28672
	ds_read_b128 v[90:93], v165 offset:16384
	ds_read_b128 v[94:97], v165 offset:17408
	ds_read_b128 v[106:109], v0
	ds_read_b128 v[110:113], v0 offset:1024
	ds_read_b128 v[114:117], v165 offset:18432
	ds_read_b128 v[118:121], v165 offset:19456
	ds_read_b128 v[166:169], v0 offset:2048
	ds_read_b128 v[154:157], v0 offset:3072
	s_waitcnt lgkmcnt(5)
	v_mfma_f32_16x16x32_bf16 v[150:153], v[90:93], v[106:109], v[150:153]
	ds_read_b128 v[170:173], v165 offset:22528
	ds_read_b128 v[174:177], v165 offset:23552
	s_mov_b32 s27, 0x2300000
	v_mfma_f32_16x16x32_bf16 v[146:149], v[94:97], v[106:109], v[146:149]
	s_add_i32 s26, s26, 1
	s_waitcnt lgkmcnt(6)
	v_mfma_f32_16x16x32_bf16 v[134:137], v[90:93], v[110:113], v[134:137]
	v_mfma_f32_16x16x32_bf16 v[130:133], v[94:97], v[110:113], v[130:133]
	s_waitcnt lgkmcnt(3)
	v_mfma_f32_16x16x32_bf16 v[98:101], v[90:93], v[166:169], v[98:101]
	v_mfma_f32_16x16x32_bf16 v[86:89], v[94:97], v[166:169], v[86:89]
	s_waitcnt lgkmcnt(2)
	v_mfma_f32_16x16x32_bf16 v[66:69], v[90:93], v[154:157], v[66:69]
	ds_read_b128 v[90:93], v165 offset:20480
	v_mfma_f32_16x16x32_bf16 v[62:65], v[94:97], v[154:157], v[62:65]
	ds_read_b128 v[94:97], v165 offset:21504
	v_mfma_f32_16x16x32_bf16 v[142:145], v[114:117], v[106:109], v[142:145]
	v_mfma_f32_16x16x32_bf16 v[138:141], v[118:121], v[106:109], v[138:141]
	s_waitcnt lgkmcnt(1)
	v_mfma_f32_16x16x32_bf16 v[102:105], v[90:93], v[106:109], v[102:105]
	s_waitcnt lgkmcnt(0)
	v_mfma_f32_16x16x32_bf16 v[82:85], v[94:97], v[106:109], v[82:85]
	v_mfma_f32_16x16x32_bf16 v[70:73], v[170:173], v[106:109], v[70:73]
	v_mfma_f32_16x16x32_bf16 v[58:61], v[174:177], v[106:109], v[58:61]
	v_lshl_add_u64 v[106:107], v[160:161], 0, s[22:23]
	v_lshl_add_u64 v[108:109], v[158:159], 0, s[22:23]
	s_add_u32 s22, s22, 64
	v_mfma_f32_16x16x32_bf16 v[126:129], v[114:117], v[110:113], v[126:129]
	s_addc_u32 s23, s23, 0
	s_cmpk_lg_i32 s22, 0x780
	v_mfma_f32_16x16x32_bf16 v[78:81], v[114:117], v[166:169], v[78:81]
	v_mfma_f32_16x16x32_bf16 v[54:57], v[114:117], v[154:157], v[54:57]
	v_add_co_u32_e32 v114, vcc, s16, v106
	s_nop 1
	v_addc_co_u32_e32 v115, vcc, 0, v107, vcc
	v_add_co_u32_e32 v106, vcc, s18, v106
	v_mfma_f32_16x16x32_bf16 v[122:125], v[118:121], v[110:113], v[122:125]
	s_nop 0
	v_addc_co_u32_e32 v107, vcc, 0, v107, vcc
	v_mfma_f32_16x16x32_bf16 v[46:49], v[90:93], v[110:113], v[46:49]
	v_mfma_f32_16x16x32_bf16 v[42:45], v[94:97], v[110:113], v[42:45]
	v_mfma_f32_16x16x32_bf16 v[38:41], v[170:173], v[110:113], v[38:41]
	v_mfma_f32_16x16x32_bf16 v[34:37], v[174:177], v[110:113], v[34:37]
	v_add_co_u32_e32 v110, vcc, s27, v108
	s_mov_b32 s27, 0x2320000
	s_nop 0
	v_addc_co_u32_e32 v111, vcc, 0, v109, vcc
	v_add_co_u32_e32 v178, vcc, s27, v108
	s_mov_b32 s27, 0x2340000
	s_nop 0
	v_addc_co_u32_e32 v179, vcc, 0, v109, vcc
	v_add_co_u32_e32 v180, vcc, s27, v108
	s_mov_b32 s27, 0x2360000
	s_nop 0
	v_addc_co_u32_e32 v181, vcc, 0, v109, vcc
	v_add_co_u32_e32 v182, vcc, s27, v108
	v_mfma_f32_16x16x32_bf16 v[74:77], v[118:121], v[166:169], v[74:77]
	s_nop 0
	v_addc_co_u32_e32 v183, vcc, 0, v109, vcc
	v_mfma_f32_16x16x32_bf16 v[50:53], v[118:121], v[154:157], v[50:53]
	global_load_dwordx4 v[118:121], v[114:115], off offset:1152
	s_nop 0
	global_load_dwordx4 v[114:117], v[106:107], off offset:1152
	v_mfma_f32_16x16x32_bf16 v[30:33], v[90:93], v[166:169], v[30:33]
	v_mfma_f32_16x16x32_bf16 v[14:17], v[90:93], v[154:157], v[14:17]
	global_load_dwordx4 v[110:113], v[110:111], off offset:128
	s_nop 0
	global_load_dwordx4 v[106:109], v[178:179], off offset:128
	global_load_dwordx4 v[90:93], v[180:181], off offset:128
	v_mfma_f32_16x16x32_bf16 v[26:29], v[94:97], v[166:169], v[26:29]
	v_mfma_f32_16x16x32_bf16 v[10:13], v[94:97], v[154:157], v[10:13]
	global_load_dwordx4 v[94:97], v[182:183], off offset:128
	s_barrier
	v_mfma_f32_16x16x32_bf16 v[22:25], v[170:173], v[166:169], v[22:25]
	v_mfma_f32_16x16x32_bf16 v[18:21], v[174:177], v[166:169], v[18:21]
	v_mfma_f32_16x16x32_bf16 v[6:9], v[170:173], v[154:157], v[6:9]
	v_mfma_f32_16x16x32_bf16 v[2:5], v[174:177], v[154:157], v[2:5]
	s_cbranch_scc1 .LBB0_238
; DI int otid() { int t; asm volatile("v_mov_b32 %0, %1" : "=v"(t) : "v"((int)threadIdx.x)); __builtin_assume(t >= 0 && t < 256); return t; }
; #define BLOADG(kt) do { \
;     _Pragma("unroll") for (int i = 0; i < 2; ++i) ra[i] = *(const u32x4*)(ap + (size_t)(64 * i) * lda + (kt) * 32); \
;     _Pragma("unroll") for (int i = 0; i < 4; ++i) rb[i] = *(const u32x4*)(bp + (size_t)((i & 1) * s1 + (i >> 1) * s2) * ldb + (kt) * 32); } while (0)
; #define BSTOREG(st) do { \
;     _Pragma("unroll") for (int i = 0; i < 2; ++i) *(u32x4*)(sA + (st) * BGA + so + 64 * i * 32) = ra[i]; \
;     _Pragma("unroll") for (int i = 0; i < 4; ++i) *(u32x4*)(sB + (st) * BGB + so + 64 * i * 32) = rb[i]; } while (0)
;     ...
;   for (int kt = 0; kt < nk; ++kt) {
;     const int cur = kt & 1;
;     if (kt + 1 < nk) { BSTOREG(cur ^ 1); if (kt + 2 < nk) BLOADG(kt + 2); }
;     const bf16_t* cA = sA + cur * BGA + (wm * 64) * 32 + fo; const bf16_t* cB = sB + cur * BGB + (wn * 128) * 32 + fo;
;     bf16x8 af[4];
; #pragma unroll
;     for (int mi = 0; mi < 4; ++mi) af[mi] = *(const bf16x8*)(cA + mi * 16 * 32);
; #pragma unroll
;     for (int nh = 0; nh < 2; ++nh) {
;       bf16x8 bfr[4];
; #pragma unroll
;       for (int ni = 0; ni < 4; ++ni) bfr[ni] = *(const bf16x8*)(cB + (nh * 4 + ni) * 16 * 32);
; #pragma unroll
;       for (int mi = 0; mi < 4; ++mi)
; #pragma unroll
;         for (int ni = 0; ni < 4; ++ni) acc[mi][nh * 4 + ni] = __builtin_amdgcn_mfma_f32_16x16x32_bf16(bfr[ni], af[mi], acc[mi][nh * 4 + ni], 0, 0, 0);
;     }
;     __syncthreads();
;   }
; DI void outproj_tile(const Params& p, int l, int tile, char* smem) {
;     ...
;   const float* xin = l == 0 ? p.x : p.out;
;   const int lane = otid() & 63, wid = otid() >> 6, wm = wid >> 1, wn = wid & 1, fr = lane & 15, fq = lane >> 4;
; #pragma unroll
;   for (int mi = 0; mi < 4; ++mi)
; #pragma unroll
;     for (int ni = 0; ni < 8; ++ni) {
;       size_t row = (size_t)mt * 128 + wm * 64 + mi * 16 + fr; int col = nt * 256 + wn * 128 + ni * 16 + fq * 4;
;       float4 xi = *(const float4*)(xin + row * 1024 + col);
;       float4 o; o.x = xi.x + acc[mi][ni][0]; o.y = xi.y + acc[mi][ni][1]; o.z = xi.z + acc[mi][ni][2]; o.w = xi.w + acc[mi][ni][3];
;       *(float4*)(p.out + row * 1024 + col) = o;
;     }
	ds_read_b128 v[158:161], v162 offset:16384
	ds_read_b128 v[166:169], v162 offset:17408
	ds_read_b128 v[170:173], v163
	ds_read_b128 v[174:177], v163 offset:1024
	ds_read_b128 v[182:185], v162 offset:18432
	ds_read_b128 v[194:197], v162 offset:19456
	s_lshl_b32 s22, s24, 19
	s_waitcnt lgkmcnt(3)
	v_mfma_f32_16x16x32_bf16 v[178:181], v[158:161], v[170:173], v[150:153]
	v_readlane_b32 s23, v255, 33
	v_readlane_b32 s4, v255, 26
	s_add_i32 s13, s13, s23
	s_waitcnt lgkmcnt(2)
	v_mfma_f32_16x16x32_bf16 v[154:157], v[158:161], v[174:177], v[134:137]
	v_readlane_b32 s23, v255, 30
	s_add_i32 s12, s12, s23
	v_readlane_b32 s23, v255, 34
	s_waitcnt lgkmcnt(1)
	v_mfma_f32_16x16x32_bf16 v[198:201], v[182:185], v[170:173], v[142:145]
	s_add_i32 s11, s11, s23
	v_readlane_b32 s5, v255, 27
	s_waitcnt lgkmcnt(0)
	v_mfma_f32_16x16x32_bf16 v[142:145], v[194:197], v[174:177], v[122:125]
	ds_read_b128 v[210:213], v163 offset:2048
	s_nop 1
	ds_read_b128 v[122:125], v163 offset:3072
	s_waitcnt vmcnt(5)
	ds_write_b128 v164, v[118:121] offset:8192
	s_waitcnt vmcnt(4)
	ds_write_b128 v164, v[114:117] offset:12288
	s_waitcnt vmcnt(3)
	ds_write_b128 v164, v[110:113] offset:32768
	s_waitcnt vmcnt(2)
	ds_write_b128 v164, v[106:109] offset:36864
	v_mfma_f32_16x16x32_bf16 v[206:209], v[194:197], v[170:173], v[138:141]
	v_mfma_f32_16x16x32_bf16 v[150:153], v[166:169], v[174:177], v[130:133]
	s_waitcnt lgkmcnt(5)
	v_mfma_f32_16x16x32_bf16 v[138:141], v[158:161], v[210:213], v[98:101]
	v_mfma_f32_16x16x32_bf16 v[130:133], v[182:185], v[210:213], v[78:81]
	s_waitcnt lgkmcnt(4)
	v_mfma_f32_16x16x32_bf16 v[78:81], v[158:161], v[122:125], v[66:69]
	ds_read_b128 v[158:161], v162 offset:20480
	s_waitcnt vmcnt(1)
	ds_write_b128 v164, v[90:93] offset:40960
	s_waitcnt vmcnt(0)
	ds_write_b128 v164, v[94:97] offset:45056
	ds_read_b128 v[114:117], v162 offset:21504
	v_mfma_f32_16x16x32_bf16 v[190:193], v[166:169], v[170:173], v[146:149]
	v_mfma_f32_16x16x32_bf16 v[146:149], v[182:185], v[174:177], v[126:129]
	v_mfma_f32_16x16x32_bf16 v[126:129], v[194:197], v[210:213], v[74:77]
	v_mfma_f32_16x16x32_bf16 v[74:77], v[166:169], v[122:125], v[62:65]
	v_mfma_f32_16x16x32_bf16 v[62:65], v[194:197], v[122:125], v[50:53]
	ds_read_b128 v[106:109], v162 offset:22528
	s_nop 1
	ds_read_b128 v[50:53], v162 offset:23552
	s_waitcnt lgkmcnt(0)
	s_barrier
	v_mfma_f32_16x16x32_bf16 v[134:137], v[166:169], v[210:213], v[86:89]
	v_mfma_f32_16x16x32_bf16 v[66:69], v[182:185], v[122:125], v[54:57]
	ds_read_b128 v[182:185], v163 offset:8192
	ds_read_b128 v[118:121], v163 offset:9216
	v_mfma_f32_16x16x32_bf16 v[164:167], v[158:161], v[170:173], v[102:105]
	ds_read_b128 v[110:113], v163 offset:10240
	ds_read_b128 v[54:57], v163 offset:11264
	s_nop 0
	ds_read_b128 v[102:105], v162 offset:32768
	ds_read_b128 v[98:101], v162 offset:33792
	v_mfma_f32_16x16x32_bf16 v[194:197], v[114:117], v[170:173], v[82:85]
	ds_read_b128 v[94:97], v162 offset:34816
	ds_read_b128 v[86:89], v162 offset:35840
	ds_read_b128 v[90:93], v162 offset:36864
	ds_read_b128 v[82:85], v162 offset:37888
	v_mfma_f32_16x16x32_bf16 v[214:217], v[106:109], v[170:173], v[70:73]
	v_mfma_f32_16x16x32_bf16 v[168:171], v[50:53], v[170:173], v[58:61]
	s_nop 1
	ds_read_b128 v[70:73], v162 offset:38912
	ds_read_b128 v[58:61], v162 offset:39936
	s_waitcnt lgkmcnt(0)
	s_barrier
	v_mov_b32 v0, v188
	v_mov_b32 v162, v188
	v_mfma_f32_16x16x32_bf16 v[46:49], v[158:161], v[174:177], v[46:49]
	v_and_b32_e32 v163, 15, v0
	v_lshrrev_b32_e32 v172, 1, v162
	v_lshlrev_b32_e32 v162, 1, v162
	v_lshrrev_b32_e32 v0, 2, v0
	v_and_b32_e32 v162, 0x80, v162
	v_and_b32_e32 v0, 12, v0
	v_mfma_f32_16x16x32_bf16 v[42:45], v[114:117], v[174:177], v[42:45]
	v_and_or_b32 v163, v172, 64, v163
	v_mfma_f32_16x16x32_bf16 v[38:41], v[106:109], v[174:177], v[38:41]
	v_mfma_f32_16x16x32_bf16 v[172:175], v[50:53], v[174:177], v[34:37]
	s_nop 2
	v_or3_b32 v34, v0, v162, s25
	v_ashrrev_i32_e32 v35, 31, v34
	v_lshl_or_b32 v0, v163, 12, s22
	v_lshl_add_u64 v[36:37], s[0:1], 0, v[0:1]
	v_lshlrev_b64 v[34:35], 2, v[34:35]
	v_lshl_add_u64 v[36:37], v[36:37], 0, v[34:35]
	global_load_dwordx4 v[218:221], v[36:37], off
	v_mfma_f32_16x16x32_bf16 v[176:179], v[102:105], v[182:185], v[178:181]
	v_lshl_add_u64 v[162:163], s[56:57], 0, v[0:1]
	v_lshl_add_u64 v[186:187], v[162:163], 0, v[34:35]
	s_lshr_b32 s22, s4, 3
	v_mfma_f32_16x16x32_bf16 v[190:193], v[98:101], v[182:185], v[190:193]
	s_add_i32 s7, s7, s22
	s_cmpk_gt_i32 s13, 0x7f
	s_waitcnt vmcnt(0)
	s_nop 0
	v_add_f32_e32 v176, v176, v218
	v_add_f32_e32 v177, v177, v219
	v_add_f32_e32 v178, v178, v220
	v_add_f32_e32 v179, v179, v221
	global_store_dwordx4 v[186:187], v[176:179], off
	global_load_dwordx4 v[176:179], v[36:37], off offset:64
	v_mfma_f32_16x16x32_bf16 v[162:165], v[90:93], v[182:185], v[164:167]
	s_waitcnt vmcnt(0)
	v_add_f32_e32 v176, v190, v176
	v_add_f32_e32 v177, v191, v177
	v_add_f32_e32 v178, v192, v178
	v_add_f32_e32 v179, v193, v179
	global_store_dwordx4 v[186:187], v[176:179], off offset:64
	global_load_dwordx4 v[176:179], v[36:37], off offset:128
	v_mfma_f32_16x16x32_bf16 v[190:193], v[94:97], v[182:185], v[198:201]
	v_mfma_f32_16x16x32_bf16 v[30:33], v[158:161], v[210:213], v[30:33]
	v_mfma_f32_16x16x32_bf16 v[14:17], v[158:161], v[122:125], v[14:17]
	s_waitcnt vmcnt(0)
	s_nop 4
	v_add_f32_e32 v176, v190, v176
	v_add_f32_e32 v177, v191, v177
	v_add_f32_e32 v178, v192, v178
	v_add_f32_e32 v179, v193, v179
	global_store_dwordx4 v[186:187], v[176:179], off offset:128
	global_load_dwordx4 v[176:179], v[36:37], off offset:192
	v_mfma_f32_16x16x32_bf16 v[190:193], v[86:89], v[182:185], v[206:209]
	v_mfma_f32_16x16x32_bf16 v[154:157], v[102:105], v[118:121], v[154:157]
	v_mfma_f32_16x16x32_bf16 v[150:153], v[98:101], v[118:121], v[150:153]
	s_waitcnt vmcnt(0)
; DI void outproj_tile(const Params& p, int l, int tile, char* smem) {
;     ...
;   for (int mi = 0; mi < 4; ++mi)
; #pragma unroll
;     for (int ni = 0; ni < 8; ++ni) {
;       size_t row = (size_t)mt * 128 + wm * 64 + mi * 16 + fr; int col = nt * 256 + wn * 128 + ni * 16 + fq * 4;
;       float4 xi = *(const float4*)(xin + row * 1024 + col);
;       float4 o; o.x = xi.x + acc[mi][ni][0]; o.y = xi.y + acc[mi][ni][1]; o.z = xi.z + acc[mi][ni][2]; o.w = xi.w + acc[mi][ni][3];
;       *(float4*)(p.out + row * 1024 + col) = o;
;     }
	s_nop 4
	v_add_f32_e32 v176, v190, v176
	v_add_f32_e32 v177, v191, v177
	v_add_f32_e32 v178, v192, v178
	v_add_f32_e32 v179, v193, v179
	global_store_dwordx4 v[186:187], v[176:179], off offset:192
	global_load_dwordx4 v[176:179], v[36:37], off offset:256
	v_mfma_f32_16x16x32_bf16 v[146:149], v[94:97], v[118:121], v[146:149]
	s_waitcnt vmcnt(0)
	v_add_f32_e32 v162, v162, v176
	v_add_f32_e32 v163, v163, v177
	v_add_f32_e32 v164, v164, v178
	v_add_f32_e32 v165, v165, v179
	global_store_dwordx4 v[186:187], v[162:165], off offset:256
	global_load_dwordx4 v[162:165], v[36:37], off offset:320
	v_mfma_f32_16x16x32_bf16 v[176:179], v[82:85], v[182:185], v[194:197]
	v_mfma_f32_16x16x32_bf16 v[142:145], v[86:89], v[118:121], v[142:145]
	v_mfma_f32_16x16x32_bf16 v[46:49], v[90:93], v[118:121], v[46:49]
	s_waitcnt vmcnt(0)
	s_nop 4
	v_add_f32_e32 v162, v176, v162
	v_add_f32_e32 v163, v177, v163
	v_add_f32_e32 v164, v178, v164
	v_add_f32_e32 v165, v179, v165
	global_store_dwordx4 v[186:187], v[162:165], off offset:320
	global_load_dwordx4 v[162:165], v[36:37], off offset:384
	v_mfma_f32_16x16x32_bf16 v[176:179], v[70:73], v[182:185], v[214:217]
	v_mfma_f32_16x16x32_bf16 v[42:45], v[82:85], v[118:121], v[42:45]
	v_mfma_f32_16x16x32_bf16 v[30:33], v[90:93], v[110:113], v[30:33]
	s_waitcnt vmcnt(0)
	s_nop 4
	v_add_f32_e32 v162, v176, v162
	v_add_f32_e32 v163, v177, v163
	v_add_f32_e32 v164, v178, v164
	v_add_f32_e32 v165, v179, v165
	global_store_dwordx4 v[186:187], v[162:165], off offset:384
	global_load_dwordx4 v[162:165], v[36:37], off offset:448
	v_mov_b32_e32 v37, v1
	v_or_b32_e32 v36, 0x10000, v0
	v_lshl_add_u64 v[158:159], s[0:1], 0, v[36:37]
	v_lshl_add_u64 v[166:167], v[158:159], 0, v[34:35]
	v_mfma_f32_16x16x32_bf16 v[158:161], v[58:61], v[182:185], v[168:171]
	v_lshl_add_u64 v[36:37], s[56:57], 0, v[36:37]
	v_mfma_f32_16x16x32_bf16 v[26:29], v[114:117], v[210:213], v[26:29]
	v_mfma_f32_16x16x32_bf16 v[26:29], v[82:85], v[110:113], v[26:29]
	s_waitcnt vmcnt(0)
	s_nop 3
	v_add_f32_e32 v158, v158, v162
	v_add_f32_e32 v159, v159, v163
	v_add_f32_e32 v160, v160, v164
	v_add_f32_e32 v161, v161, v165
	global_store_dwordx4 v[186:187], v[158:161], off offset:448
	global_load_dwordx4 v[158:161], v[166:167], off
	v_lshl_add_u64 v[162:163], v[36:37], 0, v[34:35]
	v_mfma_f32_16x16x32_bf16 v[36:39], v[70:73], v[118:121], v[38:41]
	s_waitcnt vmcnt(0)
	v_add_f32_e32 v154, v154, v158
	v_add_f32_e32 v155, v155, v159
	v_add_f32_e32 v156, v156, v160
	v_add_f32_e32 v157, v157, v161
	global_store_dwordx4 v[162:163], v[154:157], off
	global_load_dwordx4 v[154:157], v[166:167], off offset:64
	v_mfma_f32_16x16x32_bf16 v[22:25], v[106:109], v[210:213], v[22:25]
	s_waitcnt vmcnt(0)
	v_add_f32_e32 v150, v150, v154
	v_add_f32_e32 v151, v151, v155
	v_add_f32_e32 v152, v152, v156
	v_add_f32_e32 v153, v153, v157
	global_store_dwordx4 v[162:163], v[150:153], off offset:64
	global_load_dwordx4 v[150:153], v[166:167], off offset:128
	v_mfma_f32_16x16x32_bf16 v[22:25], v[70:73], v[110:113], v[22:25]
	s_waitcnt vmcnt(0)
	v_add_f32_e32 v146, v146, v150
	v_add_f32_e32 v147, v147, v151
	v_add_f32_e32 v148, v148, v152
	v_add_f32_e32 v149, v149, v153
	global_store_dwordx4 v[162:163], v[146:149], off offset:128
	global_load_dwordx4 v[146:149], v[166:167], off offset:192
	v_mfma_f32_16x16x32_bf16 v[18:21], v[50:53], v[210:213], v[18:21]
	s_waitcnt vmcnt(0)
	v_add_f32_e32 v142, v142, v146
	v_add_f32_e32 v143, v143, v147
	v_add_f32_e32 v144, v144, v148
	v_add_f32_e32 v145, v145, v149
	global_store_dwordx4 v[162:163], v[142:145], off offset:192
	global_load_dwordx4 v[142:145], v[166:167], off offset:256
	v_mfma_f32_16x16x32_bf16 v[18:21], v[58:61], v[110:113], v[18:21]
	s_waitcnt vmcnt(0)
	v_add_f32_e32 v46, v46, v142
	v_add_f32_e32 v47, v47, v143
	v_add_f32_e32 v48, v48, v144
	v_add_f32_e32 v49, v49, v145
	global_store_dwordx4 v[162:163], v[46:49], off offset:256
	global_load_dwordx4 v[46:49], v[166:167], off offset:320
	v_mfma_f32_16x16x32_bf16 v[14:17], v[90:93], v[54:57], v[14:17]
	s_waitcnt vmcnt(0)
	v_add_f32_e32 v42, v42, v46
	v_add_f32_e32 v43, v43, v47
	v_add_f32_e32 v44, v44, v48
	v_add_f32_e32 v45, v45, v49
	global_store_dwordx4 v[162:163], v[42:45], off offset:320
	global_load_dwordx4 v[42:45], v[166:167], off offset:384
	v_mfma_f32_16x16x32_bf16 v[10:13], v[114:117], v[122:125], v[10:13]
	s_waitcnt vmcnt(0)
	v_add_f32_e32 v36, v36, v42
	v_add_f32_e32 v37, v37, v43
	v_add_f32_e32 v38, v38, v44
	v_add_f32_e32 v39, v39, v45
	global_store_dwordx4 v[162:163], v[36:39], off offset:384
	global_load_dwordx4 v[36:39], v[166:167], off offset:448
	v_mov_b32_e32 v45, v1
	v_or_b32_e32 v44, 0x20000, v0
	v_lshl_add_u64 v[40:41], s[0:1], 0, v[44:45]
	v_lshl_add_u64 v[46:47], v[40:41], 0, v[34:35]
	v_mfma_f32_16x16x32_bf16 v[40:43], v[58:61], v[118:121], v[172:175]
	v_or_b32_e32 v0, 0x30000, v0
	v_mfma_f32_16x16x32_bf16 v[10:13], v[82:85], v[54:57], v[10:13]
	v_mfma_f32_16x16x32_bf16 v[6:9], v[106:109], v[122:125], v[6:9]
	s_waitcnt vmcnt(0)
; DI void outproj_tile(const Params& p, int l, int tile, char* smem) {
;     ...
;   for (int mi = 0; mi < 4; ++mi)
; #pragma unroll
;     for (int ni = 0; ni < 8; ++ni) {
;       size_t row = (size_t)mt * 128 + wm * 64 + mi * 16 + fr; int col = nt * 256 + wn * 128 + ni * 16 + fq * 4;
;       float4 xi = *(const float4*)(xin + row * 1024 + col);
;       float4 o; o.x = xi.x + acc[mi][ni][0]; o.y = xi.y + acc[mi][ni][1]; o.z = xi.z + acc[mi][ni][2]; o.w = xi.w + acc[mi][ni][3];
;       *(float4*)(p.out + row * 1024 + col) = o;
;     }
	s_nop 3
	v_add_f32_e32 v36, v40, v36
	v_add_f32_e32 v37, v41, v37
	v_add_f32_e32 v38, v42, v38
	v_add_f32_e32 v39, v43, v39
	global_store_dwordx4 v[162:163], v[36:39], off offset:448
	global_load_dwordx4 v[36:39], v[46:47], off
	v_lshl_add_u64 v[40:41], s[56:57], 0, v[44:45]
	v_lshl_add_u64 v[44:45], v[40:41], 0, v[34:35]
	v_mfma_f32_16x16x32_bf16 v[40:43], v[102:105], v[110:113], v[138:141]
	v_mfma_f32_16x16x32_bf16 v[6:9], v[70:73], v[54:57], v[6:9]
	v_mfma_f32_16x16x32_bf16 v[2:5], v[50:53], v[122:125], v[2:5]
	s_waitcnt vmcnt(0)
	s_nop 4
	v_add_f32_e32 v36, v40, v36
	v_add_f32_e32 v37, v41, v37
	v_add_f32_e32 v38, v42, v38
	v_add_f32_e32 v39, v43, v39
	global_store_dwordx4 v[44:45], v[36:39], off
	global_load_dwordx4 v[36:39], v[46:47], off offset:64
	v_mfma_f32_16x16x32_bf16 v[40:43], v[98:101], v[110:113], v[134:137]
	v_mfma_f32_16x16x32_bf16 v[2:5], v[58:61], v[54:57], v[2:5]
	s_waitcnt vmcnt(0)
	s_nop 5
	v_add_f32_e32 v36, v40, v36
	v_add_f32_e32 v37, v41, v37
	v_add_f32_e32 v38, v42, v38
	v_add_f32_e32 v39, v43, v39
	global_store_dwordx4 v[44:45], v[36:39], off offset:64
	global_load_dwordx4 v[36:39], v[46:47], off offset:128
	v_mfma_f32_16x16x32_bf16 v[40:43], v[94:97], v[110:113], v[130:133]
	s_waitcnt vmcnt(0)
	s_nop 6
	v_add_f32_e32 v36, v40, v36
	v_add_f32_e32 v37, v41, v37
	v_add_f32_e32 v38, v42, v38
	v_add_f32_e32 v39, v43, v39
	global_store_dwordx4 v[44:45], v[36:39], off offset:128
	global_load_dwordx4 v[36:39], v[46:47], off offset:192
	v_mfma_f32_16x16x32_bf16 v[40:43], v[86:89], v[110:113], v[126:129]
	s_waitcnt vmcnt(0)
	s_nop 6
	v_add_f32_e32 v36, v40, v36
	v_add_f32_e32 v37, v41, v37
	v_add_f32_e32 v38, v42, v38
	v_add_f32_e32 v39, v43, v39
	global_store_dwordx4 v[44:45], v[36:39], off offset:192
	global_load_dwordx4 v[36:39], v[46:47], off offset:256
	s_waitcnt vmcnt(0)
	v_add_f32_e32 v30, v30, v36
	v_add_f32_e32 v31, v31, v37
	v_add_f32_e32 v32, v32, v38
	v_add_f32_e32 v33, v33, v39
	global_store_dwordx4 v[44:45], v[30:33], off offset:256
	global_load_dwordx4 v[30:33], v[46:47], off offset:320
	s_waitcnt vmcnt(0)
	v_add_f32_e32 v26, v26, v30
	v_add_f32_e32 v27, v27, v31
	v_add_f32_e32 v28, v28, v32
	v_add_f32_e32 v29, v29, v33
	global_store_dwordx4 v[44:45], v[26:29], off offset:320
	global_load_dwordx4 v[26:29], v[46:47], off offset:384
	s_waitcnt vmcnt(0)
	v_add_f32_e32 v22, v22, v26
	v_add_f32_e32 v23, v23, v27
	v_add_f32_e32 v24, v24, v28
	v_add_f32_e32 v25, v25, v29
	global_store_dwordx4 v[44:45], v[22:25], off offset:384
	global_load_dwordx4 v[22:25], v[46:47], off offset:448
	v_lshl_add_u64 v[26:27], s[0:1], 0, v[0:1]
	v_lshl_add_u64 v[26:27], v[26:27], 0, v[34:35]
	s_waitcnt vmcnt(0)
	v_add_f32_e32 v18, v18, v22
	v_add_f32_e32 v19, v19, v23
	v_add_f32_e32 v20, v20, v24
	v_add_f32_e32 v21, v21, v25
	global_store_dwordx4 v[44:45], v[18:21], off offset:448
	global_load_dwordx4 v[18:21], v[26:27], off
	v_lshl_add_u64 v[22:23], s[56:57], 0, v[0:1]
	v_lshl_add_u64 v[28:29], v[22:23], 0, v[34:35]
	v_mfma_f32_16x16x32_bf16 v[22:25], v[102:105], v[54:57], v[78:81]
	s_waitcnt vmcnt(0)
	s_nop 6
	v_add_f32_e32 v18, v22, v18
	v_add_f32_e32 v19, v23, v19
	v_add_f32_e32 v20, v24, v20
	v_add_f32_e32 v21, v25, v21
	global_store_dwordx4 v[28:29], v[18:21], off
	global_load_dwordx4 v[18:21], v[26:27], off offset:64
	v_mfma_f32_16x16x32_bf16 v[22:25], v[98:101], v[54:57], v[74:77]
	s_waitcnt vmcnt(0)
	s_nop 6
	v_add_f32_e32 v18, v22, v18
	v_add_f32_e32 v19, v23, v19
	v_add_f32_e32 v20, v24, v20
	v_add_f32_e32 v21, v25, v21
	global_store_dwordx4 v[28:29], v[18:21], off offset:64
	global_load_dwordx4 v[18:21], v[26:27], off offset:128
	v_mfma_f32_16x16x32_bf16 v[22:25], v[94:97], v[54:57], v[66:69]
	s_waitcnt vmcnt(0)
	s_nop 6
	v_add_f32_e32 v18, v22, v18
	v_add_f32_e32 v19, v23, v19
	v_add_f32_e32 v20, v24, v20
	v_add_f32_e32 v21, v25, v21
	global_store_dwordx4 v[28:29], v[18:21], off offset:128
	global_load_dwordx4 v[18:21], v[26:27], off offset:192
	v_mfma_f32_16x16x32_bf16 v[22:25], v[86:89], v[54:57], v[62:65]
	s_waitcnt vmcnt(0)
	s_nop 6
	v_add_f32_e32 v18, v22, v18
	v_add_f32_e32 v19, v23, v19
	v_add_f32_e32 v20, v24, v20
	v_add_f32_e32 v21, v25, v21
	global_store_dwordx4 v[28:29], v[18:21], off offset:192
	global_load_dwordx4 v[18:21], v[26:27], off offset:256
	s_waitcnt vmcnt(0)
	v_add_f32_e32 v14, v14, v18
	v_add_f32_e32 v15, v15, v19
	v_add_f32_e32 v16, v16, v20
	v_add_f32_e32 v17, v17, v21
	global_store_dwordx4 v[28:29], v[14:17], off offset:256
	global_load_dwordx4 v[14:17], v[26:27], off offset:320
	s_waitcnt vmcnt(0)
	v_add_f32_e32 v10, v10, v14
	v_add_f32_e32 v11, v11, v15
	v_add_f32_e32 v12, v12, v16
	v_add_f32_e32 v13, v13, v17
	global_store_dwordx4 v[28:29], v[10:13], off offset:320
	global_load_dwordx4 v[10:13], v[26:27], off offset:384
	s_waitcnt vmcnt(0)
	v_add_f32_e32 v6, v6, v10
	v_add_f32_e32 v7, v7, v11
	v_add_f32_e32 v8, v8, v12
	v_add_f32_e32 v9, v9, v13
	global_store_dwordx4 v[28:29], v[6:9], off offset:384
	global_load_dwordx4 v[6:9], v[26:27], off offset:448
	s_waitcnt vmcnt(0)
	v_add_f32_e32 v2, v2, v6
	v_add_f32_e32 v3, v3, v7
	v_add_f32_e32 v4, v4, v8
	v_add_f32_e32 v5, v5, v9
	global_store_dwordx4 v[28:29], v[2:5], off offset:448
	s_cbranch_scc0 .LBB0_237

; DI unsigned pack2(float a, float b) { f2_t v = {a, b}; bf2_t r = __builtin_convertvector(v, bf2_t); return __builtin_bit_cast(unsigned, r); }
; DI void conv_tile(const float* __restrict__ src, int ld, int K, bf16_t* __restrict__ dst, int n0, int k0, int mode,
;                   const float* __restrict__ rs, float* tile, int dld) {
;     ...
;       const float sc2 = (rs ? rs[k0 + k] : 1.0f) * cscale;
;       float* tp = tile + k * 65 + n4;
;       tp[0] = v.x * sc2; tp[1] = v.y * sc2; tp[2] = v.z * sc2; tp[3] = v.w * sc2;
;     }
;   }
;   __syncthreads();
;   {
;     const int nn = tid >> 2, kq = (tid & 3) * 16;
;     unsigned w[8];
; #pragma unroll
;     for (int j = 0; j < 8; ++j) w[j] = pack2(tile[(kq + 2 * j) * 65 + nn], tile[(kq + 2 * j + 1) * 65 + nn]);
;     uint4* dp = (uint4*)(dst + (size_t)(n0 + nn) * dld + k0 + kq);
;     uint4 w0, w1; w0.x = w[0]; w0.y = w[1]; w0.z = w[2]; w0.w = w[3]; w1.x = w[4]; w1.y = w[5]; w1.z = w[6]; w1.w = w[7];
;     dp[0] = w0; dp[1] = w1;
.LBB0_256:
	s_waitcnt vmcnt(0)
	v_mul_f32_e32 v6, v13, v6
	v_mul_f32_e32 v2, v2, v6
	v_mul_f32_e32 v3, v3, v6
	v_add_u32_e32 v7, 0x30c0, v0
	ds_write2_b32 v7, v2, v3 offset1:1
	v_mul_f32_e32 v2, v4, v6
	v_mul_f32_e32 v3, v5, v6
	v_add_u32_e32 v0, 0x30c8, v0
	ds_write2_b32 v0, v2, v3 offset1:1
	v_lshlrev_b32_e32 v2, 4, v12
	v_and_b32_e32 v13, 48, v2
	v_and_b32_e32 v2, -4, v12
	v_mul_u32_u24_e32 v3, 0x41, v13
	v_lshl_add_u32 v10, v3, 2, v2
	s_waitcnt lgkmcnt(0)
	s_barrier
	ds_read2_b32 v[2:3], v10 offset1:65
	ds_read2_b32 v[4:5], v10 offset0:130 offset1:195
	v_add_u32_e32 v6, 0x400, v10
	v_add_u32_e32 v8, 0x800, v10
	v_add_u32_e32 v10, 0xc00, v10
	s_waitcnt lgkmcnt(1)
	v_cvt_pk_bf16_f32 v2, v2, v3
	s_waitcnt lgkmcnt(0)
	v_cvt_pk_bf16_f32 v3, v4, v5
	ds_read2_b32 v[4:5], v6 offset0:4 offset1:69
	ds_read2_b32 v[6:7], v6 offset0:134 offset1:199
	v_lshrrev_b32_e32 v0, 2, v12
	v_or_b32_e32 v0, s12, v0
	s_waitcnt lgkmcnt(1)
	v_cvt_pk_bf16_f32 v4, v4, v5
	s_waitcnt lgkmcnt(0)
	v_cvt_pk_bf16_f32 v5, v6, v7
	ds_read2_b32 v[6:7], v8 offset0:8 offset1:73
	ds_read2_b32 v[8:9], v8 offset0:138 offset1:203
	s_waitcnt lgkmcnt(1)
	v_cvt_pk_bf16_f32 v6, v6, v7
	s_waitcnt lgkmcnt(0)
	v_cvt_pk_bf16_f32 v7, v8, v9
	ds_read2_b32 v[8:9], v10 offset0:12 offset1:77
	ds_read2_b32 v[10:11], v10 offset0:142 offset1:207
	s_waitcnt lgkmcnt(1)
	v_cvt_pk_bf16_f32 v8, v8, v9
	s_waitcnt lgkmcnt(0)
	v_cvt_pk_bf16_f32 v9, v10, v11
	v_mul_hi_i32_i24_e32 v11, s7, v0
	v_mul_i32_i24_e32 v10, s7, v0
	v_lshl_add_u64 v[10:11], v[10:11], 1, s[22:23]
	v_lshl_add_u64 v[10:11], s[28:29], 1, v[10:11]
	v_lshlrev_b32_e32 v0, 1, v13
	v_lshl_add_u64 v[10:11], v[10:11], 0, v[0:1]
	global_store_dwordx4 v[10:11], v[2:5], off
	global_store_dwordx4 v[10:11], v[6:9], off offset:16

; DI void conv_tile(const float* __restrict__ src, int ld, int K, bf16_t* __restrict__ dst, int n0, int k0, int mode,
;                   const float* __restrict__ rs, float* tile, int dld) {
;     ...
;     for (int i = 0; i < 4; ++i) {
;       const int k = kk + 16 * i;
;       float4 v = make_float4(0.f, 0.f, 0.f, 0.f);
;       if (sc >= 0) v = *(const float4*)(src + (size_t)(k0 + k) * ld + sc);
;       const float sc2 = (rs ? rs[k0 + k] : 1.0f) * cscale;
;       float* tp = tile + k * 65 + n4;
;       tp[0] = v.x * sc2; tp[1] = v.y * sc2; tp[2] = v.z * sc2; tp[3] = v.w * sc2;
.LBB0_316:
	v_lshlrev_b32_e32 v0, 2, v7
	s_waitcnt vmcnt(0)
	v_mul_f32_e32 v10, v13, v10
	s_movk_i32 s0, 0x104
	v_mad_u32_u24 v7, v6, s0, v0
	v_mul_f32_e32 v2, v2, v10
	v_mul_f32_e32 v3, v3, v10
	ds_write2_b32 v7, v2, v3 offset1:1
	v_mul_f32_e32 v2, v4, v10
	v_mul_f32_e32 v3, v5, v10
	ds_write2_b32 v7, v2, v3 offset0:2 offset1:3
	v_mov_b32_e32 v2, 0
	v_mov_b32_e32 v3, 0
	v_mov_b32_e32 v4, 0
	v_mov_b32_e32 v5, 0
	s_and_saveexec_b64 s[0:1], s[38:39]
	s_cbranch_execz .LBB0_318
	v_or3_b32 v2, v6, s28, 16
	v_mul_hi_i32_i24_e32 v3, s26, v2
	v_mul_i32_i24_e32 v2, s26, v2
	v_lshl_add_u64 v[2:3], v[2:3], 2, v[8:9]
	global_load_dwordx4 v[2:5], v[2:3], off

; DI void conv_tile(const float* __restrict__ src, int ld, int K, bf16_t* __restrict__ dst, int n0, int k0, int mode,
;                   const float* __restrict__ rs, float* tile, int dld) {
;     ...
;     for (int i = 0; i < 4; ++i) {
;       const int k = kk + 16 * i;
;       float4 v = make_float4(0.f, 0.f, 0.f, 0.f);
;       if (sc >= 0) v = *(const float4*)(src + (size_t)(k0 + k) * ld + sc);
;       const float sc2 = (rs ? rs[k0 + k] : 1.0f) * cscale;
;       float* tp = tile + k * 65 + n4;
;       tp[0] = v.x * sc2; tp[1] = v.y * sc2; tp[2] = v.z * sc2; tp[3] = v.w * sc2;
.LBB0_321:
	v_mul_u32_u24_e32 v11, 0x104, v6
	s_waitcnt vmcnt(0)
	v_mul_f32_e32 v10, v13, v7
	v_add_u32_e32 v0, v11, v0
	v_add_u32_e32 v7, 0x1040, v0
	v_mul_f32_e32 v2, v2, v10
	v_mul_f32_e32 v3, v3, v10
	ds_write2_b32 v7, v2, v3 offset1:1
	v_add_u32_e32 v7, 0x1048, v0
	v_mul_f32_e32 v2, v4, v10
	v_mul_f32_e32 v3, v5, v10
	ds_write2_b32 v7, v2, v3 offset1:1
	v_mov_b32_e32 v2, 0
	v_mov_b32_e32 v3, 0
	v_mov_b32_e32 v4, 0
	v_mov_b32_e32 v5, 0
	s_and_saveexec_b64 vcc, s[38:39]
	s_cbranch_execz .LBB0_323
	v_or3_b32 v2, v6, s28, 32
	v_mul_hi_i32_i24_e32 v3, s26, v2
	v_mul_i32_i24_e32 v2, s26, v2
	v_lshl_add_u64 v[2:3], v[2:3], 2, v[8:9]
	global_load_dwordx4 v[2:5], v[2:3], off

; DI void conv_tile(const float* __restrict__ src, int ld, int K, bf16_t* __restrict__ dst, int n0, int k0, int mode,
;                   const float* __restrict__ rs, float* tile, int dld) {
;     ...
;     for (int i = 0; i < 4; ++i) {
;       const int k = kk + 16 * i;
;       float4 v = make_float4(0.f, 0.f, 0.f, 0.f);
;       if (sc >= 0) v = *(const float4*)(src + (size_t)(k0 + k) * ld + sc);
;       const float sc2 = (rs ? rs[k0 + k] : 1.0f) * cscale;
;       float* tp = tile + k * 65 + n4;
;       tp[0] = v.x * sc2; tp[1] = v.y * sc2; tp[2] = v.z * sc2; tp[3] = v.w * sc2;
.LBB0_326:
	s_waitcnt vmcnt(0)
	v_mul_f32_e32 v10, v13, v7
	v_mul_f32_e32 v2, v2, v10
	v_mul_f32_e32 v3, v3, v10
	v_add_u32_e32 v7, 0x2080, v0
	ds_write2_b32 v7, v2, v3 offset1:1
	v_mul_f32_e32 v2, v4, v10
	v_mul_f32_e32 v3, v5, v10
	v_add_u32_e32 v4, 0x2088, v0
	ds_write2_b32 v4, v2, v3 offset1:1
	v_mov_b32_e32 v2, 0
	v_mov_b32_e32 v3, 0
	v_mov_b32_e32 v4, 0
	v_mov_b32_e32 v5, 0
	s_and_saveexec_b64 s[0:1], s[38:39]
	s_cbranch_execz .LBB0_328
	v_or3_b32 v2, v6, s28, 48
	v_mul_hi_i32_i24_e32 v3, s26, v2
	v_mul_i32_i24_e32 v2, s26, v2
	v_lshl_add_u64 v[2:3], v[2:3], 2, v[8:9]
	global_load_dwordx4 v[2:5], v[2:3], off

; DI void norm_rows_bf16(const float* __restrict__ src, const float* __restrict__ g, bf16_t* __restrict__ dst, int item) {
;     ...
;   for (int i = 0; i < 8; ++i) {
;     size_t row = (size_t)item * 32 + wid * 8 + i;
;     const float4* s = (const float4*)(src + row * 1024);
;     float4 v[4]; float ss = 0.f;
; #pragma unroll
;     for (int j = 0; j < 4; ++j) { v[j] = s[2 * lane + (j & 1) + 128 * (j >> 1)]; ss += v[j].x * v[j].x + v[j].y * v[j].y + v[j].z * v[j].z + v[j].w * v[j].w; }
;     ss = wave_sum(ss);
;     float sc = rsqrtf(ss * (1.0f / 1024.0f) + 1e-6f);
.LBB0_334:
	v_cmp_lt_i32_e32 vcc, v252, v189
	v_mov_b32 v4, v188
	v_mov_b32 v0, v188
	s_mov_b64 s[0:1], 0x1800
	v_lshrrev_b32_e32 v0, 6, v0
	v_cndmask_b32_e32 v2, v204, v252, vcc
	v_cmp_lt_i32_e32 vcc, v191, v189
	v_lshlrev_b32_e32 v60, 2, v2
	v_and_b32_e32 v22, 63, v4
	v_cndmask_b32_e32 v2, v204, v191, vcc
	v_cmp_lt_i32_e32 vcc, v192, v189
	v_lshlrev_b32_e32 v61, 2, v2
	s_add_i32 s6, s6, s94
	v_cndmask_b32_e32 v2, v204, v192, vcc
	v_cmp_lt_i32_e32 vcc, v193, v189
	v_lshlrev_b32_e32 v62, 2, v2
	s_nop 0
	v_cndmask_b32_e32 v2, v204, v193, vcc
	v_cmp_lt_i32_e32 vcc, v194, v189
	v_lshlrev_b32_e32 v63, 2, v2
	s_nop 0
	v_cndmask_b32_e32 v2, v204, v194, vcc
	v_cmp_lt_i32_e32 vcc, v195, v189
	v_lshlrev_b32_e32 v64, 2, v2
	s_nop 0
	v_cndmask_b32_e32 v2, v204, v195, vcc
	v_lshlrev_b32_e32 v65, 2, v2
	v_lshlrev_b32_e32 v2, 5, v4
	v_and_b32_e32 v30, 0x7e0, v2
	v_lshlrev_b64 v[2:3], 15, v[0:1]
	v_lshl_or_b32 v2, v22, 5, v2
	v_lshl_add_u64 v[52:53], s[24:25], 0, v[2:3]
	global_load_dwordx4 v[18:21], v[52:53], off offset:16
	global_load_dwordx4 v[26:29], v[52:53], off
	global_load_dwordx4 v[2:5], v30, s[62:63] offset:16
	global_load_dwordx4 v[10:13], v30, s[62:63]
	s_add_u32 s24, s24, s78
	s_addc_u32 s25, s25, s79
	s_waitcnt vmcnt(3)
	v_mov_b32_e32 v17, v19
	s_waitcnt vmcnt(2)
	v_mov_b32_e32 v16, v27
	v_mov_b32_e32 v14, v26
	v_mov_b32_e32 v15, v18
	v_mul_f32_e32 v16, v16, v16
	v_mul_f32_e32 v17, v17, v17
	v_mov_b32_e32 v6, v28
	v_mov_b32_e32 v7, v20
	v_fma_f32 v14, v14, v14, v16
	v_fma_f32 v15, v15, v15, v17
	v_mov_b32_e32 v8, v29
	v_mov_b32_e32 v9, v21
	v_fma_f32 v6, v6, v6, v14
	v_fma_f32 v7, v7, v7, v15
	s_nop 0
	v_fma_f32 v56, v8, v8, v6
	v_fma_f32 v57, v9, v9, v7
	v_lshlrev_b64 v[6:7], 14, v[0:1]
	v_lshl_or_b32 v6, v22, 4, v6
	v_lshl_add_u64 v[50:51], s[22:23], 0, v[6:7]
	global_load_dwordx4 v[22:25], v[52:53], off offset:2064
	global_load_dwordx4 v[34:37], v[52:53], off offset:2048
	global_load_dwordx4 v[6:9], v30, s[62:63] offset:2064
	global_load_dwordx4 v[14:17], v30, s[62:63] offset:2048
	s_add_u32 s22, s22, s96
	s_addc_u32 s23, s23, s97
	s_cmpk_gt_i32 s6, 0x3ff
	s_waitcnt vmcnt(3)
	v_mov_b32_e32 v41, v23
	s_waitcnt vmcnt(2)
	v_mov_b32_e32 v40, v35
	v_mov_b32_e32 v38, v34
	v_mov_b32_e32 v39, v22
	v_mul_f32_e32 v40, v40, v40
	v_mul_f32_e32 v41, v41, v41
	v_mov_b32_e32 v30, v36
	v_fma_f32 v38, v38, v38, v40
	v_fma_f32 v39, v39, v39, v41
	v_add_co_u32_e32 v40, vcc, s7, v52
	v_mov_b32_e32 v31, v24
	s_nop 0
	v_addc_co_u32_e32 v41, vcc, 0, v53, vcc
	v_mov_b32_e32 v32, v37
	v_mov_b32_e32 v33, v25
	v_fma_f32 v30, v30, v30, v38
	v_fma_f32 v31, v31, v31, v39
	v_add_co_u32_e32 v54, vcc, s11, v52
	v_fma_f32 v58, v32, v32, v30
	v_fma_f32 v59, v33, v33, v31
	v_lshl_add_u64 v[30:31], v[52:53], 0, s[38:39]
	v_addc_co_u32_e32 v55, vcc, 0, v53, vcc
	global_load_dwordx4 v[42:45], v[54:55], off offset:-4096
	s_nop 0
	global_load_dwordx4 v[30:33], v[30:31], off offset:16
	v_lshl_add_u64 v[38:39], v[52:53], 0, s[0:1]
	s_waitcnt vmcnt(1)
	v_mov_b32_e32 v68, v43
	s_waitcnt vmcnt(0)
	v_mov_b32_e32 v69, v31
	v_mov_b32_e32 v66, v42
	v_mov_b32_e32 v67, v30
	v_mul_f32_e32 v68, v68, v68
	v_mul_f32_e32 v69, v69, v69
	v_mov_b32_e32 v46, v44
	v_mov_b32_e32 v47, v32
	v_fma_f32 v66, v66, v66, v68
	v_fma_f32 v67, v67, v67, v69
	v_mov_b32_e32 v48, v45
	v_mov_b32_e32 v49, v33
	v_fma_f32 v46, v46, v46, v66
	v_fma_f32 v47, v47, v47, v67
	s_nop 0
	v_fma_f32 v66, v48, v48, v46
	v_fma_f32 v67, v49, v49, v47
	global_load_dwordx4 v[46:49], v[40:41], off offset:2048
	s_nop 0
	global_load_dwordx4 v[38:41], v[38:39], off offset:16
	s_waitcnt vmcnt(1)
	v_mov_b32_e32 v74, v47
	s_waitcnt vmcnt(0)
	v_mov_b32_e32 v75, v39
	v_mov_b32_e32 v72, v46
	v_mov_b32_e32 v73, v38
	v_mul_f32_e32 v74, v74, v74
	v_mul_f32_e32 v75, v75, v75
	v_mov_b32_e32 v68, v48
	v_mov_b32_e32 v69, v40
	v_fma_f32 v72, v72, v72, v74
	v_fma_f32 v73, v73, v73, v75
	v_mov_b32_e32 v70, v49
	v_mov_b32_e32 v71, v41
	v_fma_f32 v68, v68, v68, v72
	v_fma_f32 v69, v69, v69, v73
	s_nop 0
	v_fma_f32 v68, v70, v70, v68
	v_fma_f32 v69, v71, v71, v69
	v_mov_b32_e32 v70, v66
	v_mov_b32_e32 v71, v56
	v_mov_b32_e32 v56, v67
	v_add_f32_e32 v56, v70, v56
	v_add_f32_e32 v57, v71, v57
	v_mov_b32_e32 v66, v68
	v_mov_b32_e32 v67, v58
	v_add_f32_e32 v56, v56, v66
	v_add_f32_e32 v57, v57, v67
	v_mov_b32_e32 v58, v69
	v_add_f32_e32 v56, v56, v58
	v_add_f32_e32 v57, v57, v59
	ds_bpermute_b32 v59, v60, v57
	ds_bpermute_b32 v58, v60, v56
	s_waitcnt lgkmcnt(0)
	v_add_f32_e32 v56, v56, v58
	v_add_f32_e32 v57, v57, v59
	ds_bpermute_b32 v59, v61, v57
	ds_bpermute_b32 v58, v61, v56
	s_waitcnt lgkmcnt(0)
	v_add_f32_e32 v56, v56, v58
	v_add_f32_e32 v57, v57, v59
	ds_bpermute_b32 v59, v62, v57
	ds_bpermute_b32 v58, v62, v56
	s_waitcnt lgkmcnt(0)
	v_add_f32_e32 v56, v56, v58
	v_add_f32_e32 v57, v57, v59
	ds_bpermute_b32 v59, v63, v57
	ds_bpermute_b32 v58, v63, v56
	s_waitcnt lgkmcnt(0)
	v_add_f32_e32 v56, v56, v58
	v_add_f32_e32 v57, v57, v59
	ds_bpermute_b32 v59, v64, v57
	ds_bpermute_b32 v58, v64, v56
	s_waitcnt lgkmcnt(0)
	v_add_f32_e32 v56, v56, v58
	v_add_f32_e32 v57, v57, v59
	ds_bpermute_b32 v59, v65, v57
	ds_bpermute_b32 v58, v65, v56
	s_waitcnt lgkmcnt(0)
; DI unsigned pack2(float a, float b) { f2_t v = {a, b}; bf2_t r = __builtin_convertvector(v, bf2_t); return __builtin_bit_cast(unsigned, r); }
; DI void norm_rows_bf16(const float* __restrict__ src, const float* __restrict__ g, bf16_t* __restrict__ dst, int item) {
;     ...
;     for (int j = 0; j < 4; ++j) { v[j] = s[2 * lane + (j & 1) + 128 * (j >> 1)]; ss += v[j].x * v[j].x + v[j].y * v[j].y + v[j].z * v[j].z + v[j].w * v[j].w; }
;     ss = wave_sum(ss);
;     float sc = rsqrtf(ss * (1.0f / 1024.0f) + 1e-6f);
; #pragma unroll
;     for (int jj = 0; jj < 2; ++jj) {
;       float4 g0 = ((const float4*)g)[2 * lane + 128 * jj], g1 = ((const float4*)g)[2 * lane + 1 + 128 * jj];
;       const float4 a = v[2 * jj], c = v[2 * jj + 1];
;       uint4 o; o.x = pack2(a.x * sc * g0.x, a.y * sc * g0.y); o.y = pack2(a.z * sc * g0.z, a.w * sc * g0.w);
;       o.z = pack2(c.x * sc * g1.x, c.y * sc * g1.y); o.w = pack2(c.z * sc * g1.z, c.w * sc * g1.w);
;       *(uint4*)(dst + row * 1024 + (2 * lane + 128 * jj) * 4) = o;
;     }
	v_add_f32_e32 v56, v56, v58
	v_add_f32_e32 v57, v57, v59
	v_mov_b64_e32 v[58:59], s[12:13]
	v_fma_f32 v56, v56, s14, v58
	v_fma_f32 v57, v57, s14, v58
	s_nop 0
	v_mul_f32_e32 v0, 0x4b800000, v57
	v_cmp_gt_f32_e64 s[0:1], s3, v57
	v_cmp_gt_f32_e32 vcc, s3, v56
	s_nop 0
	v_cndmask_b32_e64 v0, v57, v0, s[0:1]
	v_rsq_f32_e32 v0, v0
	s_nop 0
	v_mul_f32_e32 v57, 0x45800000, v0
	v_cndmask_b32_e64 v0, v0, v57, s[0:1]
	v_mul_f32_e32 v26, v26, v0
	v_mul_f32_e32 v27, v27, v0
	v_mul_f32_e32 v28, v28, v0
	v_mul_f32_e32 v29, v29, v0
	v_mul_f32_e32 v18, v18, v0
	v_mul_f32_e32 v19, v19, v0
	v_mul_f32_e32 v26, v10, v26
	v_mul_f32_e32 v27, v11, v27
	v_mul_f32_e32 v28, v12, v28
	v_mul_f32_e32 v29, v13, v29
	v_mul_f32_e32 v18, v2, v18
	v_mul_f32_e32 v19, v3, v19
	v_cvt_pk_bf16_f32 v26, v26, v27
	v_cvt_pk_bf16_f32 v27, v28, v29
	v_cvt_pk_bf16_f32 v28, v18, v19
	v_mul_f32_e32 v18, v20, v0
	v_mul_f32_e32 v19, v21, v0
	v_mul_f32_e32 v20, v36, v0
	v_mul_f32_e32 v21, v37, v0
	v_mul_f32_e32 v18, v4, v18
	v_mul_f32_e32 v19, v5, v19
	v_mul_f32_e32 v20, v20, v16
	v_mul_f32_e32 v21, v21, v17
	v_cvt_pk_bf16_f32 v29, v18, v19
	v_mul_f32_e32 v18, v34, v0
	v_mul_f32_e32 v19, v35, v0
	s_mov_b64 s[0:1], 0x2000
	v_mul_f32_e32 v18, v18, v14
	v_mul_f32_e32 v19, v19, v15
	global_store_dwordx4 v[50:51], v[26:29], off
	v_cvt_pk_bf16_f32 v18, v18, v19
	v_cvt_pk_bf16_f32 v19, v20, v21
	v_mul_f32_e32 v20, v22, v0
	v_mul_f32_e32 v21, v23, v0
	v_mul_f32_e32 v22, v24, v0
	v_mul_f32_e32 v23, v25, v0
	v_mul_f32_e32 v0, 0x4b800000, v56
	v_cndmask_b32_e32 v0, v56, v0, vcc
	v_rsq_f32_e32 v0, v0
	v_mul_f32_e32 v20, v20, v6
	v_mul_f32_e32 v21, v21, v7
	v_mul_f32_e32 v22, v22, v8
	v_mul_f32_e32 v23, v23, v9
	v_cvt_pk_bf16_f32 v20, v20, v21
	v_cvt_pk_bf16_f32 v21, v22, v23
	global_store_dwordx4 v[50:51], v[18:21], off offset:1024
	s_nop 1
	v_mul_f32_e32 v18, 0x45800000, v0
	v_cndmask_b32_e32 v0, v0, v18, vcc
	v_mul_f32_e32 v18, v42, v0
	v_mul_f32_e32 v19, v43, v0
	v_mul_f32_e32 v20, v44, v0
	v_mul_f32_e32 v21, v45, v0
	v_mul_f32_e32 v18, v10, v18
	v_mul_f32_e32 v19, v11, v19
	v_mul_f32_e32 v20, v12, v20
	v_mul_f32_e32 v21, v13, v21
	v_cvt_pk_bf16_f32 v18, v18, v19
	v_cvt_pk_bf16_f32 v19, v20, v21
	v_mul_f32_e32 v20, v30, v0
	v_mul_f32_e32 v21, v31, v0
	v_mul_f32_e32 v22, v32, v0
	v_mul_f32_e32 v23, v33, v0
	v_mul_f32_e32 v20, v2, v20
	v_mul_f32_e32 v21, v3, v21
	v_mul_f32_e32 v22, v4, v22
	v_mul_f32_e32 v23, v5, v23
	v_cvt_pk_bf16_f32 v20, v20, v21
	v_cvt_pk_bf16_f32 v21, v22, v23
	global_store_dwordx4 v[50:51], v[18:21], off offset:2048
	v_mul_f32_e32 v22, v40, v0
	v_mul_f32_e32 v23, v41, v0
	v_lshl_add_u64 v[30:31], v[52:53], 0, s[98:99]
	v_mul_f32_e32 v18, v46, v0
	v_mul_f32_e32 v19, v47, v0
	v_mul_f32_e32 v20, v48, v0
	v_mul_f32_e32 v21, v49, v0
	v_mul_f32_e32 v18, v14, v18
	v_mul_f32_e32 v19, v15, v19
	v_mul_f32_e32 v20, v16, v20
	v_mul_f32_e32 v21, v17, v21
	v_cvt_pk_bf16_f32 v18, v18, v19
	v_cvt_pk_bf16_f32 v19, v20, v21
	v_mul_f32_e32 v20, v38, v0
	v_mul_f32_e32 v21, v39, v0
	v_mul_f32_e32 v22, v8, v22
	v_mul_f32_e32 v23, v9, v23
	v_mul_f32_e32 v20, v6, v20
	v_mul_f32_e32 v21, v7, v21
	v_add_co_u32_e32 v42, vcc, s34, v52
	v_cvt_pk_bf16_f32 v20, v20, v21
	v_cvt_pk_bf16_f32 v21, v22, v23
	global_store_dwordx4 v[50:51], v[18:21], off offset:3072
	v_lshl_add_u64 v[22:23], v[52:53], 0, s[0:1]
	global_load_dwordx4 v[18:21], v[54:55], off
	s_nop 0
	global_load_dwordx4 v[22:25], v[22:23], off offset:16
	v_addc_co_u32_e32 v43, vcc, 0, v53, vcc
	v_add_co_u32_e32 v66, vcc, s2, v52
	v_lshl_add_u64 v[46:47], v[52:53], 0, s[86:87]
	s_nop 0
	v_addc_co_u32_e32 v67, vcc, 0, v53, vcc
	s_waitcnt vmcnt(1)
	v_mov_b32_e32 v34, v19
	s_waitcnt vmcnt(0)
	v_mov_b32_e32 v35, v23
	v_mov_b32_e32 v32, v18
	v_mov_b32_e32 v33, v22
	v_mul_f32_e32 v34, v34, v34
	v_mul_f32_e32 v35, v35, v35
	v_mov_b32_e32 v26, v20
	v_mov_b32_e32 v27, v24
	v_fma_f32 v32, v32, v32, v34
	v_fma_f32 v33, v33, v33, v35
	v_mov_b32_e32 v28, v21
	v_mov_b32_e32 v29, v25
	v_fma_f32 v26, v26, v26, v32
	v_fma_f32 v27, v27, v27, v33
	s_nop 0
	v_fma_f32 v56, v28, v28, v26
	v_fma_f32 v57, v29, v29, v27
	global_load_dwordx4 v[26:29], v[54:55], off offset:2048
	s_nop 0
	global_load_dwordx4 v[30:33], v[30:31], off offset:16
	s_waitcnt vmcnt(1)
	v_mov_b32_e32 v40, v27
	s_waitcnt vmcnt(0)
	v_mov_b32_e32 v41, v31
	v_mov_b32_e32 v38, v26
	v_mov_b32_e32 v39, v30
	v_mul_f32_e32 v40, v40, v40
	v_mul_f32_e32 v41, v41, v41
	v_mov_b32_e32 v34, v28
	v_mov_b32_e32 v35, v32
	v_fma_f32 v38, v38, v38, v40
	v_fma_f32 v39, v39, v39, v41
	v_mov_b32_e32 v36, v29
	v_mov_b32_e32 v37, v33
	v_fma_f32 v34, v34, v34, v38
	v_fma_f32 v35, v35, v35, v39
	v_lshl_add_u64 v[38:39], v[52:53], 0, s[84:85]
	v_fma_f32 v54, v36, v36, v34
	v_fma_f32 v55, v37, v37, v35
	global_load_dwordx4 v[34:37], v[66:67], off offset:-4096
	s_nop 0
	global_load_dwordx4 v[38:41], v[38:39], off offset:16
	s_waitcnt vmcnt(1)
	v_mov_b32_e32 v70, v35
	s_waitcnt vmcnt(0)
	v_mov_b32_e32 v71, v39
	v_mov_b32_e32 v68, v34
	v_mov_b32_e32 v69, v38
	v_mul_f32_e32 v70, v70, v70
	v_mul_f32_e32 v71, v71, v71
	v_mov_b32_e32 v44, v36
	v_mov_b32_e32 v45, v40
	v_fma_f32 v68, v68, v68, v70
	v_fma_f32 v69, v69, v69, v71
	v_mov_b32_e32 v48, v37
	v_mov_b32_e32 v49, v41
	v_fma_f32 v44, v44, v44, v68
	v_fma_f32 v45, v45, v45, v69
	s_nop 0
	v_fma_f32 v68, v48, v48, v44
	v_fma_f32 v69, v49, v49, v45
	global_load_dwordx4 v[42:45], v[42:43], off offset:2048
	s_nop 0
	global_load_dwordx4 v[46:49], v[46:47], off offset:16
	s_waitcnt vmcnt(1)
	v_mov_b32_e32 v76, v43
	s_waitcnt vmcnt(0)
; DI unsigned pack2(float a, float b) { f2_t v = {a, b}; bf2_t r = __builtin_convertvector(v, bf2_t); return __builtin_bit_cast(unsigned, r); }
; DI void norm_rows_bf16(const float* __restrict__ src, const float* __restrict__ g, bf16_t* __restrict__ dst, int item) {
;     ...
;   for (int i = 0; i < 8; ++i) {
;     size_t row = (size_t)item * 32 + wid * 8 + i;
;     const float4* s = (const float4*)(src + row * 1024);
;     float4 v[4]; float ss = 0.f;
; #pragma unroll
;     for (int j = 0; j < 4; ++j) { v[j] = s[2 * lane + (j & 1) + 128 * (j >> 1)]; ss += v[j].x * v[j].x + v[j].y * v[j].y + v[j].z * v[j].z + v[j].w * v[j].w; }
;     ss = wave_sum(ss);
;     float sc = rsqrtf(ss * (1.0f / 1024.0f) + 1e-6f);
; #pragma unroll
;     for (int jj = 0; jj < 2; ++jj) {
;       float4 g0 = ((const float4*)g)[2 * lane + 128 * jj], g1 = ((const float4*)g)[2 * lane + 1 + 128 * jj];
;       const float4 a = v[2 * jj], c = v[2 * jj + 1];
;       uint4 o; o.x = pack2(a.x * sc * g0.x, a.y * sc * g0.y); o.y = pack2(a.z * sc * g0.z, a.w * sc * g0.w);
;       o.z = pack2(c.x * sc * g1.x, c.y * sc * g1.y); o.w = pack2(c.z * sc * g1.z, c.w * sc * g1.w);
;       *(uint4*)(dst + row * 1024 + (2 * lane + 128 * jj) * 4) = o;
;     }
	v_mov_b32_e32 v77, v47
	v_mov_b32_e32 v74, v42
	v_mov_b32_e32 v75, v46
	v_mul_f32_e32 v76, v76, v76
	v_mul_f32_e32 v77, v77, v77
	v_mov_b32_e32 v70, v44
	v_mov_b32_e32 v71, v48
	v_fma_f32 v74, v74, v74, v76
	v_fma_f32 v75, v75, v75, v77
	v_mov_b32_e32 v72, v45
	v_mov_b32_e32 v73, v49
	v_fma_f32 v70, v70, v70, v74
	v_fma_f32 v71, v71, v71, v75
	s_nop 0
	v_fma_f32 v70, v72, v72, v70
	v_fma_f32 v71, v73, v73, v71
	v_mov_b32_e32 v72, v68
	v_mov_b32_e32 v73, v56
	v_mov_b32_e32 v56, v69
	v_add_f32_e32 v56, v72, v56
	v_add_f32_e32 v57, v73, v57
	v_mov_b32_e32 v68, v70
	v_mov_b32_e32 v69, v54
	v_add_f32_e32 v56, v56, v68
	v_add_f32_e32 v57, v57, v69
	v_mov_b32_e32 v54, v71
	v_add_f32_e32 v54, v56, v54
	v_add_f32_e32 v55, v57, v55
	ds_bpermute_b32 v57, v60, v55
	ds_bpermute_b32 v56, v60, v54
	s_waitcnt lgkmcnt(0)
	v_add_f32_e32 v54, v54, v56
	v_add_f32_e32 v55, v55, v57
	ds_bpermute_b32 v57, v61, v55
	ds_bpermute_b32 v56, v61, v54
	s_waitcnt lgkmcnt(0)
	v_add_f32_e32 v54, v54, v56
	v_add_f32_e32 v55, v55, v57
	ds_bpermute_b32 v57, v62, v55
	ds_bpermute_b32 v56, v62, v54
	s_waitcnt lgkmcnt(0)
	v_add_f32_e32 v54, v54, v56
	v_add_f32_e32 v55, v55, v57
	ds_bpermute_b32 v57, v63, v55
	ds_bpermute_b32 v56, v63, v54
	s_waitcnt lgkmcnt(0)
	v_add_f32_e32 v54, v54, v56
	v_add_f32_e32 v55, v55, v57
	ds_bpermute_b32 v57, v64, v55
	ds_bpermute_b32 v56, v64, v54
	s_waitcnt lgkmcnt(0)
	v_add_f32_e32 v54, v54, v56
	v_add_f32_e32 v55, v55, v57
	ds_bpermute_b32 v57, v65, v55
	ds_bpermute_b32 v56, v65, v54
	s_waitcnt lgkmcnt(0)
	v_add_f32_e32 v54, v54, v56
	v_add_f32_e32 v55, v55, v57
	s_nop 0
	v_fma_f32 v54, v54, s14, v58
	v_fma_f32 v55, v55, s14, v58
	s_nop 0
	v_mul_f32_e32 v0, 0x4b800000, v55
	v_cmp_gt_f32_e64 s[0:1], s3, v55
	v_cmp_gt_f32_e32 vcc, s3, v54
	s_nop 0
	v_cndmask_b32_e64 v0, v55, v0, s[0:1]
	v_rsq_f32_e32 v0, v0
	s_nop 0
	v_mul_f32_e32 v55, 0x45800000, v0
	v_cndmask_b32_e64 v0, v0, v55, s[0:1]
	v_mul_f32_e32 v18, v18, v0
	v_mul_f32_e32 v19, v19, v0
	v_mul_f32_e32 v20, v20, v0
	v_mul_f32_e32 v21, v21, v0
	v_mul_f32_e32 v18, v10, v18
	v_mul_f32_e32 v19, v11, v19
	v_mul_f32_e32 v20, v12, v20
	v_mul_f32_e32 v21, v13, v21
	v_cvt_pk_bf16_f32 v18, v18, v19
	v_cvt_pk_bf16_f32 v19, v20, v21
	v_mul_f32_e32 v20, v22, v0
	v_mul_f32_e32 v21, v23, v0
	v_mul_f32_e32 v22, v24, v0
	v_mul_f32_e32 v23, v25, v0
	v_mul_f32_e32 v20, v2, v20
	v_mul_f32_e32 v21, v3, v21
	v_mul_f32_e32 v22, v4, v22
	v_mul_f32_e32 v23, v5, v23
	v_cvt_pk_bf16_f32 v20, v20, v21
	v_cvt_pk_bf16_f32 v21, v22, v23
	v_add_co_u32_e64 v22, s[0:1], s7, v50
	v_mul_f32_e32 v24, v32, v0
	v_mul_f32_e32 v25, v33, v0
	s_nop 0
	v_addc_co_u32_e64 v23, s[0:1], 0, v51, s[0:1]
	v_add_co_u32_e64 v56, s[0:1], s11, v50
	v_mul_f32_e32 v24, v8, v24
	v_mul_f32_e32 v25, v9, v25
	s_nop 0
	v_addc_co_u32_e64 v57, s[0:1], 0, v51, s[0:1]
	global_store_dwordx4 v[56:57], v[18:21], off offset:-4096
	s_mov_b64 s[0:1], 0x4800
	s_nop 0
	v_mul_f32_e32 v18, v26, v0
	v_mul_f32_e32 v19, v27, v0
	v_mul_f32_e32 v20, v28, v0
	v_mul_f32_e32 v21, v29, v0
	v_mul_f32_e32 v18, v14, v18
	v_mul_f32_e32 v19, v15, v19
	v_mul_f32_e32 v20, v16, v20
	v_mul_f32_e32 v21, v17, v21
	v_cvt_pk_bf16_f32 v18, v18, v19
	v_cvt_pk_bf16_f32 v19, v20, v21
	v_mul_f32_e32 v20, v30, v0
	v_mul_f32_e32 v21, v31, v0
	v_mul_f32_e32 v0, 0x4b800000, v54
	v_cndmask_b32_e32 v0, v54, v0, vcc
	v_rsq_f32_e32 v0, v0
	v_mul_f32_e32 v20, v6, v20
	v_mul_f32_e32 v21, v7, v21
	v_lshl_add_u64 v[30:31], v[52:53], 0, s[0:1]
	v_cvt_pk_bf16_f32 v20, v20, v21
	v_cvt_pk_bf16_f32 v21, v24, v25
	global_store_dwordx4 v[22:23], v[18:21], off offset:1024
	s_nop 1
	v_mul_f32_e32 v18, 0x45800000, v0
	v_cndmask_b32_e32 v0, v0, v18, vcc
	v_mul_f32_e32 v18, v34, v0
	v_mul_f32_e32 v19, v35, v0
	v_mul_f32_e32 v20, v36, v0
	v_mul_f32_e32 v21, v37, v0
	v_mul_f32_e32 v18, v10, v18
	v_mul_f32_e32 v19, v11, v19
	v_mul_f32_e32 v20, v12, v20
	v_mul_f32_e32 v21, v13, v21
	v_cvt_pk_bf16_f32 v18, v18, v19
	v_cvt_pk_bf16_f32 v19, v20, v21
	v_mul_f32_e32 v20, v38, v0
	v_mul_f32_e32 v21, v39, v0
	v_mul_f32_e32 v24, v40, v0
	v_mul_f32_e32 v25, v41, v0
	v_mul_f32_e32 v20, v2, v20
	v_mul_f32_e32 v21, v3, v21
	v_mul_f32_e32 v24, v4, v24
	v_mul_f32_e32 v25, v5, v25
	v_cvt_pk_bf16_f32 v20, v20, v21
	v_cvt_pk_bf16_f32 v21, v24, v25
	global_store_dwordx4 v[22:23], v[18:21], off offset:2048
	v_mul_f32_e32 v24, v48, v0
	v_mul_f32_e32 v25, v49, v0
	s_nop 0
	v_mul_f32_e32 v18, v42, v0
	v_mul_f32_e32 v19, v43, v0
	v_mul_f32_e32 v20, v44, v0
	v_mul_f32_e32 v21, v45, v0
	v_mul_f32_e32 v18, v14, v18
	v_mul_f32_e32 v19, v15, v19
	v_mul_f32_e32 v20, v16, v20
	v_mul_f32_e32 v21, v17, v21
	v_cvt_pk_bf16_f32 v18, v18, v19
	v_cvt_pk_bf16_f32 v19, v20, v21
	v_mul_f32_e32 v20, v46, v0
	v_mul_f32_e32 v21, v47, v0
	v_mul_f32_e32 v24, v8, v24
	v_mul_f32_e32 v25, v9, v25
	v_mul_f32_e32 v20, v6, v20
	v_mul_f32_e32 v21, v7, v21
	v_add_co_u32_e32 v42, vcc, s35, v52
	v_cvt_pk_bf16_f32 v20, v20, v21
	v_cvt_pk_bf16_f32 v21, v24, v25
	global_store_dwordx4 v[22:23], v[18:21], off offset:3072
	v_lshl_add_u64 v[22:23], v[52:53], 0, s[90:91]
	global_load_dwordx4 v[18:21], v[66:67], off
	s_nop 0
	global_load_dwordx4 v[22:25], v[22:23], off offset:16
	v_addc_co_u32_e32 v43, vcc, 0, v53, vcc
	v_add_co_u32_e32 v68, vcc, s13, v52
	v_lshl_add_u64 v[46:47], v[52:53], 0, s[82:83]
	s_nop 0
	v_addc_co_u32_e32 v69, vcc, 0, v53, vcc
	s_waitcnt vmcnt(1)
	v_mov_b32_e32 v34, v19
	s_waitcnt vmcnt(0)
; DI unsigned pack2(float a, float b) { f2_t v = {a, b}; bf2_t r = __builtin_convertvector(v, bf2_t); return __builtin_bit_cast(unsigned, r); }
; DI void norm_rows_bf16(const float* __restrict__ src, const float* __restrict__ g, bf16_t* __restrict__ dst, int item) {
;     ...
;   for (int i = 0; i < 8; ++i) {
;     size_t row = (size_t)item * 32 + wid * 8 + i;
;     const float4* s = (const float4*)(src + row * 1024);
;     float4 v[4]; float ss = 0.f;
; #pragma unroll
;     for (int j = 0; j < 4; ++j) { v[j] = s[2 * lane + (j & 1) + 128 * (j >> 1)]; ss += v[j].x * v[j].x + v[j].y * v[j].y + v[j].z * v[j].z + v[j].w * v[j].w; }
;     ss = wave_sum(ss);
;     float sc = rsqrtf(ss * (1.0f / 1024.0f) + 1e-6f);
; #pragma unroll
;     for (int jj = 0; jj < 2; ++jj) {
;       float4 g0 = ((const float4*)g)[2 * lane + 128 * jj], g1 = ((const float4*)g)[2 * lane + 1 + 128 * jj];
;       const float4 a = v[2 * jj], c = v[2 * jj + 1];
;       uint4 o; o.x = pack2(a.x * sc * g0.x, a.y * sc * g0.y); o.y = pack2(a.z * sc * g0.z, a.w * sc * g0.w);
;       o.z = pack2(c.x * sc * g1.x, c.y * sc * g1.y); o.w = pack2(c.z * sc * g1.z, c.w * sc * g1.w);
;       *(uint4*)(dst + row * 1024 + (2 * lane + 128 * jj) * 4) = o;
;     }
	v_mov_b32_e32 v35, v23
	v_mov_b32_e32 v32, v18
	v_mov_b32_e32 v33, v22
	v_mul_f32_e32 v34, v34, v34
	v_mul_f32_e32 v35, v35, v35
	v_mov_b32_e32 v26, v20
	v_mov_b32_e32 v27, v24
	v_fma_f32 v32, v32, v32, v34
	v_fma_f32 v33, v33, v33, v35
	v_mov_b32_e32 v28, v21
	v_mov_b32_e32 v29, v25
	v_fma_f32 v26, v26, v26, v32
	v_fma_f32 v27, v27, v27, v33
	s_nop 0
	v_fma_f32 v54, v28, v28, v26
	v_fma_f32 v55, v29, v29, v27
	global_load_dwordx4 v[26:29], v[66:67], off offset:2048
	s_nop 0
	global_load_dwordx4 v[30:33], v[30:31], off offset:16
	s_waitcnt vmcnt(1)
	v_mov_b32_e32 v40, v27
	s_waitcnt vmcnt(0)
	v_mov_b32_e32 v41, v31
	v_mov_b32_e32 v38, v26
	v_mov_b32_e32 v39, v30
	v_mul_f32_e32 v40, v40, v40
	v_mul_f32_e32 v41, v41, v41
	v_mov_b32_e32 v34, v28
	v_mov_b32_e32 v35, v32
	v_fma_f32 v38, v38, v38, v40
	v_fma_f32 v39, v39, v39, v41
	v_mov_b32_e32 v36, v29
	v_mov_b32_e32 v37, v33
	v_fma_f32 v34, v34, v34, v38
	v_fma_f32 v35, v35, v35, v39
	v_lshl_add_u64 v[38:39], v[52:53], 0, s[42:43]
	v_fma_f32 v66, v36, v36, v34
	v_fma_f32 v67, v37, v37, v35
	global_load_dwordx4 v[34:37], v[68:69], off offset:-4096
	s_nop 0
	global_load_dwordx4 v[38:41], v[38:39], off offset:16
	s_waitcnt vmcnt(1)
	v_mov_b32_e32 v72, v35
	s_waitcnt vmcnt(0)
	v_mov_b32_e32 v73, v39
	v_mov_b32_e32 v70, v34
	v_mov_b32_e32 v71, v38
	v_mul_f32_e32 v72, v72, v72
	v_mul_f32_e32 v73, v73, v73
	v_mov_b32_e32 v44, v36
	v_mov_b32_e32 v45, v40
	v_fma_f32 v70, v70, v70, v72
	v_fma_f32 v71, v71, v71, v73
	v_mov_b32_e32 v48, v37
	v_mov_b32_e32 v49, v41
	v_fma_f32 v44, v44, v44, v70
	v_fma_f32 v45, v45, v45, v71
	s_nop 0
	v_fma_f32 v70, v48, v48, v44
	v_fma_f32 v71, v49, v49, v45
	global_load_dwordx4 v[42:45], v[42:43], off offset:2048
	s_nop 0
	global_load_dwordx4 v[46:49], v[46:47], off offset:16
	s_waitcnt vmcnt(1)
	v_mov_b32_e32 v78, v43
	s_waitcnt vmcnt(0)
	v_mov_b32_e32 v79, v47
	v_mov_b32_e32 v76, v42
	v_mov_b32_e32 v77, v46
	v_mul_f32_e32 v78, v78, v78
	v_mul_f32_e32 v79, v79, v79
	v_mov_b32_e32 v72, v44
	v_mov_b32_e32 v73, v48
	v_fma_f32 v76, v76, v76, v78
	v_fma_f32 v77, v77, v77, v79
	v_mov_b32_e32 v74, v45
	v_mov_b32_e32 v75, v49
	v_fma_f32 v72, v72, v72, v76
	v_fma_f32 v73, v73, v73, v77
	s_nop 0
	v_fma_f32 v72, v74, v74, v72
	v_fma_f32 v73, v75, v75, v73
	v_mov_b32_e32 v74, v70
	v_mov_b32_e32 v75, v54
	v_mov_b32_e32 v54, v71
	v_add_f32_e32 v54, v74, v54
	v_add_f32_e32 v55, v75, v55
	v_mov_b32_e32 v70, v72
	v_mov_b32_e32 v71, v66
	v_add_f32_e32 v54, v54, v70
	v_add_f32_e32 v55, v55, v71
	v_mov_b32_e32 v66, v73
	v_add_f32_e32 v54, v54, v66
	v_add_f32_e32 v55, v55, v67
	ds_bpermute_b32 v67, v60, v55
	ds_bpermute_b32 v66, v60, v54
	s_waitcnt lgkmcnt(0)
	v_add_f32_e32 v54, v54, v66
	v_add_f32_e32 v55, v55, v67
	ds_bpermute_b32 v67, v61, v55
	ds_bpermute_b32 v66, v61, v54
	s_waitcnt lgkmcnt(0)
	v_add_f32_e32 v54, v54, v66
	v_add_f32_e32 v55, v55, v67
	ds_bpermute_b32 v67, v62, v55
	ds_bpermute_b32 v66, v62, v54
	s_waitcnt lgkmcnt(0)
	v_add_f32_e32 v54, v54, v66
	v_add_f32_e32 v55, v55, v67
	ds_bpermute_b32 v67, v63, v55
	ds_bpermute_b32 v66, v63, v54
	s_waitcnt lgkmcnt(0)
	v_add_f32_e32 v54, v54, v66
	v_add_f32_e32 v55, v55, v67
	ds_bpermute_b32 v67, v64, v55
	ds_bpermute_b32 v66, v64, v54
	s_waitcnt lgkmcnt(0)
	v_add_f32_e32 v54, v54, v66
	v_add_f32_e32 v55, v55, v67
	ds_bpermute_b32 v67, v65, v55
	ds_bpermute_b32 v66, v65, v54
	s_waitcnt lgkmcnt(0)
	v_add_f32_e32 v54, v54, v66
	v_add_f32_e32 v55, v55, v67
	s_nop 0
	v_fma_f32 v54, v54, s14, v58
	v_fma_f32 v55, v55, s14, v58
	s_nop 0
	v_mul_f32_e32 v0, 0x4b800000, v55
	v_cmp_gt_f32_e64 s[0:1], s3, v55
	v_cmp_gt_f32_e32 vcc, s3, v54
	s_nop 0
	v_cndmask_b32_e64 v0, v55, v0, s[0:1]
	v_rsq_f32_e32 v0, v0
	s_nop 0
	v_mul_f32_e32 v55, 0x45800000, v0
	v_cndmask_b32_e64 v0, v0, v55, s[0:1]
	v_mul_f32_e32 v18, v18, v0
	v_mul_f32_e32 v19, v19, v0
	v_mul_f32_e32 v20, v20, v0
	v_mul_f32_e32 v21, v21, v0
	v_mul_f32_e32 v18, v10, v18
	v_mul_f32_e32 v19, v11, v19
	v_mul_f32_e32 v20, v12, v20
	v_mul_f32_e32 v21, v13, v21
	v_cvt_pk_bf16_f32 v18, v18, v19
	v_cvt_pk_bf16_f32 v19, v20, v21
	v_mul_f32_e32 v20, v22, v0
	v_mul_f32_e32 v21, v23, v0
	v_mul_f32_e32 v22, v24, v0
	v_mul_f32_e32 v23, v25, v0
	v_mul_f32_e32 v20, v2, v20
	v_mul_f32_e32 v21, v3, v21
	v_mul_f32_e32 v22, v4, v22
	v_mul_f32_e32 v23, v5, v23
	v_cvt_pk_bf16_f32 v20, v20, v21
	v_cvt_pk_bf16_f32 v21, v22, v23
	global_store_dwordx4 v[56:57], v[18:21], off
	v_mul_f32_e32 v22, v32, v0
	v_mul_f32_e32 v23, v33, v0
	s_mov_b64 s[0:1], 0x7000
	v_mul_f32_e32 v18, v26, v0
	v_mul_f32_e32 v19, v27, v0
	v_mul_f32_e32 v20, v28, v0
	v_mul_f32_e32 v21, v29, v0
	v_mul_f32_e32 v18, v14, v18
	v_mul_f32_e32 v19, v15, v19
	v_mul_f32_e32 v20, v16, v20
	v_mul_f32_e32 v21, v17, v21
	v_cvt_pk_bf16_f32 v18, v18, v19
	v_cvt_pk_bf16_f32 v19, v20, v21
	v_mul_f32_e32 v20, v30, v0
	v_mul_f32_e32 v21, v31, v0
	v_mul_f32_e32 v0, 0x4b800000, v54
	v_cndmask_b32_e32 v0, v54, v0, vcc
	v_rsq_f32_e32 v0, v0
	v_mul_f32_e32 v20, v6, v20
	v_mul_f32_e32 v21, v7, v21
	v_mul_f32_e32 v22, v8, v22
	v_mul_f32_e32 v23, v9, v23
	v_cvt_pk_bf16_f32 v20, v20, v21
	v_cvt_pk_bf16_f32 v21, v22, v23
	global_store_dwordx4 v[56:57], v[18:21], off offset:1024
	v_lshl_add_u64 v[30:31], v[52:53], 0, s[28:29]
	s_nop 0
	v_mul_f32_e32 v18, 0x45800000, v0
	v_cndmask_b32_e32 v0, v0, v18, vcc
	v_mul_f32_e32 v18, v34, v0
	v_mul_f32_e32 v19, v35, v0
	v_mul_f32_e32 v20, v36, v0
	v_mul_f32_e32 v21, v37, v0
	v_mul_f32_e32 v18, v10, v18
	v_mul_f32_e32 v19, v11, v19
	v_mul_f32_e32 v20, v12, v20
	v_mul_f32_e32 v21, v13, v21
	v_cvt_pk_bf16_f32 v18, v18, v19
	v_cvt_pk_bf16_f32 v19, v20, v21
	v_mul_f32_e32 v20, v38, v0
	v_mul_f32_e32 v21, v39, v0
	v_mul_f32_e32 v22, v40, v0
	v_mul_f32_e32 v23, v41, v0
	v_mul_f32_e32 v20, v2, v20
	v_mul_f32_e32 v21, v3, v21
	v_mul_f32_e32 v22, v4, v22
	v_mul_f32_e32 v23, v5, v23
	v_cvt_pk_bf16_f32 v20, v20, v21
	v_cvt_pk_bf16_f32 v21, v22, v23
	global_store_dwordx4 v[56:57], v[18:21], off offset:2048
	v_mul_f32_e32 v22, v48, v0
	v_mul_f32_e32 v23, v49, v0
	s_nop 0
	v_mul_f32_e32 v18, v42, v0
	v_mul_f32_e32 v19, v43, v0
	v_mul_f32_e32 v20, v44, v0
	v_mul_f32_e32 v21, v45, v0
	v_mul_f32_e32 v18, v14, v18
	v_mul_f32_e32 v19, v15, v19
	v_mul_f32_e32 v20, v16, v20
	v_mul_f32_e32 v21, v17, v21
	v_cvt_pk_bf16_f32 v18, v18, v19
	v_cvt_pk_bf16_f32 v19, v20, v21
	v_mul_f32_e32 v20, v46, v0
	v_mul_f32_e32 v21, v47, v0
	v_mul_f32_e32 v22, v8, v22
	v_mul_f32_e32 v23, v9, v23
	v_mul_f32_e32 v20, v6, v20
	v_mul_f32_e32 v21, v7, v21
	v_add_co_u32_e32 v42, vcc, s36, v52
	v_cvt_pk_bf16_f32 v20, v20, v21
	v_cvt_pk_bf16_f32 v21, v22, v23
	global_store_dwordx4 v[56:57], v[18:21], off offset:3072
	v_lshl_add_u64 v[22:23], v[52:53], 0, s[26:27]
	global_load_dwordx4 v[18:21], v[68:69], off
	s_nop 0
	global_load_dwordx4 v[22:25], v[22:23], off offset:16
	v_addc_co_u32_e32 v43, vcc, 0, v53, vcc
	v_lshl_add_u64 v[46:47], v[52:53], 0, s[4:5]
	s_waitcnt vmcnt(1)
; DI unsigned pack2(float a, float b) { f2_t v = {a, b}; bf2_t r = __builtin_convertvector(v, bf2_t); return __builtin_bit_cast(unsigned, r); }
; DI void norm_rows_bf16(const float* __restrict__ src, const float* __restrict__ g, bf16_t* __restrict__ dst, int item) {
;     ...
;   for (int i = 0; i < 8; ++i) {
;     size_t row = (size_t)item * 32 + wid * 8 + i;
;     const float4* s = (const float4*)(src + row * 1024);
;     float4 v[4]; float ss = 0.f;
; #pragma unroll
;     for (int j = 0; j < 4; ++j) { v[j] = s[2 * lane + (j & 1) + 128 * (j >> 1)]; ss += v[j].x * v[j].x + v[j].y * v[j].y + v[j].z * v[j].z + v[j].w * v[j].w; }
;     ss = wave_sum(ss);
;     float sc = rsqrtf(ss * (1.0f / 1024.0f) + 1e-6f);
; #pragma unroll
;     for (int jj = 0; jj < 2; ++jj) {
;       float4 g0 = ((const float4*)g)[2 * lane + 128 * jj], g1 = ((const float4*)g)[2 * lane + 1 + 128 * jj];
;       const float4 a = v[2 * jj], c = v[2 * jj + 1];
;       uint4 o; o.x = pack2(a.x * sc * g0.x, a.y * sc * g0.y); o.y = pack2(a.z * sc * g0.z, a.w * sc * g0.w);
;       o.z = pack2(c.x * sc * g1.x, c.y * sc * g1.y); o.w = pack2(c.z * sc * g1.z, c.w * sc * g1.w);
;       *(uint4*)(dst + row * 1024 + (2 * lane + 128 * jj) * 4) = o;
;     }
	v_mov_b32_e32 v34, v19
	s_waitcnt vmcnt(0)
	v_mov_b32_e32 v35, v23
	v_mov_b32_e32 v32, v18
	v_mov_b32_e32 v33, v22
	v_mul_f32_e32 v34, v34, v34
	v_mul_f32_e32 v35, v35, v35
	v_mov_b32_e32 v26, v20
	v_mov_b32_e32 v27, v24
	v_fma_f32 v32, v32, v32, v34
	v_fma_f32 v33, v33, v33, v35
	v_mov_b32_e32 v28, v21
	v_mov_b32_e32 v29, v25
	v_fma_f32 v26, v26, v26, v32
	v_fma_f32 v27, v27, v27, v33
	s_nop 0
	v_fma_f32 v54, v28, v28, v26
	v_fma_f32 v55, v29, v29, v27
	global_load_dwordx4 v[26:29], v[68:69], off offset:2048
	s_nop 0
	global_load_dwordx4 v[30:33], v[30:31], off offset:16
	s_waitcnt vmcnt(1)
	v_mov_b32_e32 v40, v27
	s_waitcnt vmcnt(0)
	v_mov_b32_e32 v41, v31
	v_mov_b32_e32 v38, v26
	v_mov_b32_e32 v39, v30
	v_mul_f32_e32 v40, v40, v40
	v_mul_f32_e32 v41, v41, v41
	v_mov_b32_e32 v34, v28
	v_mov_b32_e32 v35, v32
	v_fma_f32 v38, v38, v38, v40
	v_fma_f32 v39, v39, v39, v41
	v_mov_b32_e32 v36, v29
	v_mov_b32_e32 v37, v33
	v_fma_f32 v34, v34, v34, v38
	v_fma_f32 v35, v35, v35, v39
	v_lshl_add_u64 v[38:39], v[52:53], 0, s[0:1]
	v_fma_f32 v56, v36, v36, v34
	v_fma_f32 v57, v37, v37, v35
	global_load_dwordx4 v[34:37], v[42:43], off
	s_nop 0
	global_load_dwordx4 v[38:41], v[38:39], off offset:16
	s_waitcnt vmcnt(1)
	v_mov_b32_e32 v66, v35
	s_waitcnt vmcnt(0)
	v_mov_b32_e32 v67, v39
	v_mov_b32_e32 v52, v34
	v_mov_b32_e32 v53, v38
	v_mul_f32_e32 v66, v66, v66
	v_mul_f32_e32 v67, v67, v67
	v_mov_b32_e32 v44, v36
	v_mov_b32_e32 v45, v40
	v_fma_f32 v52, v52, v52, v66
	v_fma_f32 v53, v53, v53, v67
	v_mov_b32_e32 v48, v37
	v_mov_b32_e32 v49, v41
	v_fma_f32 v44, v44, v44, v52
	v_fma_f32 v45, v45, v45, v53
	s_nop 0
	v_fma_f32 v52, v48, v48, v44
	v_fma_f32 v53, v49, v49, v45
	global_load_dwordx4 v[42:45], v[42:43], off offset:2048
	s_nop 0
	global_load_dwordx4 v[46:49], v[46:47], off offset:16
	s_waitcnt vmcnt(1)
	v_mov_b32_e32 v72, v43
	s_waitcnt vmcnt(0)
	v_mov_b32_e32 v73, v47
	v_mov_b32_e32 v70, v42
	v_mov_b32_e32 v71, v46
	v_mul_f32_e32 v72, v72, v72
	v_mul_f32_e32 v73, v73, v73
	v_mov_b32_e32 v66, v44
	v_mov_b32_e32 v67, v48
	v_fma_f32 v70, v70, v70, v72
	v_fma_f32 v71, v71, v71, v73
	v_mov_b32_e32 v68, v45
	v_mov_b32_e32 v69, v49
	v_fma_f32 v66, v66, v66, v70
	v_fma_f32 v67, v67, v67, v71
	s_nop 0
	v_fma_f32 v66, v68, v68, v66
	v_fma_f32 v67, v69, v69, v67
	v_mov_b32_e32 v68, v52
	v_mov_b32_e32 v69, v54
	v_mov_b32_e32 v54, v53
	v_add_f32_e32 v52, v68, v54
	v_add_f32_e32 v53, v69, v55
	v_mov_b32_e32 v54, v66
	v_mov_b32_e32 v55, v56
	v_add_f32_e32 v52, v52, v54
	v_add_f32_e32 v53, v53, v55
	v_mov_b32_e32 v56, v67
	v_add_f32_e32 v52, v52, v56
	v_add_f32_e32 v53, v53, v57
	ds_bpermute_b32 v55, v60, v53
	ds_bpermute_b32 v54, v60, v52
	s_waitcnt lgkmcnt(0)
	v_add_f32_e32 v52, v52, v54
	v_add_f32_e32 v53, v53, v55
	ds_bpermute_b32 v55, v61, v53
	ds_bpermute_b32 v54, v61, v52
	s_waitcnt lgkmcnt(0)
	v_add_f32_e32 v52, v52, v54
	v_add_f32_e32 v53, v53, v55
	ds_bpermute_b32 v55, v62, v53
	ds_bpermute_b32 v54, v62, v52
	s_waitcnt lgkmcnt(0)
	v_add_f32_e32 v52, v52, v54
	v_add_f32_e32 v53, v53, v55
	ds_bpermute_b32 v55, v63, v53
	ds_bpermute_b32 v54, v63, v52
	s_waitcnt lgkmcnt(0)
	v_add_f32_e32 v52, v52, v54
	v_add_f32_e32 v53, v53, v55
	ds_bpermute_b32 v55, v64, v53
	ds_bpermute_b32 v54, v64, v52
	s_waitcnt lgkmcnt(0)
	v_add_f32_e32 v52, v52, v54
	v_add_f32_e32 v53, v53, v55
	ds_bpermute_b32 v55, v65, v53
	ds_bpermute_b32 v54, v65, v52
	s_waitcnt lgkmcnt(0)
	v_add_f32_e32 v52, v52, v54
	v_add_f32_e32 v53, v53, v55
	s_nop 0
	v_fma_f32 v52, v52, s14, v58
	v_fma_f32 v53, v53, s14, v58
	s_nop 0
	v_mul_f32_e32 v0, 0x4b800000, v53
	v_cmp_gt_f32_e64 s[0:1], s3, v53
	v_cmp_gt_f32_e32 vcc, s3, v52
	s_nop 0
	v_cndmask_b32_e64 v0, v53, v0, s[0:1]
	v_rsq_f32_e32 v0, v0
	s_nop 0
	v_mul_f32_e32 v53, 0x45800000, v0
	v_cndmask_b32_e64 v0, v0, v53, s[0:1]
	v_mul_f32_e32 v18, v18, v0
	v_mul_f32_e32 v19, v19, v0
	v_mul_f32_e32 v20, v20, v0
	v_mul_f32_e32 v21, v21, v0
	v_mul_f32_e32 v18, v10, v18
	v_mul_f32_e32 v19, v11, v19
	v_mul_f32_e32 v20, v12, v20
	v_mul_f32_e32 v21, v13, v21
	v_cvt_pk_bf16_f32 v18, v18, v19
	v_cvt_pk_bf16_f32 v19, v20, v21
	v_mul_f32_e32 v20, v22, v0
	v_mul_f32_e32 v21, v23, v0
	v_mul_f32_e32 v22, v24, v0
	v_mul_f32_e32 v23, v25, v0
	v_mul_f32_e32 v20, v2, v20
	v_mul_f32_e32 v21, v3, v21
	v_mul_f32_e32 v22, v4, v22
	v_mul_f32_e32 v23, v5, v23
	v_cvt_pk_bf16_f32 v20, v20, v21
	v_cvt_pk_bf16_f32 v21, v22, v23
	v_add_co_u32_e64 v22, s[0:1], s34, v50
	v_mul_f32_e32 v24, v32, v0
	v_mul_f32_e32 v25, v33, v0
	s_nop 0
	v_addc_co_u32_e64 v23, s[0:1], 0, v51, s[0:1]
	global_store_dwordx4 v[22:23], v[18:21], off
	v_mul_f32_e32 v24, v8, v24
	v_mul_f32_e32 v25, v9, v25
	s_nop 0
	v_mul_f32_e32 v18, v26, v0
	v_mul_f32_e32 v19, v27, v0
	v_mul_f32_e32 v20, v28, v0
	v_mul_f32_e32 v21, v29, v0
	v_mul_f32_e32 v18, v14, v18
	v_mul_f32_e32 v19, v15, v19
	v_mul_f32_e32 v20, v16, v20
	v_mul_f32_e32 v21, v17, v21
	v_cvt_pk_bf16_f32 v18, v18, v19
	v_cvt_pk_bf16_f32 v19, v20, v21
	v_mul_f32_e32 v20, v30, v0
	v_mul_f32_e32 v21, v31, v0
	v_mul_f32_e32 v0, 0x4b800000, v52
	v_cndmask_b32_e32 v0, v52, v0, vcc
	v_rsq_f32_e32 v0, v0
	v_mul_f32_e32 v20, v6, v20
	v_mul_f32_e32 v21, v7, v21
	s_nop 0
	v_cvt_pk_bf16_f32 v20, v20, v21
	v_cvt_pk_bf16_f32 v21, v24, v25
	global_store_dwordx4 v[22:23], v[18:21], off offset:1024
	s_nop 1
	v_mul_f32_e32 v18, 0x45800000, v0
	v_cndmask_b32_e32 v0, v0, v18, vcc
	v_mul_f32_e32 v18, v34, v0
	v_mul_f32_e32 v19, v35, v0
	s_nop 0
	v_mul_f32_e32 v10, v10, v18
	v_mul_f32_e32 v11, v11, v19
	v_mul_f32_e32 v18, v36, v0
	v_mul_f32_e32 v19, v37, v0
	v_cvt_pk_bf16_f32 v10, v10, v11
	v_mul_f32_e32 v12, v12, v18
	v_mul_f32_e32 v13, v13, v19
	s_nop 0
	v_cvt_pk_bf16_f32 v11, v12, v13
	v_mul_f32_e32 v12, v38, v0
	v_mul_f32_e32 v13, v39, v0
	s_nop 0
	v_mul_f32_e32 v2, v2, v12
	v_mul_f32_e32 v3, v3, v13
	s_nop 0
	v_cvt_pk_bf16_f32 v12, v2, v3
	v_mul_f32_e32 v2, v40, v0
	v_mul_f32_e32 v3, v41, v0
	s_nop 0
	v_mul_f32_e32 v2, v4, v2
	v_mul_f32_e32 v3, v5, v3
	v_mul_f32_e32 v4, v44, v0
	v_mul_f32_e32 v5, v45, v0
	v_cvt_pk_bf16_f32 v13, v2, v3
	v_mul_f32_e32 v2, v42, v0
	v_mul_f32_e32 v3, v43, v0
	v_mul_f32_e32 v4, v16, v4
	v_mul_f32_e32 v5, v17, v5
	v_mul_f32_e32 v2, v14, v2
	v_mul_f32_e32 v3, v15, v3
	global_store_dwordx4 v[22:23], v[10:13], off offset:2048
	v_cvt_pk_bf16_f32 v2, v2, v3
	v_cvt_pk_bf16_f32 v3, v4, v5
	v_mul_f32_e32 v4, v46, v0
	v_mul_f32_e32 v5, v47, v0
	s_nop 0
	v_mul_f32_e32 v4, v6, v4
	v_mul_f32_e32 v5, v7, v5
	v_mul_f32_e32 v6, v48, v0
	v_mul_f32_e32 v7, v49, v0
	v_cvt_pk_bf16_f32 v4, v4, v5
	v_mul_f32_e32 v6, v8, v6
	v_mul_f32_e32 v7, v9, v7
	s_nop 0
	v_cvt_pk_bf16_f32 v5, v6, v7
	global_store_dwordx4 v[22:23], v[2:5], off offset:3072
	s_cbranch_scc0 .LBB0_334

; DI unsigned xb_ld(unsigned* p)              { return __hip_atomic_load(p, __ATOMIC_RELAXED, __HIP_MEMORY_SCOPE_AGENT); }
; DI void xcd_barrier_complete(unsigned* bar, unsigned x, unsigned& nloc, unsigned& nx) {
;   const unsigned G = gridDim.x * gridDim.y * gridDim.z;
;   unsigned sum, cnt, mine, sp = 0u;
;   for (;;) {
;     sum = 0u; cnt = 0u; mine = 0u;
; #pragma unroll
;     for (unsigned j = 0; j < 16; ++j) { const unsigned c = xb_ld(&bar[XB_XCNT(j)]); sum += c; cnt += (c > 0u) ? 1u : 0u; mine = (j == x) ? c : mine; }
;     if (sum == G) break;
;     __builtin_amdgcn_s_sleep(1);
;     if ((++sp & 255u) == 0u) { if (xb_ld(&bar[XB_TMO])) break; if (sp > XB_SPIN_CAP) { atomicAdd(&bar[XB_TMO], 1u); break; } }
;   }
.LBB0_340:
	v_readlane_b32 s12, v253, 58
	v_readlane_b32 s13, v253, 59
	v_readlane_b32 s7, v255, 12
	s_mov_b64 s[22:23], -1
	s_mov_b64 s[24:25], -1
	s_nop 1
	global_load_dword v0, v1, s[12:13] sc1
	v_readlane_b32 s12, v253, 60
	v_readlane_b32 s13, v253, 61
	s_waitcnt lgkmcnt(0)
	s_nop 3
	global_load_dword v2, v1, s[12:13] sc1
	v_readlane_b32 s12, v253, 62
	v_readlane_b32 s13, v253, 63
	s_waitcnt vmcnt(0)
	v_add_u32_e32 v17, v2, v0
	s_nop 2
	global_load_dword v3, v1, s[12:13] sc1
	v_readlane_b32 s12, v254, 0
	v_readlane_b32 s13, v254, 1
	s_waitcnt vmcnt(0)
	v_add_u32_e32 v17, v17, v3
	s_nop 2
	global_load_dword v4, v1, s[12:13] sc1
	v_readlane_b32 s12, v254, 2
	v_readlane_b32 s13, v254, 3
	s_waitcnt vmcnt(0)
	v_add_u32_e32 v17, v17, v4
	s_nop 2
	global_load_dword v5, v1, s[12:13] sc1
	v_readlane_b32 s12, v254, 4
	v_readlane_b32 s13, v254, 5
	s_waitcnt vmcnt(0)
	v_add_u32_e32 v17, v17, v5
	s_nop 2
	global_load_dword v6, v1, s[12:13] sc1
	v_readlane_b32 s12, v254, 6
	v_readlane_b32 s13, v254, 7
	s_waitcnt vmcnt(0)
	v_add_u32_e32 v17, v17, v6
	s_nop 2
	global_load_dword v7, v1, s[12:13] sc1
	v_readlane_b32 s12, v254, 8
	v_readlane_b32 s13, v254, 9
	s_waitcnt vmcnt(0)
	v_add_u32_e32 v17, v17, v7
	s_nop 2
	global_load_dword v8, v1, s[12:13] sc1
	v_readlane_b32 s12, v254, 10
	v_readlane_b32 s13, v254, 11
	s_waitcnt vmcnt(0)
	v_add_u32_e32 v17, v17, v8
	s_nop 2
	global_load_dword v9, v1, s[12:13] sc1
	v_readlane_b32 s12, v254, 12
	v_readlane_b32 s13, v254, 13
	s_waitcnt vmcnt(0)
	v_add_u32_e32 v17, v17, v9
	s_nop 2
	global_load_dword v10, v1, s[12:13] sc1
	v_readlane_b32 s12, v254, 14
	v_readlane_b32 s13, v254, 15
	s_waitcnt vmcnt(0)
	v_add_u32_e32 v17, v17, v10
	s_nop 2
	global_load_dword v11, v1, s[12:13] sc1
	v_readlane_b32 s12, v254, 16
	v_readlane_b32 s13, v254, 17
	s_waitcnt vmcnt(0)
	v_add_u32_e32 v17, v17, v11
	s_nop 2
	global_load_dword v12, v1, s[12:13] sc1
	v_readlane_b32 s12, v254, 18
	v_readlane_b32 s13, v254, 19
	s_waitcnt vmcnt(0)
	v_add_u32_e32 v17, v17, v12
	s_nop 2
	global_load_dword v13, v1, s[12:13] sc1
	v_readlane_b32 s12, v254, 20
	v_readlane_b32 s13, v254, 21
	s_waitcnt vmcnt(0)
	v_add_u32_e32 v17, v17, v13
	s_nop 2
	global_load_dword v14, v1, s[12:13] sc1
	v_readlane_b32 s12, v254, 22
	v_readlane_b32 s13, v254, 23
	s_waitcnt vmcnt(0)
	v_add_u32_e32 v17, v17, v14
	s_nop 2
	global_load_dword v15, v1, s[12:13] sc1
	v_readlane_b32 s12, v254, 24
	v_readlane_b32 s13, v254, 25
	s_waitcnt vmcnt(0)
	v_add_u32_e32 v17, v17, v15
	s_nop 2
	global_load_dword v16, v1, s[12:13] sc1
	s_waitcnt vmcnt(0)
	v_add_u32_e32 v17, v17, v16
	v_cmp_eq_u32_e32 vcc, s7, v17
	s_cbranch_vccnz .LBB0_339
	s_and_b32 s7, s6, 0xff
	s_cmp_eq_u32 s7, 0
	s_mov_b64 s[26:27], -1
	s_nop 0
	s_cbranch_scc0 .LBB0_344
	v_readlane_b32 s12, v253, 56
	v_readlane_b32 s13, v253, 57
	s_nop 4
	global_load_dword v17, v1, s[12:13] sc1
	s_waitcnt vmcnt(0)
	v_cmp_eq_u32_e32 vcc, 0, v17
	s_cbranch_vccnz .LBB0_346
	s_mov_b64 s[26:27], 0

; DI unsigned xb_ld(unsigned* p)              { return __hip_atomic_load(p, __ATOMIC_RELAXED, __HIP_MEMORY_SCOPE_AGENT); }
; DI unsigned xb_add(unsigned* p, unsigned v) { return __hip_atomic_fetch_add(p, v, __ATOMIC_RELAXED, __HIP_MEMORY_SCOPE_AGENT); }
; #define XB_SPIN(cond, bar) do { unsigned _sp = 0; while (cond) { __builtin_amdgcn_s_sleep(1); \
;     if ((++_sp & 255u) == 0u) { if (xb_ld(&(bar)[XB_TMO])) break; if (_sp > XB_SPIN_CAP) { atomicAdd(&(bar)[XB_TMO], 1u); break; } } } } while (0)
; DI void xcd_barrier(const XcdBarrier& b) {
;     ...
;       else XB_SPIN(xb_ld(&bar[XB_TOPGEN]) == tg, bar);
;       __builtin_amdgcn_fence(__ATOMIC_ACQUIRE, "agent");
;       xb_add(&bar[XB_XGEN(b.x)], 1u);
;       asm volatile("s_waitcnt vmcnt(0)" ::: "memory");
;     } else {
;       XB_SPIN(xb_ld(&bar[XB_XGEN(b.x)]) == gen, bar);
.LBB0_358:
	s_and_b32 s7, s6, 0xff
	s_mov_b64 s[30:31], -1
	s_cmp_lg_u32 s7, 0
	s_mov_b64 vcc, -1
	s_nop 0
	s_cbranch_scc1 .LBB0_361
	v_readlane_b32 s12, v253, 56
	v_readlane_b32 s13, v253, 57
	s_nop 4
	global_load_dword v2, v1, s[12:13] sc1
	s_waitcnt vmcnt(0)
	v_cmp_eq_u32_e32 vcc, 0, v2
	s_cbranch_vccnz .LBB0_363
	s_mov_b64 vcc, 0
	s_mov_b64 s[38:39], -1

; DI unsigned xb_ld(unsigned* p)              { return __hip_atomic_load(p, __ATOMIC_RELAXED, __HIP_MEMORY_SCOPE_AGENT); }
; DI unsigned xb_add(unsigned* p, unsigned v) { return __hip_atomic_fetch_add(p, v, __ATOMIC_RELAXED, __HIP_MEMORY_SCOPE_AGENT); }
; #define XB_SPIN(cond, bar) do { unsigned _sp = 0; while (cond) { __builtin_amdgcn_s_sleep(1); \
;     if ((++_sp & 255u) == 0u) { if (xb_ld(&(bar)[XB_TMO])) break; if (_sp > XB_SPIN_CAP) { atomicAdd(&(bar)[XB_TMO], 1u); break; } } } } while (0)
; DI void xcd_barrier(const XcdBarrier& b) {
;     ...
;       else XB_SPIN(xb_ld(&bar[XB_TOPGEN]) == tg, bar);
;       __builtin_amdgcn_fence(__ATOMIC_ACQUIRE, "agent");
;       xb_add(&bar[XB_XGEN(b.x)], 1u);
;       asm volatile("s_waitcnt vmcnt(0)" ::: "memory");
;     } else {
;       XB_SPIN(xb_ld(&bar[XB_XGEN(b.x)]) == gen, bar);
.LBB0_375:
	s_and_b32 s7, s6, 0xff
	s_mov_b64 s[30:31], -1
	s_cmp_lg_u32 s7, 0
	s_mov_b64 s[34:35], -1
	s_nop 0
	s_cbranch_scc1 .LBB0_378
	v_readlane_b32 s12, v253, 56
	v_readlane_b32 s13, v253, 57
	s_nop 4
	global_load_dword v2, v1, s[12:13] sc1
	s_waitcnt vmcnt(0)
	v_cmp_eq_u32_e32 vcc, 0, v2
	s_cbranch_vccnz .LBB0_380
	s_mov_b64 s[34:35], 0
	s_mov_b64 s[38:39], -1
